# GEMM phases: one static s_setprio 1 for the younger wave half (waves 4-7) per phase, per-K-phase priority flips removed
# speedup vs baseline: 1.0056x; 1.0056x over previous
; #define PG8_STAGE(bufoff, gbase, voff) do { _Pragma("unroll") for (int _i = 0; _i < 2; ++_i) \
;         __builtin_amdgcn_global_load_lds((const unsigned*)((const char*)(gbase) + (voff)[_i]), (LAS unsigned*)(lds + (bufoff) + ldsw + _i * 8192), 16, 0, 0); } while (0)
; #define PG8_WAIT_V(n) asm volatile("s_waitcnt vmcnt(" #n ")" ::: "memory")
; #define PG8_BAR __builtin_amdgcn_s_barrier()
;     __device__ __forceinline__ const char* aptr(const Unit& u) const { return (const char*)(A + (size_t)u.pm * 256 * 2048); }
; template <class Epi, class Sched>
; __device__ __forceinline__ void gemm_phase(LAS unsigned char* lds, const int K, const int lda, Sched& S, const Epi& E) {
;     const int tid = opaque_tid(), wid = __builtin_amdgcn_readfirstlane(tid >> 6), lane = tid & 63, wr = wid >> 2, wc = wid & 3, fr = lane & 15, fq = lane >> 4;
;     const int nt = K / BK;
;     unsigned voffA[2], voffB[2];
; #pragma unroll
;     for (int i = 0; i < 2; ++i) { int R, C; stage_rc(tid * 16 + i * 8192, R, C); const int Rb = (R & ~31) + perm32(R & 31);
;         voffA[i] = (unsigned)(R * lda + C) * 2u; voffB[i] = (unsigned)(Rb * K + C) * 2u; }
;     const size_t kstep = (size_t)(BK * 2);
;     const size_t hstepA = (size_t)HALF * lda * 2, hstepB = (size_t)HALF * K * 2;
;     const unsigned ldsw = (unsigned)wid * 1024u;
;     const int aoff = lds_byte(wr * 64 + fr, fq * 8), boff = lds_byte(wc * 32 + fr, fq * 8);
;     ...
;     Unit cur, nxt; int ui = 0;
;     if (!S.next(0, cur)) return;
;     f32x4 acc[2][2][4][2];
; #pragma unroll
;     for (int a = 0; a < 2; ++a)
; #pragma unroll
;         for (int b = 0; b < 2; ++b)
; #pragma unroll
;             for (int m = 0; m < 4; ++m)
; #pragma unroll
;                 for (int n = 0; n < 2; ++n) acc[a][b][m][n] = (f32x4){0.f, 0.f, 0.f, 0.f};
;     bf16x8 At[4][2], B0[2][2], B1[2][2];
;     const char* cA = S.aptr(cur); const char* cB = S.bptr(cur);
;     PG8_STAGE(PG8_SB(0, 0), cB, voffB); PG8_STAGE(PG8_SA(0, 0), cA, voffA); PG8_STAGE(PG8_SB(0, 1), cB + hstepB, voffB); PG8_STAGE(PG8_SA(0, 1), cA + hstepA, voffA);
;     if (wr == 1) PG8_BAR;
;     PG8_WAIT_V(4); PG8_BAR;
;     PG8_STAGE(PG8_SB(1, 0), cB + kstep, voffB); PG8_STAGE(PG8_SA(1, 0), cA + kstep, voffA); PG8_STAGE(PG8_SB(1, 1), cB + hstepB + kstep, voffB);
;     PG8_WAIT_V(6); PG8_BAR;
.LBB0_87:
	s_add_u32 s0, s74, 0xe085000
	s_addc_u32 s1, s75, 0
	v_writelane_b32 v252, s0, 40
	v_cndmask_b32_e64 v0, 0, 1, s[4:5]
	s_andn2_b64 vcc, exec, s[4:5]
	v_writelane_b32 v252, s1, 41
	v_cmp_ne_u32_e64 s[0:1], 1, v0
	s_nop 1
	v_writelane_b32 v252, s0, 42
	s_nop 1
	v_writelane_b32 v252, s1, 43
	s_cbranch_vccnz .LBB0_203
	v_ashrrev_i32_e32 v1, 31, v8
	v_lshrrev_b32_e32 v1, 26, v1
	v_add_u32_e32 v1, v8, v1
	v_ashrrev_i32_e32 v9, 6, v1
	v_bfe_i32 v1, v8, 27, 1
	v_lshlrev_b32_e32 v0, 4, v8
	v_lshrrev_b32_e32 v1, 22, v1
	v_add_u32_e32 v1, v0, v1
	v_and_b32_e32 v1, 0xfffffc00, v1
	v_sub_u32_e32 v1, v0, v1
	v_lshrrev_b32_e32 v2, 4, v1
	v_bitop3_b32 v2, v2, v1, 32 bitop3:0x6c
	v_ashrrev_i32_e32 v1, 31, v1
	v_lshrrev_b32_e32 v1, 26, v1
	v_add_u32_e32 v1, v2, v1
	v_ashrrev_i32_e32 v10, 6, v1
	v_lshlrev_b32_e32 v3, 3, v9
	v_mul_i32_i24_e32 v4, 64, v10
	v_and_b32_e32 v3, -16, v3
	v_sub_u32_e32 v2, v2, v4
	v_mov_b32_e32 v4, 1
	v_add_u32_e32 v1, v10, v3
	v_lshlrev_b32_e32 v3, 5, v9
	v_ashrrev_i16_sdwa v2, v4, sext(v2) dst_sel:DWORD dst_unused:UNUSED_PAD src0_sel:DWORD src1_sel:BYTE_0
	v_and_b32_e32 v3, 32, v3
	v_bfe_i32 v11, v2, 0, 16
	v_and_b32_e32 v6, 3, v10
	s_mov_b32 s0, 0xfffe0
	v_add_lshl_u32 v3, v3, v11, 1
	v_add_u32_e32 v0, 0x2000, v0
	v_lshlrev_b32_e32 v2, 1, v1
	v_lshrrev_b32_e32 v5, 2, v1
	v_and_or_b32 v6, v1, s0, v6
	v_lshl_add_u32 v128, v1, 12, v3
	v_ashrrev_i32_e32 v1, 31, v0
	v_lshrrev_b32_e32 v1, 22, v1
	v_add_u32_e32 v1, v0, v1
	v_ashrrev_i32_e32 v12, 10, v1
	v_mul_i32_i24_e32 v1, 0x400, v12
	v_sub_u32_e32 v0, v0, v1
	v_and_b32_e32 v2, 24, v2
	v_and_b32_e32 v5, 4, v5
	v_lshrrev_b32_e32 v1, 4, v0
	v_or3_b32 v2, v6, v5, v2
	v_bitop3_b32 v0, v1, v0, 32 bitop3:0x6c
	v_lshl_add_u32 v130, v2, 12, v3
	v_ashrrev_i32_e32 v2, 31, v0
	v_lshrrev_b32_e32 v2, 26, v2
	v_add_u32_e32 v2, v0, v2
	v_lshlrev_b32_e32 v1, 3, v12
	v_ashrrev_i32_e32 v13, 6, v2
	v_and_b32_e32 v2, 0xc0, v2
	v_and_b32_e32 v1, -16, v1
	v_sub_u32_e32 v0, v0, v2
	v_add_u32_e32 v1, v13, v1
	v_ashrrev_i16_sdwa v0, v4, sext(v0) dst_sel:DWORD dst_unused:UNUSED_PAD src0_sel:DWORD src1_sel:BYTE_0
	v_and_b32_e32 v4, 3, v13
	s_ashr_i32 s4, s14, 6
	s_ashr_i32 s63, s62, 31
	s_ashr_i32 s3, s2, 31
	s_ashr_i32 s6, s14, 8
	v_and_or_b32 v4, v1, s0, v4
	s_lshl_b32 s0, s4, 10
	s_lshl_b64 s[10:11], s[62:63], 20
	s_lshl_b64 s[12:13], s[2:3], 20
	v_readlane_b32 s16, v252, 17
	v_readlane_b32 s17, v252, 18
	s_add_u32 s68, s16, s12
	v_lshlrev_b32_e32 v3, 5, v12
	v_bfe_i32 v14, v0, 0, 16
	v_lshlrev_b32_e32 v0, 1, v1
	v_lshrrev_b32_e32 v2, 2, v1
	s_addc_u32 s69, s17, s13
	s_add_i32 s1, s0, 0
	v_and_b32_e32 v3, 32, v3
	v_and_b32_e32 v0, 24, v0
	v_and_b32_e32 v2, 4, v2
	s_add_i32 m0, s1, 0x10000
	v_or3_b32 v0, v4, v2, v0
	v_add_lshl_u32 v2, v3, v14, 1
	global_load_lds_dwordx4 v130, s[68:69]
	s_add_i32 m0, s1, 0x12000
	v_lshl_add_u32 v134, v0, 12, v2
	s_add_u32 s66, s34, s10
	global_load_lds_dwordx4 v134, s[68:69]
	s_addc_u32 s67, s35, s11
	s_mov_b32 m0, s1
	s_add_i32 s15, s1, 0x2000
	v_lshl_add_u32 v132, v1, 12, v2
	global_load_lds_dwordx4 v128, s[66:67]
	s_mov_b32 m0, s15
	s_add_u32 s10, s68, 0x80000
	global_load_lds_dwordx4 v132, s[66:67]
	s_addc_u32 s11, s69, 0
	s_add_i32 m0, s1, 0x14000
	v_mov_b32_e32 v137, 0
	global_load_lds_dwordx4 v130, s[10:11]
	s_add_i32 m0, s1, 0x16000
	v_mov_b32_e32 v131, v137
	global_load_lds_dwordx4 v134, s[10:11]
	s_add_u32 s10, s66, 0x80000
	s_addc_u32 s11, s67, 0
	s_add_i32 s16, s1, 0x4000
	s_mov_b32 m0, s16
	s_add_i32 s17, s1, 0x6000
	global_load_lds_dwordx4 v128, s[10:11]
	s_mov_b32 m0, s17
	v_mov_b32_e32 v135, v137
	global_load_lds_dwordx4 v132, s[10:11]
	v_mov_b32_e32 v129, v137
	v_mov_b32_e32 v133, v137
	s_mov_b32 s3, 0
	v_lshl_add_u64 v[6:7], s[68:69], 0, v[130:131]
	v_lshl_add_u64 v[4:5], s[68:69], 0, v[134:135]
	v_lshl_add_u64 v[2:3], s[66:67], 0, v[128:129]
	s_cmp_lg_u32 s6, 1
	v_lshl_add_u64 v[0:1], s[66:67], 0, v[132:133]
	s_cbranch_scc1 .LBB0_90
	s_setprio 1
	s_nop 0
	s_nop 0
	s_nop 0
	s_nop 0
	s_nop 0
	s_nop 0
	s_nop 0
	s_barrier

; #define PG8_STAGE(bufoff, gbase, voff) do { _Pragma("unroll") for (int _i = 0; _i < 2; ++_i) \
;         __builtin_amdgcn_global_load_lds((const unsigned*)((const char*)(gbase) + (voff)[_i]), (LAS unsigned*)(lds + (bufoff) + ldsw + _i * 8192), 16, 0, 0); } while (0)
; #define PG8_LDA(dst, b, h) do { _Pragma("unroll") for (int m = 0; m < 4; ++m) _Pragma("unroll") for (int k = 0; k < 2; ++k) dst[m][k] = *(const LAS bf16x8*)(lds + PG8_SA(b, h) + aoff + m * 2048 + k * 1024); } while (0)
; #define PG8_LDB(dst, b, h) do { _Pragma("unroll") for (int n = 0; n < 2; ++n) _Pragma("unroll") for (int k = 0; k < 2; ++k) dst[n][k] = *(const LAS bf16x8*)(lds + PG8_SB(b, h) + boff + n * 2048 + k * 1024); } while (0)
; #define PG8_MMA(ai, bj, At, Bt) do { __builtin_amdgcn_s_setprio(1); _Pragma("unroll") for (int m = 0; m < 4; ++m) _Pragma("unroll") for (int n = 0; n < 2; ++n) _Pragma("unroll") for (int k = 0; k < 2; ++k) \
;         acc[ai][bj][m][n] = __builtin_amdgcn_mfma_f32_16x16x32_bf16(Bt[n][k], At[m][k], acc[ai][bj][m][n], 0, 0, 0); __builtin_amdgcn_s_setprio(0); } while (0)
; #define PG8_WAIT_L(n) asm volatile("s_waitcnt lgkmcnt(" #n ")" ::: "memory")
; #define PG8_BAR __builtin_amdgcn_s_barrier()
; #define PG8_SCHED __builtin_amdgcn_sched_barrier(0)
; template <class Epi, class Sched>
; __device__ __forceinline__ void gemm_phase(LAS unsigned char* lds, const int K, const int lda, Sched& S, const Epi& E) {
;     ...
;             PG8_LDB(B0, 0, 0); PG8_SCHED; PG8_LDA(At, 0, 0); PG8_STAGE(PG8_SA(1, 1), a1 + hstepA, voffA);
;             PG8_WAIT_L(8); PG8_BAR; PG8_WAIT_L(0); PG8_MMA(0, 0, At, B0); PG8_BAR; PG8_SCHED;
;             PG8_LDB(B1, 0, 1); PG8_STAGE(PG8_SB(0, 0), b2, voffB);
;             PG8_BAR; PG8_WAIT_L(0); PG8_MMA(0, 1, At, B1); PG8_BAR;
;             PG8_LDA(At, 0, 1); PG8_STAGE(PG8_SA(0, 0), a2, voffA);
;             PG8_BAR; PG8_WAIT_L(0); PG8_MMA(1, 0, At, B0); PG8_BAR; PG8_SCHED;
.LBB0_101:
	ds_read_b128 v[148:151], v145
	ds_read_b128 v[152:155], v145 offset:1024
	ds_read_b128 v[156:159], v145 offset:2048
	ds_read_b128 v[160:163], v145 offset:3072
	s_add_u32 s31, s66, 0xfff80080
	s_addc_u32 s63, s67, -1
	s_cmp_eq_u32 s30, 28
	s_cselect_b32 s79, s11, s63
	s_cselect_b32 s78, s25, s31
	s_cselect_b32 s69, s13, s29
	s_cselect_b32 s68, s27, s28
	v_lshl_add_u64 v[196:197], s[66:67], 0, v[140:141]
	s_add_i32 m0, s1, 0xc000
	ds_read_b128 v[164:167], v146
	ds_read_b128 v[168:171], v146 offset:1024
	ds_read_b128 v[172:175], v146 offset:2048
	ds_read_b128 v[176:179], v146 offset:3072
	ds_read_b128 v[180:183], v146 offset:4096
	ds_read_b128 v[184:187], v146 offset:5120
	ds_read_b128 v[188:191], v146 offset:6144
	ds_read_b128 v[192:195], v146 offset:7168
	global_load_lds_dwordx4 v[196:197], off
	v_lshl_add_u64 v[196:197], s[66:67], 0, v[142:143]
	s_add_i32 m0, s1, 0xe000
	s_nop 0
	global_load_lds_dwordx4 v[196:197], off
	s_waitcnt lgkmcnt(8)
	s_barrier
	s_waitcnt lgkmcnt(0)
	s_waitcnt lgkmcnt(0)
	v_mfma_f32_16x16x32_bf16 v[124:127], v[148:151], v[164:167], v[124:127]
	v_mfma_f32_16x16x32_bf16 v[120:123], v[156:159], v[164:167], v[120:123]
	v_mfma_f32_16x16x32_bf16 v[116:119], v[148:151], v[172:175], v[116:119]
	v_mfma_f32_16x16x32_bf16 v[112:115], v[156:159], v[172:175], v[112:115]
	v_mfma_f32_16x16x32_bf16 v[108:111], v[148:151], v[180:183], v[108:111]
	v_mfma_f32_16x16x32_bf16 v[104:107], v[156:159], v[180:183], v[104:107]
	v_mfma_f32_16x16x32_bf16 v[100:103], v[148:151], v[188:191], v[100:103]
	v_mfma_f32_16x16x32_bf16 v[96:99], v[156:159], v[188:191], v[96:99]
	v_mfma_f32_16x16x32_bf16 v[124:127], v[152:155], v[168:171], v[124:127]
	v_mfma_f32_16x16x32_bf16 v[120:123], v[160:163], v[168:171], v[120:123]
	v_mfma_f32_16x16x32_bf16 v[116:119], v[152:155], v[176:179], v[116:119]
	v_mfma_f32_16x16x32_bf16 v[112:115], v[160:163], v[176:179], v[112:115]
	v_mfma_f32_16x16x32_bf16 v[108:111], v[152:155], v[184:187], v[108:111]
	v_mfma_f32_16x16x32_bf16 v[104:107], v[160:163], v[184:187], v[104:107]
	v_mfma_f32_16x16x32_bf16 v[100:103], v[152:155], v[192:195], v[100:103]
	v_mfma_f32_16x16x32_bf16 v[96:99], v[160:163], v[192:195], v[96:99]
	s_barrier
	s_add_i32 s31, s21, s0
	v_lshl_add_u64 v[212:213], s[68:69], 0, v[130:131]
	s_mov_b32 m0, s31
	ds_read_b128 v[196:199], v147
	ds_read_b128 v[200:203], v147 offset:1024
	ds_read_b128 v[204:207], v147 offset:2048
	ds_read_b128 v[208:211], v147 offset:3072
	global_load_lds_dwordx4 v[212:213], off
	v_lshl_add_u64 v[216:217], s[68:69], 0, v[134:135]
	s_add_i32 m0, s31, 0x2000
	s_nop 0
	global_load_lds_dwordx4 v[216:217], off
	s_barrier
	s_waitcnt lgkmcnt(0)
	s_waitcnt lgkmcnt(0)
	v_mfma_f32_16x16x32_bf16 v[60:63], v[196:199], v[164:167], v[60:63]
	v_mfma_f32_16x16x32_bf16 v[56:59], v[204:207], v[164:167], v[56:59]
	v_mfma_f32_16x16x32_bf16 v[52:55], v[196:199], v[172:175], v[52:55]
	v_mfma_f32_16x16x32_bf16 v[48:51], v[204:207], v[172:175], v[48:51]
	v_mfma_f32_16x16x32_bf16 v[44:47], v[196:199], v[180:183], v[44:47]
	v_mfma_f32_16x16x32_bf16 v[40:43], v[204:207], v[180:183], v[40:43]
	v_mfma_f32_16x16x32_bf16 v[36:39], v[196:199], v[188:191], v[36:39]
	v_mfma_f32_16x16x32_bf16 v[32:35], v[204:207], v[188:191], v[32:35]
	v_mfma_f32_16x16x32_bf16 v[60:63], v[200:203], v[168:171], v[60:63]
	v_mfma_f32_16x16x32_bf16 v[56:59], v[208:211], v[168:171], v[56:59]
	v_mfma_f32_16x16x32_bf16 v[52:55], v[200:203], v[176:179], v[52:55]
	v_mfma_f32_16x16x32_bf16 v[48:51], v[208:211], v[176:179], v[48:51]
	v_mfma_f32_16x16x32_bf16 v[44:47], v[200:203], v[184:187], v[44:47]
	v_mfma_f32_16x16x32_bf16 v[40:43], v[208:211], v[184:187], v[40:43]
	v_mfma_f32_16x16x32_bf16 v[36:39], v[200:203], v[192:195], v[36:39]
	v_mfma_f32_16x16x32_bf16 v[32:35], v[208:211], v[192:195], v[32:35]
	s_mov_b32 m0, s1
	v_lshl_add_u64 v[218:219], s[78:79], 0, v[128:129]
	s_barrier
	ds_read_b128 v[164:167], v146 offset:16384
	ds_read_b128 v[168:171], v146 offset:17408
	ds_read_b128 v[172:175], v146 offset:18432
	ds_read_b128 v[176:179], v146 offset:19456
	ds_read_b128 v[180:183], v146 offset:20480
	ds_read_b128 v[184:187], v146 offset:21504
	ds_read_b128 v[188:191], v146 offset:22528
	ds_read_b128 v[192:195], v146 offset:23552
	global_load_lds_dwordx4 v[218:219], off
	v_lshl_add_u64 v[220:221], s[78:79], 0, v[132:133]
	s_mov_b32 m0, s15
	s_nop 0
	global_load_lds_dwordx4 v[220:221], off
	s_barrier
	s_waitcnt lgkmcnt(0)
	s_waitcnt lgkmcnt(0)
	v_mfma_f32_16x16x32_bf16 v[92:95], v[148:151], v[164:167], v[92:95]
	v_mfma_f32_16x16x32_bf16 v[88:91], v[156:159], v[164:167], v[88:91]
	v_mfma_f32_16x16x32_bf16 v[84:87], v[148:151], v[172:175], v[84:87]
	v_mfma_f32_16x16x32_bf16 v[80:83], v[156:159], v[172:175], v[80:83]
	v_mfma_f32_16x16x32_bf16 v[76:79], v[148:151], v[180:183], v[76:79]
	v_mfma_f32_16x16x32_bf16 v[72:75], v[156:159], v[180:183], v[72:75]
	v_mfma_f32_16x16x32_bf16 v[68:71], v[148:151], v[188:191], v[68:71]
	v_mfma_f32_16x16x32_bf16 v[64:67], v[156:159], v[188:191], v[64:67]
	v_mfma_f32_16x16x32_bf16 v[92:95], v[152:155], v[168:171], v[92:95]
	v_mfma_f32_16x16x32_bf16 v[88:91], v[160:163], v[168:171], v[88:91]
	v_mfma_f32_16x16x32_bf16 v[84:87], v[152:155], v[176:179], v[84:87]
	v_mfma_f32_16x16x32_bf16 v[80:83], v[160:163], v[176:179], v[80:83]
	v_mfma_f32_16x16x32_bf16 v[76:79], v[152:155], v[184:187], v[76:79]
	v_mfma_f32_16x16x32_bf16 v[72:75], v[160:163], v[184:187], v[72:75]
	v_mfma_f32_16x16x32_bf16 v[68:71], v[152:155], v[192:195], v[68:71]
	v_mfma_f32_16x16x32_bf16 v[64:67], v[160:163], v[192:195], v[64:67]
	s_barrier
; #define PG8_STAGE(bufoff, gbase, voff) do { _Pragma("unroll") for (int _i = 0; _i < 2; ++_i) \
;         __builtin_amdgcn_global_load_lds((const unsigned*)((const char*)(gbase) + (voff)[_i]), (LAS unsigned*)(lds + (bufoff) + ldsw + _i * 8192), 16, 0, 0); } while (0)
; #define PG8_LDA(dst, b, h) do { _Pragma("unroll") for (int m = 0; m < 4; ++m) _Pragma("unroll") for (int k = 0; k < 2; ++k) dst[m][k] = *(const LAS bf16x8*)(lds + PG8_SA(b, h) + aoff + m * 2048 + k * 1024); } while (0)
; #define PG8_LDB(dst, b, h) do { _Pragma("unroll") for (int n = 0; n < 2; ++n) _Pragma("unroll") for (int k = 0; k < 2; ++k) dst[n][k] = *(const LAS bf16x8*)(lds + PG8_SB(b, h) + boff + n * 2048 + k * 1024); } while (0)
; #define PG8_MMA(ai, bj, At, Bt) do { __builtin_amdgcn_s_setprio(1); _Pragma("unroll") for (int m = 0; m < 4; ++m) _Pragma("unroll") for (int n = 0; n < 2; ++n) _Pragma("unroll") for (int k = 0; k < 2; ++k) \
;         acc[ai][bj][m][n] = __builtin_amdgcn_mfma_f32_16x16x32_bf16(Bt[n][k], At[m][k], acc[ai][bj][m][n], 0, 0, 0); __builtin_amdgcn_s_setprio(0); } while (0)
; #define PG8_WAIT_V(n) asm volatile("s_waitcnt vmcnt(" #n ")" ::: "memory")
; #define PG8_WAIT_L(n) asm volatile("s_waitcnt lgkmcnt(" #n ")" ::: "memory")
; #define PG8_BAR __builtin_amdgcn_s_barrier()
; #define PG8_SCHED __builtin_amdgcn_sched_barrier(0)
; template <class Epi, class Sched>
; __device__ __forceinline__ void gemm_phase(LAS unsigned char* lds, const int K, const int lda, Sched& S, const Epi& E) {
;     ...
;             PG8_STAGE(PG8_SB(0, 1), b2 + hstepB, voffB);
;             PG8_WAIT_V(6); PG8_BAR; PG8_MMA(1, 1, At, B1); PG8_BAR;
;             PG8_LDB(B0, 1, 0); PG8_SCHED; PG8_LDA(At, 1, 0); PG8_STAGE(PG8_SA(0, 1), a2 + hstepA, voffA);
;             PG8_WAIT_L(8); PG8_BAR; PG8_WAIT_L(0); PG8_MMA(0, 0, At, B0); PG8_BAR; PG8_SCHED;
;             PG8_LDB(B1, 1, 1); PG8_STAGE(PG8_SB(1, 0), b3, voffB);
;             PG8_BAR; PG8_WAIT_L(0); PG8_MMA(0, 1, At, B1); PG8_BAR;
	s_add_u32 s80, s68, 0x80000
	s_addc_u32 s81, s69, 0
	s_add_i32 s31, s22, s0
	v_lshl_add_u64 v[148:149], s[80:81], 0, v[130:131]
	s_mov_b32 m0, s31
	s_nop 0
	global_load_lds_dwordx4 v[148:149], off
	v_lshl_add_u64 v[148:149], s[80:81], 0, v[134:135]
	s_add_i32 m0, s31, 0x2000
	s_nop 0
	global_load_lds_dwordx4 v[148:149], off
	s_waitcnt vmcnt(6)
	s_barrier
	v_mfma_f32_16x16x32_bf16 v[28:31], v[196:199], v[164:167], v[28:31]
	v_mfma_f32_16x16x32_bf16 v[24:27], v[204:207], v[164:167], v[24:27]
	v_mfma_f32_16x16x32_bf16 v[20:23], v[196:199], v[172:175], v[20:23]
	v_mfma_f32_16x16x32_bf16 v[16:19], v[204:207], v[172:175], v[16:19]
	v_mfma_f32_16x16x32_bf16 v[12:15], v[196:199], v[180:183], v[12:15]
	v_mfma_f32_16x16x32_bf16 v[8:11], v[204:207], v[180:183], v[8:11]
	v_mfma_f32_16x16x32_bf16 v[4:7], v[196:199], v[188:191], v[4:7]
	v_mfma_f32_16x16x32_bf16 v[0:3], v[204:207], v[188:191], v[0:3]
	v_mfma_f32_16x16x32_bf16 v[28:31], v[200:203], v[168:171], v[28:31]
	v_mfma_f32_16x16x32_bf16 v[24:27], v[208:211], v[168:171], v[24:27]
	v_mfma_f32_16x16x32_bf16 v[20:23], v[200:203], v[176:179], v[20:23]
	v_mfma_f32_16x16x32_bf16 v[16:19], v[208:211], v[176:179], v[16:19]
	v_mfma_f32_16x16x32_bf16 v[12:15], v[200:203], v[184:187], v[12:15]
	v_mfma_f32_16x16x32_bf16 v[8:11], v[208:211], v[184:187], v[8:11]
	v_mfma_f32_16x16x32_bf16 v[4:7], v[200:203], v[192:195], v[4:7]
	v_mfma_f32_16x16x32_bf16 v[0:3], v[208:211], v[192:195], v[0:3]
	s_add_i32 s31, 0, 0x18000
	v_add_u32_e32 v136, s31, v144
	s_barrier
	ds_read_b128 v[148:151], v136
	ds_read_b128 v[152:155], v136 offset:1024
	ds_read_b128 v[156:159], v136 offset:2048
	ds_read_b128 v[160:163], v136 offset:3072
	s_add_u32 s78, s78, 0x80000
	s_addc_u32 s79, s79, 0
	s_mov_b32 m0, s16
	v_lshl_add_u64 v[196:197], s[78:79], 0, v[128:129]
	ds_read_b128 v[164:167], v146 offset:32768
	ds_read_b128 v[168:171], v146 offset:33792
	ds_read_b128 v[172:175], v146 offset:34816
	ds_read_b128 v[176:179], v146 offset:35840
	ds_read_b128 v[180:183], v146 offset:36864
	ds_read_b128 v[184:187], v146 offset:37888
	ds_read_b128 v[188:191], v146 offset:38912
	ds_read_b128 v[192:195], v146 offset:39936
	global_load_lds_dwordx4 v[196:197], off
	v_lshl_add_u64 v[196:197], s[78:79], 0, v[132:133]
	s_mov_b32 m0, s17
	s_nop 0
	global_load_lds_dwordx4 v[196:197], off
	s_waitcnt lgkmcnt(8)
	s_barrier
	s_waitcnt lgkmcnt(0)
	s_waitcnt lgkmcnt(0)
	v_mfma_f32_16x16x32_bf16 v[124:127], v[148:151], v[164:167], v[124:127]
	v_mfma_f32_16x16x32_bf16 v[120:123], v[156:159], v[164:167], v[120:123]
	v_mfma_f32_16x16x32_bf16 v[116:119], v[148:151], v[172:175], v[116:119]
	v_mfma_f32_16x16x32_bf16 v[112:115], v[156:159], v[172:175], v[112:115]
	v_mfma_f32_16x16x32_bf16 v[108:111], v[148:151], v[180:183], v[108:111]
	v_mfma_f32_16x16x32_bf16 v[104:107], v[156:159], v[180:183], v[104:107]
	v_mfma_f32_16x16x32_bf16 v[100:103], v[148:151], v[188:191], v[100:103]
	v_mfma_f32_16x16x32_bf16 v[96:99], v[156:159], v[188:191], v[96:99]
	v_mfma_f32_16x16x32_bf16 v[124:127], v[152:155], v[168:171], v[124:127]
	v_mfma_f32_16x16x32_bf16 v[120:123], v[160:163], v[168:171], v[120:123]
	v_mfma_f32_16x16x32_bf16 v[116:119], v[152:155], v[176:179], v[116:119]
	v_mfma_f32_16x16x32_bf16 v[112:115], v[160:163], v[176:179], v[112:115]
	v_mfma_f32_16x16x32_bf16 v[108:111], v[152:155], v[184:187], v[108:111]
	v_mfma_f32_16x16x32_bf16 v[104:107], v[160:163], v[184:187], v[104:107]
	v_mfma_f32_16x16x32_bf16 v[100:103], v[152:155], v[192:195], v[100:103]
	v_mfma_f32_16x16x32_bf16 v[96:99], v[160:163], v[192:195], v[96:99]
	s_barrier
	s_add_i32 s63, 0, 0x1c000
	s_add_i32 s31, s31, s0
	v_add_u32_e32 v136, s63, v144
	v_lshl_add_u64 v[212:213], v[212:213], 0, s[4:5]
	s_mov_b32 m0, s31
	ds_read_b128 v[196:199], v136
	ds_read_b128 v[200:203], v136 offset:1024
	ds_read_b128 v[204:207], v136 offset:2048
	ds_read_b128 v[208:211], v136 offset:3072
	global_load_lds_dwordx4 v[212:213], off
	v_lshl_add_u64 v[212:213], v[216:217], 0, s[4:5]
	s_add_i32 m0, s31, 0x2000
	s_nop 0
	global_load_lds_dwordx4 v[212:213], off
	s_barrier
	s_waitcnt lgkmcnt(0)
	s_waitcnt lgkmcnt(0)
	v_mfma_f32_16x16x32_bf16 v[60:63], v[196:199], v[164:167], v[60:63]
	v_mfma_f32_16x16x32_bf16 v[56:59], v[204:207], v[164:167], v[56:59]
	v_mfma_f32_16x16x32_bf16 v[52:55], v[196:199], v[172:175], v[52:55]
	v_mfma_f32_16x16x32_bf16 v[48:51], v[204:207], v[172:175], v[48:51]
	v_mfma_f32_16x16x32_bf16 v[44:47], v[196:199], v[180:183], v[44:47]
	v_mfma_f32_16x16x32_bf16 v[40:43], v[204:207], v[180:183], v[40:43]
	v_mfma_f32_16x16x32_bf16 v[36:39], v[196:199], v[188:191], v[36:39]
	v_mfma_f32_16x16x32_bf16 v[32:35], v[204:207], v[188:191], v[32:35]
	v_mfma_f32_16x16x32_bf16 v[60:63], v[200:203], v[168:171], v[60:63]
	v_mfma_f32_16x16x32_bf16 v[56:59], v[208:211], v[168:171], v[56:59]
	v_mfma_f32_16x16x32_bf16 v[52:55], v[200:203], v[176:179], v[52:55]
	v_mfma_f32_16x16x32_bf16 v[48:51], v[208:211], v[176:179], v[48:51]
	v_mfma_f32_16x16x32_bf16 v[44:47], v[200:203], v[184:187], v[44:47]
	v_mfma_f32_16x16x32_bf16 v[40:43], v[208:211], v[184:187], v[40:43]
	v_mfma_f32_16x16x32_bf16 v[36:39], v[200:203], v[192:195], v[36:39]
	v_mfma_f32_16x16x32_bf16 v[32:35], v[208:211], v[192:195], v[32:35]
	s_mov_b32 m0, s19
	v_lshl_add_u64 v[212:213], v[218:219], 0, s[4:5]
	s_barrier
; __device__ __forceinline__ float sigm(float x) { return __builtin_amdgcn_rcpf(1.f + __expf(-x)); }
; #define PG8_STAGE(bufoff, gbase, voff) do { _Pragma("unroll") for (int _i = 0; _i < 2; ++_i) \
;         __builtin_amdgcn_global_load_lds((const unsigned*)((const char*)(gbase) + (voff)[_i]), (LAS unsigned*)(lds + (bufoff) + ldsw + _i * 8192), 16, 0, 0); } while (0)
; #define PG8_LDA(dst, b, h) do { _Pragma("unroll") for (int m = 0; m < 4; ++m) _Pragma("unroll") for (int k = 0; k < 2; ++k) dst[m][k] = *(const LAS bf16x8*)(lds + PG8_SA(b, h) + aoff + m * 2048 + k * 1024); } while (0)
; #define PG8_WAIT_V(n) asm volatile("s_waitcnt vmcnt(" #n ")" ::: "memory")
; #define PG8_WAIT_L(n) asm volatile("s_waitcnt lgkmcnt(" #n ")" ::: "memory")
; #define PG8_BAR __builtin_amdgcn_s_barrier()
; #define PG8_SCHED __builtin_amdgcn_sched_barrier(0)
; template <class Epi, class Sched>
; __device__ __forceinline__ void gemm_phase(LAS unsigned char* lds, const int K, const int lda, Sched& S, const Epi& E) {
;     ...
;             PG8_LDA(At, 1, 1); PG8_STAGE(PG8_SA(1, 0), a3, voffA);
;             PG8_BAR; PG8_WAIT_L(0); PG8_MMA(1, 0, At, B0); PG8_BAR; PG8_SCHED;
;             PG8_STAGE(PG8_SB(1, 1), b3 + hstepB, voffB);
;             PG8_WAIT_V(6); PG8_BAR; PG8_MMA(1, 1, At, B1); PG8_BAR;
;         }
;     __device__ __forceinline__ void operator()(f32x4 (&acc)[2][2][4][2], const Unit& u, int wr, int wc, int fr, int fq) const {
; #pragma unroll
;         for (int bj = 0; bj < 2; ++bj) {
;             const int colb = u.pn * 256 + bj * 128;
;             if (colb >= NIN) continue;
;             const int act = colb >= OFF_MERGE ? 2 : (colb >= OFF_GATE ? 1 : 0);
;             u16* pb = proj + (size_t)(u.pm * 256 + wr * 64 + fr) * NIN + colb + wc * 32 + 8 * fq;
; #pragma unroll
;             for (int ai = 0; ai < 2; ++ai)
; #pragma unroll
;                 for (int m = 0; m < 4; ++m) {
;                     f32x4 v0 = acc[ai][bj][m][0], v1 = acc[ai][bj][m][1];
;                     if (act == 1) {
; #pragma unroll
;                         for (int j = 0; j < 4; ++j) { v0[j] = v0[j] * sigm(v0[j]); v1[j] = v1[j] * sigm(v1[j]); }
;                     } else if (act == 2) {
; #pragma unroll
;                         for (int j = 0; j < 4; ++j) { v0[j] = sigm(v0[j]); v1[j] = sigm(v1[j]); }
	ds_read_b128 v[164:167], v146 offset:49152
	ds_read_b128 v[168:171], v146 offset:50176
	ds_read_b128 v[172:175], v146 offset:51200
	ds_read_b128 v[176:179], v146 offset:52224
	ds_read_b128 v[180:183], v146 offset:53248
	ds_read_b128 v[184:187], v146 offset:54272
	ds_read_b128 v[188:191], v146 offset:55296
	ds_read_b128 v[192:195], v146 offset:56320
	global_load_lds_dwordx4 v[212:213], off
	v_lshl_add_u64 v[212:213], v[220:221], 0, s[4:5]
	s_mov_b32 m0, s20
	s_nop 0
	global_load_lds_dwordx4 v[212:213], off
	s_barrier
	s_waitcnt lgkmcnt(0)
	s_waitcnt lgkmcnt(0)
	v_mfma_f32_16x16x32_bf16 v[92:95], v[148:151], v[164:167], v[92:95]
	v_mfma_f32_16x16x32_bf16 v[88:91], v[156:159], v[164:167], v[88:91]
	v_mfma_f32_16x16x32_bf16 v[84:87], v[148:151], v[172:175], v[84:87]
	v_mfma_f32_16x16x32_bf16 v[80:83], v[156:159], v[172:175], v[80:83]
	v_mfma_f32_16x16x32_bf16 v[76:79], v[148:151], v[180:183], v[76:79]
	v_mfma_f32_16x16x32_bf16 v[72:75], v[156:159], v[180:183], v[72:75]
	v_mfma_f32_16x16x32_bf16 v[68:71], v[148:151], v[188:191], v[68:71]
	v_mfma_f32_16x16x32_bf16 v[64:67], v[156:159], v[188:191], v[64:67]
	v_mfma_f32_16x16x32_bf16 v[92:95], v[152:155], v[168:171], v[92:95]
	v_mfma_f32_16x16x32_bf16 v[88:91], v[160:163], v[168:171], v[88:91]
	v_mfma_f32_16x16x32_bf16 v[84:87], v[152:155], v[176:179], v[84:87]
	v_mfma_f32_16x16x32_bf16 v[80:83], v[160:163], v[176:179], v[80:83]
	v_mfma_f32_16x16x32_bf16 v[76:79], v[152:155], v[184:187], v[76:79]
	v_mfma_f32_16x16x32_bf16 v[72:75], v[160:163], v[184:187], v[72:75]
	v_mfma_f32_16x16x32_bf16 v[68:71], v[152:155], v[192:195], v[68:71]
	v_mfma_f32_16x16x32_bf16 v[64:67], v[160:163], v[192:195], v[64:67]
	s_barrier
	s_add_u32 s68, s68, 0x80080
	s_addc_u32 s69, s69, 0
	s_add_i32 s31, s63, s0
	v_lshl_add_u64 v[148:149], s[68:69], 0, v[130:131]
	s_mov_b32 m0, s31
	s_nop 0
	global_load_lds_dwordx4 v[148:149], off
	v_lshl_add_u64 v[148:149], s[68:69], 0, v[134:135]
	s_add_i32 m0, s31, 0x2000
	s_nop 0
	global_load_lds_dwordx4 v[148:149], off
	s_waitcnt vmcnt(6)
	s_barrier
	v_mfma_f32_16x16x32_bf16 v[28:31], v[196:199], v[164:167], v[28:31]
	v_mfma_f32_16x16x32_bf16 v[24:27], v[204:207], v[164:167], v[24:27]
	v_mfma_f32_16x16x32_bf16 v[20:23], v[196:199], v[172:175], v[20:23]
	v_mfma_f32_16x16x32_bf16 v[16:19], v[204:207], v[172:175], v[16:19]
	v_mfma_f32_16x16x32_bf16 v[12:15], v[196:199], v[180:183], v[12:15]
	v_mfma_f32_16x16x32_bf16 v[8:11], v[204:207], v[180:183], v[8:11]
	v_mfma_f32_16x16x32_bf16 v[4:7], v[196:199], v[188:191], v[4:7]
	v_mfma_f32_16x16x32_bf16 v[0:3], v[204:207], v[188:191], v[0:3]
	v_mfma_f32_16x16x32_bf16 v[28:31], v[200:203], v[168:171], v[28:31]
	v_mfma_f32_16x16x32_bf16 v[24:27], v[208:211], v[168:171], v[24:27]
	v_mfma_f32_16x16x32_bf16 v[20:23], v[200:203], v[176:179], v[20:23]
	v_mfma_f32_16x16x32_bf16 v[16:19], v[208:211], v[176:179], v[16:19]
	v_mfma_f32_16x16x32_bf16 v[12:15], v[200:203], v[184:187], v[12:15]
	v_mfma_f32_16x16x32_bf16 v[8:11], v[208:211], v[184:187], v[8:11]
	v_mfma_f32_16x16x32_bf16 v[4:7], v[200:203], v[192:195], v[4:7]
	v_mfma_f32_16x16x32_bf16 v[0:3], v[208:211], v[192:195], v[0:3]
	s_add_i32 s30, s30, 2
	s_add_u32 s66, s66, 0x100
	s_addc_u32 s67, s67, 0
	s_add_u32 s28, s28, 0x100
	s_addc_u32 s29, s29, 0
	s_cmp_gt_u32 s30, 29
	s_barrier
	s_cbranch_scc0 .LBB0_101
	s_lshl_b32 s66, s2, 8
	s_cmp_gt_i32 s2, 58
	s_cbranch_scc1 .LBB0_152
	s_cmp_gt_i32 s2, 22
	s_cselect_b64 s[28:29], -1, 0
	v_cndmask_b32_e64 v136, 0, 1, s[28:29]
	s_cmp_lt_i32 s2, 35
	v_readfirstlane_b32 s2, v136
	s_cselect_b32 s11, s2, 2
	s_cmp_gt_i32 s11, 1
	s_mov_b64 s[68:69], -1
	s_cbranch_scc0 .LBB0_105
	v_mul_f32_e32 v136, 0xbfb8aa3b, v124
	v_exp_f32_e32 v136, v136
	v_mul_f32_e32 v148, 0xbfb8aa3b, v120
	v_exp_f32_e32 v148, v148
	v_mul_f32_e32 v150, 0xbfb8aa3b, v121
	v_add_f32_e32 v136, 1.0, v136
	v_exp_f32_e32 v151, v150
	v_add_f32_e32 v149, 1.0, v148
	v_rcp_f32_e32 v148, v136
	v_mul_f32_e32 v136, 0xbfb8aa3b, v125
	v_exp_f32_e32 v136, v136
	v_rcp_f32_e32 v149, v149
	s_mov_b64 s[68:69], 0
	v_add_f32_e32 v136, 1.0, v136
	v_rcp_f32_e32 v150, v136
	v_add_f32_e32 v136, 1.0, v151
	v_mul_f32_e32 v151, 0xbfb8aa3b, v126
	v_exp_f32_e32 v152, v151
	v_mul_f32_e32 v151, 0xbfb8aa3b, v122
	v_exp_f32_e32 v153, v151
	v_rcp_f32_e32 v151, v136
	v_add_f32_e32 v136, 1.0, v152
	v_rcp_f32_e32 v152, v136
	v_add_f32_e32 v136, 1.0, v153
	v_mul_f32_e32 v153, 0xbfb8aa3b, v127
	v_exp_f32_e32 v154, v153
	v_mul_f32_e32 v153, 0xbfb8aa3b, v123
	v_exp_f32_e32 v156, v153
	v_rcp_f32_e32 v153, v136
	v_add_f32_e32 v136, 1.0, v154
	v_rcp_f32_e32 v155, v136
	v_add_f32_e32 v136, 1.0, v156
	v_rcp_f32_e32 v154, v136

; #define PG8_WAIT_V(n) asm volatile("s_waitcnt vmcnt(" #n ")" ::: "memory")
; #define PG8_BAR __builtin_amdgcn_s_barrier()
; template <class Epi, class Sched>
; __device__ __forceinline__ void gemm_phase(LAS unsigned char* lds, const int K, const int lda, Sched& S, const Epi& E) {
;     ...
;     PG8_WAIT_V(0);
;     if (wr == 0) PG8_BAR;
;     PG8_BAR;
.LBB0_200:
	s_waitcnt vmcnt(0)
	s_setprio 0
	s_nop 0
	s_nop 0
	s_nop 0
	s_nop 0
	s_nop 0
	s_nop 0
	s_nop 0
	s_cmpk_gt_u32 s14, 0xff
	s_cbranch_scc1 .LBB0_202
	s_barrier

; #define PG8_STAGE(bufoff, gbase, voff) do { _Pragma("unroll") for (int _i = 0; _i < 2; ++_i) \
;         __builtin_amdgcn_global_load_lds((const unsigned*)((const char*)(gbase) + (voff)[_i]), (LAS unsigned*)(lds + (bufoff) + ldsw + _i * 8192), 16, 0, 0); } while (0)
; #define PG8_WAIT_V(n) asm volatile("s_waitcnt vmcnt(" #n ")" ::: "memory")
; #define PG8_BAR __builtin_amdgcn_s_barrier()
;     __device__ __forceinline__ const char* aptr(const Unit& u) const { return (const char*)(A + (size_t)u.pm * 256 * 2048); }
; template <class Epi, class Sched>
; __device__ __forceinline__ void gemm_phase(LAS unsigned char* lds, const int K, const int lda, Sched& S, const Epi& E) {
;     const int tid = opaque_tid(), wid = __builtin_amdgcn_readfirstlane(tid >> 6), lane = tid & 63, wr = wid >> 2, wc = wid & 3, fr = lane & 15, fq = lane >> 4;
;     const int nt = K / BK;
;     unsigned voffA[2], voffB[2];
; #pragma unroll
;     for (int i = 0; i < 2; ++i) { int R, C; stage_rc(tid * 16 + i * 8192, R, C); const int Rb = (R & ~31) + perm32(R & 31);
;         voffA[i] = (unsigned)(R * lda + C) * 2u; voffB[i] = (unsigned)(Rb * K + C) * 2u; }
;     const size_t kstep = (size_t)(BK * 2);
;     const size_t hstepA = (size_t)HALF * lda * 2, hstepB = (size_t)HALF * K * 2;
;     const unsigned ldsw = (unsigned)wid * 1024u;
;     const int aoff = lds_byte(wr * 64 + fr, fq * 8), boff = lds_byte(wc * 32 + fr, fq * 8);
;     ...
;     Unit cur, nxt; int ui = 0;
;     if (!S.next(0, cur)) return;
;     f32x4 acc[2][2][4][2];
; #pragma unroll
;     for (int a = 0; a < 2; ++a)
; #pragma unroll
;         for (int b = 0; b < 2; ++b)
; #pragma unroll
;             for (int m = 0; m < 4; ++m)
; #pragma unroll
;                 for (int n = 0; n < 2; ++n) acc[a][b][m][n] = (f32x4){0.f, 0.f, 0.f, 0.f};
;     bf16x8 At[4][2], B0[2][2], B1[2][2];
;     const char* cA = S.aptr(cur); const char* cB = S.bptr(cur);
;     PG8_STAGE(PG8_SB(0, 0), cB, voffB); PG8_STAGE(PG8_SA(0, 0), cA, voffA); PG8_STAGE(PG8_SB(0, 1), cB + hstepB, voffB); PG8_STAGE(PG8_SA(0, 1), cA + hstepA, voffA);
;     if (wr == 1) PG8_BAR;
;     PG8_WAIT_V(4); PG8_BAR;
;     PG8_STAGE(PG8_SB(1, 0), cB + kstep, voffB); PG8_STAGE(PG8_SA(1, 0), cA + kstep, voffA); PG8_STAGE(PG8_SB(1, 1), cB + hstepB + kstep, voffB);
;     PG8_WAIT_V(6); PG8_BAR;
.LBB0_633:
	s_andn2_b64 vcc, exec, s[4:5]
	s_cbranch_vccnz .LBB0_763
	v_ashrrev_i32_e32 v1, 31, v8
	v_lshrrev_b32_e32 v1, 26, v1
	v_add_u32_e32 v1, v8, v1
	v_ashrrev_i32_e32 v9, 6, v1
	v_bfe_i32 v1, v8, 27, 1
	v_lshlrev_b32_e32 v0, 4, v8
	v_lshrrev_b32_e32 v1, 22, v1
	v_add_u32_e32 v1, v0, v1
	v_and_b32_e32 v1, 0xfffffc00, v1
	v_sub_u32_e32 v1, v0, v1
	v_lshrrev_b32_e32 v2, 4, v1
	v_bitop3_b32 v2, v2, v1, 32 bitop3:0x6c
	v_ashrrev_i32_e32 v1, 31, v1
	v_lshrrev_b32_e32 v1, 26, v1
	v_add_u32_e32 v1, v2, v1
	v_ashrrev_i32_e32 v10, 6, v1
	v_lshlrev_b32_e32 v3, 3, v9
	v_mul_i32_i24_e32 v4, 64, v10
	v_and_b32_e32 v3, -16, v3
	v_sub_u32_e32 v2, v2, v4
	v_mov_b32_e32 v169, 1
	v_add_u32_e32 v1, v10, v3
	v_lshlrev_b32_e32 v3, 5, v9
	v_ashrrev_i16_sdwa v2, v169, sext(v2) dst_sel:DWORD dst_unused:UNUSED_PAD src0_sel:DWORD src1_sel:BYTE_0
	v_and_b32_e32 v3, 32, v3
	v_bfe_i32 v11, v2, 0, 16
	v_and_b32_e32 v5, 3, v10
	s_mov_b32 s1, 0xfffe0
	v_add_lshl_u32 v3, v3, v11, 1
	v_add_u32_e32 v0, 0x2000, v0
	v_lshlrev_b32_e32 v2, 1, v1
	v_lshrrev_b32_e32 v4, 2, v1
	v_and_or_b32 v5, v1, s1, v5
	v_lshl_add_u32 v128, v1, 12, v3
	v_ashrrev_i32_e32 v1, 31, v0
	v_lshrrev_b32_e32 v1, 22, v1
	v_add_u32_e32 v1, v0, v1
	v_ashrrev_i32_e32 v12, 10, v1
	v_mul_i32_i24_e32 v1, 0x400, v12
	v_sub_u32_e32 v0, v0, v1
	v_and_b32_e32 v2, 24, v2
	v_and_b32_e32 v4, 4, v4
	v_lshrrev_b32_e32 v1, 4, v0
	v_or3_b32 v2, v5, v4, v2
	v_bitop3_b32 v0, v1, v0, 32 bitop3:0x6c
	v_lshl_add_u32 v130, v2, 12, v3
	v_ashrrev_i32_e32 v2, 31, v0
	v_lshrrev_b32_e32 v2, 26, v2
	v_lshlrev_b32_e32 v1, 3, v12
	v_add_u32_e32 v2, v0, v2
	v_and_b32_e32 v1, -16, v1
	v_ashrrev_i32_e32 v13, 6, v2
	v_add_u32_e32 v1, v13, v1
	v_and_b32_e32 v2, 0xc0, v2
	v_and_b32_e32 v4, 3, v13
	s_ashr_i32 s17, s0, 6
	s_ashr_i32 s11, s10, 31
	s_ashr_i32 s7, s6, 31
	s_ashr_i32 s16, s0, 8
	v_sub_u32_e32 v0, v0, v2
	v_and_or_b32 v4, v1, s1, v4
	s_lshl_b32 s1, s17, 10
	s_lshl_b64 s[14:15], s[10:11], 20
	s_lshl_b64 s[4:5], s[6:7], 20
	v_readlane_b32 s12, v252, 17
	v_ashrrev_i16_sdwa v0, v169, sext(v0) dst_sel:DWORD dst_unused:UNUSED_PAD src0_sel:DWORD src1_sel:BYTE_0
	v_readlane_b32 s13, v252, 18
	s_add_u32 s4, s12, s4
	v_lshlrev_b32_e32 v3, 5, v12
	v_bfe_i32 v14, v0, 0, 16
	v_lshlrev_b32_e32 v0, 1, v1
	v_lshrrev_b32_e32 v2, 2, v1
	s_addc_u32 s5, s13, s5
	s_add_i32 s12, s1, 0
	v_and_b32_e32 v3, 32, v3
	v_and_b32_e32 v0, 24, v0
	v_and_b32_e32 v2, 4, v2
	s_add_i32 m0, s12, 0x10000
	v_or3_b32 v0, v4, v2, v0
	v_add_lshl_u32 v2, v3, v14, 1
	global_load_lds_dwordx4 v130, s[4:5]
	s_add_i32 m0, s12, 0x12000
	v_lshl_add_u32 v134, v0, 12, v2
	s_add_u32 s80, s34, s14
	global_load_lds_dwordx4 v134, s[4:5]
	s_addc_u32 s81, s35, s15
	s_mov_b32 m0, s12
	s_add_i32 s13, s12, 0x2000
	v_lshl_add_u32 v132, v1, 12, v2
	global_load_lds_dwordx4 v128, s[80:81]
	s_mov_b32 m0, s13
	s_add_u32 s14, s4, 0x80000
	global_load_lds_dwordx4 v132, s[80:81]
	s_addc_u32 s15, s5, 0
	s_add_i32 m0, s12, 0x14000
	v_mov_b32_e32 v137, 0
	global_load_lds_dwordx4 v130, s[14:15]
	s_add_i32 m0, s12, 0x16000
	s_add_u32 s18, s80, 0x80000
	global_load_lds_dwordx4 v134, s[14:15]
	s_addc_u32 s19, s81, 0
	s_add_i32 s14, s12, 0x4000
	s_mov_b32 m0, s14
	s_add_i32 s15, s12, 0x6000
	global_load_lds_dwordx4 v128, s[18:19]
	s_mov_b32 m0, s15
	v_mov_b32_e32 v131, v137
	global_load_lds_dwordx4 v132, s[18:19]
	v_mov_b32_e32 v135, v137
	v_mov_b32_e32 v129, v137
	v_mov_b32_e32 v133, v137
	s_mov_b32 s11, 0
	v_lshl_add_u64 v[6:7], s[4:5], 0, v[130:131]
	v_lshl_add_u64 v[4:5], s[4:5], 0, v[134:135]
	v_lshl_add_u64 v[2:3], s[80:81], 0, v[128:129]
	v_lshl_add_u64 v[0:1], s[80:81], 0, v[132:133]
	s_cmp_lg_u32 s16, 1
	s_mov_b64 s[62:63], 0x80000
	s_cbranch_scc1 .LBB0_636
	s_setprio 1
	s_nop 0
	s_nop 0
	s_nop 0
	s_nop 0
	s_nop 0
	s_nop 0
	s_nop 0
	s_barrier

; #define PG8_STAGE(bufoff, gbase, voff) do { _Pragma("unroll") for (int _i = 0; _i < 2; ++_i) \
;         __builtin_amdgcn_global_load_lds((const unsigned*)((const char*)(gbase) + (voff)[_i]), (LAS unsigned*)(lds + (bufoff) + ldsw + _i * 8192), 16, 0, 0); } while (0)
; #define PG8_LDA(dst, b, h) do { _Pragma("unroll") for (int m = 0; m < 4; ++m) _Pragma("unroll") for (int k = 0; k < 2; ++k) dst[m][k] = *(const LAS bf16x8*)(lds + PG8_SA(b, h) + aoff + m * 2048 + k * 1024); } while (0)
; #define PG8_LDB(dst, b, h) do { _Pragma("unroll") for (int n = 0; n < 2; ++n) _Pragma("unroll") for (int k = 0; k < 2; ++k) dst[n][k] = *(const LAS bf16x8*)(lds + PG8_SB(b, h) + boff + n * 2048 + k * 1024); } while (0)
; #define PG8_MMA(ai, bj, At, Bt) do { __builtin_amdgcn_s_setprio(1); _Pragma("unroll") for (int m = 0; m < 4; ++m) _Pragma("unroll") for (int n = 0; n < 2; ++n) _Pragma("unroll") for (int k = 0; k < 2; ++k) \
;         acc[ai][bj][m][n] = __builtin_amdgcn_mfma_f32_16x16x32_bf16(Bt[n][k], At[m][k], acc[ai][bj][m][n], 0, 0, 0); __builtin_amdgcn_s_setprio(0); } while (0)
; #define PG8_WAIT_L(n) asm volatile("s_waitcnt lgkmcnt(" #n ")" ::: "memory")
; #define PG8_BAR __builtin_amdgcn_s_barrier()
; #define PG8_SCHED __builtin_amdgcn_sched_barrier(0)
; template <class Epi, class Sched>
; __device__ __forceinline__ void gemm_phase(LAS unsigned char* lds, const int K, const int lda, Sched& S, const Epi& E) {
;     ...
;         for (int t = 0; t < nt; t += 2) {
;             const bool last = (t == nt - 2);
;             const char* a1 = cA + (size_t)(t + 1) * kstep;
;             const char* a2 = last ? nA : cA + (size_t)(t + 2) * kstep; const char* b2 = last ? nB : cB + (size_t)(t + 2) * kstep;
;             const char* a3 = a2 + kstep; const char* b3 = b2 + kstep;
;             PG8_LDB(B0, 0, 0); PG8_SCHED; PG8_LDA(At, 0, 0); PG8_STAGE(PG8_SA(1, 1), a1 + hstepA, voffA);
;             PG8_WAIT_L(8); PG8_BAR; PG8_WAIT_L(0); PG8_MMA(0, 0, At, B0); PG8_BAR; PG8_SCHED;
;             PG8_LDB(B1, 0, 1); PG8_STAGE(PG8_SB(0, 0), b2, voffB);
;             PG8_BAR; PG8_WAIT_L(0); PG8_MMA(0, 1, At, B1); PG8_BAR;
;             PG8_LDA(At, 0, 1); PG8_STAGE(PG8_SA(0, 0), a2, voffA);
;             PG8_BAR; PG8_WAIT_L(0); PG8_MMA(1, 0, At, B0); PG8_BAR; PG8_SCHED;
.LBB0_657:
	v_add_u32_e32 v149, s19, v171
	ds_read_b128 v[164:167], v149
	ds_read_b128 v[180:183], v149 offset:1024
	ds_read_b128 v[184:187], v149 offset:2048
	ds_read_b128 v[188:191], v149 offset:3072
	s_cmpk_eq_i32 s6, 0xf00
	v_lshl_add_u64 v[162:163], v[144:145], 0, s[6:7]
	v_lshl_add_u64 v[162:163], v[162:163], 0, s[80:81]
	s_cselect_b64 vcc, -1, 0
	v_cndmask_b32_e32 v213, v163, v139, vcc
	v_cndmask_b32_e32 v212, v162, v136, vcc
	v_lshl_add_u64 v[162:163], v[154:155], 0, s[6:7]
	v_cndmask_b32_e32 v163, v163, v147, vcc
	v_cndmask_b32_e32 v162, v162, v156, vcc
	v_lshl_add_u64 v[228:229], v[158:159], 0, s[6:7]
	s_add_i32 m0, s12, 0xc000
	ds_read_b128 v[192:195], v174
	ds_read_b128 v[196:199], v174 offset:1024
	ds_read_b128 v[200:203], v174 offset:2048
	ds_read_b128 v[204:207], v174 offset:3072
	ds_read_b128 v[208:211], v174 offset:4096
	ds_read_b128 v[216:219], v174 offset:5120
	ds_read_b128 v[220:223], v174 offset:6144
	ds_read_b128 v[224:227], v174 offset:7168
	global_load_lds_dwordx4 v[228:229], off
	v_lshl_add_u64 v[228:229], v[160:161], 0, s[6:7]
	s_add_i32 m0, s12, 0xe000
	s_nop 0
	global_load_lds_dwordx4 v[228:229], off
	s_waitcnt lgkmcnt(8)
	s_barrier
	s_waitcnt lgkmcnt(0)
	s_waitcnt lgkmcnt(0)
	v_mfma_f32_16x16x32_bf16 v[124:127], v[164:167], v[192:195], v[124:127]
	v_mfma_f32_16x16x32_bf16 v[120:123], v[184:187], v[192:195], v[120:123]
	v_mfma_f32_16x16x32_bf16 v[116:119], v[164:167], v[200:203], v[116:119]
	v_mfma_f32_16x16x32_bf16 v[112:115], v[184:187], v[200:203], v[112:115]
	v_mfma_f32_16x16x32_bf16 v[108:111], v[164:167], v[208:211], v[108:111]
	v_mfma_f32_16x16x32_bf16 v[104:107], v[184:187], v[208:211], v[104:107]
	v_mfma_f32_16x16x32_bf16 v[100:103], v[164:167], v[220:223], v[100:103]
	v_mfma_f32_16x16x32_bf16 v[96:99], v[184:187], v[220:223], v[96:99]
	v_mfma_f32_16x16x32_bf16 v[124:127], v[180:183], v[196:199], v[124:127]
	v_mfma_f32_16x16x32_bf16 v[120:123], v[188:191], v[196:199], v[120:123]
	v_mfma_f32_16x16x32_bf16 v[116:119], v[180:183], v[204:207], v[116:119]
	v_mfma_f32_16x16x32_bf16 v[112:115], v[188:191], v[204:207], v[112:115]
	v_mfma_f32_16x16x32_bf16 v[108:111], v[180:183], v[216:219], v[108:111]
	v_mfma_f32_16x16x32_bf16 v[104:107], v[188:191], v[216:219], v[104:107]
	v_mfma_f32_16x16x32_bf16 v[100:103], v[180:183], v[224:227], v[100:103]
	v_mfma_f32_16x16x32_bf16 v[96:99], v[188:191], v[224:227], v[96:99]
	s_barrier
	s_add_i32 s22, s19, s1
	v_add_u32_e32 v149, s20, v171
	v_lshl_add_u64 v[244:245], v[162:163], 0, v[130:131]
	s_mov_b32 m0, s22
	ds_read_b128 v[228:231], v149
	ds_read_b128 v[232:235], v149 offset:1024
	ds_read_b128 v[236:239], v149 offset:2048
	ds_read_b128 v[240:243], v149 offset:3072
	global_load_lds_dwordx4 v[244:245], off
	v_lshl_add_u64 v[246:247], v[162:163], 0, v[134:135]
	s_add_i32 m0, s22, 0x2000
	s_nop 0
	global_load_lds_dwordx4 v[246:247], off
	s_barrier
	s_waitcnt lgkmcnt(0)
	s_waitcnt lgkmcnt(0)
	v_mfma_f32_16x16x32_bf16 v[92:95], v[228:231], v[192:195], v[92:95]
	v_mfma_f32_16x16x32_bf16 v[88:91], v[236:239], v[192:195], v[88:91]
	v_mfma_f32_16x16x32_bf16 v[84:87], v[228:231], v[200:203], v[84:87]
	v_mfma_f32_16x16x32_bf16 v[80:83], v[236:239], v[200:203], v[80:83]
	v_mfma_f32_16x16x32_bf16 v[76:79], v[228:231], v[208:211], v[76:79]
	v_mfma_f32_16x16x32_bf16 v[72:75], v[236:239], v[208:211], v[72:75]
	v_mfma_f32_16x16x32_bf16 v[68:71], v[228:231], v[220:223], v[68:71]
	v_mfma_f32_16x16x32_bf16 v[64:67], v[236:239], v[220:223], v[64:67]
	v_mfma_f32_16x16x32_bf16 v[92:95], v[232:235], v[196:199], v[92:95]
	v_mfma_f32_16x16x32_bf16 v[88:91], v[240:243], v[196:199], v[88:91]
	v_mfma_f32_16x16x32_bf16 v[84:87], v[232:235], v[204:207], v[84:87]
	v_mfma_f32_16x16x32_bf16 v[80:83], v[240:243], v[204:207], v[80:83]
	v_mfma_f32_16x16x32_bf16 v[76:79], v[232:235], v[216:219], v[76:79]
	v_mfma_f32_16x16x32_bf16 v[72:75], v[240:243], v[216:219], v[72:75]
	v_mfma_f32_16x16x32_bf16 v[68:71], v[232:235], v[224:227], v[68:71]
	v_mfma_f32_16x16x32_bf16 v[64:67], v[240:243], v[224:227], v[64:67]
	s_mov_b32 m0, s12
	v_lshl_add_u64 v[248:249], v[212:213], 0, v[128:129]
	s_barrier
	ds_read_b128 v[192:195], v174 offset:16384
	ds_read_b128 v[196:199], v174 offset:17408
	ds_read_b128 v[200:203], v174 offset:18432
	ds_read_b128 v[204:207], v174 offset:19456
	ds_read_b128 v[208:211], v174 offset:20480
	ds_read_b128 v[216:219], v174 offset:21504
	ds_read_b128 v[220:223], v174 offset:22528
	ds_read_b128 v[224:227], v174 offset:23552
	global_load_lds_dwordx4 v[248:249], off
	v_lshl_add_u64 v[250:251], v[212:213], 0, v[132:133]
	s_mov_b32 m0, s13
	s_nop 0
	global_load_lds_dwordx4 v[250:251], off
	s_barrier
	s_waitcnt lgkmcnt(0)
	s_waitcnt lgkmcnt(0)
	v_mfma_f32_16x16x32_bf16 v[60:63], v[164:167], v[192:195], v[60:63]
	v_mfma_f32_16x16x32_bf16 v[56:59], v[184:187], v[192:195], v[56:59]
	v_mfma_f32_16x16x32_bf16 v[52:55], v[164:167], v[200:203], v[52:55]
	v_mfma_f32_16x16x32_bf16 v[48:51], v[184:187], v[200:203], v[48:51]
	v_mfma_f32_16x16x32_bf16 v[44:47], v[164:167], v[208:211], v[44:47]
	v_mfma_f32_16x16x32_bf16 v[40:43], v[184:187], v[208:211], v[40:43]
	v_mfma_f32_16x16x32_bf16 v[36:39], v[164:167], v[220:223], v[36:39]
	v_mfma_f32_16x16x32_bf16 v[32:35], v[184:187], v[220:223], v[32:35]
	v_mfma_f32_16x16x32_bf16 v[60:63], v[180:183], v[196:199], v[60:63]
	v_mfma_f32_16x16x32_bf16 v[56:59], v[188:191], v[196:199], v[56:59]
	v_mfma_f32_16x16x32_bf16 v[52:55], v[180:183], v[204:207], v[52:55]
	v_mfma_f32_16x16x32_bf16 v[48:51], v[188:191], v[204:207], v[48:51]
	v_mfma_f32_16x16x32_bf16 v[44:47], v[180:183], v[216:219], v[44:47]
	v_mfma_f32_16x16x32_bf16 v[40:43], v[188:191], v[216:219], v[40:43]
	v_mfma_f32_16x16x32_bf16 v[36:39], v[180:183], v[224:227], v[36:39]
	v_mfma_f32_16x16x32_bf16 v[32:35], v[188:191], v[224:227], v[32:35]
	s_barrier
; #define PG8_STAGE(bufoff, gbase, voff) do { _Pragma("unroll") for (int _i = 0; _i < 2; ++_i) \
;         __builtin_amdgcn_global_load_lds((const unsigned*)((const char*)(gbase) + (voff)[_i]), (LAS unsigned*)(lds + (bufoff) + ldsw + _i * 8192), 16, 0, 0); } while (0)
; #define PG8_LDA(dst, b, h) do { _Pragma("unroll") for (int m = 0; m < 4; ++m) _Pragma("unroll") for (int k = 0; k < 2; ++k) dst[m][k] = *(const LAS bf16x8*)(lds + PG8_SA(b, h) + aoff + m * 2048 + k * 1024); } while (0)
; #define PG8_LDB(dst, b, h) do { _Pragma("unroll") for (int n = 0; n < 2; ++n) _Pragma("unroll") for (int k = 0; k < 2; ++k) dst[n][k] = *(const LAS bf16x8*)(lds + PG8_SB(b, h) + boff + n * 2048 + k * 1024); } while (0)
; #define PG8_MMA(ai, bj, At, Bt) do { __builtin_amdgcn_s_setprio(1); _Pragma("unroll") for (int m = 0; m < 4; ++m) _Pragma("unroll") for (int n = 0; n < 2; ++n) _Pragma("unroll") for (int k = 0; k < 2; ++k) \
;         acc[ai][bj][m][n] = __builtin_amdgcn_mfma_f32_16x16x32_bf16(Bt[n][k], At[m][k], acc[ai][bj][m][n], 0, 0, 0); __builtin_amdgcn_s_setprio(0); } while (0)
; #define PG8_WAIT_V(n) asm volatile("s_waitcnt vmcnt(" #n ")" ::: "memory")
; #define PG8_WAIT_L(n) asm volatile("s_waitcnt lgkmcnt(" #n ")" ::: "memory")
; #define PG8_BAR __builtin_amdgcn_s_barrier()
; #define PG8_SCHED __builtin_amdgcn_sched_barrier(0)
; template <class Epi, class Sched>
; __device__ __forceinline__ void gemm_phase(LAS unsigned char* lds, const int K, const int lda, Sched& S, const Epi& E) {
;     ...
;             PG8_STAGE(PG8_SB(0, 1), b2 + hstepB, voffB);
;             PG8_WAIT_V(6); PG8_BAR; PG8_MMA(1, 1, At, B1); PG8_BAR;
;             PG8_LDB(B0, 1, 0); PG8_SCHED; PG8_LDA(At, 1, 0); PG8_STAGE(PG8_SA(0, 1), a2 + hstepA, voffA);
;             PG8_WAIT_L(8); PG8_BAR; PG8_WAIT_L(0); PG8_MMA(0, 0, At, B0); PG8_BAR; PG8_SCHED;
;             PG8_LDB(B1, 1, 1); PG8_STAGE(PG8_SB(1, 0), b3, voffB);
;             PG8_BAR; PG8_WAIT_L(0); PG8_MMA(0, 1, At, B1); PG8_BAR;
;             PG8_LDA(At, 1, 1); PG8_STAGE(PG8_SA(1, 0), a3, voffA);
;             PG8_BAR; PG8_WAIT_L(0); PG8_MMA(1, 0, At, B0); PG8_BAR; PG8_SCHED;
	v_lshl_add_u64 v[164:165], v[162:163], 0, s[62:63]
	s_add_i32 s22, s20, s1
	v_lshl_add_u64 v[166:167], v[164:165], 0, v[130:131]
	s_mov_b32 m0, s22
	v_lshl_add_u64 v[164:165], v[164:165], 0, v[134:135]
	global_load_lds_dwordx4 v[166:167], off
	s_add_i32 m0, s22, 0x2000
	s_nop 0
	global_load_lds_dwordx4 v[164:165], off
	s_waitcnt vmcnt(6)
	s_barrier
	v_mfma_f32_16x16x32_bf16 v[28:31], v[228:231], v[192:195], v[28:31]
	v_mfma_f32_16x16x32_bf16 v[24:27], v[236:239], v[192:195], v[24:27]
	v_mfma_f32_16x16x32_bf16 v[20:23], v[228:231], v[200:203], v[20:23]
	v_mfma_f32_16x16x32_bf16 v[16:19], v[236:239], v[200:203], v[16:19]
	v_mfma_f32_16x16x32_bf16 v[12:15], v[228:231], v[208:211], v[12:15]
	v_mfma_f32_16x16x32_bf16 v[8:11], v[236:239], v[208:211], v[8:11]
	v_mfma_f32_16x16x32_bf16 v[4:7], v[228:231], v[220:223], v[4:7]
	v_mfma_f32_16x16x32_bf16 v[0:3], v[236:239], v[220:223], v[0:3]
	v_mfma_f32_16x16x32_bf16 v[28:31], v[232:235], v[196:199], v[28:31]
	v_mfma_f32_16x16x32_bf16 v[24:27], v[240:243], v[196:199], v[24:27]
	v_mfma_f32_16x16x32_bf16 v[20:23], v[232:235], v[204:207], v[20:23]
	v_mfma_f32_16x16x32_bf16 v[16:19], v[240:243], v[204:207], v[16:19]
	v_mfma_f32_16x16x32_bf16 v[12:15], v[232:235], v[216:219], v[12:15]
	v_mfma_f32_16x16x32_bf16 v[8:11], v[240:243], v[216:219], v[8:11]
	v_mfma_f32_16x16x32_bf16 v[4:7], v[232:235], v[224:227], v[4:7]
	v_mfma_f32_16x16x32_bf16 v[0:3], v[240:243], v[224:227], v[0:3]
	s_add_i32 s22, 0, 0x18000
	v_add_u32_e32 v149, s22, v171
	s_barrier
	ds_read_b128 v[164:167], v149
	ds_read_b128 v[180:183], v149 offset:1024
	ds_read_b128 v[184:187], v149 offset:2048
	ds_read_b128 v[188:191], v149 offset:3072
	v_lshl_add_u64 v[212:213], v[212:213], 0, s[62:63]
	s_mov_b32 m0, s14
	v_lshl_add_u64 v[228:229], v[212:213], 0, v[128:129]
	ds_read_b128 v[192:195], v174 offset:32768
	ds_read_b128 v[196:199], v174 offset:33792
	ds_read_b128 v[200:203], v174 offset:34816
	ds_read_b128 v[204:207], v174 offset:35840
	ds_read_b128 v[208:211], v174 offset:36864
	ds_read_b128 v[216:219], v174 offset:37888
	ds_read_b128 v[220:223], v174 offset:38912
	ds_read_b128 v[224:227], v174 offset:39936
	global_load_lds_dwordx4 v[228:229], off
	v_lshl_add_u64 v[212:213], v[212:213], 0, v[132:133]
	s_mov_b32 m0, s15
	s_nop 0
	global_load_lds_dwordx4 v[212:213], off
	s_waitcnt lgkmcnt(8)
	s_barrier
	s_waitcnt lgkmcnt(0)
	s_waitcnt lgkmcnt(0)
	v_mfma_f32_16x16x32_bf16 v[124:127], v[164:167], v[192:195], v[124:127]
	v_mfma_f32_16x16x32_bf16 v[120:123], v[184:187], v[192:195], v[120:123]
	v_mfma_f32_16x16x32_bf16 v[116:119], v[164:167], v[200:203], v[116:119]
	v_mfma_f32_16x16x32_bf16 v[112:115], v[184:187], v[200:203], v[112:115]
	v_mfma_f32_16x16x32_bf16 v[108:111], v[164:167], v[208:211], v[108:111]
	v_mfma_f32_16x16x32_bf16 v[104:107], v[184:187], v[208:211], v[104:107]
	v_mfma_f32_16x16x32_bf16 v[100:103], v[164:167], v[220:223], v[100:103]
	v_mfma_f32_16x16x32_bf16 v[96:99], v[184:187], v[220:223], v[96:99]
	v_mfma_f32_16x16x32_bf16 v[124:127], v[180:183], v[196:199], v[124:127]
	v_mfma_f32_16x16x32_bf16 v[120:123], v[188:191], v[196:199], v[120:123]
	v_mfma_f32_16x16x32_bf16 v[116:119], v[180:183], v[204:207], v[116:119]
	v_mfma_f32_16x16x32_bf16 v[112:115], v[188:191], v[204:207], v[112:115]
	v_mfma_f32_16x16x32_bf16 v[108:111], v[180:183], v[216:219], v[108:111]
	v_mfma_f32_16x16x32_bf16 v[104:107], v[188:191], v[216:219], v[104:107]
	v_mfma_f32_16x16x32_bf16 v[100:103], v[180:183], v[224:227], v[100:103]
	v_mfma_f32_16x16x32_bf16 v[96:99], v[188:191], v[224:227], v[96:99]
	s_barrier
	s_add_i32 s23, 0, 0x1c000
	s_add_i32 s22, s22, s1
	v_add_u32_e32 v149, s23, v171
	v_lshl_add_u64 v[212:213], v[244:245], 0, s[66:67]
	s_mov_b32 m0, s22
	ds_read_b128 v[228:231], v149
	ds_read_b128 v[232:235], v149 offset:1024
	ds_read_b128 v[236:239], v149 offset:2048
	ds_read_b128 v[240:243], v149 offset:3072
	global_load_lds_dwordx4 v[212:213], off
	v_lshl_add_u64 v[212:213], v[246:247], 0, s[66:67]
	s_add_i32 m0, s22, 0x2000
	s_nop 0
	global_load_lds_dwordx4 v[212:213], off
	s_barrier
	s_waitcnt lgkmcnt(0)
	s_waitcnt lgkmcnt(0)
	v_mfma_f32_16x16x32_bf16 v[92:95], v[228:231], v[192:195], v[92:95]
	v_mfma_f32_16x16x32_bf16 v[88:91], v[236:239], v[192:195], v[88:91]
	v_mfma_f32_16x16x32_bf16 v[84:87], v[228:231], v[200:203], v[84:87]
	v_mfma_f32_16x16x32_bf16 v[80:83], v[236:239], v[200:203], v[80:83]
	v_mfma_f32_16x16x32_bf16 v[76:79], v[228:231], v[208:211], v[76:79]
	v_mfma_f32_16x16x32_bf16 v[72:75], v[236:239], v[208:211], v[72:75]
	v_mfma_f32_16x16x32_bf16 v[68:71], v[228:231], v[220:223], v[68:71]
	v_mfma_f32_16x16x32_bf16 v[64:67], v[236:239], v[220:223], v[64:67]
	v_mfma_f32_16x16x32_bf16 v[92:95], v[232:235], v[196:199], v[92:95]
	v_mfma_f32_16x16x32_bf16 v[88:91], v[240:243], v[196:199], v[88:91]
	v_mfma_f32_16x16x32_bf16 v[84:87], v[232:235], v[204:207], v[84:87]
	v_mfma_f32_16x16x32_bf16 v[80:83], v[240:243], v[204:207], v[80:83]
	v_mfma_f32_16x16x32_bf16 v[76:79], v[232:235], v[216:219], v[76:79]
	v_mfma_f32_16x16x32_bf16 v[72:75], v[240:243], v[216:219], v[72:75]
	v_mfma_f32_16x16x32_bf16 v[68:71], v[232:235], v[224:227], v[68:71]
	v_mfma_f32_16x16x32_bf16 v[64:67], v[240:243], v[224:227], v[64:67]
	s_mov_b32 m0, s17
	v_lshl_add_u64 v[212:213], v[248:249], 0, s[66:67]
	s_barrier
; __device__ __forceinline__ float sigm(float x) { return __builtin_amdgcn_rcpf(1.f + __expf(-x)); }
; #define PG8_STAGE(bufoff, gbase, voff) do { _Pragma("unroll") for (int _i = 0; _i < 2; ++_i) \
;         __builtin_amdgcn_global_load_lds((const unsigned*)((const char*)(gbase) + (voff)[_i]), (LAS unsigned*)(lds + (bufoff) + ldsw + _i * 8192), 16, 0, 0); } while (0)
; #define PG8_MMA(ai, bj, At, Bt) do { __builtin_amdgcn_s_setprio(1); _Pragma("unroll") for (int m = 0; m < 4; ++m) _Pragma("unroll") for (int n = 0; n < 2; ++n) _Pragma("unroll") for (int k = 0; k < 2; ++k) \
;         acc[ai][bj][m][n] = __builtin_amdgcn_mfma_f32_16x16x32_bf16(Bt[n][k], At[m][k], acc[ai][bj][m][n], 0, 0, 0); __builtin_amdgcn_s_setprio(0); } while (0)
; #define PG8_WAIT_V(n) asm volatile("s_waitcnt vmcnt(" #n ")" ::: "memory")
; #define PG8_WAIT_L(n) asm volatile("s_waitcnt lgkmcnt(" #n ")" ::: "memory")
; #define PG8_BAR __builtin_amdgcn_s_barrier()
; #define PG8_SCHED __builtin_amdgcn_sched_barrier(0)
; template <class Epi, class Sched>
; __device__ __forceinline__ void gemm_phase(LAS unsigned char* lds, const int K, const int lda, Sched& S, const Epi& E) {
;     ...
;             PG8_BAR; PG8_WAIT_L(0); PG8_MMA(1, 0, At, B0); PG8_BAR; PG8_SCHED;
;             PG8_STAGE(PG8_SB(1, 1), b3 + hstepB, voffB);
;             PG8_WAIT_V(6); PG8_BAR; PG8_MMA(1, 1, At, B1); PG8_BAR;
;     __device__ __forceinline__ void operator()(f32x4 (&acc)[2][2][4][2], const Unit& u, int wr, int wc, int fr, int fq) const {
; #pragma unroll
;         for (int bj = 0; bj < 2; ++bj) {
;             const int colb = u.pn * 256 + bj * 128;
;             if (colb >= NIN) continue;
;             const int act = colb >= OFF_MERGE ? 2 : (colb >= OFF_GATE ? 1 : 0);
;             u16* pb = proj + (size_t)(u.pm * 256 + wr * 64 + fr) * NIN + colb + wc * 32 + 8 * fq;
; #pragma unroll
;             for (int ai = 0; ai < 2; ++ai)
; #pragma unroll
;                 for (int m = 0; m < 4; ++m) {
;                     f32x4 v0 = acc[ai][bj][m][0], v1 = acc[ai][bj][m][1];
;                     if (act == 1) {
; #pragma unroll
;                         for (int j = 0; j < 4; ++j) { v0[j] = v0[j] * sigm(v0[j]); v1[j] = v1[j] * sigm(v1[j]); }
	ds_read_b128 v[192:195], v174 offset:49152
	ds_read_b128 v[196:199], v174 offset:50176
	ds_read_b128 v[200:203], v174 offset:51200
	ds_read_b128 v[204:207], v174 offset:52224
	ds_read_b128 v[208:211], v174 offset:53248
	ds_read_b128 v[216:219], v174 offset:54272
	ds_read_b128 v[220:223], v174 offset:55296
	ds_read_b128 v[224:227], v174 offset:56320
	global_load_lds_dwordx4 v[212:213], off
	v_lshl_add_u64 v[212:213], v[250:251], 0, s[66:67]
	s_mov_b32 m0, s18
	s_nop 0
	global_load_lds_dwordx4 v[212:213], off
	s_barrier
	s_waitcnt lgkmcnt(0)
	s_waitcnt lgkmcnt(0)
	v_mfma_f32_16x16x32_bf16 v[60:63], v[164:167], v[192:195], v[60:63]
	v_mfma_f32_16x16x32_bf16 v[56:59], v[184:187], v[192:195], v[56:59]
	v_mfma_f32_16x16x32_bf16 v[52:55], v[164:167], v[200:203], v[52:55]
	v_mfma_f32_16x16x32_bf16 v[48:51], v[184:187], v[200:203], v[48:51]
	v_mfma_f32_16x16x32_bf16 v[44:47], v[164:167], v[208:211], v[44:47]
	v_mfma_f32_16x16x32_bf16 v[40:43], v[184:187], v[208:211], v[40:43]
	v_mfma_f32_16x16x32_bf16 v[36:39], v[164:167], v[220:223], v[36:39]
	v_mfma_f32_16x16x32_bf16 v[32:35], v[184:187], v[220:223], v[32:35]
	v_mfma_f32_16x16x32_bf16 v[60:63], v[180:183], v[196:199], v[60:63]
	v_mfma_f32_16x16x32_bf16 v[56:59], v[188:191], v[196:199], v[56:59]
	v_mfma_f32_16x16x32_bf16 v[52:55], v[180:183], v[204:207], v[52:55]
	v_mfma_f32_16x16x32_bf16 v[48:51], v[188:191], v[204:207], v[48:51]
	v_mfma_f32_16x16x32_bf16 v[44:47], v[180:183], v[216:219], v[44:47]
	v_mfma_f32_16x16x32_bf16 v[40:43], v[188:191], v[216:219], v[40:43]
	v_mfma_f32_16x16x32_bf16 v[36:39], v[180:183], v[224:227], v[36:39]
	v_mfma_f32_16x16x32_bf16 v[32:35], v[188:191], v[224:227], v[32:35]
	s_barrier
	v_lshl_add_u64 v[162:163], v[162:163], 0, s[68:69]
	s_add_i32 s22, s23, s1
	v_lshl_add_u64 v[164:165], v[162:163], 0, v[130:131]
	s_mov_b32 m0, s22
	v_lshl_add_u64 v[162:163], v[162:163], 0, v[134:135]
	global_load_lds_dwordx4 v[164:165], off
	s_add_i32 m0, s22, 0x2000
	s_nop 0
	global_load_lds_dwordx4 v[162:163], off
	s_waitcnt vmcnt(6)
	s_barrier
	v_mfma_f32_16x16x32_bf16 v[28:31], v[228:231], v[192:195], v[28:31]
	v_mfma_f32_16x16x32_bf16 v[24:27], v[236:239], v[192:195], v[24:27]
	v_mfma_f32_16x16x32_bf16 v[20:23], v[228:231], v[200:203], v[20:23]
	v_mfma_f32_16x16x32_bf16 v[16:19], v[236:239], v[200:203], v[16:19]
	v_mfma_f32_16x16x32_bf16 v[12:15], v[228:231], v[208:211], v[12:15]
	v_mfma_f32_16x16x32_bf16 v[8:11], v[236:239], v[208:211], v[8:11]
	v_mfma_f32_16x16x32_bf16 v[4:7], v[228:231], v[220:223], v[4:7]
	v_mfma_f32_16x16x32_bf16 v[0:3], v[236:239], v[220:223], v[0:3]
	v_mfma_f32_16x16x32_bf16 v[28:31], v[232:235], v[196:199], v[28:31]
	v_mfma_f32_16x16x32_bf16 v[24:27], v[240:243], v[196:199], v[24:27]
	v_mfma_f32_16x16x32_bf16 v[20:23], v[232:235], v[204:207], v[20:23]
	v_mfma_f32_16x16x32_bf16 v[16:19], v[240:243], v[204:207], v[16:19]
	v_mfma_f32_16x16x32_bf16 v[12:15], v[232:235], v[216:219], v[12:15]
	v_mfma_f32_16x16x32_bf16 v[8:11], v[240:243], v[216:219], v[8:11]
	v_mfma_f32_16x16x32_bf16 v[4:7], v[232:235], v[224:227], v[4:7]
	v_mfma_f32_16x16x32_bf16 v[0:3], v[240:243], v[224:227], v[0:3]
	s_add_i32 s10, s10, 2
	s_add_u32 s6, s6, 0x100
	s_addc_u32 s7, s7, 0
	s_cmp_gt_u32 s10, 29
	s_barrier
	s_cbranch_scc0 .LBB0_657
	v_lshlrev_b32_e32 v156, 8, v172
	v_cmp_gt_i32_e32 vcc, 59, v172
	s_and_saveexec_b64 s[6:7], vcc
	s_cbranch_execz .LBB0_708
	v_cmp_lt_i32_e32 vcc, 22, v172
	s_nop 1
	v_cndmask_b32_e64 v136, 0, 1, vcc
	v_cmp_gt_i32_e32 vcc, 35, v172
	s_nop 1
	v_cndmask_b32_e32 v139, 2, v136, vcc
	v_cmp_lt_i32_e32 vcc, 1, v139
	s_and_saveexec_b64 s[22:23], vcc
	s_xor_b64 s[82:83], exec, s[22:23]
	s_cbranch_execz .LBB0_661
	v_mul_f32_e32 v136, 0xbfb8aa3b, v124
	v_exp_f32_e32 v136, v136
	v_mul_f32_e32 v147, 0xbfb8aa3b, v120
	v_exp_f32_e32 v147, v147
	v_mul_f32_e32 v149, 0xbfb8aa3b, v121
	v_add_f32_e32 v136, 1.0, v136
	v_rcp_f32_e32 v160, v136
	v_mul_f32_e32 v136, 0xbfb8aa3b, v125
	v_exp_f32_e32 v136, v136
	v_exp_f32_e32 v149, v149
	v_add_f32_e32 v147, 1.0, v147
	v_rcp_f32_e32 v162, v147
	v_add_f32_e32 v136, 1.0, v136
	v_mul_f32_e32 v147, 0xbfb8aa3b, v126
	v_rcp_f32_e32 v161, v136
	v_add_f32_e32 v136, 1.0, v149
	v_exp_f32_e32 v147, v147
	v_mul_f32_e32 v149, 0xbfb8aa3b, v122
	v_exp_f32_e32 v149, v149
	v_rcp_f32_e32 v163, v136
	v_add_f32_e32 v136, 1.0, v147
	v_mul_f32_e32 v147, 0xbfb8aa3b, v127
	v_rcp_f32_e32 v164, v136
	v_add_f32_e32 v136, 1.0, v149
	v_exp_f32_e32 v147, v147
	v_mul_f32_e32 v149, 0xbfb8aa3b, v123
	v_exp_f32_e32 v149, v149
	v_rcp_f32_e32 v166, v136
	v_add_f32_e32 v136, 1.0, v147
	v_rcp_f32_e32 v165, v136
	v_add_f32_e32 v136, 1.0, v149
	v_rcp_f32_e32 v167, v136

; #define PG8_WAIT_V(n) asm volatile("s_waitcnt vmcnt(" #n ")" ::: "memory")
; #define PG8_BAR __builtin_amdgcn_s_barrier()
; template <class Epi, class Sched>
; __device__ __forceinline__ void gemm_phase(LAS unsigned char* lds, const int K, const int lda, Sched& S, const Epi& E) {
;     ...
;     PG8_WAIT_V(0);
;     if (wr == 0) PG8_BAR;
;     PG8_BAR;
.LBB0_760:
	s_or_b64 exec, exec, s[78:79]
	s_waitcnt vmcnt(0)
	s_setprio 0
	s_nop 0
	s_nop 0
	s_nop 0
	s_nop 0
	s_nop 0
	s_nop 0
	s_nop 0
	s_cmpk_gt_u32 s0, 0xff
	s_cbranch_scc1 .LBB0_762
	s_barrier

; #define PG8_STAGE(bufoff, gbase, voff) do { _Pragma("unroll") for (int _i = 0; _i < 2; ++_i) \
;         __builtin_amdgcn_global_load_lds((const unsigned*)((const char*)(gbase) + (voff)[_i]), (LAS unsigned*)(lds + (bufoff) + ldsw + _i * 8192), 16, 0, 0); } while (0)
; #define PG8_WAIT_V(n) asm volatile("s_waitcnt vmcnt(" #n ")" ::: "memory")
; #define PG8_BAR __builtin_amdgcn_s_barrier()
;     __device__ __forceinline__ const char* aptr(const Unit& u) const { return (const char*)(A + (size_t)u.pm * 256 * 2048); }
;     __device__ __forceinline__ const char* bptr(const Unit& u) const { return (const char*)(Bt + (size_t)u.pn * 256 * 2048); }
;     __device__ __forceinline__ const char* aptr(const Unit& u) const { return (const char*)(A + (size_t)u.pm * 256 * 2048); }
; template <class Epi, class Sched>
; __device__ __forceinline__ void gemm_phase(LAS unsigned char* lds, const int K, const int lda, Sched& S, const Epi& E) {
;     const int tid = opaque_tid(), wid = __builtin_amdgcn_readfirstlane(tid >> 6), lane = tid & 63, wr = wid >> 2, wc = wid & 3, fr = lane & 15, fq = lane >> 4;
;     const int nt = K / BK;
;     unsigned voffA[2], voffB[2];
; #pragma unroll
;     for (int i = 0; i < 2; ++i) { int R, C; stage_rc(tid * 16 + i * 8192, R, C); const int Rb = (R & ~31) + perm32(R & 31);
;         voffA[i] = (unsigned)(R * lda + C) * 2u; voffB[i] = (unsigned)(Rb * K + C) * 2u; }
;     const size_t kstep = (size_t)(BK * 2);
;     const size_t hstepA = (size_t)HALF * lda * 2, hstepB = (size_t)HALF * K * 2;
;     const unsigned ldsw = (unsigned)wid * 1024u;
;     const int aoff = lds_byte(wr * 64 + fr, fq * 8), boff = lds_byte(wc * 32 + fr, fq * 8);
;     ...
;     Unit cur, nxt; int ui = 0;
;     if (!S.next(0, cur)) return;
;     f32x4 acc[2][2][4][2];
; #pragma unroll
;     for (int a = 0; a < 2; ++a)
; #pragma unroll
;         for (int b = 0; b < 2; ++b)
; #pragma unroll
;             for (int m = 0; m < 4; ++m)
; #pragma unroll
;                 for (int n = 0; n < 2; ++n) acc[a][b][m][n] = (f32x4){0.f, 0.f, 0.f, 0.f};
;     bf16x8 At[4][2], B0[2][2], B1[2][2];
;     const char* cA = S.aptr(cur); const char* cB = S.bptr(cur);
;     PG8_STAGE(PG8_SB(0, 0), cB, voffB); PG8_STAGE(PG8_SA(0, 0), cA, voffA); PG8_STAGE(PG8_SB(0, 1), cB + hstepB, voffB); PG8_STAGE(PG8_SA(0, 1), cA + hstepA, voffA);
;     if (wr == 1) PG8_BAR;
;     PG8_WAIT_V(4); PG8_BAR;
.LBB0_1275:
	s_andn2_b64 vcc, exec, s[8:9]
	s_cbranch_vccnz .LBB0_1379
	v_ashrrev_i32_e32 v1, 31, v8
	v_lshrrev_b32_e32 v1, 26, v1
	v_add_u32_e32 v1, v8, v1
	v_ashrrev_i32_e32 v9, 6, v1
	v_bfe_i32 v1, v8, 27, 1
	v_lshlrev_b32_e32 v0, 4, v8
	v_lshrrev_b32_e32 v1, 22, v1
	v_add_u32_e32 v1, v0, v1
	v_and_b32_e32 v1, 0xfffffc00, v1
	v_sub_u32_e32 v1, v0, v1
	v_lshrrev_b32_e32 v2, 4, v1
	v_bitop3_b32 v2, v2, v1, 32 bitop3:0x6c
	v_ashrrev_i32_e32 v1, 31, v1
	v_lshrrev_b32_e32 v1, 26, v1
	v_add_u32_e32 v1, v2, v1
	v_ashrrev_i32_e32 v10, 6, v1
	v_lshlrev_b32_e32 v3, 3, v9
	v_mul_i32_i24_e32 v4, 64, v10
	v_and_b32_e32 v3, -16, v3
	v_sub_u32_e32 v2, v2, v4
	v_mov_b32_e32 v4, 1
	v_add_u32_e32 v1, v10, v3
	v_lshlrev_b32_e32 v3, 5, v9
	v_ashrrev_i16_sdwa v2, v4, sext(v2) dst_sel:DWORD dst_unused:UNUSED_PAD src0_sel:DWORD src1_sel:BYTE_0
	v_and_b32_e32 v3, 32, v3
	v_bfe_i32 v11, v2, 0, 16
	v_and_b32_e32 v6, 3, v10
	s_mov_b32 s3, 0xfffe0
	v_add_lshl_u32 v3, v3, v11, 1
	v_add_u32_e32 v0, 0x2000, v0
	v_lshlrev_b32_e32 v2, 1, v1
	v_lshrrev_b32_e32 v5, 2, v1
	v_and_or_b32 v6, v1, s3, v6
	v_lshl_add_u32 v128, v1, 12, v3
	v_ashrrev_i32_e32 v1, 31, v0
	v_lshrrev_b32_e32 v1, 22, v1
	v_add_u32_e32 v1, v0, v1
	v_ashrrev_i32_e32 v12, 10, v1
	v_mul_i32_i24_e32 v1, 0x400, v12
	v_sub_u32_e32 v0, v0, v1
	v_and_b32_e32 v2, 24, v2
	v_and_b32_e32 v5, 4, v5
	v_lshrrev_b32_e32 v1, 4, v0
	v_or3_b32 v2, v6, v5, v2
	v_bitop3_b32 v0, v1, v0, 32 bitop3:0x6c
	v_lshl_add_u32 v130, v2, 12, v3
	v_ashrrev_i32_e32 v2, 31, v0
	v_lshrrev_b32_e32 v2, 26, v2
	v_add_u32_e32 v2, v0, v2
	v_lshlrev_b32_e32 v1, 3, v12
	v_ashrrev_i32_e32 v13, 6, v2
	v_and_b32_e32 v2, 0xc0, v2
	v_and_b32_e32 v1, -16, v1
	v_sub_u32_e32 v0, v0, v2
	v_add_u32_e32 v1, v13, v1
	v_ashrrev_i16_sdwa v0, v4, sext(v0) dst_sel:DWORD dst_unused:UNUSED_PAD src0_sel:DWORD src1_sel:BYTE_0
	v_and_b32_e32 v4, 3, v13
	v_and_or_b32 v4, v1, s3, v4
	s_ashr_i32 s16, s1, 6
	s_ashr_i32 s7, s6, 31
	s_ashr_i32 s3, s2, 31
	s_ashr_i32 s10, s1, 8
	s_lshl_b32 s12, s16, 10
	s_lshl_b64 s[8:9], s[6:7], 20
	s_lshl_b64 s[14:15], s[2:3], 20
	v_readlane_b32 s18, v252, 17
	v_readlane_b32 s19, v252, 18
	s_add_u32 s86, s18, s14
	v_lshlrev_b32_e32 v3, 5, v12
	v_bfe_i32 v14, v0, 0, 16
	v_lshlrev_b32_e32 v0, 1, v1
	v_lshrrev_b32_e32 v2, 2, v1
	s_addc_u32 s87, s19, s15
	s_add_i32 s3, s12, 0
	v_and_b32_e32 v3, 32, v3
	v_and_b32_e32 v0, 24, v0
	v_and_b32_e32 v2, 4, v2
	s_add_i32 m0, s3, 0x10000
	v_or3_b32 v0, v4, v2, v0
	v_add_lshl_u32 v2, v3, v14, 1
	global_load_lds_dwordx4 v130, s[86:87]
	s_add_i32 m0, s3, 0x12000
	v_lshl_add_u32 v134, v0, 12, v2
	s_add_u32 s8, s34, s8
	global_load_lds_dwordx4 v134, s[86:87]
	s_addc_u32 s9, s35, s9
	s_mov_b32 m0, s3
	s_add_i32 s7, s3, 0x2000
	v_lshl_add_u32 v132, v1, 12, v2
	global_load_lds_dwordx4 v128, s[8:9]
	s_mov_b32 m0, s7
	s_add_u32 s14, s86, 0x80000
	global_load_lds_dwordx4 v132, s[8:9]
	s_addc_u32 s15, s87, 0
	s_add_i32 m0, s3, 0x14000
	v_mov_b32_e32 v137, 0
	global_load_lds_dwordx4 v130, s[14:15]
	s_add_i32 m0, s3, 0x16000
	s_add_u32 s18, s8, 0x80000
	s_addc_u32 s19, s9, 0
	s_add_i32 s13, s3, 0x4000
	global_load_lds_dwordx4 v134, s[14:15]
	s_mov_b32 m0, s13
	s_add_i32 s14, s3, 0x6000
	global_load_lds_dwordx4 v128, s[18:19]
	s_mov_b32 m0, s14
	v_mov_b32_e32 v131, v137
	global_load_lds_dwordx4 v132, s[18:19]
	v_mov_b32_e32 v135, v137
	v_mov_b32_e32 v129, v137
	v_mov_b32_e32 v133, v137
	s_mov_b32 s11, 0
	v_lshl_add_u64 v[6:7], s[86:87], 0, v[130:131]
	v_lshl_add_u64 v[4:5], s[86:87], 0, v[134:135]
	v_lshl_add_u64 v[2:3], s[8:9], 0, v[128:129]
	s_cmp_lg_u32 s10, 1
	v_lshl_add_u64 v[0:1], s[8:9], 0, v[132:133]
	s_cbranch_scc1 .LBB0_1278
	s_setprio 1
	s_nop 0
	s_nop 0
	s_nop 0
	s_nop 0
	s_nop 0
	s_nop 0
	s_nop 0
	s_barrier

; #define PG8_STAGE(bufoff, gbase, voff) do { _Pragma("unroll") for (int _i = 0; _i < 2; ++_i) \
;         __builtin_amdgcn_global_load_lds((const unsigned*)((const char*)(gbase) + (voff)[_i]), (LAS unsigned*)(lds + (bufoff) + ldsw + _i * 8192), 16, 0, 0); } while (0)
; #define PG8_LDA(dst, b, h) do { _Pragma("unroll") for (int m = 0; m < 4; ++m) _Pragma("unroll") for (int k = 0; k < 2; ++k) dst[m][k] = *(const LAS bf16x8*)(lds + PG8_SA(b, h) + aoff + m * 2048 + k * 1024); } while (0)
; #define PG8_LDB(dst, b, h) do { _Pragma("unroll") for (int n = 0; n < 2; ++n) _Pragma("unroll") for (int k = 0; k < 2; ++k) dst[n][k] = *(const LAS bf16x8*)(lds + PG8_SB(b, h) + boff + n * 2048 + k * 1024); } while (0)
; #define PG8_MMA(ai, bj, At, Bt) do { __builtin_amdgcn_s_setprio(1); _Pragma("unroll") for (int m = 0; m < 4; ++m) _Pragma("unroll") for (int n = 0; n < 2; ++n) _Pragma("unroll") for (int k = 0; k < 2; ++k) \
;         acc[ai][bj][m][n] = __builtin_amdgcn_mfma_f32_16x16x32_bf16(Bt[n][k], At[m][k], acc[ai][bj][m][n], 0, 0, 0); __builtin_amdgcn_s_setprio(0); } while (0)
; #define PG8_WAIT_L(n) asm volatile("s_waitcnt lgkmcnt(" #n ")" ::: "memory")
; #define PG8_BAR __builtin_amdgcn_s_barrier()
; #define PG8_SCHED __builtin_amdgcn_sched_barrier(0)
; template <class Epi, class Sched>
; __device__ __forceinline__ void gemm_phase(LAS unsigned char* lds, const int K, const int lda, Sched& S, const Epi& E) {
;     ...
;         for (int t = 0; t < nt; t += 2) {
;             const bool last = (t == nt - 2);
;             const char* a1 = cA + (size_t)(t + 1) * kstep;
;             const char* a2 = last ? nA : cA + (size_t)(t + 2) * kstep; const char* b2 = last ? nB : cB + (size_t)(t + 2) * kstep;
;             const char* a3 = a2 + kstep; const char* b3 = b2 + kstep;
;             PG8_LDB(B0, 0, 0); PG8_SCHED; PG8_LDA(At, 0, 0); PG8_STAGE(PG8_SA(1, 1), a1 + hstepA, voffA);
;             PG8_WAIT_L(8); PG8_BAR; PG8_WAIT_L(0); PG8_MMA(0, 0, At, B0); PG8_BAR; PG8_SCHED;
;             PG8_LDB(B1, 0, 1); PG8_STAGE(PG8_SB(0, 0), b2, voffB);
;             PG8_BAR; PG8_WAIT_L(0); PG8_MMA(0, 1, At, B1); PG8_BAR;
;             PG8_LDA(At, 0, 1); PG8_STAGE(PG8_SA(0, 0), a2, voffA);
;             PG8_BAR; PG8_WAIT_L(0); PG8_MMA(1, 0, At, B0); PG8_BAR; PG8_SCHED;
.LBB0_1289:
	v_add_u32_e32 v136, s19, v154
	s_add_u32 s31, s8, s86
	ds_read_b128 v[148:151], v136
	ds_read_b128 v[156:159], v136 offset:1024
	ds_read_b128 v[160:163], v136 offset:2048
	ds_read_b128 v[164:167], v136 offset:3072
	s_addc_u32 s52, s9, s87
	s_add_u32 s31, s31, 0x100
	s_addc_u32 s52, s52, 0
	s_add_u32 s53, s24, s86
	s_addc_u32 s54, s25, s87
	s_cmpk_eq_i32 s86, 0xf00
	s_cselect_b32 s91, s10, s52
	s_cselect_b32 s90, s27, s31
	s_cselect_b32 s89, s28, s54
	s_cselect_b32 s88, s29, s53
	v_lshl_add_u64 v[152:153], v[144:145], 0, s[86:87]
	s_add_i32 m0, s3, 0xc000
	ds_read_b128 v[168:171], v155
	ds_read_b128 v[172:175], v155 offset:1024
	ds_read_b128 v[176:179], v155 offset:2048
	ds_read_b128 v[180:183], v155 offset:3072
	ds_read_b128 v[184:187], v155 offset:4096
	ds_read_b128 v[188:191], v155 offset:5120
	ds_read_b128 v[192:195], v155 offset:6144
	ds_read_b128 v[196:199], v155 offset:7168
	global_load_lds_dwordx4 v[152:153], off
	v_lshl_add_u64 v[152:153], v[146:147], 0, s[86:87]
	s_add_i32 m0, s3, 0xe000
	s_nop 0
	global_load_lds_dwordx4 v[152:153], off
	s_waitcnt lgkmcnt(8)
	s_barrier
	s_waitcnt lgkmcnt(0)
	s_waitcnt lgkmcnt(0)
	v_mfma_f32_16x16x32_bf16 v[124:127], v[148:151], v[168:171], v[124:127]
	v_mfma_f32_16x16x32_bf16 v[120:123], v[160:163], v[168:171], v[120:123]
	v_mfma_f32_16x16x32_bf16 v[116:119], v[148:151], v[176:179], v[116:119]
	v_mfma_f32_16x16x32_bf16 v[112:115], v[160:163], v[176:179], v[112:115]
	v_mfma_f32_16x16x32_bf16 v[108:111], v[148:151], v[184:187], v[108:111]
	v_mfma_f32_16x16x32_bf16 v[104:107], v[160:163], v[184:187], v[104:107]
	v_mfma_f32_16x16x32_bf16 v[100:103], v[148:151], v[192:195], v[100:103]
	v_mfma_f32_16x16x32_bf16 v[96:99], v[160:163], v[192:195], v[96:99]
	v_mfma_f32_16x16x32_bf16 v[124:127], v[156:159], v[172:175], v[124:127]
	v_mfma_f32_16x16x32_bf16 v[120:123], v[164:167], v[172:175], v[120:123]
	v_mfma_f32_16x16x32_bf16 v[116:119], v[156:159], v[180:183], v[116:119]
	v_mfma_f32_16x16x32_bf16 v[112:115], v[164:167], v[180:183], v[112:115]
	v_mfma_f32_16x16x32_bf16 v[108:111], v[156:159], v[188:191], v[108:111]
	v_mfma_f32_16x16x32_bf16 v[104:107], v[164:167], v[188:191], v[104:107]
	v_mfma_f32_16x16x32_bf16 v[100:103], v[156:159], v[196:199], v[100:103]
	v_mfma_f32_16x16x32_bf16 v[96:99], v[164:167], v[196:199], v[96:99]
	s_barrier
	s_add_i32 s31, s19, s12
	v_add_u32_e32 v136, s20, v154
	v_lshl_add_u64 v[152:153], s[88:89], 0, v[130:131]
	s_mov_b32 m0, s31
	ds_read_b128 v[200:203], v136
	ds_read_b128 v[204:207], v136 offset:1024
	ds_read_b128 v[208:211], v136 offset:2048
	ds_read_b128 v[216:219], v136 offset:3072
	global_load_lds_dwordx4 v[152:153], off
	v_lshl_add_u64 v[212:213], s[88:89], 0, v[134:135]
	s_add_i32 m0, s31, 0x2000
	s_nop 0
	global_load_lds_dwordx4 v[212:213], off
	s_barrier
	s_waitcnt lgkmcnt(0)
	s_waitcnt lgkmcnt(0)
	v_mfma_f32_16x16x32_bf16 v[92:95], v[200:203], v[168:171], v[92:95]
	v_mfma_f32_16x16x32_bf16 v[88:91], v[208:211], v[168:171], v[88:91]
	v_mfma_f32_16x16x32_bf16 v[84:87], v[200:203], v[176:179], v[84:87]
	v_mfma_f32_16x16x32_bf16 v[80:83], v[208:211], v[176:179], v[80:83]
	v_mfma_f32_16x16x32_bf16 v[76:79], v[200:203], v[184:187], v[76:79]
	v_mfma_f32_16x16x32_bf16 v[72:75], v[208:211], v[184:187], v[72:75]
	v_mfma_f32_16x16x32_bf16 v[68:71], v[200:203], v[192:195], v[68:71]
	v_mfma_f32_16x16x32_bf16 v[64:67], v[208:211], v[192:195], v[64:67]
	v_mfma_f32_16x16x32_bf16 v[92:95], v[204:207], v[172:175], v[92:95]
	v_mfma_f32_16x16x32_bf16 v[88:91], v[216:219], v[172:175], v[88:91]
	v_mfma_f32_16x16x32_bf16 v[84:87], v[204:207], v[180:183], v[84:87]
	v_mfma_f32_16x16x32_bf16 v[80:83], v[216:219], v[180:183], v[80:83]
	v_mfma_f32_16x16x32_bf16 v[76:79], v[204:207], v[188:191], v[76:79]
	v_mfma_f32_16x16x32_bf16 v[72:75], v[216:219], v[188:191], v[72:75]
	v_mfma_f32_16x16x32_bf16 v[68:71], v[204:207], v[196:199], v[68:71]
	v_mfma_f32_16x16x32_bf16 v[64:67], v[216:219], v[196:199], v[64:67]
	s_mov_b32 m0, s3
	v_lshl_add_u64 v[220:221], s[90:91], 0, v[128:129]
	s_barrier
	ds_read_b128 v[168:171], v155 offset:16384
	ds_read_b128 v[172:175], v155 offset:17408
	ds_read_b128 v[176:179], v155 offset:18432
	ds_read_b128 v[180:183], v155 offset:19456
	ds_read_b128 v[184:187], v155 offset:20480
	ds_read_b128 v[188:191], v155 offset:21504
	ds_read_b128 v[192:195], v155 offset:22528
	ds_read_b128 v[196:199], v155 offset:23552
	global_load_lds_dwordx4 v[220:221], off
	v_lshl_add_u64 v[222:223], s[90:91], 0, v[132:133]
	s_mov_b32 m0, s7
	s_nop 0
	global_load_lds_dwordx4 v[222:223], off
	s_barrier
	s_waitcnt lgkmcnt(0)
	s_waitcnt lgkmcnt(0)
	v_mfma_f32_16x16x32_bf16 v[60:63], v[148:151], v[168:171], v[60:63]
	v_mfma_f32_16x16x32_bf16 v[56:59], v[160:163], v[168:171], v[56:59]
	v_mfma_f32_16x16x32_bf16 v[52:55], v[148:151], v[176:179], v[52:55]
	v_mfma_f32_16x16x32_bf16 v[48:51], v[160:163], v[176:179], v[48:51]
	v_mfma_f32_16x16x32_bf16 v[44:47], v[148:151], v[184:187], v[44:47]
	v_mfma_f32_16x16x32_bf16 v[40:43], v[160:163], v[184:187], v[40:43]
	v_mfma_f32_16x16x32_bf16 v[36:39], v[148:151], v[192:195], v[36:39]
	v_mfma_f32_16x16x32_bf16 v[32:35], v[160:163], v[192:195], v[32:35]
	v_mfma_f32_16x16x32_bf16 v[60:63], v[156:159], v[172:175], v[60:63]
	v_mfma_f32_16x16x32_bf16 v[56:59], v[164:167], v[172:175], v[56:59]
	v_mfma_f32_16x16x32_bf16 v[52:55], v[156:159], v[180:183], v[52:55]
	v_mfma_f32_16x16x32_bf16 v[48:51], v[164:167], v[180:183], v[48:51]
	v_mfma_f32_16x16x32_bf16 v[44:47], v[156:159], v[188:191], v[44:47]
	v_mfma_f32_16x16x32_bf16 v[40:43], v[164:167], v[188:191], v[40:43]
	v_mfma_f32_16x16x32_bf16 v[36:39], v[156:159], v[196:199], v[36:39]
	v_mfma_f32_16x16x32_bf16 v[32:35], v[164:167], v[196:199], v[32:35]
	s_barrier
; #define PG8_STAGE(bufoff, gbase, voff) do { _Pragma("unroll") for (int _i = 0; _i < 2; ++_i) \
;         __builtin_amdgcn_global_load_lds((const unsigned*)((const char*)(gbase) + (voff)[_i]), (LAS unsigned*)(lds + (bufoff) + ldsw + _i * 8192), 16, 0, 0); } while (0)
; #define PG8_LDA(dst, b, h) do { _Pragma("unroll") for (int m = 0; m < 4; ++m) _Pragma("unroll") for (int k = 0; k < 2; ++k) dst[m][k] = *(const LAS bf16x8*)(lds + PG8_SA(b, h) + aoff + m * 2048 + k * 1024); } while (0)
; #define PG8_LDB(dst, b, h) do { _Pragma("unroll") for (int n = 0; n < 2; ++n) _Pragma("unroll") for (int k = 0; k < 2; ++k) dst[n][k] = *(const LAS bf16x8*)(lds + PG8_SB(b, h) + boff + n * 2048 + k * 1024); } while (0)
; #define PG8_MMA(ai, bj, At, Bt) do { __builtin_amdgcn_s_setprio(1); _Pragma("unroll") for (int m = 0; m < 4; ++m) _Pragma("unroll") for (int n = 0; n < 2; ++n) _Pragma("unroll") for (int k = 0; k < 2; ++k) \
;         acc[ai][bj][m][n] = __builtin_amdgcn_mfma_f32_16x16x32_bf16(Bt[n][k], At[m][k], acc[ai][bj][m][n], 0, 0, 0); __builtin_amdgcn_s_setprio(0); } while (0)
; #define PG8_WAIT_V(n) asm volatile("s_waitcnt vmcnt(" #n ")" ::: "memory")
; #define PG8_WAIT_L(n) asm volatile("s_waitcnt lgkmcnt(" #n ")" ::: "memory")
; #define PG8_BAR __builtin_amdgcn_s_barrier()
; #define PG8_SCHED __builtin_amdgcn_sched_barrier(0)
; template <class Epi, class Sched>
; __device__ __forceinline__ void gemm_phase(LAS unsigned char* lds, const int K, const int lda, Sched& S, const Epi& E) {
;     ...
;             PG8_STAGE(PG8_SB(0, 1), b2 + hstepB, voffB);
;             PG8_WAIT_V(6); PG8_BAR; PG8_MMA(1, 1, At, B1); PG8_BAR;
;             PG8_LDB(B0, 1, 0); PG8_SCHED; PG8_LDA(At, 1, 0); PG8_STAGE(PG8_SA(0, 1), a2 + hstepA, voffA);
;             PG8_WAIT_L(8); PG8_BAR; PG8_WAIT_L(0); PG8_MMA(0, 0, At, B0); PG8_BAR; PG8_SCHED;
;             PG8_LDB(B1, 1, 1); PG8_STAGE(PG8_SB(1, 0), b3, voffB);
;             PG8_BAR; PG8_WAIT_L(0); PG8_MMA(0, 1, At, B1); PG8_BAR;
;             PG8_LDA(At, 1, 1); PG8_STAGE(PG8_SA(1, 0), a3, voffA);
;             PG8_BAR; PG8_WAIT_L(0); PG8_MMA(1, 0, At, B0); PG8_BAR; PG8_SCHED;
	s_add_u32 s52, s88, 0x80000
	s_addc_u32 s53, s89, 0
	s_add_i32 s31, s20, s12
	v_lshl_add_u64 v[148:149], s[52:53], 0, v[130:131]
	s_mov_b32 m0, s31
	s_nop 0
	global_load_lds_dwordx4 v[148:149], off
	v_lshl_add_u64 v[148:149], s[52:53], 0, v[134:135]
	s_add_i32 m0, s31, 0x2000
	s_nop 0
	global_load_lds_dwordx4 v[148:149], off
	s_waitcnt vmcnt(6)
	s_barrier
	v_mfma_f32_16x16x32_bf16 v[28:31], v[200:203], v[168:171], v[28:31]
	v_mfma_f32_16x16x32_bf16 v[24:27], v[208:211], v[168:171], v[24:27]
	v_mfma_f32_16x16x32_bf16 v[20:23], v[200:203], v[176:179], v[20:23]
	v_mfma_f32_16x16x32_bf16 v[16:19], v[208:211], v[176:179], v[16:19]
	v_mfma_f32_16x16x32_bf16 v[12:15], v[200:203], v[184:187], v[12:15]
	v_mfma_f32_16x16x32_bf16 v[8:11], v[208:211], v[184:187], v[8:11]
	v_mfma_f32_16x16x32_bf16 v[4:7], v[200:203], v[192:195], v[4:7]
	v_mfma_f32_16x16x32_bf16 v[0:3], v[208:211], v[192:195], v[0:3]
	v_mfma_f32_16x16x32_bf16 v[28:31], v[204:207], v[172:175], v[28:31]
	v_mfma_f32_16x16x32_bf16 v[24:27], v[216:219], v[172:175], v[24:27]
	v_mfma_f32_16x16x32_bf16 v[20:23], v[204:207], v[180:183], v[20:23]
	v_mfma_f32_16x16x32_bf16 v[16:19], v[216:219], v[180:183], v[16:19]
	v_mfma_f32_16x16x32_bf16 v[12:15], v[204:207], v[188:191], v[12:15]
	v_mfma_f32_16x16x32_bf16 v[8:11], v[216:219], v[188:191], v[8:11]
	v_mfma_f32_16x16x32_bf16 v[4:7], v[204:207], v[196:199], v[4:7]
	v_mfma_f32_16x16x32_bf16 v[0:3], v[216:219], v[196:199], v[0:3]
	s_add_i32 s31, 0, 0x18000
	v_add_u32_e32 v136, s31, v154
	s_barrier
	ds_read_b128 v[148:151], v136
	ds_read_b128 v[156:159], v136 offset:1024
	ds_read_b128 v[160:163], v136 offset:2048
	ds_read_b128 v[164:167], v136 offset:3072
	s_add_u32 s52, s90, 0x80000
	s_addc_u32 s53, s91, 0
	s_mov_b32 m0, s13
	v_lshl_add_u64 v[200:201], s[52:53], 0, v[128:129]
	ds_read_b128 v[168:171], v155 offset:32768
	ds_read_b128 v[172:175], v155 offset:33792
	ds_read_b128 v[176:179], v155 offset:34816
	ds_read_b128 v[180:183], v155 offset:35840
	ds_read_b128 v[184:187], v155 offset:36864
	ds_read_b128 v[188:191], v155 offset:37888
	ds_read_b128 v[192:195], v155 offset:38912
	ds_read_b128 v[196:199], v155 offset:39936
	global_load_lds_dwordx4 v[200:201], off
	v_lshl_add_u64 v[200:201], s[52:53], 0, v[132:133]
	s_mov_b32 m0, s14
	s_nop 0
	global_load_lds_dwordx4 v[200:201], off
	s_waitcnt lgkmcnt(8)
	s_barrier
	s_waitcnt lgkmcnt(0)
	s_waitcnt lgkmcnt(0)
	v_mfma_f32_16x16x32_bf16 v[124:127], v[148:151], v[168:171], v[124:127]
	v_mfma_f32_16x16x32_bf16 v[120:123], v[160:163], v[168:171], v[120:123]
	v_mfma_f32_16x16x32_bf16 v[116:119], v[148:151], v[176:179], v[116:119]
	v_mfma_f32_16x16x32_bf16 v[112:115], v[160:163], v[176:179], v[112:115]
	v_mfma_f32_16x16x32_bf16 v[108:111], v[148:151], v[184:187], v[108:111]
	v_mfma_f32_16x16x32_bf16 v[104:107], v[160:163], v[184:187], v[104:107]
	v_mfma_f32_16x16x32_bf16 v[100:103], v[148:151], v[192:195], v[100:103]
	v_mfma_f32_16x16x32_bf16 v[96:99], v[160:163], v[192:195], v[96:99]
	v_mfma_f32_16x16x32_bf16 v[124:127], v[156:159], v[172:175], v[124:127]
	v_mfma_f32_16x16x32_bf16 v[120:123], v[164:167], v[172:175], v[120:123]
	v_mfma_f32_16x16x32_bf16 v[116:119], v[156:159], v[180:183], v[116:119]
	v_mfma_f32_16x16x32_bf16 v[112:115], v[164:167], v[180:183], v[112:115]
	v_mfma_f32_16x16x32_bf16 v[108:111], v[156:159], v[188:191], v[108:111]
	v_mfma_f32_16x16x32_bf16 v[104:107], v[164:167], v[188:191], v[104:107]
	v_mfma_f32_16x16x32_bf16 v[100:103], v[156:159], v[196:199], v[100:103]
	v_mfma_f32_16x16x32_bf16 v[96:99], v[164:167], v[196:199], v[96:99]
	s_barrier
	s_add_i32 s54, 0, 0x1c000
	s_add_i32 s31, s31, s12
	v_add_u32_e32 v136, s54, v154
	v_lshl_add_u64 v[152:153], v[152:153], 0, s[62:63]
	s_mov_b32 m0, s31
	ds_read_b128 v[200:203], v136
	ds_read_b128 v[204:207], v136 offset:1024
	ds_read_b128 v[208:211], v136 offset:2048
	ds_read_b128 v[216:219], v136 offset:3072
	global_load_lds_dwordx4 v[152:153], off
	v_lshl_add_u64 v[152:153], v[212:213], 0, s[62:63]
	s_add_i32 m0, s31, 0x2000
	s_nop 0
	global_load_lds_dwordx4 v[152:153], off
	s_barrier
	s_waitcnt lgkmcnt(0)
	s_waitcnt lgkmcnt(0)
	v_mfma_f32_16x16x32_bf16 v[92:95], v[200:203], v[168:171], v[92:95]
	v_mfma_f32_16x16x32_bf16 v[88:91], v[208:211], v[168:171], v[88:91]
	v_mfma_f32_16x16x32_bf16 v[84:87], v[200:203], v[176:179], v[84:87]
	v_mfma_f32_16x16x32_bf16 v[80:83], v[208:211], v[176:179], v[80:83]
	v_mfma_f32_16x16x32_bf16 v[76:79], v[200:203], v[184:187], v[76:79]
	v_mfma_f32_16x16x32_bf16 v[72:75], v[208:211], v[184:187], v[72:75]
	v_mfma_f32_16x16x32_bf16 v[68:71], v[200:203], v[192:195], v[68:71]
	v_mfma_f32_16x16x32_bf16 v[64:67], v[208:211], v[192:195], v[64:67]
	v_mfma_f32_16x16x32_bf16 v[92:95], v[204:207], v[172:175], v[92:95]
	v_mfma_f32_16x16x32_bf16 v[88:91], v[216:219], v[172:175], v[88:91]
	v_mfma_f32_16x16x32_bf16 v[84:87], v[204:207], v[180:183], v[84:87]
	v_mfma_f32_16x16x32_bf16 v[80:83], v[216:219], v[180:183], v[80:83]
	v_mfma_f32_16x16x32_bf16 v[76:79], v[204:207], v[188:191], v[76:79]
	v_mfma_f32_16x16x32_bf16 v[72:75], v[216:219], v[188:191], v[72:75]
	v_mfma_f32_16x16x32_bf16 v[68:71], v[204:207], v[196:199], v[68:71]
	v_mfma_f32_16x16x32_bf16 v[64:67], v[216:219], v[196:199], v[64:67]
	s_mov_b32 m0, s17
	v_lshl_add_u64 v[152:153], v[220:221], 0, s[62:63]
	s_barrier
; __device__ __forceinline__ float sigm(float x) { return __builtin_amdgcn_rcpf(1.f + __expf(-x)); }
; #define PG8_STAGE(bufoff, gbase, voff) do { _Pragma("unroll") for (int _i = 0; _i < 2; ++_i) \
;         __builtin_amdgcn_global_load_lds((const unsigned*)((const char*)(gbase) + (voff)[_i]), (LAS unsigned*)(lds + (bufoff) + ldsw + _i * 8192), 16, 0, 0); } while (0)
; #define PG8_MMA(ai, bj, At, Bt) do { __builtin_amdgcn_s_setprio(1); _Pragma("unroll") for (int m = 0; m < 4; ++m) _Pragma("unroll") for (int n = 0; n < 2; ++n) _Pragma("unroll") for (int k = 0; k < 2; ++k) \
;         acc[ai][bj][m][n] = __builtin_amdgcn_mfma_f32_16x16x32_bf16(Bt[n][k], At[m][k], acc[ai][bj][m][n], 0, 0, 0); __builtin_amdgcn_s_setprio(0); } while (0)
; #define PG8_WAIT_V(n) asm volatile("s_waitcnt vmcnt(" #n ")" ::: "memory")
; #define PG8_WAIT_L(n) asm volatile("s_waitcnt lgkmcnt(" #n ")" ::: "memory")
; #define PG8_BAR __builtin_amdgcn_s_barrier()
; #define PG8_SCHED __builtin_amdgcn_sched_barrier(0)
; template <class Epi, class Sched>
; __device__ __forceinline__ void gemm_phase(LAS unsigned char* lds, const int K, const int lda, Sched& S, const Epi& E) {
;     ...
;             PG8_BAR; PG8_WAIT_L(0); PG8_MMA(1, 0, At, B0); PG8_BAR; PG8_SCHED;
;             PG8_STAGE(PG8_SB(1, 1), b3 + hstepB, voffB);
;             PG8_WAIT_V(6); PG8_BAR; PG8_MMA(1, 1, At, B1); PG8_BAR;
;     __device__ __forceinline__ void operator()(f32x4 (&acc)[2][2][4][2], const Unit& u, int wr, int wc, int fr, int fq) const {
;     ...
;         for (int bj = 0; bj < 2; ++bj) {
;             const int colb = u.pn * 256 + bj * 128;
;             if (colb >= NIN) continue;
;             const int act = colb >= OFF_MERGE ? 2 : (colb >= OFF_GATE ? 1 : 0);
;             u16* pb = proj + (size_t)(u.pm * 256 + wr * 64 + fr) * NIN + colb + wc * 32 + 8 * fq;
; #pragma unroll
;             for (int ai = 0; ai < 2; ++ai)
; #pragma unroll
;                 for (int m = 0; m < 4; ++m) {
;                     f32x4 v0 = acc[ai][bj][m][0], v1 = acc[ai][bj][m][1];
;                     if (act == 1) {
; #pragma unroll
;                         for (int j = 0; j < 4; ++j) { v0[j] = v0[j] * sigm(v0[j]); v1[j] = v1[j] * sigm(v1[j]); }
;                     } else if (act == 2) {
; #pragma unroll
;                         for (int j = 0; j < 4; ++j) { v0[j] = sigm(v0[j]); v1[j] = sigm(v1[j]); }
	ds_read_b128 v[168:171], v155 offset:49152
	ds_read_b128 v[172:175], v155 offset:50176
	ds_read_b128 v[176:179], v155 offset:51200
	ds_read_b128 v[180:183], v155 offset:52224
	ds_read_b128 v[184:187], v155 offset:53248
	ds_read_b128 v[188:191], v155 offset:54272
	ds_read_b128 v[192:195], v155 offset:55296
	ds_read_b128 v[196:199], v155 offset:56320
	global_load_lds_dwordx4 v[152:153], off
	v_lshl_add_u64 v[152:153], v[222:223], 0, s[62:63]
	s_mov_b32 m0, s18
	s_nop 0
	global_load_lds_dwordx4 v[152:153], off
	s_barrier
	s_waitcnt lgkmcnt(0)
	s_waitcnt lgkmcnt(0)
	v_mfma_f32_16x16x32_bf16 v[60:63], v[148:151], v[168:171], v[60:63]
	v_mfma_f32_16x16x32_bf16 v[56:59], v[160:163], v[168:171], v[56:59]
	v_mfma_f32_16x16x32_bf16 v[52:55], v[148:151], v[176:179], v[52:55]
	v_mfma_f32_16x16x32_bf16 v[48:51], v[160:163], v[176:179], v[48:51]
	v_mfma_f32_16x16x32_bf16 v[44:47], v[148:151], v[184:187], v[44:47]
	v_mfma_f32_16x16x32_bf16 v[40:43], v[160:163], v[184:187], v[40:43]
	v_mfma_f32_16x16x32_bf16 v[36:39], v[148:151], v[192:195], v[36:39]
	v_mfma_f32_16x16x32_bf16 v[32:35], v[160:163], v[192:195], v[32:35]
	v_mfma_f32_16x16x32_bf16 v[60:63], v[156:159], v[172:175], v[60:63]
	v_mfma_f32_16x16x32_bf16 v[56:59], v[164:167], v[172:175], v[56:59]
	v_mfma_f32_16x16x32_bf16 v[52:55], v[156:159], v[180:183], v[52:55]
	v_mfma_f32_16x16x32_bf16 v[48:51], v[164:167], v[180:183], v[48:51]
	v_mfma_f32_16x16x32_bf16 v[44:47], v[156:159], v[188:191], v[44:47]
	v_mfma_f32_16x16x32_bf16 v[40:43], v[164:167], v[188:191], v[40:43]
	v_mfma_f32_16x16x32_bf16 v[36:39], v[156:159], v[196:199], v[36:39]
	v_mfma_f32_16x16x32_bf16 v[32:35], v[164:167], v[196:199], v[32:35]
	s_barrier
	s_add_u32 s52, s88, 0x80080
	s_addc_u32 s53, s89, 0
	s_add_i32 s31, s54, s12
	v_lshl_add_u64 v[148:149], s[52:53], 0, v[130:131]
	s_mov_b32 m0, s31
	s_nop 0
	global_load_lds_dwordx4 v[148:149], off
	v_lshl_add_u64 v[148:149], s[52:53], 0, v[134:135]
	s_add_i32 m0, s31, 0x2000
	s_nop 0
	global_load_lds_dwordx4 v[148:149], off
	s_waitcnt vmcnt(6)
	s_barrier
	v_mfma_f32_16x16x32_bf16 v[28:31], v[200:203], v[168:171], v[28:31]
	v_mfma_f32_16x16x32_bf16 v[24:27], v[208:211], v[168:171], v[24:27]
	v_mfma_f32_16x16x32_bf16 v[20:23], v[200:203], v[176:179], v[20:23]
	v_mfma_f32_16x16x32_bf16 v[16:19], v[208:211], v[176:179], v[16:19]
	v_mfma_f32_16x16x32_bf16 v[12:15], v[200:203], v[184:187], v[12:15]
	v_mfma_f32_16x16x32_bf16 v[8:11], v[208:211], v[184:187], v[8:11]
	v_mfma_f32_16x16x32_bf16 v[4:7], v[200:203], v[192:195], v[4:7]
	v_mfma_f32_16x16x32_bf16 v[0:3], v[208:211], v[192:195], v[0:3]
	v_mfma_f32_16x16x32_bf16 v[28:31], v[204:207], v[172:175], v[28:31]
	v_mfma_f32_16x16x32_bf16 v[24:27], v[216:219], v[172:175], v[24:27]
	v_mfma_f32_16x16x32_bf16 v[20:23], v[204:207], v[180:183], v[20:23]
	v_mfma_f32_16x16x32_bf16 v[16:19], v[216:219], v[180:183], v[16:19]
	v_mfma_f32_16x16x32_bf16 v[12:15], v[204:207], v[188:191], v[12:15]
	v_mfma_f32_16x16x32_bf16 v[8:11], v[216:219], v[188:191], v[8:11]
	v_mfma_f32_16x16x32_bf16 v[4:7], v[204:207], v[196:199], v[4:7]
	v_mfma_f32_16x16x32_bf16 v[0:3], v[216:219], v[196:199], v[0:3]
	s_add_i32 s30, s30, 2
	s_add_u32 s86, s86, 0x100
	s_addc_u32 s87, s87, 0
	s_cmp_gt_u32 s30, 29
	s_barrier
	s_cbranch_scc0 .LBB0_1289
	s_lshl_b32 s86, s2, 8
	s_cmp_gt_i32 s2, 58
	s_cbranch_scc1 .LBB0_1333
	s_cmp_gt_i32 s2, 22
	s_cselect_b64 s[28:29], -1, 0
	v_cndmask_b32_e64 v136, 0, 1, s[28:29]
	s_cmp_lt_i32 s2, 35
	v_readfirstlane_b32 s10, v136
	s_cselect_b32 s27, s10, 2
	s_cmp_gt_i32 s27, 1
	s_mov_b64 s[88:89], -1
	s_cbranch_scc0 .LBB0_1293
	v_mul_f32_e32 v136, 0xbfb8aa3b, v124
	v_exp_f32_e32 v136, v136
	v_mul_f32_e32 v144, 0xbfb8aa3b, v120
	v_exp_f32_e32 v144, v144
	v_mul_f32_e32 v145, 0xbfb8aa3b, v121
	v_add_f32_e32 v136, 1.0, v136
	v_rcp_f32_e32 v146, v136
	v_mul_f32_e32 v136, 0xbfb8aa3b, v125
	v_exp_f32_e32 v136, v136
	v_exp_f32_e32 v145, v145
	v_add_f32_e32 v144, 1.0, v144
	v_rcp_f32_e32 v148, v144
	v_add_f32_e32 v136, 1.0, v136
	v_mul_f32_e32 v144, 0xbfb8aa3b, v126
	v_rcp_f32_e32 v147, v136
	v_add_f32_e32 v136, 1.0, v145
	v_exp_f32_e32 v144, v144
	v_mul_f32_e32 v145, 0xbfb8aa3b, v122
	v_exp_f32_e32 v145, v145
	v_rcp_f32_e32 v149, v136
	v_add_f32_e32 v136, 1.0, v144
	v_mul_f32_e32 v144, 0xbfb8aa3b, v127
	v_rcp_f32_e32 v150, v136
	v_add_f32_e32 v136, 1.0, v145
	v_exp_f32_e32 v144, v144
	v_mul_f32_e32 v145, 0xbfb8aa3b, v123
	v_exp_f32_e32 v145, v145
	v_rcp_f32_e32 v152, v136
	v_add_f32_e32 v136, 1.0, v144
	v_rcp_f32_e32 v151, v136
	v_add_f32_e32 v136, 1.0, v145
	v_rcp_f32_e32 v153, v136
	s_mov_b64 s[88:89], 0

; #define PG8_WAIT_V(n) asm volatile("s_waitcnt vmcnt(" #n ")" ::: "memory")
; #define PG8_BAR __builtin_amdgcn_s_barrier()
; template <class Epi, class Sched>
; __device__ __forceinline__ void gemm_phase(LAS unsigned char* lds, const int K, const int lda, Sched& S, const Epi& E) {
;     ...
;     PG8_WAIT_V(0);
;     if (wr == 0) PG8_BAR;
;     PG8_BAR;
.LBB0_1376:
	s_waitcnt vmcnt(0)
	s_setprio 0
	s_nop 0
	s_nop 0
	s_nop 0
	s_nop 0
	s_nop 0
	s_nop 0
	s_nop 0
	s_cmpk_gt_u32 s1, 0xff
	s_cbranch_scc1 .LBB0_1378
	s_barrier

; #define PG8_STAGE(bufoff, gbase, voff) do { _Pragma("unroll") for (int _i = 0; _i < 2; ++_i) \
;         __builtin_amdgcn_global_load_lds((const unsigned*)((const char*)(gbase) + (voff)[_i]), (LAS unsigned*)(lds + (bufoff) + ldsw + _i * 8192), 16, 0, 0); } while (0)
; #define PG8_BAR __builtin_amdgcn_s_barrier()
;     __device__ __forceinline__ const char* aptr(const Unit& u) const { return (const char*)(A + (size_t)u.pm * 256 * 2048); }
;     __device__ __forceinline__ const char* bptr(const Unit& u) const { return (const char*)(Bt + (size_t)u.pn * 256 * 2048); }
;     __device__ __forceinline__ const char* aptr(const Unit& u) const { return (const char*)(A + (size_t)u.pm * 256 * NIN + OFF_GATE + u.z * 1024); }
; template <class Epi, class Sched>
; __device__ __forceinline__ void gemm_phase(LAS unsigned char* lds, const int K, const int lda, Sched& S, const Epi& E) {
;     const int tid = opaque_tid(), wid = __builtin_amdgcn_readfirstlane(tid >> 6), lane = tid & 63, wr = wid >> 2, wc = wid & 3, fr = lane & 15, fq = lane >> 4;
;     const int nt = K / BK;
;     unsigned voffA[2], voffB[2];
; #pragma unroll
;     for (int i = 0; i < 2; ++i) { int R, C; stage_rc(tid * 16 + i * 8192, R, C); const int Rb = (R & ~31) + perm32(R & 31);
;         voffA[i] = (unsigned)(R * lda + C) * 2u; voffB[i] = (unsigned)(Rb * K + C) * 2u; }
;     const size_t kstep = (size_t)(BK * 2);
;     const size_t hstepA = (size_t)HALF * lda * 2, hstepB = (size_t)HALF * K * 2;
;     const unsigned ldsw = (unsigned)wid * 1024u;
;     const int aoff = lds_byte(wr * 64 + fr, fq * 8), boff = lds_byte(wc * 32 + fr, fq * 8);
;     ...
;     Unit cur, nxt; int ui = 0;
;     if (!S.next(0, cur)) return;
;     f32x4 acc[2][2][4][2];
; #pragma unroll
;     for (int a = 0; a < 2; ++a)
; #pragma unroll
;         for (int b = 0; b < 2; ++b)
; #pragma unroll
;             for (int m = 0; m < 4; ++m)
; #pragma unroll
;                 for (int n = 0; n < 2; ++n) acc[a][b][m][n] = (f32x4){0.f, 0.f, 0.f, 0.f};
;     bf16x8 At[4][2], B0[2][2], B1[2][2];
;     const char* cA = S.aptr(cur); const char* cB = S.bptr(cur);
;     PG8_STAGE(PG8_SB(0, 0), cB, voffB); PG8_STAGE(PG8_SA(0, 0), cA, voffA); PG8_STAGE(PG8_SB(0, 1), cB + hstepB, voffB); PG8_STAGE(PG8_SA(0, 1), cA + hstepA, voffA);
;     if (wr == 1) PG8_BAR;
.LBB0_2041:
	v_cndmask_b32_e64 v0, 0, 1, s[6:7]
	v_cmp_ne_u32_e64 s[96:97], 1, v0
	s_andn2_b64 vcc, exec, s[6:7]
	s_cbranch_vccnz .LBB0_2187
	v_ashrrev_i32_e32 v1, 31, v5
	v_lshrrev_b32_e32 v1, 26, v1
	v_add_u32_e32 v1, v5, v1
	v_ashrrev_i32_e32 v4, 6, v1
	v_bfe_i32 v1, v5, 27, 1
	v_lshlrev_b32_e32 v0, 4, v5
	v_lshrrev_b32_e32 v1, 22, v1
	v_add_u32_e32 v1, v0, v1
	v_and_b32_e32 v1, 0xfffffc00, v1
	v_sub_u32_e32 v1, v0, v1
	v_lshrrev_b32_e32 v2, 4, v1
	v_bitop3_b32 v2, v2, v1, 32 bitop3:0x6c
	v_ashrrev_i32_e32 v1, 31, v1
	v_lshrrev_b32_e32 v1, 26, v1
	v_lshlrev_b32_e32 v3, 3, v4
	v_add_u32_e32 v1, v2, v1
	v_and_b32_e32 v3, -16, v3
	v_ashrrev_i32_e32 v7, 6, v1
	v_add_u32_e32 v1, v7, v3
	v_lshlrev_b32_e32 v3, 5, v4
	v_and_b32_e32 v6, 32, v3
	v_mul_i32_i24_e32 v3, 64, v7
	v_sub_u32_e32 v2, v2, v3
	v_mov_b32_e32 v3, 1
	v_ashrrev_i16_sdwa v2, v3, sext(v2) dst_sel:DWORD dst_unused:UNUSED_PAD src0_sel:DWORD src1_sel:BYTE_0
	v_bfe_i32 v8, v2, 0, 16
	v_lshlrev_b32_e32 v9, 1, v1
	v_lshrrev_b32_e32 v10, 2, v1
	v_and_b32_e32 v11, 3, v7
	s_mov_b32 s1, 0x1fffe0
	s_movk_i32 s10, 0x3a80
	v_add_u32_e32 v2, v6, v8
	v_and_b32_e32 v9, 24, v9
	v_and_b32_e32 v10, 4, v10
	v_and_or_b32 v11, v1, s1, v11
	v_mul_lo_u32 v1, v1, s10
	v_or3_b32 v9, v11, v10, v9
	v_add_lshl_u32 v192, v2, v1, 1
	v_lshlrev_b32_e32 v1, 1, v2
	v_add_u32_e32 v0, 0x2000, v0
	v_lshl_add_u32 v194, v9, 11, v1
	v_ashrrev_i32_e32 v1, 31, v0
	v_lshrrev_b32_e32 v1, 22, v1
	v_add_u32_e32 v1, v0, v1
	v_ashrrev_i32_e32 v9, 10, v1
	v_mul_i32_i24_e32 v1, 0x400, v9
	v_sub_u32_e32 v0, v0, v1
	v_lshrrev_b32_e32 v1, 4, v0
	v_bitop3_b32 v0, v1, v0, 32 bitop3:0x6c
	v_ashrrev_i32_e32 v2, 31, v0
	v_lshrrev_b32_e32 v2, 26, v2
	v_lshlrev_b32_e32 v1, 3, v9
	v_add_u32_e32 v2, v0, v2
	v_and_b32_e32 v1, -16, v1
	v_ashrrev_i32_e32 v10, 6, v2
	v_add_u32_e32 v1, v10, v1
	v_and_b32_e32 v13, 3, v10
	s_ashr_i32 s17, s0, 6
	s_ashr_i32 s14, s0, 8
	v_and_or_b32 v13, v1, s1, v13
	s_lshl_b32 s1, s17, 10
	s_mul_i32 s3, s21, 0x750000
	v_readlane_b32 s6, v252, 40
	s_mul_hi_i32 s2, s21, 0x750000
	v_readlane_b32 s7, v252, 41
	s_add_u32 s15, s6, s3
	v_and_b32_e32 v2, 0xc0, v2
	s_addc_u32 s16, s7, s2
	s_ashr_i32 s5, s4, 31
	v_sub_u32_e32 v0, v0, v2
	s_lshl_b64 s[2:3], s[4:5], 19
	v_readlane_b32 s5, v252, 39
	v_lshlrev_b32_e32 v11, 5, v9
	v_ashrrev_i16_sdwa v0, v3, sext(v0) dst_sel:DWORD dst_unused:UNUSED_PAD src0_sel:DWORD src1_sel:BYTE_0
	s_add_u32 s8, s5, s2
	v_readlane_b32 s2, v252, 19
	v_and_b32_e32 v11, 32, v11
	v_bfe_i32 v12, v0, 0, 16
	v_lshlrev_b32_e32 v2, 1, v1
	v_lshrrev_b32_e32 v3, 2, v1
	s_addc_u32 s9, s2, s3
	s_add_i32 s2, s1, 0
	v_add_u32_e32 v0, v11, v12
	v_and_b32_e32 v2, 24, v2
	v_and_b32_e32 v3, 4, v3
	v_mul_lo_u32 v1, v1, s10
	s_add_i32 m0, s2, 0x10000
	v_or3_b32 v2, v13, v3, v2
	v_add_lshl_u32 v196, v0, v1, 1
	v_lshlrev_b32_e32 v0, 1, v0
	global_load_lds_dwordx4 v194, s[8:9]
	s_add_i32 m0, s2, 0x12000
	v_lshl_add_u32 v198, v2, 11, v0
	s_add_u32 s6, s15, 0x2d00
	global_load_lds_dwordx4 v198, s[8:9]
	s_addc_u32 s7, s16, 0
	s_mov_b32 m0, s2
	s_add_i32 s3, s2, 0x2000
	global_load_lds_dwordx4 v192, s[6:7]
	s_mov_b32 m0, s3
	s_add_u32 s12, s8, 0x40000
	global_load_lds_dwordx4 v196, s[6:7]
	s_addc_u32 s13, s9, 0
	s_add_i32 m0, s2, 0x14000
	v_mov_b32_e32 v201, 0
	global_load_lds_dwordx4 v194, s[12:13]
	s_add_i32 m0, s2, 0x16000
	s_add_u32 s18, s15, 0x3aad00
	global_load_lds_dwordx4 v198, s[12:13]
	s_addc_u32 s19, s16, 0
	s_add_i32 s12, s2, 0x4000
	s_mov_b32 m0, s12
	s_add_i32 s13, s2, 0x6000
	global_load_lds_dwordx4 v192, s[18:19]
	s_mov_b32 m0, s13
	v_mov_b32_e32 v195, v201
	global_load_lds_dwordx4 v196, s[18:19]
	v_mov_b32_e32 v199, v201
	s_mov_b32 s11, 0
	v_lshl_add_u64 v[2:3], s[8:9], 0, v[194:195]
	v_lshl_add_u64 v[0:1], s[8:9], 0, v[198:199]
	v_mov_b32_e32 v193, v201
	s_cmp_lg_u32 s14, 1
	v_mov_b32_e32 v197, v201
	s_cbranch_scc1 .LBB0_2044
	s_setprio 1
	s_nop 0
	s_nop 0
	s_nop 0
	s_nop 0
	s_nop 0
	s_nop 0
	s_nop 0
	s_barrier

; #define PG8_STAGE(bufoff, gbase, voff) do { _Pragma("unroll") for (int _i = 0; _i < 2; ++_i) \
;         __builtin_amdgcn_global_load_lds((const unsigned*)((const char*)(gbase) + (voff)[_i]), (LAS unsigned*)(lds + (bufoff) + ldsw + _i * 8192), 16, 0, 0); } while (0)
; #define PG8_LDA(dst, b, h) do { _Pragma("unroll") for (int m = 0; m < 4; ++m) _Pragma("unroll") for (int k = 0; k < 2; ++k) dst[m][k] = *(const LAS bf16x8*)(lds + PG8_SA(b, h) + aoff + m * 2048 + k * 1024); } while (0)
; #define PG8_LDB(dst, b, h) do { _Pragma("unroll") for (int n = 0; n < 2; ++n) _Pragma("unroll") for (int k = 0; k < 2; ++k) dst[n][k] = *(const LAS bf16x8*)(lds + PG8_SB(b, h) + boff + n * 2048 + k * 1024); } while (0)
; #define PG8_MMA(ai, bj, At, Bt) do { __builtin_amdgcn_s_setprio(1); _Pragma("unroll") for (int m = 0; m < 4; ++m) _Pragma("unroll") for (int n = 0; n < 2; ++n) _Pragma("unroll") for (int k = 0; k < 2; ++k) \
;         acc[ai][bj][m][n] = __builtin_amdgcn_mfma_f32_16x16x32_bf16(Bt[n][k], At[m][k], acc[ai][bj][m][n], 0, 0, 0); __builtin_amdgcn_s_setprio(0); } while (0)
; #define PG8_WAIT_L(n) asm volatile("s_waitcnt lgkmcnt(" #n ")" ::: "memory")
; #define PG8_BAR __builtin_amdgcn_s_barrier()
; #define PG8_SCHED __builtin_amdgcn_sched_barrier(0)
; template <class Epi, class Sched>
; __device__ __forceinline__ void gemm_phase(LAS unsigned char* lds, const int K, const int lda, Sched& S, const Epi& E) {
;     ...
;         for (int t = 0; t < nt; t += 2) {
;             const bool last = (t == nt - 2);
;             const char* a1 = cA + (size_t)(t + 1) * kstep;
;             const char* a2 = last ? nA : cA + (size_t)(t + 2) * kstep; const char* b2 = last ? nB : cB + (size_t)(t + 2) * kstep;
;             const char* a3 = a2 + kstep; const char* b3 = b2 + kstep;
;             PG8_LDB(B0, 0, 0); PG8_SCHED; PG8_LDA(At, 0, 0); PG8_STAGE(PG8_SA(1, 1), a1 + hstepA, voffA);
;             PG8_WAIT_L(8); PG8_BAR; PG8_WAIT_L(0); PG8_MMA(0, 0, At, B0); PG8_BAR; PG8_SCHED;
;             PG8_LDB(B1, 0, 1); PG8_STAGE(PG8_SB(0, 0), b2, voffB);
;             PG8_BAR; PG8_WAIT_L(0); PG8_MMA(0, 1, At, B1); PG8_BAR;
;             PG8_LDA(At, 0, 1); PG8_STAGE(PG8_SA(0, 0), a2, voffA);
;             PG8_BAR; PG8_WAIT_L(0); PG8_MMA(1, 0, At, B0); PG8_BAR; PG8_SCHED;
.LBB0_2052:
	v_add_u32_e32 v140, s16, v216
	ds_read_b128 v[128:131], v140
	ds_read_b128 v[132:135], v140 offset:1024
	ds_read_b128 v[136:139], v140 offset:2048
	ds_read_b128 v[140:143], v140 offset:3072
	s_add_u32 s8, s6, 0x100
	s_addc_u32 s9, s7, 0
	s_cmp_eq_u32 s25, 12
	s_cselect_b32 s85, s77, s9
	s_cselect_b32 s84, s76, s8
	s_cselect_b32 s83, s5, s24
	s_cselect_b32 s82, s22, s23
	v_lshl_add_u64 v[176:177], s[6:7], 0, v[202:203]
	s_add_i32 m0, s2, 0xc000
	ds_read_b128 v[144:147], v217
	ds_read_b128 v[148:151], v217 offset:1024
	ds_read_b128 v[152:155], v217 offset:2048
	ds_read_b128 v[156:159], v217 offset:3072
	ds_read_b128 v[160:163], v217 offset:4096
	ds_read_b128 v[164:167], v217 offset:5120
	ds_read_b128 v[168:171], v217 offset:6144
	ds_read_b128 v[172:175], v217 offset:7168
	global_load_lds_dwordx4 v[176:177], off
	v_lshl_add_u64 v[176:177], s[6:7], 0, v[204:205]
	s_add_i32 m0, s2, 0xe000
	s_nop 0
	global_load_lds_dwordx4 v[176:177], off
	s_waitcnt lgkmcnt(8)
	s_barrier
	s_waitcnt lgkmcnt(0)
	s_waitcnt lgkmcnt(0)
	v_mfma_f32_16x16x32_bf16 v[124:127], v[128:131], v[144:147], v[124:127]
	v_mfma_f32_16x16x32_bf16 v[120:123], v[136:139], v[144:147], v[120:123]
	v_mfma_f32_16x16x32_bf16 v[116:119], v[128:131], v[152:155], v[116:119]
	v_mfma_f32_16x16x32_bf16 v[112:115], v[136:139], v[152:155], v[112:115]
	v_mfma_f32_16x16x32_bf16 v[108:111], v[128:131], v[160:163], v[108:111]
	v_mfma_f32_16x16x32_bf16 v[104:107], v[136:139], v[160:163], v[104:107]
	v_mfma_f32_16x16x32_bf16 v[100:103], v[128:131], v[168:171], v[100:103]
	v_mfma_f32_16x16x32_bf16 v[96:99], v[136:139], v[168:171], v[96:99]
	v_mfma_f32_16x16x32_bf16 v[124:127], v[132:135], v[148:151], v[124:127]
	v_mfma_f32_16x16x32_bf16 v[120:123], v[140:143], v[148:151], v[120:123]
	v_mfma_f32_16x16x32_bf16 v[116:119], v[132:135], v[156:159], v[116:119]
	v_mfma_f32_16x16x32_bf16 v[112:115], v[140:143], v[156:159], v[112:115]
	v_mfma_f32_16x16x32_bf16 v[108:111], v[132:135], v[164:167], v[108:111]
	v_mfma_f32_16x16x32_bf16 v[104:107], v[140:143], v[164:167], v[104:107]
	v_mfma_f32_16x16x32_bf16 v[100:103], v[132:135], v[172:175], v[100:103]
	v_mfma_f32_16x16x32_bf16 v[96:99], v[140:143], v[172:175], v[96:99]
	s_barrier
	s_add_i32 s6, s16, s1
	v_add_u32_e32 v188, s17, v216
	v_lshl_add_u64 v[206:207], s[82:83], 0, v[194:195]
	s_mov_b32 m0, s6
	ds_read_b128 v[176:179], v188
	ds_read_b128 v[180:183], v188 offset:1024
	ds_read_b128 v[184:187], v188 offset:2048
	ds_read_b128 v[188:191], v188 offset:3072
	global_load_lds_dwordx4 v[206:207], off
	v_lshl_add_u64 v[208:209], s[82:83], 0, v[198:199]
	s_add_i32 m0, s6, 0x2000
	s_nop 0
	global_load_lds_dwordx4 v[208:209], off
	s_barrier
	s_waitcnt lgkmcnt(0)
	s_waitcnt lgkmcnt(0)
	v_mfma_f32_16x16x32_bf16 v[92:95], v[176:179], v[144:147], v[92:95]
	v_mfma_f32_16x16x32_bf16 v[88:91], v[184:187], v[144:147], v[88:91]
	v_mfma_f32_16x16x32_bf16 v[84:87], v[176:179], v[152:155], v[84:87]
	v_mfma_f32_16x16x32_bf16 v[80:83], v[184:187], v[152:155], v[80:83]
	v_mfma_f32_16x16x32_bf16 v[76:79], v[176:179], v[160:163], v[76:79]
	v_mfma_f32_16x16x32_bf16 v[72:75], v[184:187], v[160:163], v[72:75]
	v_mfma_f32_16x16x32_bf16 v[68:71], v[176:179], v[168:171], v[68:71]
	v_mfma_f32_16x16x32_bf16 v[64:67], v[184:187], v[168:171], v[64:67]
	v_mfma_f32_16x16x32_bf16 v[92:95], v[180:183], v[148:151], v[92:95]
	v_mfma_f32_16x16x32_bf16 v[88:91], v[188:191], v[148:151], v[88:91]
	v_mfma_f32_16x16x32_bf16 v[84:87], v[180:183], v[156:159], v[84:87]
	v_mfma_f32_16x16x32_bf16 v[80:83], v[188:191], v[156:159], v[80:83]
	v_mfma_f32_16x16x32_bf16 v[76:79], v[180:183], v[164:167], v[76:79]
	v_mfma_f32_16x16x32_bf16 v[72:75], v[188:191], v[164:167], v[72:75]
	v_mfma_f32_16x16x32_bf16 v[68:71], v[180:183], v[172:175], v[68:71]
	v_mfma_f32_16x16x32_bf16 v[64:67], v[188:191], v[172:175], v[64:67]
	s_mov_b32 m0, s2
	v_lshl_add_u64 v[210:211], s[84:85], 0, v[192:193]
	s_barrier
	ds_read_b128 v[144:147], v217 offset:16384
	ds_read_b128 v[148:151], v217 offset:17408
	ds_read_b128 v[152:155], v217 offset:18432
	ds_read_b128 v[156:159], v217 offset:19456
	ds_read_b128 v[160:163], v217 offset:20480
	ds_read_b128 v[164:167], v217 offset:21504
	ds_read_b128 v[168:171], v217 offset:22528
	ds_read_b128 v[172:175], v217 offset:23552
	global_load_lds_dwordx4 v[210:211], off
	v_lshl_add_u64 v[212:213], s[84:85], 0, v[196:197]
	s_mov_b32 m0, s3
	s_nop 0
	global_load_lds_dwordx4 v[212:213], off
	s_barrier
	s_waitcnt lgkmcnt(0)
	s_waitcnt lgkmcnt(0)
	v_mfma_f32_16x16x32_bf16 v[60:63], v[128:131], v[144:147], v[60:63]
	v_mfma_f32_16x16x32_bf16 v[56:59], v[136:139], v[144:147], v[56:59]
	v_mfma_f32_16x16x32_bf16 v[52:55], v[128:131], v[152:155], v[52:55]
	v_mfma_f32_16x16x32_bf16 v[48:51], v[136:139], v[152:155], v[48:51]
	v_mfma_f32_16x16x32_bf16 v[44:47], v[128:131], v[160:163], v[44:47]
	v_mfma_f32_16x16x32_bf16 v[40:43], v[136:139], v[160:163], v[40:43]
	v_mfma_f32_16x16x32_bf16 v[36:39], v[128:131], v[168:171], v[36:39]
	v_mfma_f32_16x16x32_bf16 v[32:35], v[136:139], v[168:171], v[32:35]
	v_mfma_f32_16x16x32_bf16 v[60:63], v[132:135], v[148:151], v[60:63]
	v_mfma_f32_16x16x32_bf16 v[56:59], v[140:143], v[148:151], v[56:59]
	v_mfma_f32_16x16x32_bf16 v[52:55], v[132:135], v[156:159], v[52:55]
	v_mfma_f32_16x16x32_bf16 v[48:51], v[140:143], v[156:159], v[48:51]
	v_mfma_f32_16x16x32_bf16 v[44:47], v[132:135], v[164:167], v[44:47]
	v_mfma_f32_16x16x32_bf16 v[40:43], v[140:143], v[164:167], v[40:43]
	v_mfma_f32_16x16x32_bf16 v[36:39], v[132:135], v[172:175], v[36:39]
	v_mfma_f32_16x16x32_bf16 v[32:35], v[140:143], v[172:175], v[32:35]
	s_barrier
; #define PG8_STAGE(bufoff, gbase, voff) do { _Pragma("unroll") for (int _i = 0; _i < 2; ++_i) \
;         __builtin_amdgcn_global_load_lds((const unsigned*)((const char*)(gbase) + (voff)[_i]), (LAS unsigned*)(lds + (bufoff) + ldsw + _i * 8192), 16, 0, 0); } while (0)
; #define PG8_LDA(dst, b, h) do { _Pragma("unroll") for (int m = 0; m < 4; ++m) _Pragma("unroll") for (int k = 0; k < 2; ++k) dst[m][k] = *(const LAS bf16x8*)(lds + PG8_SA(b, h) + aoff + m * 2048 + k * 1024); } while (0)
; #define PG8_LDB(dst, b, h) do { _Pragma("unroll") for (int n = 0; n < 2; ++n) _Pragma("unroll") for (int k = 0; k < 2; ++k) dst[n][k] = *(const LAS bf16x8*)(lds + PG8_SB(b, h) + boff + n * 2048 + k * 1024); } while (0)
; #define PG8_MMA(ai, bj, At, Bt) do { __builtin_amdgcn_s_setprio(1); _Pragma("unroll") for (int m = 0; m < 4; ++m) _Pragma("unroll") for (int n = 0; n < 2; ++n) _Pragma("unroll") for (int k = 0; k < 2; ++k) \
;         acc[ai][bj][m][n] = __builtin_amdgcn_mfma_f32_16x16x32_bf16(Bt[n][k], At[m][k], acc[ai][bj][m][n], 0, 0, 0); __builtin_amdgcn_s_setprio(0); } while (0)
; #define PG8_WAIT_V(n) asm volatile("s_waitcnt vmcnt(" #n ")" ::: "memory")
; #define PG8_WAIT_L(n) asm volatile("s_waitcnt lgkmcnt(" #n ")" ::: "memory")
; #define PG8_BAR __builtin_amdgcn_s_barrier()
; #define PG8_SCHED __builtin_amdgcn_sched_barrier(0)
; template <class Epi, class Sched>
; __device__ __forceinline__ void gemm_phase(LAS unsigned char* lds, const int K, const int lda, Sched& S, const Epi& E) {
;     ...
;             PG8_STAGE(PG8_SB(0, 1), b2 + hstepB, voffB);
;             PG8_WAIT_V(6); PG8_BAR; PG8_MMA(1, 1, At, B1); PG8_BAR;
;             PG8_LDB(B0, 1, 0); PG8_SCHED; PG8_LDA(At, 1, 0); PG8_STAGE(PG8_SA(0, 1), a2 + hstepA, voffA);
;             PG8_WAIT_L(8); PG8_BAR; PG8_WAIT_L(0); PG8_MMA(0, 0, At, B0); PG8_BAR; PG8_SCHED;
;             PG8_LDB(B1, 1, 1); PG8_STAGE(PG8_SB(1, 0), b3, voffB);
;             PG8_BAR; PG8_WAIT_L(0); PG8_MMA(0, 1, At, B1); PG8_BAR;
;             PG8_LDA(At, 1, 1); PG8_STAGE(PG8_SA(1, 0), a3, voffA);
;             PG8_BAR; PG8_WAIT_L(0); PG8_MMA(1, 0, At, B0); PG8_BAR; PG8_SCHED;
	s_add_u32 s6, s82, 0x40000
	s_addc_u32 s7, s83, 0
	s_add_i32 s27, s17, s1
	v_lshl_add_u64 v[128:129], s[6:7], 0, v[194:195]
	s_mov_b32 m0, s27
	s_nop 0
	global_load_lds_dwordx4 v[128:129], off
	v_lshl_add_u64 v[128:129], s[6:7], 0, v[198:199]
	s_add_i32 m0, s27, 0x2000
	s_nop 0
	global_load_lds_dwordx4 v[128:129], off
	s_waitcnt vmcnt(6)
	s_barrier
	v_mfma_f32_16x16x32_bf16 v[28:31], v[176:179], v[144:147], v[28:31]
	v_mfma_f32_16x16x32_bf16 v[24:27], v[184:187], v[144:147], v[24:27]
	v_mfma_f32_16x16x32_bf16 v[20:23], v[176:179], v[152:155], v[20:23]
	v_mfma_f32_16x16x32_bf16 v[16:19], v[184:187], v[152:155], v[16:19]
	v_mfma_f32_16x16x32_bf16 v[12:15], v[176:179], v[160:163], v[12:15]
	v_mfma_f32_16x16x32_bf16 v[8:11], v[184:187], v[160:163], v[8:11]
	v_mfma_f32_16x16x32_bf16 v[4:7], v[176:179], v[168:171], v[4:7]
	v_mfma_f32_16x16x32_bf16 v[0:3], v[184:187], v[168:171], v[0:3]
	v_mfma_f32_16x16x32_bf16 v[28:31], v[180:183], v[148:151], v[28:31]
	v_mfma_f32_16x16x32_bf16 v[24:27], v[188:191], v[148:151], v[24:27]
	v_mfma_f32_16x16x32_bf16 v[20:23], v[180:183], v[156:159], v[20:23]
	v_mfma_f32_16x16x32_bf16 v[16:19], v[188:191], v[156:159], v[16:19]
	v_mfma_f32_16x16x32_bf16 v[12:15], v[180:183], v[164:167], v[12:15]
	v_mfma_f32_16x16x32_bf16 v[8:11], v[188:191], v[164:167], v[8:11]
	v_mfma_f32_16x16x32_bf16 v[4:7], v[180:183], v[172:175], v[4:7]
	v_mfma_f32_16x16x32_bf16 v[0:3], v[188:191], v[172:175], v[0:3]
	s_add_i32 s27, 0, 0x18000
	v_add_u32_e32 v140, s27, v216
	s_barrier
	ds_read_b128 v[128:131], v140
	ds_read_b128 v[132:135], v140 offset:1024
	ds_read_b128 v[136:139], v140 offset:2048
	ds_read_b128 v[140:143], v140 offset:3072
	s_add_u32 s6, s84, 0x3a8000
	s_addc_u32 s7, s85, 0
	s_mov_b32 m0, s12
	v_lshl_add_u64 v[176:177], s[6:7], 0, v[192:193]
	ds_read_b128 v[144:147], v217 offset:32768
	ds_read_b128 v[148:151], v217 offset:33792
	ds_read_b128 v[152:155], v217 offset:34816
	ds_read_b128 v[156:159], v217 offset:35840
	ds_read_b128 v[160:163], v217 offset:36864
	ds_read_b128 v[164:167], v217 offset:37888
	ds_read_b128 v[168:171], v217 offset:38912
	ds_read_b128 v[172:175], v217 offset:39936
	global_load_lds_dwordx4 v[176:177], off
	v_lshl_add_u64 v[176:177], s[6:7], 0, v[196:197]
	s_mov_b32 m0, s13
	s_nop 0
	global_load_lds_dwordx4 v[176:177], off
	s_waitcnt lgkmcnt(8)
	s_barrier
	s_waitcnt lgkmcnt(0)
	s_waitcnt lgkmcnt(0)
	v_mfma_f32_16x16x32_bf16 v[124:127], v[128:131], v[144:147], v[124:127]
	v_mfma_f32_16x16x32_bf16 v[120:123], v[136:139], v[144:147], v[120:123]
	v_mfma_f32_16x16x32_bf16 v[116:119], v[128:131], v[152:155], v[116:119]
	v_mfma_f32_16x16x32_bf16 v[112:115], v[136:139], v[152:155], v[112:115]
	v_mfma_f32_16x16x32_bf16 v[108:111], v[128:131], v[160:163], v[108:111]
	v_mfma_f32_16x16x32_bf16 v[104:107], v[136:139], v[160:163], v[104:107]
	v_mfma_f32_16x16x32_bf16 v[100:103], v[128:131], v[168:171], v[100:103]
	v_mfma_f32_16x16x32_bf16 v[96:99], v[136:139], v[168:171], v[96:99]
	v_mfma_f32_16x16x32_bf16 v[124:127], v[132:135], v[148:151], v[124:127]
	v_mfma_f32_16x16x32_bf16 v[120:123], v[140:143], v[148:151], v[120:123]
	v_mfma_f32_16x16x32_bf16 v[116:119], v[132:135], v[156:159], v[116:119]
	v_mfma_f32_16x16x32_bf16 v[112:115], v[140:143], v[156:159], v[112:115]
	v_mfma_f32_16x16x32_bf16 v[108:111], v[132:135], v[164:167], v[108:111]
	v_mfma_f32_16x16x32_bf16 v[104:107], v[140:143], v[164:167], v[104:107]
	v_mfma_f32_16x16x32_bf16 v[100:103], v[132:135], v[172:175], v[100:103]
	v_mfma_f32_16x16x32_bf16 v[96:99], v[140:143], v[172:175], v[96:99]
	s_barrier
	s_add_i32 s28, 0, 0x1c000
	s_add_i32 s6, s27, s1
	v_add_u32_e32 v188, s28, v216
	v_lshl_add_u64 v[206:207], v[206:207], 0, s[62:63]
	s_mov_b32 m0, s6
	ds_read_b128 v[176:179], v188
	ds_read_b128 v[180:183], v188 offset:1024
	ds_read_b128 v[184:187], v188 offset:2048
	ds_read_b128 v[188:191], v188 offset:3072
	global_load_lds_dwordx4 v[206:207], off
	v_lshl_add_u64 v[206:207], v[208:209], 0, s[62:63]
	s_add_i32 m0, s6, 0x2000
	s_nop 0
	global_load_lds_dwordx4 v[206:207], off
	s_barrier
	s_waitcnt lgkmcnt(0)
	s_waitcnt lgkmcnt(0)
	v_mfma_f32_16x16x32_bf16 v[92:95], v[176:179], v[144:147], v[92:95]
	v_mfma_f32_16x16x32_bf16 v[88:91], v[184:187], v[144:147], v[88:91]
	v_mfma_f32_16x16x32_bf16 v[84:87], v[176:179], v[152:155], v[84:87]
	v_mfma_f32_16x16x32_bf16 v[80:83], v[184:187], v[152:155], v[80:83]
	v_mfma_f32_16x16x32_bf16 v[76:79], v[176:179], v[160:163], v[76:79]
	v_mfma_f32_16x16x32_bf16 v[72:75], v[184:187], v[160:163], v[72:75]
	v_mfma_f32_16x16x32_bf16 v[68:71], v[176:179], v[168:171], v[68:71]
	v_mfma_f32_16x16x32_bf16 v[64:67], v[184:187], v[168:171], v[64:67]
	v_mfma_f32_16x16x32_bf16 v[92:95], v[180:183], v[148:151], v[92:95]
	v_mfma_f32_16x16x32_bf16 v[88:91], v[188:191], v[148:151], v[88:91]
	v_mfma_f32_16x16x32_bf16 v[84:87], v[180:183], v[156:159], v[84:87]
	v_mfma_f32_16x16x32_bf16 v[80:83], v[188:191], v[156:159], v[80:83]
	v_mfma_f32_16x16x32_bf16 v[76:79], v[180:183], v[164:167], v[76:79]
	v_mfma_f32_16x16x32_bf16 v[72:75], v[188:191], v[164:167], v[72:75]
	v_mfma_f32_16x16x32_bf16 v[68:71], v[180:183], v[172:175], v[68:71]
	v_mfma_f32_16x16x32_bf16 v[64:67], v[188:191], v[172:175], v[64:67]
	s_mov_b32 m0, s14
	v_lshl_add_u64 v[206:207], v[210:211], 0, s[62:63]
	s_barrier
; #define PG8_STAGE(bufoff, gbase, voff) do { _Pragma("unroll") for (int _i = 0; _i < 2; ++_i) \
;         __builtin_amdgcn_global_load_lds((const unsigned*)((const char*)(gbase) + (voff)[_i]), (LAS unsigned*)(lds + (bufoff) + ldsw + _i * 8192), 16, 0, 0); } while (0)
; #define PG8_MMA(ai, bj, At, Bt) do { __builtin_amdgcn_s_setprio(1); _Pragma("unroll") for (int m = 0; m < 4; ++m) _Pragma("unroll") for (int n = 0; n < 2; ++n) _Pragma("unroll") for (int k = 0; k < 2; ++k) \
;         acc[ai][bj][m][n] = __builtin_amdgcn_mfma_f32_16x16x32_bf16(Bt[n][k], At[m][k], acc[ai][bj][m][n], 0, 0, 0); __builtin_amdgcn_s_setprio(0); } while (0)
; #define PG8_WAIT_V(n) asm volatile("s_waitcnt vmcnt(" #n ")" ::: "memory")
; #define PG8_WAIT_L(n) asm volatile("s_waitcnt lgkmcnt(" #n ")" ::: "memory")
; #define PG8_BAR __builtin_amdgcn_s_barrier()
; #define PG8_SCHED __builtin_amdgcn_sched_barrier(0)
; template <class Epi, class Sched>
; __device__ __forceinline__ void gemm_phase(LAS unsigned char* lds, const int K, const int lda, Sched& S, const Epi& E) {
;     ...
;             PG8_BAR; PG8_WAIT_L(0); PG8_MMA(1, 0, At, B0); PG8_BAR; PG8_SCHED;
;             PG8_STAGE(PG8_SB(1, 1), b3 + hstepB, voffB);
;             PG8_WAIT_V(6); PG8_BAR; PG8_MMA(1, 1, At, B1); PG8_BAR;
;     __device__ __forceinline__ void operator()(f32x4 (&acc)[2][2][4][2], const Unit& u, int wr, int wc, int fr, int fq) const {
;         const int b = u.z;
;         const u16* gbase = proj + (size_t)(u.pm * 256 + wr * 64 + fr) * NIN + OFF_MERGE + b * 2048 + u.pn * 256 + wc * 32 + 8 * fq;
;         u16* mbase = merged + (size_t)(u.pm * 256 + wr * 64 + fr) * 2048 + u.pn * 256 + wc * 32 + 8 * fq;
; #pragma unroll
;         for (int ai = 0; ai < 2; ++ai) {
;             u32x4 g[4][2], gn[4][2];
; #pragma unroll
;             for (int m = 0; m < 4; ++m)
; #pragma unroll
;                 for (int bj = 0; bj < 2; ++bj) {
;                     const u16* gp = gbase + (size_t)(ai * 128 + m * 16) * NIN + bj * 128;
;                     g[m][bj] = *(const u32x4*)gp;
;                     if (b < 2) gn[m][bj] = *(const u32x4*)(gp + 2048);
;                 }
	ds_read_b128 v[144:147], v217 offset:49152
	ds_read_b128 v[148:151], v217 offset:50176
	ds_read_b128 v[152:155], v217 offset:51200
	ds_read_b128 v[156:159], v217 offset:52224
	ds_read_b128 v[160:163], v217 offset:53248
	ds_read_b128 v[164:167], v217 offset:54272
	ds_read_b128 v[168:171], v217 offset:55296
	ds_read_b128 v[172:175], v217 offset:56320
	global_load_lds_dwordx4 v[206:207], off
	v_lshl_add_u64 v[206:207], v[212:213], 0, s[62:63]
	s_mov_b32 m0, s15
	s_nop 0
	global_load_lds_dwordx4 v[206:207], off
	s_barrier
	s_waitcnt lgkmcnt(0)
	s_waitcnt lgkmcnt(0)
	v_mfma_f32_16x16x32_bf16 v[60:63], v[128:131], v[144:147], v[60:63]
	v_mfma_f32_16x16x32_bf16 v[56:59], v[136:139], v[144:147], v[56:59]
	v_mfma_f32_16x16x32_bf16 v[52:55], v[128:131], v[152:155], v[52:55]
	v_mfma_f32_16x16x32_bf16 v[48:51], v[136:139], v[152:155], v[48:51]
	v_mfma_f32_16x16x32_bf16 v[44:47], v[128:131], v[160:163], v[44:47]
	v_mfma_f32_16x16x32_bf16 v[40:43], v[136:139], v[160:163], v[40:43]
	v_mfma_f32_16x16x32_bf16 v[36:39], v[128:131], v[168:171], v[36:39]
	v_mfma_f32_16x16x32_bf16 v[32:35], v[136:139], v[168:171], v[32:35]
	v_mfma_f32_16x16x32_bf16 v[60:63], v[132:135], v[148:151], v[60:63]
	v_mfma_f32_16x16x32_bf16 v[56:59], v[140:143], v[148:151], v[56:59]
	v_mfma_f32_16x16x32_bf16 v[52:55], v[132:135], v[156:159], v[52:55]
	v_mfma_f32_16x16x32_bf16 v[48:51], v[140:143], v[156:159], v[48:51]
	v_mfma_f32_16x16x32_bf16 v[44:47], v[132:135], v[164:167], v[44:47]
	v_mfma_f32_16x16x32_bf16 v[40:43], v[140:143], v[164:167], v[40:43]
	v_mfma_f32_16x16x32_bf16 v[36:39], v[132:135], v[172:175], v[36:39]
	v_mfma_f32_16x16x32_bf16 v[32:35], v[140:143], v[172:175], v[32:35]
	s_barrier
	s_add_u32 s6, s82, 0x40080
	s_addc_u32 s7, s83, 0
	s_add_i32 s27, s28, s1
	v_lshl_add_u64 v[128:129], s[6:7], 0, v[194:195]
	s_mov_b32 m0, s27
	s_nop 0
	global_load_lds_dwordx4 v[128:129], off
	v_lshl_add_u64 v[128:129], s[6:7], 0, v[198:199]
	s_add_i32 m0, s27, 0x2000
	s_nop 0
	global_load_lds_dwordx4 v[128:129], off
	s_waitcnt vmcnt(6)
	s_barrier
	v_mfma_f32_16x16x32_bf16 v[28:31], v[176:179], v[144:147], v[28:31]
	v_mfma_f32_16x16x32_bf16 v[24:27], v[184:187], v[144:147], v[24:27]
	v_mfma_f32_16x16x32_bf16 v[20:23], v[176:179], v[152:155], v[20:23]
	v_mfma_f32_16x16x32_bf16 v[16:19], v[184:187], v[152:155], v[16:19]
	v_mfma_f32_16x16x32_bf16 v[12:15], v[176:179], v[160:163], v[12:15]
	v_mfma_f32_16x16x32_bf16 v[8:11], v[184:187], v[160:163], v[8:11]
	v_mfma_f32_16x16x32_bf16 v[4:7], v[176:179], v[168:171], v[4:7]
	v_mfma_f32_16x16x32_bf16 v[0:3], v[184:187], v[168:171], v[0:3]
	v_mfma_f32_16x16x32_bf16 v[28:31], v[180:183], v[148:151], v[28:31]
	v_mfma_f32_16x16x32_bf16 v[24:27], v[188:191], v[148:151], v[24:27]
	v_mfma_f32_16x16x32_bf16 v[20:23], v[180:183], v[156:159], v[20:23]
	v_mfma_f32_16x16x32_bf16 v[16:19], v[188:191], v[156:159], v[16:19]
	v_mfma_f32_16x16x32_bf16 v[12:15], v[180:183], v[164:167], v[12:15]
	v_mfma_f32_16x16x32_bf16 v[8:11], v[188:191], v[164:167], v[8:11]
	v_mfma_f32_16x16x32_bf16 v[4:7], v[180:183], v[172:175], v[4:7]
	v_mfma_f32_16x16x32_bf16 v[0:3], v[188:191], v[172:175], v[0:3]
	s_add_i32 s25, s25, 2
	s_add_u32 s23, s23, 0x100
	s_addc_u32 s24, s24, 0
	s_cmp_gt_u32 s25, 13
	s_mov_b64 s[6:7], s[8:9]
	s_barrier
	s_cbranch_scc0 .LBB0_2052
	v_readlane_b32 s6, v252, 40
	v_readlane_b32 s7, v252, 41
	v_lshl_add_u32 v206, s21, 8, v215
	s_movk_i32 s5, 0x7500
	v_mov_b64_e32 v[128:129], s[6:7]
	v_mad_i64_i32 v[128:129], s[6:7], v206, s5, v[128:129]
	s_lshl_b32 s6, s20, 11
	s_ashr_i32 s7, s6, 31
	v_lshl_add_u64 v[128:129], s[6:7], 1, v[128:129]
	s_lshl_b32 s6, s4, 8
	s_ashr_i32 s7, s6, 31
	v_lshl_add_u64 v[128:129], s[6:7], 1, v[128:129]
	v_lshl_add_u64 v[128:129], v[128:129], 0, s[10:11]
	v_lshl_add_u64 v[128:129], v[128:129], 0, v[200:201]
	v_add_co_u32_e32 v130, vcc, 0x4000, v128
	s_mov_b64 s[4:5], 0x4500
	s_nop 0
	v_addc_co_u32_e32 v131, vcc, 0, v129, vcc
	global_load_dwordx4 v[188:191], v[130:131], off offset:1280
	s_cmp_lt_i32 s20, 2
	v_lshl_add_u64 v[208:209], v[128:129], 0, s[4:5]
	s_cselect_b64 s[4:5], -1, 0
	s_cmp_gt_i32 s20, 1
	s_cselect_b64 s[82:83], -1, 0
	s_and_b64 vcc, exec, s[82:83]
	s_cbranch_vccnz .LBB0_2055
	v_add_co_u32_e32 v128, vcc, 0x1000, v208
	s_nop 1
	v_addc_co_u32_e32 v129, vcc, 0, v209, vcc
	global_load_dwordx4 v[156:159], v[128:129], off

; #define PG8_WAIT_V(n) asm volatile("s_waitcnt vmcnt(" #n ")" ::: "memory")
; #define PG8_BAR __builtin_amdgcn_s_barrier()
; template <class Epi, class Sched>
; __device__ __forceinline__ void gemm_phase(LAS unsigned char* lds, const int K, const int lda, Sched& S, const Epi& E) {
;     ...
;     PG8_WAIT_V(0);
;     if (wr == 0) PG8_BAR;
;     PG8_BAR;
.LBB0_2184:
	s_waitcnt vmcnt(0)
	s_setprio 0
	s_nop 0
	s_nop 0
	s_nop 0
	s_nop 0
	s_nop 0
	s_nop 0
	s_nop 0
	s_cmpk_gt_u32 s0, 0xff
	s_cbranch_scc1 .LBB0_2186
	s_barrier

; #define PG8_STAGE(bufoff, gbase, voff) do { _Pragma("unroll") for (int _i = 0; _i < 2; ++_i) \
;         __builtin_amdgcn_global_load_lds((const unsigned*)((const char*)(gbase) + (voff)[_i]), (LAS unsigned*)(lds + (bufoff) + ldsw + _i * 8192), 16, 0, 0); } while (0)
; #define PG8_BAR __builtin_amdgcn_s_barrier()
;     __device__ __forceinline__ const char* aptr(const Unit& u) const { return (const char*)(A + (size_t)u.pm * 256 * 2048); }
;     __device__ __forceinline__ const char* bptr(const Unit& u) const { return (const char*)(Bt + (size_t)u.pn * 256 * 2048); }
; template <class Epi, class Sched>
; __device__ __forceinline__ void gemm_phase(LAS unsigned char* lds, const int K, const int lda, Sched& S, const Epi& E) {
;     const int tid = opaque_tid(), wid = __builtin_amdgcn_readfirstlane(tid >> 6), lane = tid & 63, wr = wid >> 2, wc = wid & 3, fr = lane & 15, fq = lane >> 4;
;     const int nt = K / BK;
;     unsigned voffA[2], voffB[2];
; #pragma unroll
;     for (int i = 0; i < 2; ++i) { int R, C; stage_rc(tid * 16 + i * 8192, R, C); const int Rb = (R & ~31) + perm32(R & 31);
;         voffA[i] = (unsigned)(R * lda + C) * 2u; voffB[i] = (unsigned)(Rb * K + C) * 2u; }
;     const size_t kstep = (size_t)(BK * 2);
;     const size_t hstepA = (size_t)HALF * lda * 2, hstepB = (size_t)HALF * K * 2;
;     const unsigned ldsw = (unsigned)wid * 1024u;
;     const int aoff = lds_byte(wr * 64 + fr, fq * 8), boff = lds_byte(wc * 32 + fr, fq * 8);
;     ...
;     Unit cur, nxt; int ui = 0;
;     if (!S.next(0, cur)) return;
;     f32x4 acc[2][2][4][2];
; #pragma unroll
;     for (int a = 0; a < 2; ++a)
; #pragma unroll
;         for (int b = 0; b < 2; ++b)
; #pragma unroll
;             for (int m = 0; m < 4; ++m)
; #pragma unroll
;                 for (int n = 0; n < 2; ++n) acc[a][b][m][n] = (f32x4){0.f, 0.f, 0.f, 0.f};
;     bf16x8 At[4][2], B0[2][2], B1[2][2];
;     const char* cA = S.aptr(cur); const char* cB = S.bptr(cur);
;     PG8_STAGE(PG8_SB(0, 0), cB, voffB); PG8_STAGE(PG8_SA(0, 0), cA, voffA); PG8_STAGE(PG8_SB(0, 1), cB + hstepB, voffB); PG8_STAGE(PG8_SA(0, 1), cA + hstepA, voffA);
;     if (wr == 1) PG8_BAR;
; __device__ __forceinline__ int xcd_remap(int L, int nwg) {
;     const int q = nwg >> 3, r = nwg & 7, xcd = L & 7, off = L >> 3;
;     return (xcd < r ? xcd * (q + 1) : r * (q + 1) + (xcd - r) * q) + off;
; }
.LBB0_2244:
	s_or_b64 exec, exec, s[6:7]
	s_mov_b64 s[0:1], src_shared_base
	s_waitcnt lgkmcnt(0)
	s_barrier
	s_getreg_b32 s0, hwreg(HW_REG_HW_ID, 0, 6)
	s_and_b32 s0, s0, 63
	s_lshl_b32 s0, s0, 2
	s_add_i32 s0, s0, 0
	s_add_i32 s0, s0, 0x20100
	v_mov_b32_e32 v0, s0
	v_mov_b32_e32 v1, s1
	flat_load_dword v0, v[0:1] sc0 sc1
	s_waitcnt vmcnt(0)
	s_and_b64 vcc, exec, s[96:97]
	s_waitcnt lgkmcnt(0)
	v_readfirstlane_b32 s0, v0
	s_nop 1
	v_lshl_or_b32 v11, s0, 6, v214
	s_nop 0
	v_readfirstlane_b32 s0, v11
	s_cbranch_vccnz .LBB0_2260
	v_lshlrev_b32_e32 v0, 4, v11
	v_add_u32_e32 v1, 0x2000, v0
	v_ashrrev_i32_e32 v2, 31, v1
	v_lshrrev_b32_e32 v2, 22, v2
	v_add_u32_e32 v2, v1, v2
	v_ashrrev_i32_e32 v8, 10, v2
	v_mul_i32_i24_e32 v2, 0x400, v8
	v_sub_u32_e32 v1, v1, v2
	v_lshrrev_b32_e32 v2, 4, v1
	v_bitop3_b32 v1, v2, v1, 32 bitop3:0x6c
	v_ashrrev_i32_e32 v2, 31, v1
	v_lshrrev_b32_e32 v2, 26, v2
	v_add_u32_e32 v2, v1, v2
	v_lshlrev_b32_e32 v3, 3, v8
	v_ashrrev_i32_e32 v9, 6, v2
	v_and_b32_e32 v3, -16, v3
	v_add_u32_e32 v3, v9, v3
	v_and_b32_e32 v4, 3, v9
	s_mov_b32 s2, 0xfffe0
	v_lshrrev_b32_e32 v5, 2, v3
	v_lshlrev_b32_e32 v6, 1, v3
	v_and_b32_e32 v2, 0xc0, v2
	v_and_or_b32 v4, v3, s2, v4
	v_and_b32_e32 v5, 4, v5
	v_and_b32_e32 v6, 24, v6
	v_sub_u32_e32 v1, v1, v2
	v_mov_b32_e32 v2, 1
	v_or3_b32 v4, v4, v5, v6
	v_lshlrev_b32_e32 v5, 5, v8
	v_ashrrev_i16_sdwa v1, v2, sext(v1) dst_sel:DWORD dst_unused:UNUSED_PAD src0_sel:DWORD src1_sel:BYTE_0
	v_and_b32_e32 v5, 32, v5
	v_bfe_i32 v10, v1, 0, 16
	v_add_lshl_u32 v1, v5, v10, 1
	v_lshl_add_u32 v156, v4, 12, v1
	v_lshl_add_u32 v158, v3, 12, v1
	v_bfe_i32 v1, v11, 27, 1
	v_lshrrev_b32_e32 v1, 22, v1
	v_add_u32_e32 v1, v0, v1
	v_and_b32_e32 v1, 0xfffffc00, v1
	v_sub_u32_e32 v0, v0, v1
	v_lshrrev_b32_e32 v1, 4, v0
	v_bitop3_b32 v1, v1, v0, 32 bitop3:0x6c
	v_ashrrev_i32_e32 v0, 31, v0
	v_lshrrev_b32_e32 v0, 26, v0
	v_add_u32_e32 v0, v1, v0
	v_ashrrev_i32_e32 v12, 6, v0
	v_ashrrev_i32_e32 v0, 31, v11
	v_lshrrev_b32_e32 v0, 26, v0
	v_add_u32_e32 v0, v11, v0
	v_ashrrev_i32_e32 v13, 6, v0
	v_lshlrev_b32_e32 v0, 3, v13
	v_and_b32_e32 v0, -16, v0
	v_add_u32_e32 v0, v12, v0
	v_and_b32_e32 v3, 3, v12
	v_and_or_b32 v3, v0, s2, v3
	s_lshl_b32 s2, s92, 6
	s_and_b32 s2, s2, 0x1c0
	s_ashr_i32 s3, s92, 3
	s_add_i32 s2, s2, s3
	s_ashr_i32 s3, s2, 31
	s_lshr_b32 s3, s3, 26
	s_add_i32 s3, s2, s3
	s_ashr_i32 s6, s3, 6
	s_andn2_b32 s3, s3, 63
	s_sub_i32 s2, s2, s3
	s_bfe_i32 s3, s2, 0x80000
	s_bfe_u32 s3, s3, 0x3000c
	s_add_i32 s3, s2, s3
	s_bfe_i32 s7, s3, 0x80000
	s_and_b32 s3, s3, 0xf8
	v_lshrrev_b32_e32 v4, 2, v0
	v_lshlrev_b32_e32 v5, 1, v0
	s_sub_i32 s2, s2, s3
	v_and_b32_e32 v4, 4, v4
	v_and_b32_e32 v5, 24, v5
	s_lshl_b32 s6, s6, 3
	s_sext_i32_i16 s7, s7
	s_sext_i32_i8 s2, s2
	v_or3_b32 v3, v3, v4, v5
	v_mul_i32_i24_e32 v5, 64, v12
	s_lshr_b32 s8, s7, 3
	s_add_i32 s68, s6, s2
	s_ashr_i32 s5, s0, 6
	v_sub_u32_e32 v1, v1, v5
	s_ashr_i32 s69, s68, 31
	s_bfe_i64 s[2:3], s[8:9], 0x100000
	s_ashr_i32 s4, s0, 8
	s_lshl_b32 s1, s5, 10
	v_lshlrev_b32_e32 v4, 5, v13
	v_ashrrev_i16_sdwa v1, v2, sext(v1) dst_sel:DWORD dst_unused:UNUSED_PAD src0_sel:DWORD src1_sel:BYTE_0
	s_lshl_b64 s[6:7], s[68:69], 20
	s_lshl_b64 s[2:3], s[2:3], 20
	v_and_b32_e32 v4, 32, v4
	v_bfe_i32 v14, v1, 0, 16
	s_add_u32 s78, s95, s2
	v_readlane_b32 s2, v252, 37
	v_add_lshl_u32 v1, v4, v14, 1
	s_addc_u32 s79, s2, s3
	s_add_i32 s2, s1, 0
	v_lshl_add_u32 v160, v3, 12, v1
	s_add_i32 m0, s2, 0x10000
	v_lshl_add_u32 v162, v0, 12, v1
	global_load_lds_dwordx4 v160, s[78:79]
	s_add_i32 m0, s2, 0x12000
	s_add_u32 s76, s34, s6
	global_load_lds_dwordx4 v156, s[78:79]
	s_addc_u32 s77, s35, s7
	s_mov_b32 m0, s2
	s_add_i32 s3, s2, 0x2000
	global_load_lds_dwordx4 v162, s[76:77]
	s_mov_b32 m0, s3
	s_add_u32 s6, s78, 0x80000
	global_load_lds_dwordx4 v158, s[76:77]
	s_addc_u32 s7, s79, 0
	s_add_i32 m0, s2, 0x14000
	v_mov_b32_e32 v165, 0
	global_load_lds_dwordx4 v160, s[6:7]
	s_add_i32 m0, s2, 0x16000
	v_mov_b32_e32 v161, v165
	global_load_lds_dwordx4 v156, s[6:7]
	s_add_u32 s6, s76, 0x80000
	s_addc_u32 s7, s77, 0
	s_add_i32 s12, s2, 0x4000
	s_mov_b32 m0, s12
	s_add_i32 s13, s2, 0x6000
	global_load_lds_dwordx4 v162, s[6:7]
	s_mov_b32 m0, s13
	v_mov_b32_e32 v157, v165
	global_load_lds_dwordx4 v158, s[6:7]
	v_mov_b32_e32 v163, v165
	v_mov_b32_e32 v159, v165
	v_lshl_add_u64 v[6:7], s[78:79], 0, v[160:161]
	v_lshl_add_u64 v[4:5], s[78:79], 0, v[156:157]
	v_lshl_add_u64 v[2:3], s[76:77], 0, v[162:163]
	s_cmp_lg_u32 s4, 1
	v_lshl_add_u64 v[0:1], s[76:77], 0, v[158:159]
	s_cbranch_scc1 .LBB0_2247
	s_setprio 1
	s_nop 0
	s_nop 0
	s_nop 0
	s_nop 0
	s_nop 0
	s_nop 0
	s_nop 0
	s_barrier

; #define PG8_STAGE(bufoff, gbase, voff) do { _Pragma("unroll") for (int _i = 0; _i < 2; ++_i) \
;         __builtin_amdgcn_global_load_lds((const unsigned*)((const char*)(gbase) + (voff)[_i]), (LAS unsigned*)(lds + (bufoff) + ldsw + _i * 8192), 16, 0, 0); } while (0)
; #define PG8_LDA(dst, b, h) do { _Pragma("unroll") for (int m = 0; m < 4; ++m) _Pragma("unroll") for (int k = 0; k < 2; ++k) dst[m][k] = *(const LAS bf16x8*)(lds + PG8_SA(b, h) + aoff + m * 2048 + k * 1024); } while (0)
; #define PG8_LDB(dst, b, h) do { _Pragma("unroll") for (int n = 0; n < 2; ++n) _Pragma("unroll") for (int k = 0; k < 2; ++k) dst[n][k] = *(const LAS bf16x8*)(lds + PG8_SB(b, h) + boff + n * 2048 + k * 1024); } while (0)
; #define PG8_MMA(ai, bj, At, Bt) do { __builtin_amdgcn_s_setprio(1); _Pragma("unroll") for (int m = 0; m < 4; ++m) _Pragma("unroll") for (int n = 0; n < 2; ++n) _Pragma("unroll") for (int k = 0; k < 2; ++k) \
;         acc[ai][bj][m][n] = __builtin_amdgcn_mfma_f32_16x16x32_bf16(Bt[n][k], At[m][k], acc[ai][bj][m][n], 0, 0, 0); __builtin_amdgcn_s_setprio(0); } while (0)
; #define PG8_WAIT_L(n) asm volatile("s_waitcnt lgkmcnt(" #n ")" ::: "memory")
; #define PG8_BAR __builtin_amdgcn_s_barrier()
; #define PG8_SCHED __builtin_amdgcn_sched_barrier(0)
; template <class Epi, class Sched>
; __device__ __forceinline__ void gemm_phase(LAS unsigned char* lds, const int K, const int lda, Sched& S, const Epi& E) {
;     ...
;         for (int t = 0; t < nt; t += 2) {
;             const bool last = (t == nt - 2);
;             const char* a1 = cA + (size_t)(t + 1) * kstep;
;             const char* a2 = last ? nA : cA + (size_t)(t + 2) * kstep; const char* b2 = last ? nB : cB + (size_t)(t + 2) * kstep;
;             const char* a3 = a2 + kstep; const char* b3 = b2 + kstep;
;             PG8_LDB(B0, 0, 0); PG8_SCHED; PG8_LDA(At, 0, 0); PG8_STAGE(PG8_SA(1, 1), a1 + hstepA, voffA);
;             PG8_WAIT_L(8); PG8_BAR; PG8_WAIT_L(0); PG8_MMA(0, 0, At, B0); PG8_BAR; PG8_SCHED;
;             PG8_LDB(B1, 0, 1); PG8_STAGE(PG8_SB(0, 0), b2, voffB);
;             PG8_BAR; PG8_WAIT_L(0); PG8_MMA(0, 1, At, B1); PG8_BAR;
;             PG8_LDA(At, 0, 1); PG8_STAGE(PG8_SA(0, 0), a2, voffA);
;             PG8_BAR; PG8_WAIT_L(0); PG8_MMA(1, 0, At, B0); PG8_BAR; PG8_SCHED;
.LBB0_2252:
	ds_read_b128 v[128:131], v177
	ds_read_b128 v[132:135], v177 offset:1024
	ds_read_b128 v[136:139], v177 offset:2048
	ds_read_b128 v[140:143], v177 offset:3072
	s_add_u32 s31, s76, 0xfff80080
	s_addc_u32 s52, s77, -1
	s_cmp_eq_u32 s30, 28
	s_cselect_b32 s81, s4, s52
	s_cselect_b32 s80, s5, s31
	s_cselect_b32 s79, s9, s29
	s_cselect_b32 s78, s11, s28
	v_lshl_add_u64 v[196:197], s[76:77], 0, v[166:167]
	s_add_i32 m0, s2, 0xc000
	ds_read_b128 v[144:147], v178
	ds_read_b128 v[148:151], v178 offset:1024
	ds_read_b128 v[152:155], v178 offset:2048
	ds_read_b128 v[170:173], v178 offset:3072
	ds_read_b128 v[180:183], v178 offset:4096
	ds_read_b128 v[184:187], v178 offset:5120
	ds_read_b128 v[188:191], v178 offset:6144
	ds_read_b128 v[192:195], v178 offset:7168
	global_load_lds_dwordx4 v[196:197], off
	v_lshl_add_u64 v[196:197], s[76:77], 0, v[168:169]
	s_add_i32 m0, s2, 0xe000
	s_nop 0
	global_load_lds_dwordx4 v[196:197], off
	s_waitcnt lgkmcnt(8)
	s_barrier
	s_waitcnt lgkmcnt(0)
	s_waitcnt lgkmcnt(0)
	v_mfma_f32_16x16x32_bf16 v[124:127], v[128:131], v[144:147], v[124:127]
	v_mfma_f32_16x16x32_bf16 v[120:123], v[136:139], v[144:147], v[120:123]
	v_mfma_f32_16x16x32_bf16 v[116:119], v[128:131], v[152:155], v[116:119]
	v_mfma_f32_16x16x32_bf16 v[104:107], v[136:139], v[152:155], v[104:107]
	v_mfma_f32_16x16x32_bf16 v[100:103], v[128:131], v[180:183], v[100:103]
	v_mfma_f32_16x16x32_bf16 v[88:91], v[136:139], v[180:183], v[88:91]
	v_mfma_f32_16x16x32_bf16 v[76:79], v[128:131], v[188:191], v[76:79]
	v_mfma_f32_16x16x32_bf16 v[72:75], v[136:139], v[188:191], v[72:75]
	v_mfma_f32_16x16x32_bf16 v[124:127], v[132:135], v[148:151], v[124:127]
	v_mfma_f32_16x16x32_bf16 v[120:123], v[140:143], v[148:151], v[120:123]
	v_mfma_f32_16x16x32_bf16 v[116:119], v[132:135], v[170:173], v[116:119]
	v_mfma_f32_16x16x32_bf16 v[104:107], v[140:143], v[170:173], v[104:107]
	v_mfma_f32_16x16x32_bf16 v[100:103], v[132:135], v[184:187], v[100:103]
	v_mfma_f32_16x16x32_bf16 v[88:91], v[140:143], v[184:187], v[88:91]
	v_mfma_f32_16x16x32_bf16 v[76:79], v[132:135], v[192:195], v[76:79]
	v_mfma_f32_16x16x32_bf16 v[72:75], v[140:143], v[192:195], v[72:75]
	s_barrier
	s_add_i32 s31, s17, s1
	v_lshl_add_u64 v[212:213], s[78:79], 0, v[160:161]
	s_mov_b32 m0, s31
	ds_read_b128 v[196:199], v179
	ds_read_b128 v[200:203], v179 offset:1024
	ds_read_b128 v[204:207], v179 offset:2048
	ds_read_b128 v[208:211], v179 offset:3072
	global_load_lds_dwordx4 v[212:213], off
	v_lshl_add_u64 v[216:217], s[78:79], 0, v[156:157]
	s_add_i32 m0, s31, 0x2000
	s_nop 0
	global_load_lds_dwordx4 v[216:217], off
	s_barrier
	s_waitcnt lgkmcnt(0)
	s_waitcnt lgkmcnt(0)
	v_mfma_f32_16x16x32_bf16 v[112:115], v[196:199], v[144:147], v[112:115]
	v_mfma_f32_16x16x32_bf16 v[108:111], v[204:207], v[144:147], v[108:111]
	v_mfma_f32_16x16x32_bf16 v[96:99], v[196:199], v[152:155], v[96:99]
	v_mfma_f32_16x16x32_bf16 v[92:95], v[204:207], v[152:155], v[92:95]
	v_mfma_f32_16x16x32_bf16 v[84:87], v[196:199], v[180:183], v[84:87]
	v_mfma_f32_16x16x32_bf16 v[80:83], v[204:207], v[180:183], v[80:83]
	v_mfma_f32_16x16x32_bf16 v[68:71], v[196:199], v[188:191], v[68:71]
	v_mfma_f32_16x16x32_bf16 v[64:67], v[204:207], v[188:191], v[64:67]
	v_mfma_f32_16x16x32_bf16 v[112:115], v[200:203], v[148:151], v[112:115]
	v_mfma_f32_16x16x32_bf16 v[108:111], v[208:211], v[148:151], v[108:111]
	v_mfma_f32_16x16x32_bf16 v[96:99], v[200:203], v[170:173], v[96:99]
	v_mfma_f32_16x16x32_bf16 v[92:95], v[208:211], v[170:173], v[92:95]
	v_mfma_f32_16x16x32_bf16 v[84:87], v[200:203], v[184:187], v[84:87]
	v_mfma_f32_16x16x32_bf16 v[80:83], v[208:211], v[184:187], v[80:83]
	v_mfma_f32_16x16x32_bf16 v[68:71], v[200:203], v[192:195], v[68:71]
	v_mfma_f32_16x16x32_bf16 v[64:67], v[208:211], v[192:195], v[64:67]
	s_mov_b32 m0, s2
	v_lshl_add_u64 v[218:219], s[80:81], 0, v[162:163]
	s_barrier
	ds_read_b128 v[144:147], v178 offset:16384
	ds_read_b128 v[148:151], v178 offset:17408
	ds_read_b128 v[152:155], v178 offset:18432
	ds_read_b128 v[170:173], v178 offset:19456
	ds_read_b128 v[180:183], v178 offset:20480
	ds_read_b128 v[184:187], v178 offset:21504
	ds_read_b128 v[188:191], v178 offset:22528
	ds_read_b128 v[192:195], v178 offset:23552
	global_load_lds_dwordx4 v[218:219], off
	v_lshl_add_u64 v[220:221], s[80:81], 0, v[158:159]
	s_mov_b32 m0, s3
	s_nop 0
	global_load_lds_dwordx4 v[220:221], off
	s_barrier
	s_waitcnt lgkmcnt(0)
	s_waitcnt lgkmcnt(0)
	v_mfma_f32_16x16x32_bf16 v[60:63], v[128:131], v[144:147], v[60:63]
	v_mfma_f32_16x16x32_bf16 v[56:59], v[136:139], v[144:147], v[56:59]
	v_mfma_f32_16x16x32_bf16 v[52:55], v[128:131], v[152:155], v[52:55]
	v_mfma_f32_16x16x32_bf16 v[40:43], v[136:139], v[152:155], v[40:43]
	v_mfma_f32_16x16x32_bf16 v[32:35], v[128:131], v[180:183], v[32:35]
	v_mfma_f32_16x16x32_bf16 v[24:27], v[136:139], v[180:183], v[24:27]
	v_mfma_f32_16x16x32_bf16 v[20:23], v[128:131], v[188:191], v[20:23]
	v_mfma_f32_16x16x32_bf16 v[8:11], v[136:139], v[188:191], v[8:11]
	v_mfma_f32_16x16x32_bf16 v[60:63], v[132:135], v[148:151], v[60:63]
	v_mfma_f32_16x16x32_bf16 v[56:59], v[140:143], v[148:151], v[56:59]
	v_mfma_f32_16x16x32_bf16 v[52:55], v[132:135], v[170:173], v[52:55]
	v_mfma_f32_16x16x32_bf16 v[40:43], v[140:143], v[170:173], v[40:43]
	v_mfma_f32_16x16x32_bf16 v[32:35], v[132:135], v[184:187], v[32:35]
	v_mfma_f32_16x16x32_bf16 v[24:27], v[140:143], v[184:187], v[24:27]
	v_mfma_f32_16x16x32_bf16 v[20:23], v[132:135], v[192:195], v[20:23]
	v_mfma_f32_16x16x32_bf16 v[8:11], v[140:143], v[192:195], v[8:11]
	s_barrier
; #define PG8_STAGE(bufoff, gbase, voff) do { _Pragma("unroll") for (int _i = 0; _i < 2; ++_i) \
;         __builtin_amdgcn_global_load_lds((const unsigned*)((const char*)(gbase) + (voff)[_i]), (LAS unsigned*)(lds + (bufoff) + ldsw + _i * 8192), 16, 0, 0); } while (0)
; #define PG8_LDA(dst, b, h) do { _Pragma("unroll") for (int m = 0; m < 4; ++m) _Pragma("unroll") for (int k = 0; k < 2; ++k) dst[m][k] = *(const LAS bf16x8*)(lds + PG8_SA(b, h) + aoff + m * 2048 + k * 1024); } while (0)
; #define PG8_LDB(dst, b, h) do { _Pragma("unroll") for (int n = 0; n < 2; ++n) _Pragma("unroll") for (int k = 0; k < 2; ++k) dst[n][k] = *(const LAS bf16x8*)(lds + PG8_SB(b, h) + boff + n * 2048 + k * 1024); } while (0)
; #define PG8_MMA(ai, bj, At, Bt) do { __builtin_amdgcn_s_setprio(1); _Pragma("unroll") for (int m = 0; m < 4; ++m) _Pragma("unroll") for (int n = 0; n < 2; ++n) _Pragma("unroll") for (int k = 0; k < 2; ++k) \
;         acc[ai][bj][m][n] = __builtin_amdgcn_mfma_f32_16x16x32_bf16(Bt[n][k], At[m][k], acc[ai][bj][m][n], 0, 0, 0); __builtin_amdgcn_s_setprio(0); } while (0)
; #define PG8_WAIT_V(n) asm volatile("s_waitcnt vmcnt(" #n ")" ::: "memory")
; #define PG8_WAIT_L(n) asm volatile("s_waitcnt lgkmcnt(" #n ")" ::: "memory")
; #define PG8_BAR __builtin_amdgcn_s_barrier()
; #define PG8_SCHED __builtin_amdgcn_sched_barrier(0)
; template <class Epi, class Sched>
; __device__ __forceinline__ void gemm_phase(LAS unsigned char* lds, const int K, const int lda, Sched& S, const Epi& E) {
;     ...
;             PG8_STAGE(PG8_SB(0, 1), b2 + hstepB, voffB);
;             PG8_WAIT_V(6); PG8_BAR; PG8_MMA(1, 1, At, B1); PG8_BAR;
;             PG8_LDB(B0, 1, 0); PG8_SCHED; PG8_LDA(At, 1, 0); PG8_STAGE(PG8_SA(0, 1), a2 + hstepA, voffA);
;             PG8_WAIT_L(8); PG8_BAR; PG8_WAIT_L(0); PG8_MMA(0, 0, At, B0); PG8_BAR; PG8_SCHED;
;             PG8_LDB(B1, 1, 1); PG8_STAGE(PG8_SB(1, 0), b3, voffB);
;             PG8_BAR; PG8_WAIT_L(0); PG8_MMA(0, 1, At, B1); PG8_BAR;
;             PG8_LDA(At, 1, 1); PG8_STAGE(PG8_SA(1, 0), a3, voffA);
;             PG8_BAR; PG8_WAIT_L(0); PG8_MMA(1, 0, At, B0); PG8_BAR; PG8_SCHED;
	s_add_u32 s52, s78, 0x80000
	s_addc_u32 s53, s79, 0
	s_add_i32 s31, s18, s1
	v_lshl_add_u64 v[128:129], s[52:53], 0, v[160:161]
	s_mov_b32 m0, s31
	s_nop 0
	global_load_lds_dwordx4 v[128:129], off
	v_lshl_add_u64 v[128:129], s[52:53], 0, v[156:157]
	s_add_i32 m0, s31, 0x2000
	s_nop 0
	global_load_lds_dwordx4 v[128:129], off
	s_waitcnt vmcnt(6)
	s_barrier
	v_mfma_f32_16x16x32_bf16 v[48:51], v[196:199], v[144:147], v[48:51]
	v_mfma_f32_16x16x32_bf16 v[44:47], v[204:207], v[144:147], v[44:47]
	v_mfma_f32_16x16x32_bf16 v[36:39], v[196:199], v[152:155], v[36:39]
	v_mfma_f32_16x16x32_bf16 v[28:31], v[204:207], v[152:155], v[28:31]
	v_mfma_f32_16x16x32_bf16 v[16:19], v[196:199], v[180:183], v[16:19]
	v_mfma_f32_16x16x32_bf16 v[12:15], v[204:207], v[180:183], v[12:15]
	v_mfma_f32_16x16x32_bf16 v[4:7], v[196:199], v[188:191], v[4:7]
	v_mfma_f32_16x16x32_bf16 v[0:3], v[204:207], v[188:191], v[0:3]
	v_mfma_f32_16x16x32_bf16 v[48:51], v[200:203], v[148:151], v[48:51]
	v_mfma_f32_16x16x32_bf16 v[44:47], v[208:211], v[148:151], v[44:47]
	v_mfma_f32_16x16x32_bf16 v[36:39], v[200:203], v[170:173], v[36:39]
	v_mfma_f32_16x16x32_bf16 v[28:31], v[208:211], v[170:173], v[28:31]
	v_mfma_f32_16x16x32_bf16 v[16:19], v[200:203], v[184:187], v[16:19]
	v_mfma_f32_16x16x32_bf16 v[12:15], v[208:211], v[184:187], v[12:15]
	v_mfma_f32_16x16x32_bf16 v[4:7], v[200:203], v[192:195], v[4:7]
	v_mfma_f32_16x16x32_bf16 v[0:3], v[208:211], v[192:195], v[0:3]
	s_add_i32 s31, 0, 0x18000
	v_add_u32_e32 v140, s31, v175
	s_barrier
	ds_read_b128 v[128:131], v140
	ds_read_b128 v[132:135], v140 offset:1024
	ds_read_b128 v[136:139], v140 offset:2048
	ds_read_b128 v[140:143], v140 offset:3072
	s_add_u32 s52, s80, 0x80000
	s_addc_u32 s53, s81, 0
	s_mov_b32 m0, s12
	v_lshl_add_u64 v[196:197], s[52:53], 0, v[162:163]
	ds_read_b128 v[144:147], v178 offset:32768
	ds_read_b128 v[148:151], v178 offset:33792
	ds_read_b128 v[152:155], v178 offset:34816
	ds_read_b128 v[170:173], v178 offset:35840
	ds_read_b128 v[180:183], v178 offset:36864
	ds_read_b128 v[184:187], v178 offset:37888
	ds_read_b128 v[188:191], v178 offset:38912
	ds_read_b128 v[192:195], v178 offset:39936
	global_load_lds_dwordx4 v[196:197], off
	v_lshl_add_u64 v[196:197], s[52:53], 0, v[158:159]
	s_mov_b32 m0, s13
	s_nop 0
	global_load_lds_dwordx4 v[196:197], off
	s_waitcnt lgkmcnt(8)
	s_barrier
	s_waitcnt lgkmcnt(0)
	s_waitcnt lgkmcnt(0)
	v_mfma_f32_16x16x32_bf16 v[124:127], v[128:131], v[144:147], v[124:127]
	v_mfma_f32_16x16x32_bf16 v[120:123], v[136:139], v[144:147], v[120:123]
	v_mfma_f32_16x16x32_bf16 v[116:119], v[128:131], v[152:155], v[116:119]
	v_mfma_f32_16x16x32_bf16 v[104:107], v[136:139], v[152:155], v[104:107]
	v_mfma_f32_16x16x32_bf16 v[100:103], v[128:131], v[180:183], v[100:103]
	v_mfma_f32_16x16x32_bf16 v[88:91], v[136:139], v[180:183], v[88:91]
	v_mfma_f32_16x16x32_bf16 v[76:79], v[128:131], v[188:191], v[76:79]
	v_mfma_f32_16x16x32_bf16 v[72:75], v[136:139], v[188:191], v[72:75]
	v_mfma_f32_16x16x32_bf16 v[124:127], v[132:135], v[148:151], v[124:127]
	v_mfma_f32_16x16x32_bf16 v[120:123], v[140:143], v[148:151], v[120:123]
	v_mfma_f32_16x16x32_bf16 v[116:119], v[132:135], v[170:173], v[116:119]
	v_mfma_f32_16x16x32_bf16 v[104:107], v[140:143], v[170:173], v[104:107]
	v_mfma_f32_16x16x32_bf16 v[100:103], v[132:135], v[184:187], v[100:103]
	v_mfma_f32_16x16x32_bf16 v[88:91], v[140:143], v[184:187], v[88:91]
	v_mfma_f32_16x16x32_bf16 v[76:79], v[132:135], v[192:195], v[76:79]
	v_mfma_f32_16x16x32_bf16 v[72:75], v[140:143], v[192:195], v[72:75]
	s_barrier
	s_add_i32 s69, 0, 0x1c000
	s_add_i32 s31, s31, s1
	v_add_u32_e32 v164, s69, v175
	v_lshl_add_u64 v[212:213], v[212:213], 0, s[6:7]
	s_mov_b32 m0, s31
	ds_read_b128 v[196:199], v164
	ds_read_b128 v[200:203], v164 offset:1024
	ds_read_b128 v[204:207], v164 offset:2048
	ds_read_b128 v[208:211], v164 offset:3072
	global_load_lds_dwordx4 v[212:213], off
	v_lshl_add_u64 v[212:213], v[216:217], 0, s[6:7]
	s_add_i32 m0, s31, 0x2000
	s_nop 0
	global_load_lds_dwordx4 v[212:213], off
	s_barrier
	s_waitcnt lgkmcnt(0)
	s_waitcnt lgkmcnt(0)
	v_mfma_f32_16x16x32_bf16 v[112:115], v[196:199], v[144:147], v[112:115]
	v_mfma_f32_16x16x32_bf16 v[108:111], v[204:207], v[144:147], v[108:111]
	v_mfma_f32_16x16x32_bf16 v[96:99], v[196:199], v[152:155], v[96:99]
	v_mfma_f32_16x16x32_bf16 v[92:95], v[204:207], v[152:155], v[92:95]
	v_mfma_f32_16x16x32_bf16 v[84:87], v[196:199], v[180:183], v[84:87]
	v_mfma_f32_16x16x32_bf16 v[80:83], v[204:207], v[180:183], v[80:83]
	v_mfma_f32_16x16x32_bf16 v[68:71], v[196:199], v[188:191], v[68:71]
	v_mfma_f32_16x16x32_bf16 v[64:67], v[204:207], v[188:191], v[64:67]
	v_mfma_f32_16x16x32_bf16 v[112:115], v[200:203], v[148:151], v[112:115]
	v_mfma_f32_16x16x32_bf16 v[108:111], v[208:211], v[148:151], v[108:111]
	v_mfma_f32_16x16x32_bf16 v[96:99], v[200:203], v[170:173], v[96:99]
	v_mfma_f32_16x16x32_bf16 v[92:95], v[208:211], v[170:173], v[92:95]
	v_mfma_f32_16x16x32_bf16 v[84:87], v[200:203], v[184:187], v[84:87]
	v_mfma_f32_16x16x32_bf16 v[80:83], v[208:211], v[184:187], v[80:83]
	v_mfma_f32_16x16x32_bf16 v[68:71], v[200:203], v[192:195], v[68:71]
	v_mfma_f32_16x16x32_bf16 v[64:67], v[208:211], v[192:195], v[64:67]
	s_mov_b32 m0, s14
	v_lshl_add_u64 v[212:213], v[218:219], 0, s[6:7]
	s_barrier
; #define PG8_STAGE(bufoff, gbase, voff) do { _Pragma("unroll") for (int _i = 0; _i < 2; ++_i) \
;         __builtin_amdgcn_global_load_lds((const unsigned*)((const char*)(gbase) + (voff)[_i]), (LAS unsigned*)(lds + (bufoff) + ldsw + _i * 8192), 16, 0, 0); } while (0)
; #define PG8_MMA(ai, bj, At, Bt) do { __builtin_amdgcn_s_setprio(1); _Pragma("unroll") for (int m = 0; m < 4; ++m) _Pragma("unroll") for (int n = 0; n < 2; ++n) _Pragma("unroll") for (int k = 0; k < 2; ++k) \
;         acc[ai][bj][m][n] = __builtin_amdgcn_mfma_f32_16x16x32_bf16(Bt[n][k], At[m][k], acc[ai][bj][m][n], 0, 0, 0); __builtin_amdgcn_s_setprio(0); } while (0)
; #define PG8_WAIT_V(n) asm volatile("s_waitcnt vmcnt(" #n ")" ::: "memory")
; #define PG8_WAIT_L(n) asm volatile("s_waitcnt lgkmcnt(" #n ")" ::: "memory")
; #define PG8_BAR __builtin_amdgcn_s_barrier()
; #define PG8_SCHED __builtin_amdgcn_sched_barrier(0)
; template <class Epi, class Sched>
; __device__ __forceinline__ void gemm_phase(LAS unsigned char* lds, const int K, const int lda, Sched& S, const Epi& E) {
;     ...
;             PG8_BAR; PG8_WAIT_L(0); PG8_MMA(1, 0, At, B0); PG8_BAR; PG8_SCHED;
;             PG8_STAGE(PG8_SB(1, 1), b3 + hstepB, voffB);
;             PG8_WAIT_V(6); PG8_BAR; PG8_MMA(1, 1, At, B1); PG8_BAR;
;     __device__ __forceinline__ void operator()(f32x4 (&acc)[2][2][4][2], const Unit& u, int wr, int wc, int fr, int fq) const {
;         const int r0 = u.pm * 256 + wr * 64 + fr, c0 = u.pn * 256 + wc * 32 + 8 * fq;
;         const float* src = (r0 < MP ? xp + (size_t)r0 * D : xs + (size_t)(r0 - MP) * D) + c0;
;         float* dst = out + (size_t)r0 * D + c0;
	ds_read_b128 v[144:147], v178 offset:49152
	ds_read_b128 v[148:151], v178 offset:50176
	ds_read_b128 v[152:155], v178 offset:51200
	ds_read_b128 v[170:173], v178 offset:52224
	ds_read_b128 v[180:183], v178 offset:53248
	ds_read_b128 v[184:187], v178 offset:54272
	ds_read_b128 v[188:191], v178 offset:55296
	ds_read_b128 v[192:195], v178 offset:56320
	global_load_lds_dwordx4 v[212:213], off
	v_lshl_add_u64 v[212:213], v[220:221], 0, s[6:7]
	s_mov_b32 m0, s15
	s_nop 0
	global_load_lds_dwordx4 v[212:213], off
	s_barrier
	s_waitcnt lgkmcnt(0)
	s_waitcnt lgkmcnt(0)
	v_mfma_f32_16x16x32_bf16 v[60:63], v[128:131], v[144:147], v[60:63]
	v_mfma_f32_16x16x32_bf16 v[56:59], v[136:139], v[144:147], v[56:59]
	v_mfma_f32_16x16x32_bf16 v[52:55], v[128:131], v[152:155], v[52:55]
	v_mfma_f32_16x16x32_bf16 v[40:43], v[136:139], v[152:155], v[40:43]
	v_mfma_f32_16x16x32_bf16 v[32:35], v[128:131], v[180:183], v[32:35]
	v_mfma_f32_16x16x32_bf16 v[24:27], v[136:139], v[180:183], v[24:27]
	v_mfma_f32_16x16x32_bf16 v[20:23], v[128:131], v[188:191], v[20:23]
	v_mfma_f32_16x16x32_bf16 v[8:11], v[136:139], v[188:191], v[8:11]
	v_mfma_f32_16x16x32_bf16 v[60:63], v[132:135], v[148:151], v[60:63]
	v_mfma_f32_16x16x32_bf16 v[56:59], v[140:143], v[148:151], v[56:59]
	v_mfma_f32_16x16x32_bf16 v[52:55], v[132:135], v[170:173], v[52:55]
	v_mfma_f32_16x16x32_bf16 v[40:43], v[140:143], v[170:173], v[40:43]
	v_mfma_f32_16x16x32_bf16 v[32:35], v[132:135], v[184:187], v[32:35]
	v_mfma_f32_16x16x32_bf16 v[24:27], v[140:143], v[184:187], v[24:27]
	v_mfma_f32_16x16x32_bf16 v[20:23], v[132:135], v[192:195], v[20:23]
	v_mfma_f32_16x16x32_bf16 v[8:11], v[140:143], v[192:195], v[8:11]
	s_barrier
	s_add_u32 s52, s78, 0x80080
	s_addc_u32 s53, s79, 0
	s_add_i32 s31, s69, s1
	v_lshl_add_u64 v[128:129], s[52:53], 0, v[160:161]
	s_mov_b32 m0, s31
	s_nop 0
	global_load_lds_dwordx4 v[128:129], off
	v_lshl_add_u64 v[128:129], s[52:53], 0, v[156:157]
	s_add_i32 m0, s31, 0x2000
	s_nop 0
	global_load_lds_dwordx4 v[128:129], off
	s_waitcnt vmcnt(6)
	s_barrier
	v_mfma_f32_16x16x32_bf16 v[48:51], v[196:199], v[144:147], v[48:51]
	v_mfma_f32_16x16x32_bf16 v[44:47], v[204:207], v[144:147], v[44:47]
	v_mfma_f32_16x16x32_bf16 v[36:39], v[196:199], v[152:155], v[36:39]
	v_mfma_f32_16x16x32_bf16 v[28:31], v[204:207], v[152:155], v[28:31]
	v_mfma_f32_16x16x32_bf16 v[16:19], v[196:199], v[180:183], v[16:19]
	v_mfma_f32_16x16x32_bf16 v[12:15], v[204:207], v[180:183], v[12:15]
	v_mfma_f32_16x16x32_bf16 v[4:7], v[196:199], v[188:191], v[4:7]
	v_mfma_f32_16x16x32_bf16 v[0:3], v[204:207], v[188:191], v[0:3]
	v_mfma_f32_16x16x32_bf16 v[48:51], v[200:203], v[148:151], v[48:51]
	v_mfma_f32_16x16x32_bf16 v[44:47], v[208:211], v[148:151], v[44:47]
	v_mfma_f32_16x16x32_bf16 v[36:39], v[200:203], v[170:173], v[36:39]
	v_mfma_f32_16x16x32_bf16 v[28:31], v[208:211], v[170:173], v[28:31]
	v_mfma_f32_16x16x32_bf16 v[16:19], v[200:203], v[184:187], v[16:19]
	v_mfma_f32_16x16x32_bf16 v[12:15], v[208:211], v[184:187], v[12:15]
	v_mfma_f32_16x16x32_bf16 v[4:7], v[200:203], v[192:195], v[4:7]
	v_mfma_f32_16x16x32_bf16 v[0:3], v[208:211], v[192:195], v[0:3]
	s_add_i32 s30, s30, 2
	s_add_u32 s76, s76, 0x100
	s_addc_u32 s77, s77, 0
	s_add_u32 s28, s28, 0x100
	s_addc_u32 s29, s29, 0
	s_cmp_gt_u32 s30, 29
	s_barrier
	s_cbranch_scc0 .LBB0_2252
	v_lshl_add_u32 v130, s68, 8, v174
	s_movk_i32 s4, 0x3fff
	v_cmp_lt_i32_e32 vcc, s4, v130
	s_and_saveexec_b64 s[4:5], vcc
	s_xor_b64 s[68:69], exec, s[4:5]
	s_cbranch_execz .LBB0_2255
	v_add_u32_e32 v164, 0xffffc000, v130
	v_readlane_b32 s36, v252, 21
	v_lshlrev_b64 v[128:129], 13, v[164:165]
	v_readlane_b32 s38, v252, 23
	v_readlane_b32 s39, v252, 24
	v_mov_b32_e32 v131, v165
	v_readlane_b32 s37, v252, 22
	v_readlane_b32 s40, v252, 25
	v_readlane_b32 s41, v252, 26
	v_readlane_b32 s42, v252, 27
	v_readlane_b32 s43, v252, 28
	v_readlane_b32 s44, v252, 29
	v_readlane_b32 s45, v252, 30
	v_readlane_b32 s46, v252, 31
	v_readlane_b32 s47, v252, 32
	v_readlane_b32 s48, v252, 33
	v_readlane_b32 s49, v252, 34
	v_readlane_b32 s50, v252, 35
	v_readlane_b32 s51, v252, 36
	v_lshl_add_u64 v[132:133], s[38:39], 0, v[128:129]
	v_lshlrev_b64 v[128:129], 13, v[130:131]

; #define PG8_STAGE(bufoff, gbase, voff) do { _Pragma("unroll") for (int _i = 0; _i < 2; ++_i) \
;         __builtin_amdgcn_global_load_lds((const unsigned*)((const char*)(gbase) + (voff)[_i]), (LAS unsigned*)(lds + (bufoff) + ldsw + _i * 8192), 16, 0, 0); } while (0)
; #define PG8_BAR __builtin_amdgcn_s_barrier()
;     __device__ __forceinline__ const char* aptr(const Unit& u) const { return (const char*)(A + (size_t)u.pm * 256 * 2048); }
;     __device__ __forceinline__ const char* bptr(const Unit& u) const { return (const char*)(Bt + (size_t)u.pn * 256 * 2048); }
;     __device__ __forceinline__ const char* aptr(const Unit& u) const { return (const char*)(A + (size_t)u.pm * 256 * NIN + OFF_GATE + u.z * 1024); }
; template <class Epi, class Sched>
; __device__ __forceinline__ void gemm_phase(LAS unsigned char* lds, const int K, const int lda, Sched& S, const Epi& E) {
;     const int tid = opaque_tid(), wid = __builtin_amdgcn_readfirstlane(tid >> 6), lane = tid & 63, wr = wid >> 2, wc = wid & 3, fr = lane & 15, fq = lane >> 4;
;     const int nt = K / BK;
;     unsigned voffA[2], voffB[2];
; #pragma unroll
;     for (int i = 0; i < 2; ++i) { int R, C; stage_rc(tid * 16 + i * 8192, R, C); const int Rb = (R & ~31) + perm32(R & 31);
;         voffA[i] = (unsigned)(R * lda + C) * 2u; voffB[i] = (unsigned)(Rb * K + C) * 2u; }
;     const size_t kstep = (size_t)(BK * 2);
;     const size_t hstepA = (size_t)HALF * lda * 2, hstepB = (size_t)HALF * K * 2;
;     const unsigned ldsw = (unsigned)wid * 1024u;
;     const int aoff = lds_byte(wr * 64 + fr, fq * 8), boff = lds_byte(wc * 32 + fr, fq * 8);
;     ...
;     Unit cur, nxt; int ui = 0;
;     if (!S.next(0, cur)) return;
;     f32x4 acc[2][2][4][2];
; #pragma unroll
;     for (int a = 0; a < 2; ++a)
; #pragma unroll
;         for (int b = 0; b < 2; ++b)
; #pragma unroll
;             for (int m = 0; m < 4; ++m)
; #pragma unroll
;                 for (int n = 0; n < 2; ++n) acc[a][b][m][n] = (f32x4){0.f, 0.f, 0.f, 0.f};
;     bf16x8 At[4][2], B0[2][2], B1[2][2];
;     const char* cA = S.aptr(cur); const char* cB = S.bptr(cur);
;     PG8_STAGE(PG8_SB(0, 0), cB, voffB); PG8_STAGE(PG8_SA(0, 0), cA, voffA); PG8_STAGE(PG8_SB(0, 1), cB + hstepB, voffB); PG8_STAGE(PG8_SA(0, 1), cA + hstepA, voffA);
;     if (wr == 1) PG8_BAR;
.LBB0_2398:
	v_readlane_b32 s0, v252, 42
	s_add_u32 s18, s74, 0x3b05000
	v_readlane_b32 s1, v252, 43
	s_addc_u32 s19, s75, 0
	s_and_b64 vcc, exec, s[0:1]
	s_cbranch_vccnz .LBB0_2514
	v_ashrrev_i32_e32 v1, 31, v8
	v_lshrrev_b32_e32 v1, 26, v1
	v_add_u32_e32 v1, v8, v1
	v_ashrrev_i32_e32 v9, 6, v1
	v_bfe_i32 v1, v8, 27, 1
	v_lshlrev_b32_e32 v0, 4, v8
	v_lshrrev_b32_e32 v1, 22, v1
	v_add_u32_e32 v1, v0, v1
	v_and_b32_e32 v1, 0xfffffc00, v1
	v_sub_u32_e32 v1, v0, v1
	v_lshrrev_b32_e32 v2, 4, v1
	v_bitop3_b32 v2, v2, v1, 32 bitop3:0x6c
	v_ashrrev_i32_e32 v1, 31, v1
	v_lshrrev_b32_e32 v1, 26, v1
	v_add_u32_e32 v1, v2, v1
	v_ashrrev_i32_e32 v10, 6, v1
	v_lshlrev_b32_e32 v3, 3, v9
	v_mul_i32_i24_e32 v4, 64, v10
	v_and_b32_e32 v3, -16, v3
	v_sub_u32_e32 v2, v2, v4
	v_mov_b32_e32 v4, 1
	v_add_u32_e32 v1, v10, v3
	v_lshlrev_b32_e32 v3, 5, v9
	v_ashrrev_i16_sdwa v2, v4, sext(v2) dst_sel:DWORD dst_unused:UNUSED_PAD src0_sel:DWORD src1_sel:BYTE_0
	v_and_b32_e32 v3, 32, v3
	v_bfe_i32 v11, v2, 0, 16
	v_and_b32_e32 v6, 3, v10
	s_mov_b32 s1, 0xfffe0
	v_add_lshl_u32 v3, v3, v11, 1
	v_add_u32_e32 v0, 0x2000, v0
	v_lshlrev_b32_e32 v2, 1, v1
	v_lshrrev_b32_e32 v5, 2, v1
	v_and_or_b32 v6, v1, s1, v6
	v_lshl_add_u32 v128, v1, 12, v3
	v_ashrrev_i32_e32 v1, 31, v0
	v_lshrrev_b32_e32 v1, 22, v1
	v_add_u32_e32 v1, v0, v1
	v_ashrrev_i32_e32 v12, 10, v1
	v_mul_i32_i24_e32 v1, 0x400, v12
	v_sub_u32_e32 v0, v0, v1
	v_and_b32_e32 v2, 24, v2
	v_and_b32_e32 v5, 4, v5
	v_lshrrev_b32_e32 v1, 4, v0
	v_or3_b32 v2, v6, v5, v2
	v_bitop3_b32 v0, v1, v0, 32 bitop3:0x6c
	v_lshl_add_u32 v130, v2, 12, v3
	v_ashrrev_i32_e32 v2, 31, v0
	v_lshrrev_b32_e32 v2, 26, v2
	v_add_u32_e32 v2, v0, v2
	v_lshlrev_b32_e32 v1, 3, v12
	v_ashrrev_i32_e32 v13, 6, v2
	v_and_b32_e32 v2, 0xc0, v2
	s_ashr_i32 s4, s2, 6
	s_ashr_i32 s67, s66, 31
	s_ashr_i32 s77, s76, 31
	s_ashr_i32 s0, s2, 8
	v_and_b32_e32 v1, -16, v1
	v_sub_u32_e32 v0, v0, v2
	s_lshl_b32 s3, s4, 10
	s_lshl_b64 s[6:7], s[66:67], 20
	s_lshl_b64 s[8:9], s[76:77], 20
	v_add_u32_e32 v1, v13, v1
	v_ashrrev_i16_sdwa v0, v4, sext(v0) dst_sel:DWORD dst_unused:UNUSED_PAD src0_sel:DWORD src1_sel:BYTE_0
	s_add_u32 s78, s18, s8
	v_lshlrev_b32_e32 v3, 5, v12
	v_bfe_i32 v14, v0, 0, 16
	v_lshlrev_b32_e32 v0, 1, v1
	v_lshrrev_b32_e32 v2, 2, v1
	v_and_b32_e32 v4, 3, v13
	s_addc_u32 s79, s19, s9
	s_add_i32 s12, s3, 0
	v_and_b32_e32 v3, 32, v3
	v_and_b32_e32 v0, 24, v0
	v_and_b32_e32 v2, 4, v2
	v_and_or_b32 v4, v1, s1, v4
	s_add_i32 m0, s12, 0x10000
	v_or3_b32 v0, v4, v2, v0
	v_add_lshl_u32 v2, v3, v14, 1
	global_load_lds_dwordx4 v130, s[78:79]
	s_add_i32 m0, s12, 0x12000
	v_lshl_add_u32 v134, v0, 12, v2
	s_add_u32 s68, s34, s6
	global_load_lds_dwordx4 v134, s[78:79]
	s_addc_u32 s69, s35, s7
	s_mov_b32 m0, s12
	s_add_i32 s13, s12, 0x2000
	v_lshl_add_u32 v132, v1, 12, v2
	global_load_lds_dwordx4 v128, s[68:69]
	s_mov_b32 m0, s13
	s_add_u32 s6, s78, 0x80000
	global_load_lds_dwordx4 v132, s[68:69]
	s_addc_u32 s7, s79, 0
	s_add_i32 m0, s12, 0x14000
	v_mov_b32_e32 v137, 0
	global_load_lds_dwordx4 v130, s[6:7]
	s_add_i32 m0, s12, 0x16000
	v_mov_b32_e32 v131, v137
	global_load_lds_dwordx4 v134, s[6:7]
	s_add_u32 s6, s68, 0x80000
	s_addc_u32 s7, s69, 0
	s_add_i32 s14, s12, 0x4000
	s_mov_b32 m0, s14
	s_add_i32 s15, s12, 0x6000
	global_load_lds_dwordx4 v128, s[6:7]
	s_mov_b32 m0, s15
	v_mov_b32_e32 v135, v137
	global_load_lds_dwordx4 v132, s[6:7]
	v_mov_b32_e32 v129, v137
	v_mov_b32_e32 v133, v137
	s_mov_b32 s1, 0
	v_lshl_add_u64 v[6:7], s[78:79], 0, v[130:131]
	v_lshl_add_u64 v[4:5], s[78:79], 0, v[134:135]
	v_lshl_add_u64 v[2:3], s[68:69], 0, v[128:129]
	s_cmp_lg_u32 s0, 1
	v_lshl_add_u64 v[0:1], s[68:69], 0, v[132:133]
	s_cbranch_scc1 .LBB0_2401
	s_setprio 1
	s_nop 0
	s_nop 0
	s_nop 0
	s_nop 0
	s_nop 0
	s_nop 0
	s_nop 0
	s_barrier

; #define PG8_STAGE(bufoff, gbase, voff) do { _Pragma("unroll") for (int _i = 0; _i < 2; ++_i) \
;         __builtin_amdgcn_global_load_lds((const unsigned*)((const char*)(gbase) + (voff)[_i]), (LAS unsigned*)(lds + (bufoff) + ldsw + _i * 8192), 16, 0, 0); } while (0)
; #define PG8_LDA(dst, b, h) do { _Pragma("unroll") for (int m = 0; m < 4; ++m) _Pragma("unroll") for (int k = 0; k < 2; ++k) dst[m][k] = *(const LAS bf16x8*)(lds + PG8_SA(b, h) + aoff + m * 2048 + k * 1024); } while (0)
; #define PG8_LDB(dst, b, h) do { _Pragma("unroll") for (int n = 0; n < 2; ++n) _Pragma("unroll") for (int k = 0; k < 2; ++k) dst[n][k] = *(const LAS bf16x8*)(lds + PG8_SB(b, h) + boff + n * 2048 + k * 1024); } while (0)
; #define PG8_MMA(ai, bj, At, Bt) do { __builtin_amdgcn_s_setprio(1); _Pragma("unroll") for (int m = 0; m < 4; ++m) _Pragma("unroll") for (int n = 0; n < 2; ++n) _Pragma("unroll") for (int k = 0; k < 2; ++k) \
;         acc[ai][bj][m][n] = __builtin_amdgcn_mfma_f32_16x16x32_bf16(Bt[n][k], At[m][k], acc[ai][bj][m][n], 0, 0, 0); __builtin_amdgcn_s_setprio(0); } while (0)
; #define PG8_WAIT_L(n) asm volatile("s_waitcnt lgkmcnt(" #n ")" ::: "memory")
; #define PG8_BAR __builtin_amdgcn_s_barrier()
; #define PG8_SCHED __builtin_amdgcn_sched_barrier(0)
; template <class Epi, class Sched>
; __device__ __forceinline__ void gemm_phase(LAS unsigned char* lds, const int K, const int lda, Sched& S, const Epi& E) {
;     ...
;         for (int t = 0; t < nt; t += 2) {
;             const bool last = (t == nt - 2);
;             const char* a1 = cA + (size_t)(t + 1) * kstep;
;             const char* a2 = last ? nA : cA + (size_t)(t + 2) * kstep; const char* b2 = last ? nB : cB + (size_t)(t + 2) * kstep;
;             const char* a3 = a2 + kstep; const char* b3 = b2 + kstep;
;             PG8_LDB(B0, 0, 0); PG8_SCHED; PG8_LDA(At, 0, 0); PG8_STAGE(PG8_SA(1, 1), a1 + hstepA, voffA);
;             PG8_WAIT_L(8); PG8_BAR; PG8_WAIT_L(0); PG8_MMA(0, 0, At, B0); PG8_BAR; PG8_SCHED;
;             PG8_LDB(B1, 0, 1); PG8_STAGE(PG8_SB(0, 0), b2, voffB);
;             PG8_BAR; PG8_WAIT_L(0); PG8_MMA(0, 1, At, B1); PG8_BAR;
;             PG8_LDA(At, 0, 1); PG8_STAGE(PG8_SA(0, 0), a2, voffA);
;             PG8_BAR; PG8_WAIT_L(0); PG8_MMA(1, 0, At, B0); PG8_BAR; PG8_SCHED;
.LBB0_2412:
	ds_read_b128 v[148:151], v145
	ds_read_b128 v[152:155], v145 offset:1024
	ds_read_b128 v[156:159], v145 offset:2048
	ds_read_b128 v[160:163], v145 offset:3072
	s_add_u32 s52, s68, 0xfff80080
	s_addc_u32 s53, s69, -1
	s_cmp_eq_u32 s31, 28
	s_cselect_b32 s81, s0, s53
	s_cselect_b32 s80, s4, s52
	s_cselect_b32 s79, s5, s29
	s_cselect_b32 s78, s11, s28
	v_lshl_add_u64 v[196:197], s[68:69], 0, v[140:141]
	s_add_i32 m0, s12, 0xc000
	ds_read_b128 v[164:167], v146
	ds_read_b128 v[168:171], v146 offset:1024
	ds_read_b128 v[172:175], v146 offset:2048
	ds_read_b128 v[176:179], v146 offset:3072
	ds_read_b128 v[180:183], v146 offset:4096
	ds_read_b128 v[184:187], v146 offset:5120
	ds_read_b128 v[188:191], v146 offset:6144
	ds_read_b128 v[192:195], v146 offset:7168
	global_load_lds_dwordx4 v[196:197], off
	v_lshl_add_u64 v[196:197], s[68:69], 0, v[142:143]
	s_add_i32 m0, s12, 0xe000
	s_nop 0
	global_load_lds_dwordx4 v[196:197], off
	s_waitcnt lgkmcnt(8)
	s_barrier
	s_waitcnt lgkmcnt(0)
	s_waitcnt lgkmcnt(0)
	v_mfma_f32_16x16x32_bf16 v[124:127], v[148:151], v[164:167], v[124:127]
	v_mfma_f32_16x16x32_bf16 v[120:123], v[156:159], v[164:167], v[120:123]
	v_mfma_f32_16x16x32_bf16 v[116:119], v[148:151], v[172:175], v[116:119]
	v_mfma_f32_16x16x32_bf16 v[112:115], v[156:159], v[172:175], v[112:115]
	v_mfma_f32_16x16x32_bf16 v[108:111], v[148:151], v[180:183], v[108:111]
	v_mfma_f32_16x16x32_bf16 v[104:107], v[156:159], v[180:183], v[104:107]
	v_mfma_f32_16x16x32_bf16 v[100:103], v[148:151], v[188:191], v[100:103]
	v_mfma_f32_16x16x32_bf16 v[96:99], v[156:159], v[188:191], v[96:99]
	v_mfma_f32_16x16x32_bf16 v[124:127], v[152:155], v[168:171], v[124:127]
	v_mfma_f32_16x16x32_bf16 v[120:123], v[160:163], v[168:171], v[120:123]
	v_mfma_f32_16x16x32_bf16 v[116:119], v[152:155], v[176:179], v[116:119]
	v_mfma_f32_16x16x32_bf16 v[112:115], v[160:163], v[176:179], v[112:115]
	v_mfma_f32_16x16x32_bf16 v[108:111], v[152:155], v[184:187], v[108:111]
	v_mfma_f32_16x16x32_bf16 v[104:107], v[160:163], v[184:187], v[104:107]
	v_mfma_f32_16x16x32_bf16 v[100:103], v[152:155], v[192:195], v[100:103]
	v_mfma_f32_16x16x32_bf16 v[96:99], v[160:163], v[192:195], v[96:99]
	s_barrier
	s_add_i32 s52, s23, s3
	v_lshl_add_u64 v[212:213], s[78:79], 0, v[130:131]
	s_mov_b32 m0, s52
	ds_read_b128 v[196:199], v147
	ds_read_b128 v[200:203], v147 offset:1024
	ds_read_b128 v[204:207], v147 offset:2048
	ds_read_b128 v[208:211], v147 offset:3072
	global_load_lds_dwordx4 v[212:213], off
	v_lshl_add_u64 v[216:217], s[78:79], 0, v[134:135]
	s_add_i32 m0, s52, 0x2000
	s_nop 0
	global_load_lds_dwordx4 v[216:217], off
	s_barrier
	s_waitcnt lgkmcnt(0)
	s_waitcnt lgkmcnt(0)
	v_mfma_f32_16x16x32_bf16 v[60:63], v[196:199], v[164:167], v[60:63]
	v_mfma_f32_16x16x32_bf16 v[56:59], v[204:207], v[164:167], v[56:59]
	v_mfma_f32_16x16x32_bf16 v[52:55], v[196:199], v[172:175], v[52:55]
	v_mfma_f32_16x16x32_bf16 v[48:51], v[204:207], v[172:175], v[48:51]
	v_mfma_f32_16x16x32_bf16 v[44:47], v[196:199], v[180:183], v[44:47]
	v_mfma_f32_16x16x32_bf16 v[40:43], v[204:207], v[180:183], v[40:43]
	v_mfma_f32_16x16x32_bf16 v[36:39], v[196:199], v[188:191], v[36:39]
	v_mfma_f32_16x16x32_bf16 v[32:35], v[204:207], v[188:191], v[32:35]
	v_mfma_f32_16x16x32_bf16 v[60:63], v[200:203], v[168:171], v[60:63]
	v_mfma_f32_16x16x32_bf16 v[56:59], v[208:211], v[168:171], v[56:59]
	v_mfma_f32_16x16x32_bf16 v[52:55], v[200:203], v[176:179], v[52:55]
	v_mfma_f32_16x16x32_bf16 v[48:51], v[208:211], v[176:179], v[48:51]
	v_mfma_f32_16x16x32_bf16 v[44:47], v[200:203], v[184:187], v[44:47]
	v_mfma_f32_16x16x32_bf16 v[40:43], v[208:211], v[184:187], v[40:43]
	v_mfma_f32_16x16x32_bf16 v[36:39], v[200:203], v[192:195], v[36:39]
	v_mfma_f32_16x16x32_bf16 v[32:35], v[208:211], v[192:195], v[32:35]
	s_mov_b32 m0, s12
	v_lshl_add_u64 v[218:219], s[80:81], 0, v[128:129]
	s_barrier
	ds_read_b128 v[164:167], v146 offset:16384
	ds_read_b128 v[168:171], v146 offset:17408
	ds_read_b128 v[172:175], v146 offset:18432
	ds_read_b128 v[176:179], v146 offset:19456
	ds_read_b128 v[180:183], v146 offset:20480
	ds_read_b128 v[184:187], v146 offset:21504
	ds_read_b128 v[188:191], v146 offset:22528
	ds_read_b128 v[192:195], v146 offset:23552
	global_load_lds_dwordx4 v[218:219], off
	v_lshl_add_u64 v[220:221], s[80:81], 0, v[132:133]
	s_mov_b32 m0, s13
	s_nop 0
	global_load_lds_dwordx4 v[220:221], off
	s_barrier
	s_waitcnt lgkmcnt(0)
	s_waitcnt lgkmcnt(0)
	v_mfma_f32_16x16x32_bf16 v[92:95], v[148:151], v[164:167], v[92:95]
	v_mfma_f32_16x16x32_bf16 v[88:91], v[156:159], v[164:167], v[88:91]
	v_mfma_f32_16x16x32_bf16 v[84:87], v[148:151], v[172:175], v[84:87]
	v_mfma_f32_16x16x32_bf16 v[80:83], v[156:159], v[172:175], v[80:83]
	v_mfma_f32_16x16x32_bf16 v[76:79], v[148:151], v[180:183], v[76:79]
	v_mfma_f32_16x16x32_bf16 v[72:75], v[156:159], v[180:183], v[72:75]
	v_mfma_f32_16x16x32_bf16 v[68:71], v[148:151], v[188:191], v[68:71]
	v_mfma_f32_16x16x32_bf16 v[64:67], v[156:159], v[188:191], v[64:67]
	v_mfma_f32_16x16x32_bf16 v[92:95], v[152:155], v[168:171], v[92:95]
	v_mfma_f32_16x16x32_bf16 v[88:91], v[160:163], v[168:171], v[88:91]
	v_mfma_f32_16x16x32_bf16 v[84:87], v[152:155], v[176:179], v[84:87]
	v_mfma_f32_16x16x32_bf16 v[80:83], v[160:163], v[176:179], v[80:83]
	v_mfma_f32_16x16x32_bf16 v[76:79], v[152:155], v[184:187], v[76:79]
	v_mfma_f32_16x16x32_bf16 v[72:75], v[160:163], v[184:187], v[72:75]
	v_mfma_f32_16x16x32_bf16 v[68:71], v[152:155], v[192:195], v[68:71]
	v_mfma_f32_16x16x32_bf16 v[64:67], v[160:163], v[192:195], v[64:67]
	s_barrier
; #define PG8_STAGE(bufoff, gbase, voff) do { _Pragma("unroll") for (int _i = 0; _i < 2; ++_i) \
;         __builtin_amdgcn_global_load_lds((const unsigned*)((const char*)(gbase) + (voff)[_i]), (LAS unsigned*)(lds + (bufoff) + ldsw + _i * 8192), 16, 0, 0); } while (0)
; #define PG8_LDA(dst, b, h) do { _Pragma("unroll") for (int m = 0; m < 4; ++m) _Pragma("unroll") for (int k = 0; k < 2; ++k) dst[m][k] = *(const LAS bf16x8*)(lds + PG8_SA(b, h) + aoff + m * 2048 + k * 1024); } while (0)
; #define PG8_LDB(dst, b, h) do { _Pragma("unroll") for (int n = 0; n < 2; ++n) _Pragma("unroll") for (int k = 0; k < 2; ++k) dst[n][k] = *(const LAS bf16x8*)(lds + PG8_SB(b, h) + boff + n * 2048 + k * 1024); } while (0)
; #define PG8_MMA(ai, bj, At, Bt) do { __builtin_amdgcn_s_setprio(1); _Pragma("unroll") for (int m = 0; m < 4; ++m) _Pragma("unroll") for (int n = 0; n < 2; ++n) _Pragma("unroll") for (int k = 0; k < 2; ++k) \
;         acc[ai][bj][m][n] = __builtin_amdgcn_mfma_f32_16x16x32_bf16(Bt[n][k], At[m][k], acc[ai][bj][m][n], 0, 0, 0); __builtin_amdgcn_s_setprio(0); } while (0)
; #define PG8_WAIT_V(n) asm volatile("s_waitcnt vmcnt(" #n ")" ::: "memory")
; #define PG8_WAIT_L(n) asm volatile("s_waitcnt lgkmcnt(" #n ")" ::: "memory")
; #define PG8_BAR __builtin_amdgcn_s_barrier()
; #define PG8_SCHED __builtin_amdgcn_sched_barrier(0)
; template <class Epi, class Sched>
; __device__ __forceinline__ void gemm_phase(LAS unsigned char* lds, const int K, const int lda, Sched& S, const Epi& E) {
;     ...
;             PG8_STAGE(PG8_SB(0, 1), b2 + hstepB, voffB);
;             PG8_WAIT_V(6); PG8_BAR; PG8_MMA(1, 1, At, B1); PG8_BAR;
;             PG8_LDB(B0, 1, 0); PG8_SCHED; PG8_LDA(At, 1, 0); PG8_STAGE(PG8_SA(0, 1), a2 + hstepA, voffA);
;             PG8_WAIT_L(8); PG8_BAR; PG8_WAIT_L(0); PG8_MMA(0, 0, At, B0); PG8_BAR; PG8_SCHED;
;             PG8_LDB(B1, 1, 1); PG8_STAGE(PG8_SB(1, 0), b3, voffB);
;             PG8_BAR; PG8_WAIT_L(0); PG8_MMA(0, 1, At, B1); PG8_BAR;
;             PG8_LDA(At, 1, 1); PG8_STAGE(PG8_SA(1, 0), a3, voffA);
;             PG8_BAR; PG8_WAIT_L(0); PG8_MMA(1, 0, At, B0); PG8_BAR; PG8_SCHED;
	s_add_u32 s52, s78, 0x80000
	s_addc_u32 s53, s79, 0
	s_add_i32 s67, s24, s3
	v_lshl_add_u64 v[148:149], s[52:53], 0, v[130:131]
	s_mov_b32 m0, s67
	s_nop 0
	global_load_lds_dwordx4 v[148:149], off
	v_lshl_add_u64 v[148:149], s[52:53], 0, v[134:135]
	s_add_i32 m0, s67, 0x2000
	s_nop 0
	global_load_lds_dwordx4 v[148:149], off
	s_waitcnt vmcnt(6)
	s_barrier
	v_mfma_f32_16x16x32_bf16 v[28:31], v[196:199], v[164:167], v[28:31]
	v_mfma_f32_16x16x32_bf16 v[24:27], v[204:207], v[164:167], v[24:27]
	v_mfma_f32_16x16x32_bf16 v[20:23], v[196:199], v[172:175], v[20:23]
	v_mfma_f32_16x16x32_bf16 v[16:19], v[204:207], v[172:175], v[16:19]
	v_mfma_f32_16x16x32_bf16 v[12:15], v[196:199], v[180:183], v[12:15]
	v_mfma_f32_16x16x32_bf16 v[8:11], v[204:207], v[180:183], v[8:11]
	v_mfma_f32_16x16x32_bf16 v[4:7], v[196:199], v[188:191], v[4:7]
	v_mfma_f32_16x16x32_bf16 v[0:3], v[204:207], v[188:191], v[0:3]
	v_mfma_f32_16x16x32_bf16 v[28:31], v[200:203], v[168:171], v[28:31]
	v_mfma_f32_16x16x32_bf16 v[24:27], v[208:211], v[168:171], v[24:27]
	v_mfma_f32_16x16x32_bf16 v[20:23], v[200:203], v[176:179], v[20:23]
	v_mfma_f32_16x16x32_bf16 v[16:19], v[208:211], v[176:179], v[16:19]
	v_mfma_f32_16x16x32_bf16 v[12:15], v[200:203], v[184:187], v[12:15]
	v_mfma_f32_16x16x32_bf16 v[8:11], v[208:211], v[184:187], v[8:11]
	v_mfma_f32_16x16x32_bf16 v[4:7], v[200:203], v[192:195], v[4:7]
	v_mfma_f32_16x16x32_bf16 v[0:3], v[208:211], v[192:195], v[0:3]
	s_add_i32 s67, 0, 0x18000
	v_add_u32_e32 v136, s67, v144
	s_barrier
	ds_read_b128 v[148:151], v136
	ds_read_b128 v[152:155], v136 offset:1024
	ds_read_b128 v[156:159], v136 offset:2048
	ds_read_b128 v[160:163], v136 offset:3072
	s_add_u32 s52, s80, 0x80000
	s_addc_u32 s53, s81, 0
	s_mov_b32 m0, s14
	v_lshl_add_u64 v[196:197], s[52:53], 0, v[128:129]
	ds_read_b128 v[164:167], v146 offset:32768
	ds_read_b128 v[168:171], v146 offset:33792
	ds_read_b128 v[172:175], v146 offset:34816
	ds_read_b128 v[176:179], v146 offset:35840
	ds_read_b128 v[180:183], v146 offset:36864
	ds_read_b128 v[184:187], v146 offset:37888
	ds_read_b128 v[188:191], v146 offset:38912
	ds_read_b128 v[192:195], v146 offset:39936
	global_load_lds_dwordx4 v[196:197], off
	v_lshl_add_u64 v[196:197], s[52:53], 0, v[132:133]
	s_mov_b32 m0, s15
	s_nop 0
	global_load_lds_dwordx4 v[196:197], off
	s_waitcnt lgkmcnt(8)
	s_barrier
	s_waitcnt lgkmcnt(0)
	s_waitcnt lgkmcnt(0)
	v_mfma_f32_16x16x32_bf16 v[124:127], v[148:151], v[164:167], v[124:127]
	v_mfma_f32_16x16x32_bf16 v[120:123], v[156:159], v[164:167], v[120:123]
	v_mfma_f32_16x16x32_bf16 v[116:119], v[148:151], v[172:175], v[116:119]
	v_mfma_f32_16x16x32_bf16 v[112:115], v[156:159], v[172:175], v[112:115]
	v_mfma_f32_16x16x32_bf16 v[108:111], v[148:151], v[180:183], v[108:111]
	v_mfma_f32_16x16x32_bf16 v[104:107], v[156:159], v[180:183], v[104:107]
	v_mfma_f32_16x16x32_bf16 v[100:103], v[148:151], v[188:191], v[100:103]
	v_mfma_f32_16x16x32_bf16 v[96:99], v[156:159], v[188:191], v[96:99]
	v_mfma_f32_16x16x32_bf16 v[124:127], v[152:155], v[168:171], v[124:127]
	v_mfma_f32_16x16x32_bf16 v[120:123], v[160:163], v[168:171], v[120:123]
	v_mfma_f32_16x16x32_bf16 v[116:119], v[152:155], v[176:179], v[116:119]
	v_mfma_f32_16x16x32_bf16 v[112:115], v[160:163], v[176:179], v[112:115]
	v_mfma_f32_16x16x32_bf16 v[108:111], v[152:155], v[184:187], v[108:111]
	v_mfma_f32_16x16x32_bf16 v[104:107], v[160:163], v[184:187], v[104:107]
	v_mfma_f32_16x16x32_bf16 v[100:103], v[152:155], v[192:195], v[100:103]
	v_mfma_f32_16x16x32_bf16 v[96:99], v[160:163], v[192:195], v[96:99]
	s_barrier
	s_add_i32 s77, 0, 0x1c000
	s_add_i32 s52, s67, s3
	v_add_u32_e32 v136, s77, v144
	v_lshl_add_u64 v[212:213], v[212:213], 0, s[6:7]
	s_mov_b32 m0, s52
	ds_read_b128 v[196:199], v136
	ds_read_b128 v[200:203], v136 offset:1024
	ds_read_b128 v[204:207], v136 offset:2048
	ds_read_b128 v[208:211], v136 offset:3072
	global_load_lds_dwordx4 v[212:213], off
	v_lshl_add_u64 v[212:213], v[216:217], 0, s[6:7]
	s_add_i32 m0, s52, 0x2000
	s_nop 0
	global_load_lds_dwordx4 v[212:213], off
	s_barrier
	s_waitcnt lgkmcnt(0)
	s_waitcnt lgkmcnt(0)
	v_mfma_f32_16x16x32_bf16 v[60:63], v[196:199], v[164:167], v[60:63]
	v_mfma_f32_16x16x32_bf16 v[56:59], v[204:207], v[164:167], v[56:59]
	v_mfma_f32_16x16x32_bf16 v[52:55], v[196:199], v[172:175], v[52:55]
	v_mfma_f32_16x16x32_bf16 v[48:51], v[204:207], v[172:175], v[48:51]
	v_mfma_f32_16x16x32_bf16 v[44:47], v[196:199], v[180:183], v[44:47]
	v_mfma_f32_16x16x32_bf16 v[40:43], v[204:207], v[180:183], v[40:43]
	v_mfma_f32_16x16x32_bf16 v[36:39], v[196:199], v[188:191], v[36:39]
	v_mfma_f32_16x16x32_bf16 v[32:35], v[204:207], v[188:191], v[32:35]
	v_mfma_f32_16x16x32_bf16 v[60:63], v[200:203], v[168:171], v[60:63]
	v_mfma_f32_16x16x32_bf16 v[56:59], v[208:211], v[168:171], v[56:59]
	v_mfma_f32_16x16x32_bf16 v[52:55], v[200:203], v[176:179], v[52:55]
	v_mfma_f32_16x16x32_bf16 v[48:51], v[208:211], v[176:179], v[48:51]
	v_mfma_f32_16x16x32_bf16 v[44:47], v[200:203], v[184:187], v[44:47]
	v_mfma_f32_16x16x32_bf16 v[40:43], v[208:211], v[184:187], v[40:43]
	v_mfma_f32_16x16x32_bf16 v[36:39], v[200:203], v[192:195], v[36:39]
	v_mfma_f32_16x16x32_bf16 v[32:35], v[208:211], v[192:195], v[32:35]
	s_mov_b32 m0, s21
	v_lshl_add_u64 v[212:213], v[218:219], 0, s[6:7]
	s_barrier
; __device__ __forceinline__ float sigm(float x) { return __builtin_amdgcn_rcpf(1.f + __expf(-x)); }
; #define PG8_STAGE(bufoff, gbase, voff) do { _Pragma("unroll") for (int _i = 0; _i < 2; ++_i) \
;         __builtin_amdgcn_global_load_lds((const unsigned*)((const char*)(gbase) + (voff)[_i]), (LAS unsigned*)(lds + (bufoff) + ldsw + _i * 8192), 16, 0, 0); } while (0)
; #define PG8_MMA(ai, bj, At, Bt) do { __builtin_amdgcn_s_setprio(1); _Pragma("unroll") for (int m = 0; m < 4; ++m) _Pragma("unroll") for (int n = 0; n < 2; ++n) _Pragma("unroll") for (int k = 0; k < 2; ++k) \
;         acc[ai][bj][m][n] = __builtin_amdgcn_mfma_f32_16x16x32_bf16(Bt[n][k], At[m][k], acc[ai][bj][m][n], 0, 0, 0); __builtin_amdgcn_s_setprio(0); } while (0)
; #define PG8_WAIT_V(n) asm volatile("s_waitcnt vmcnt(" #n ")" ::: "memory")
; #define PG8_WAIT_L(n) asm volatile("s_waitcnt lgkmcnt(" #n ")" ::: "memory")
; #define PG8_BAR __builtin_amdgcn_s_barrier()
; #define PG8_SCHED __builtin_amdgcn_sched_barrier(0)
; template <class Epi, class Sched>
; __device__ __forceinline__ void gemm_phase(LAS unsigned char* lds, const int K, const int lda, Sched& S, const Epi& E) {
;     ...
;             PG8_BAR; PG8_WAIT_L(0); PG8_MMA(1, 0, At, B0); PG8_BAR; PG8_SCHED;
;             PG8_STAGE(PG8_SB(1, 1), b3 + hstepB, voffB);
;             PG8_WAIT_V(6); PG8_BAR; PG8_MMA(1, 1, At, B1); PG8_BAR;
;     __device__ __forceinline__ void operator()(f32x4 (&acc)[2][2][4][2], const Unit& u, int wr, int wc, int fr, int fq) const {
;     ...
;         for (int bj = 0; bj < 2; ++bj) {
;             const int colb = u.pn * 256 + bj * 128;
;             if (colb >= NIN) continue;
;             const int act = colb >= OFF_MERGE ? 2 : (colb >= OFF_GATE ? 1 : 0);
;             u16* pb = proj + (size_t)(u.pm * 256 + wr * 64 + fr) * NIN + colb + wc * 32 + 8 * fq;
; #pragma unroll
;             for (int ai = 0; ai < 2; ++ai)
; #pragma unroll
;                 for (int m = 0; m < 4; ++m) {
;                     f32x4 v0 = acc[ai][bj][m][0], v1 = acc[ai][bj][m][1];
;                     if (act == 1) {
; #pragma unroll
;                         for (int j = 0; j < 4; ++j) { v0[j] = v0[j] * sigm(v0[j]); v1[j] = v1[j] * sigm(v1[j]); }
;                     } else if (act == 2) {
; #pragma unroll
;                         for (int j = 0; j < 4; ++j) { v0[j] = sigm(v0[j]); v1[j] = sigm(v1[j]); }
	ds_read_b128 v[164:167], v146 offset:49152
	ds_read_b128 v[168:171], v146 offset:50176
	ds_read_b128 v[172:175], v146 offset:51200
	ds_read_b128 v[176:179], v146 offset:52224
	ds_read_b128 v[180:183], v146 offset:53248
	ds_read_b128 v[184:187], v146 offset:54272
	ds_read_b128 v[188:191], v146 offset:55296
	ds_read_b128 v[192:195], v146 offset:56320
	global_load_lds_dwordx4 v[212:213], off
	v_lshl_add_u64 v[212:213], v[220:221], 0, s[6:7]
	s_mov_b32 m0, s22
	s_nop 0
	global_load_lds_dwordx4 v[212:213], off
	s_barrier
	s_waitcnt lgkmcnt(0)
	s_waitcnt lgkmcnt(0)
	v_mfma_f32_16x16x32_bf16 v[92:95], v[148:151], v[164:167], v[92:95]
	v_mfma_f32_16x16x32_bf16 v[88:91], v[156:159], v[164:167], v[88:91]
	v_mfma_f32_16x16x32_bf16 v[84:87], v[148:151], v[172:175], v[84:87]
	v_mfma_f32_16x16x32_bf16 v[80:83], v[156:159], v[172:175], v[80:83]
	v_mfma_f32_16x16x32_bf16 v[76:79], v[148:151], v[180:183], v[76:79]
	v_mfma_f32_16x16x32_bf16 v[72:75], v[156:159], v[180:183], v[72:75]
	v_mfma_f32_16x16x32_bf16 v[68:71], v[148:151], v[188:191], v[68:71]
	v_mfma_f32_16x16x32_bf16 v[64:67], v[156:159], v[188:191], v[64:67]
	v_mfma_f32_16x16x32_bf16 v[92:95], v[152:155], v[168:171], v[92:95]
	v_mfma_f32_16x16x32_bf16 v[88:91], v[160:163], v[168:171], v[88:91]
	v_mfma_f32_16x16x32_bf16 v[84:87], v[152:155], v[176:179], v[84:87]
	v_mfma_f32_16x16x32_bf16 v[80:83], v[160:163], v[176:179], v[80:83]
	v_mfma_f32_16x16x32_bf16 v[76:79], v[152:155], v[184:187], v[76:79]
	v_mfma_f32_16x16x32_bf16 v[72:75], v[160:163], v[184:187], v[72:75]
	v_mfma_f32_16x16x32_bf16 v[68:71], v[152:155], v[192:195], v[68:71]
	v_mfma_f32_16x16x32_bf16 v[64:67], v[160:163], v[192:195], v[64:67]
	s_barrier
	s_add_u32 s52, s78, 0x80080
	s_addc_u32 s53, s79, 0
	s_add_i32 s67, s77, s3
	v_lshl_add_u64 v[148:149], s[52:53], 0, v[130:131]
	s_mov_b32 m0, s67
	s_nop 0
	global_load_lds_dwordx4 v[148:149], off
	v_lshl_add_u64 v[148:149], s[52:53], 0, v[134:135]
	s_add_i32 m0, s67, 0x2000
	s_nop 0
	global_load_lds_dwordx4 v[148:149], off
	s_waitcnt vmcnt(6)
	s_barrier
	v_mfma_f32_16x16x32_bf16 v[28:31], v[196:199], v[164:167], v[28:31]
	v_mfma_f32_16x16x32_bf16 v[24:27], v[204:207], v[164:167], v[24:27]
	v_mfma_f32_16x16x32_bf16 v[20:23], v[196:199], v[172:175], v[20:23]
	v_mfma_f32_16x16x32_bf16 v[16:19], v[204:207], v[172:175], v[16:19]
	v_mfma_f32_16x16x32_bf16 v[12:15], v[196:199], v[180:183], v[12:15]
	v_mfma_f32_16x16x32_bf16 v[8:11], v[204:207], v[180:183], v[8:11]
	v_mfma_f32_16x16x32_bf16 v[4:7], v[196:199], v[188:191], v[4:7]
	v_mfma_f32_16x16x32_bf16 v[0:3], v[204:207], v[188:191], v[0:3]
	v_mfma_f32_16x16x32_bf16 v[28:31], v[200:203], v[168:171], v[28:31]
	v_mfma_f32_16x16x32_bf16 v[24:27], v[208:211], v[168:171], v[24:27]
	v_mfma_f32_16x16x32_bf16 v[20:23], v[200:203], v[176:179], v[20:23]
	v_mfma_f32_16x16x32_bf16 v[16:19], v[208:211], v[176:179], v[16:19]
	v_mfma_f32_16x16x32_bf16 v[12:15], v[200:203], v[184:187], v[12:15]
	v_mfma_f32_16x16x32_bf16 v[8:11], v[208:211], v[184:187], v[8:11]
	v_mfma_f32_16x16x32_bf16 v[4:7], v[200:203], v[192:195], v[4:7]
	v_mfma_f32_16x16x32_bf16 v[0:3], v[208:211], v[192:195], v[0:3]
	s_add_i32 s31, s31, 2
	s_add_u32 s68, s68, 0x100
	s_addc_u32 s69, s69, 0
	s_add_u32 s28, s28, 0x100
	s_addc_u32 s29, s29, 0
	s_cmp_gt_u32 s31, 29
	s_barrier
	s_cbranch_scc0 .LBB0_2412
	s_lshl_b32 s68, s76, 8
	s_cmp_gt_i32 s76, 58
	s_cbranch_scc1 .LBB0_2463
	s_cmp_gt_i32 s76, 22
	s_cselect_b64 s[4:5], -1, 0
	v_cndmask_b32_e64 v136, 0, 1, s[4:5]
	s_cmp_lt_i32 s76, 35
	v_readfirstlane_b32 s0, v136
	s_cselect_b32 s11, s0, 2
	s_cmp_gt_i32 s11, 1
	s_mov_b64 s[76:77], -1
	s_cbranch_scc0 .LBB0_2416
	v_mul_f32_e32 v136, 0xbfb8aa3b, v124
	v_exp_f32_e32 v136, v136
	v_mul_f32_e32 v148, 0xbfb8aa3b, v120
	v_exp_f32_e32 v148, v148
	v_mul_f32_e32 v150, 0xbfb8aa3b, v121
	v_add_f32_e32 v136, 1.0, v136
	v_exp_f32_e32 v151, v150
	v_add_f32_e32 v149, 1.0, v148
	v_rcp_f32_e32 v148, v136
	v_mul_f32_e32 v136, 0xbfb8aa3b, v125
	v_exp_f32_e32 v136, v136
	v_rcp_f32_e32 v149, v149
	s_mov_b64 s[76:77], 0
	v_add_f32_e32 v136, 1.0, v136
	v_rcp_f32_e32 v150, v136
	v_add_f32_e32 v136, 1.0, v151
	v_mul_f32_e32 v151, 0xbfb8aa3b, v126
	v_exp_f32_e32 v152, v151
	v_mul_f32_e32 v151, 0xbfb8aa3b, v122
	v_exp_f32_e32 v153, v151
	v_rcp_f32_e32 v151, v136
	v_add_f32_e32 v136, 1.0, v152
	v_rcp_f32_e32 v152, v136
	v_add_f32_e32 v136, 1.0, v153
	v_mul_f32_e32 v153, 0xbfb8aa3b, v127
	v_exp_f32_e32 v154, v153
	v_mul_f32_e32 v153, 0xbfb8aa3b, v123
	v_exp_f32_e32 v156, v153
	v_rcp_f32_e32 v153, v136
	v_add_f32_e32 v136, 1.0, v154
	v_rcp_f32_e32 v155, v136
	v_add_f32_e32 v136, 1.0, v156
	v_rcp_f32_e32 v154, v136

; #define PG8_WAIT_V(n) asm volatile("s_waitcnt vmcnt(" #n ")" ::: "memory")
; #define PG8_BAR __builtin_amdgcn_s_barrier()
; template <class Epi, class Sched>
; __device__ __forceinline__ void gemm_phase(LAS unsigned char* lds, const int K, const int lda, Sched& S, const Epi& E) {
;     ...
;     PG8_WAIT_V(0);
;     if (wr == 0) PG8_BAR;
;     PG8_BAR;
.LBB0_2511:
	s_waitcnt vmcnt(0)
	s_setprio 0
	s_nop 0
	s_nop 0
	s_nop 0
	s_nop 0
	s_nop 0
	s_nop 0
	s_nop 0
	s_cmpk_gt_u32 s2, 0xff
	s_cbranch_scc1 .LBB0_2513
	s_barrier

; #define PG8_STAGE(bufoff, gbase, voff) do { _Pragma("unroll") for (int _i = 0; _i < 2; ++_i) \
;         __builtin_amdgcn_global_load_lds((const unsigned*)((const char*)(gbase) + (voff)[_i]), (LAS unsigned*)(lds + (bufoff) + ldsw + _i * 8192), 16, 0, 0); } while (0)
; #define PG8_BAR __builtin_amdgcn_s_barrier()
;     __device__ __forceinline__ const char* aptr(const Unit& u) const { return (const char*)(A + (size_t)u.pm * 256 * 2048); }
;     __device__ __forceinline__ const char* bptr(const Unit& u) const { return (const char*)(Bt + (size_t)u.pn * 256 * 2048); }
;     __device__ __forceinline__ const char* aptr(const Unit& u) const { return (const char*)(A + (size_t)u.pm * 256 * NIN + OFF_GATE + u.z * 1024); }
; template <class Epi, class Sched>
; __device__ __forceinline__ void gemm_phase(LAS unsigned char* lds, const int K, const int lda, Sched& S, const Epi& E) {
;     const int tid = opaque_tid(), wid = __builtin_amdgcn_readfirstlane(tid >> 6), lane = tid & 63, wr = wid >> 2, wc = wid & 3, fr = lane & 15, fq = lane >> 4;
;     const int nt = K / BK;
;     unsigned voffA[2], voffB[2];
; #pragma unroll
;     for (int i = 0; i < 2; ++i) { int R, C; stage_rc(tid * 16 + i * 8192, R, C); const int Rb = (R & ~31) + perm32(R & 31);
;         voffA[i] = (unsigned)(R * lda + C) * 2u; voffB[i] = (unsigned)(Rb * K + C) * 2u; }
;     const size_t kstep = (size_t)(BK * 2);
;     const size_t hstepA = (size_t)HALF * lda * 2, hstepB = (size_t)HALF * K * 2;
;     const unsigned ldsw = (unsigned)wid * 1024u;
;     const int aoff = lds_byte(wr * 64 + fr, fq * 8), boff = lds_byte(wc * 32 + fr, fq * 8);
;     ...
;     Unit cur, nxt; int ui = 0;
;     if (!S.next(0, cur)) return;
;     f32x4 acc[2][2][4][2];
; #pragma unroll
;     for (int a = 0; a < 2; ++a)
; #pragma unroll
;         for (int b = 0; b < 2; ++b)
; #pragma unroll
;             for (int m = 0; m < 4; ++m)
; #pragma unroll
;                 for (int n = 0; n < 2; ++n) acc[a][b][m][n] = (f32x4){0.f, 0.f, 0.f, 0.f};
;     bf16x8 At[4][2], B0[2][2], B1[2][2];
;     const char* cA = S.aptr(cur); const char* cB = S.bptr(cur);
;     PG8_STAGE(PG8_SB(0, 0), cB, voffB); PG8_STAGE(PG8_SA(0, 0), cA, voffA); PG8_STAGE(PG8_SB(0, 1), cB + hstepB, voffB); PG8_STAGE(PG8_SA(0, 1), cA + hstepA, voffA);
;     if (wr == 1) PG8_BAR;
.LBB0_2944:
	s_andn2_b64 vcc, exec, s[6:7]
	s_cbranch_vccnz .LBB0_3074
	v_ashrrev_i32_e32 v1, 31, v8
	v_lshrrev_b32_e32 v1, 26, v1
	v_add_u32_e32 v1, v8, v1
	v_ashrrev_i32_e32 v9, 6, v1
	v_bfe_i32 v1, v8, 27, 1
	v_lshlrev_b32_e32 v0, 4, v8
	v_lshrrev_b32_e32 v1, 22, v1
	v_add_u32_e32 v1, v0, v1
	v_and_b32_e32 v1, 0xfffffc00, v1
	v_sub_u32_e32 v1, v0, v1
	v_lshrrev_b32_e32 v2, 4, v1
	v_bitop3_b32 v2, v2, v1, 32 bitop3:0x6c
	v_ashrrev_i32_e32 v1, 31, v1
	v_lshrrev_b32_e32 v1, 26, v1
	v_add_u32_e32 v1, v2, v1
	v_ashrrev_i32_e32 v10, 6, v1
	v_lshlrev_b32_e32 v3, 3, v9
	v_mul_i32_i24_e32 v4, 64, v10
	v_and_b32_e32 v3, -16, v3
	v_sub_u32_e32 v2, v2, v4
	v_mov_b32_e32 v169, 1
	v_add_u32_e32 v1, v10, v3
	v_lshlrev_b32_e32 v3, 5, v9
	v_ashrrev_i16_sdwa v2, v169, sext(v2) dst_sel:DWORD dst_unused:UNUSED_PAD src0_sel:DWORD src1_sel:BYTE_0
	v_and_b32_e32 v3, 32, v3
	v_bfe_i32 v11, v2, 0, 16
	v_and_b32_e32 v5, 3, v10
	s_mov_b32 s3, 0xfffe0
	v_add_lshl_u32 v3, v3, v11, 1
	v_add_u32_e32 v0, 0x2000, v0
	v_lshlrev_b32_e32 v2, 1, v1
	v_lshrrev_b32_e32 v4, 2, v1
	v_and_or_b32 v5, v1, s3, v5
	v_lshl_add_u32 v128, v1, 12, v3
	v_ashrrev_i32_e32 v1, 31, v0
	v_lshrrev_b32_e32 v1, 22, v1
	v_add_u32_e32 v1, v0, v1
	v_ashrrev_i32_e32 v12, 10, v1
	v_mul_i32_i24_e32 v1, 0x400, v12
	v_sub_u32_e32 v0, v0, v1
	v_and_b32_e32 v2, 24, v2
	v_and_b32_e32 v4, 4, v4
	v_lshrrev_b32_e32 v1, 4, v0
	v_or3_b32 v2, v5, v4, v2
	v_bitop3_b32 v0, v1, v0, 32 bitop3:0x6c
	v_lshl_add_u32 v130, v2, 12, v3
	v_ashrrev_i32_e32 v2, 31, v0
	v_lshrrev_b32_e32 v2, 26, v2
	v_lshlrev_b32_e32 v1, 3, v12
	v_add_u32_e32 v2, v0, v2
	v_and_b32_e32 v1, -16, v1
	v_ashrrev_i32_e32 v13, 6, v2
	v_add_u32_e32 v1, v13, v1
	v_and_b32_e32 v2, 0xc0, v2
	v_and_b32_e32 v4, 3, v13
	s_ashr_i32 s5, s2, 6
	s_ashr_i32 s13, s12, 31
	s_ashr_i32 s9, s8, 31
	s_ashr_i32 s4, s2, 8
	v_sub_u32_e32 v0, v0, v2
	v_and_or_b32 v4, v1, s3, v4
	s_lshl_b32 s3, s5, 10
	s_lshl_b64 s[20:21], s[12:13], 20
	s_lshl_b64 s[6:7], s[8:9], 20
	v_ashrrev_i16_sdwa v0, v169, sext(v0) dst_sel:DWORD dst_unused:UNUSED_PAD src0_sel:DWORD src1_sel:BYTE_0
	s_add_u32 s6, s18, s6
	v_lshlrev_b32_e32 v3, 5, v12
	v_bfe_i32 v14, v0, 0, 16
	v_lshlrev_b32_e32 v0, 1, v1
	v_lshrrev_b32_e32 v2, 2, v1
	s_addc_u32 s7, s19, s7
	s_add_i32 s14, s3, 0
	v_and_b32_e32 v3, 32, v3
	v_and_b32_e32 v0, 24, v0
	v_and_b32_e32 v2, 4, v2
	s_add_i32 m0, s14, 0x10000
	v_or3_b32 v0, v4, v2, v0
	v_add_lshl_u32 v2, v3, v14, 1
	global_load_lds_dwordx4 v130, s[6:7]
	s_add_i32 m0, s14, 0x12000
	v_lshl_add_u32 v134, v0, 12, v2
	s_add_u32 s62, s34, s20
	global_load_lds_dwordx4 v134, s[6:7]
	s_addc_u32 s63, s35, s21
	s_mov_b32 m0, s14
	s_add_i32 s15, s14, 0x2000
	v_lshl_add_u32 v132, v1, 12, v2
	global_load_lds_dwordx4 v128, s[62:63]
	s_mov_b32 m0, s15
	s_add_u32 s20, s6, 0x80000
	global_load_lds_dwordx4 v132, s[62:63]
	s_addc_u32 s21, s7, 0
	s_add_i32 m0, s14, 0x14000
	v_mov_b32_e32 v137, 0
	global_load_lds_dwordx4 v130, s[20:21]
	s_add_i32 m0, s14, 0x16000
	s_add_u32 s22, s62, 0x80000
	global_load_lds_dwordx4 v134, s[20:21]
	s_addc_u32 s23, s63, 0
	s_add_i32 s20, s14, 0x4000
	s_mov_b32 m0, s20
	s_add_i32 s21, s14, 0x6000
	global_load_lds_dwordx4 v128, s[22:23]
	s_mov_b32 m0, s21
	v_mov_b32_e32 v131, v137
	global_load_lds_dwordx4 v132, s[22:23]
	v_mov_b32_e32 v135, v137
	v_mov_b32_e32 v129, v137
	v_mov_b32_e32 v133, v137
	s_mov_b32 s13, 0
	v_lshl_add_u64 v[6:7], s[6:7], 0, v[130:131]
	v_lshl_add_u64 v[4:5], s[6:7], 0, v[134:135]
	v_lshl_add_u64 v[2:3], s[62:63], 0, v[128:129]
	v_lshl_add_u64 v[0:1], s[62:63], 0, v[132:133]
	s_cmp_lg_u32 s4, 1
	s_mov_b64 s[30:31], 0x80000
	s_cbranch_scc1 .LBB0_2947
	s_setprio 1
	s_nop 0
	s_nop 0
	s_nop 0
	s_nop 0
	s_nop 0
	s_nop 0
	s_nop 0
	s_barrier

; #define PG8_STAGE(bufoff, gbase, voff) do { _Pragma("unroll") for (int _i = 0; _i < 2; ++_i) \
;         __builtin_amdgcn_global_load_lds((const unsigned*)((const char*)(gbase) + (voff)[_i]), (LAS unsigned*)(lds + (bufoff) + ldsw + _i * 8192), 16, 0, 0); } while (0)
; #define PG8_LDA(dst, b, h) do { _Pragma("unroll") for (int m = 0; m < 4; ++m) _Pragma("unroll") for (int k = 0; k < 2; ++k) dst[m][k] = *(const LAS bf16x8*)(lds + PG8_SA(b, h) + aoff + m * 2048 + k * 1024); } while (0)
; #define PG8_LDB(dst, b, h) do { _Pragma("unroll") for (int n = 0; n < 2; ++n) _Pragma("unroll") for (int k = 0; k < 2; ++k) dst[n][k] = *(const LAS bf16x8*)(lds + PG8_SB(b, h) + boff + n * 2048 + k * 1024); } while (0)
; #define PG8_MMA(ai, bj, At, Bt) do { __builtin_amdgcn_s_setprio(1); _Pragma("unroll") for (int m = 0; m < 4; ++m) _Pragma("unroll") for (int n = 0; n < 2; ++n) _Pragma("unroll") for (int k = 0; k < 2; ++k) \
;         acc[ai][bj][m][n] = __builtin_amdgcn_mfma_f32_16x16x32_bf16(Bt[n][k], At[m][k], acc[ai][bj][m][n], 0, 0, 0); __builtin_amdgcn_s_setprio(0); } while (0)
; #define PG8_WAIT_L(n) asm volatile("s_waitcnt lgkmcnt(" #n ")" ::: "memory")
; #define PG8_BAR __builtin_amdgcn_s_barrier()
; #define PG8_SCHED __builtin_amdgcn_sched_barrier(0)
; template <class Epi, class Sched>
; __device__ __forceinline__ void gemm_phase(LAS unsigned char* lds, const int K, const int lda, Sched& S, const Epi& E) {
;     ...
;         for (int t = 0; t < nt; t += 2) {
;             const bool last = (t == nt - 2);
;             const char* a1 = cA + (size_t)(t + 1) * kstep;
;             const char* a2 = last ? nA : cA + (size_t)(t + 2) * kstep; const char* b2 = last ? nB : cB + (size_t)(t + 2) * kstep;
;             const char* a3 = a2 + kstep; const char* b3 = b2 + kstep;
;             PG8_LDB(B0, 0, 0); PG8_SCHED; PG8_LDA(At, 0, 0); PG8_STAGE(PG8_SA(1, 1), a1 + hstepA, voffA);
;             PG8_WAIT_L(8); PG8_BAR; PG8_WAIT_L(0); PG8_MMA(0, 0, At, B0); PG8_BAR; PG8_SCHED;
;             PG8_LDB(B1, 0, 1); PG8_STAGE(PG8_SB(0, 0), b2, voffB);
;             PG8_BAR; PG8_WAIT_L(0); PG8_MMA(0, 1, At, B1); PG8_BAR;
;             PG8_LDA(At, 0, 1); PG8_STAGE(PG8_SA(0, 0), a2, voffA);
;             PG8_BAR; PG8_WAIT_L(0); PG8_MMA(1, 0, At, B0); PG8_BAR; PG8_SCHED;
.LBB0_2968:
	v_add_u32_e32 v149, s25, v171
	ds_read_b128 v[164:167], v149
	ds_read_b128 v[180:183], v149 offset:1024
	ds_read_b128 v[184:187], v149 offset:2048
	ds_read_b128 v[188:191], v149 offset:3072
	s_cmpk_eq_i32 s8, 0xf00
	v_lshl_add_u64 v[162:163], v[144:145], 0, s[8:9]
	v_lshl_add_u64 v[162:163], v[162:163], 0, s[62:63]
	s_cselect_b64 vcc, -1, 0
	v_cndmask_b32_e32 v213, v163, v139, vcc
	v_cndmask_b32_e32 v212, v162, v136, vcc
	v_lshl_add_u64 v[162:163], v[154:155], 0, s[8:9]
	v_cndmask_b32_e32 v163, v163, v147, vcc
	v_cndmask_b32_e32 v162, v162, v156, vcc
	v_lshl_add_u64 v[228:229], v[158:159], 0, s[8:9]
	s_add_i32 m0, s14, 0xc000
	ds_read_b128 v[192:195], v174
	ds_read_b128 v[196:199], v174 offset:1024
	ds_read_b128 v[200:203], v174 offset:2048
	ds_read_b128 v[204:207], v174 offset:3072
	ds_read_b128 v[208:211], v174 offset:4096
	ds_read_b128 v[216:219], v174 offset:5120
	ds_read_b128 v[220:223], v174 offset:6144
	ds_read_b128 v[224:227], v174 offset:7168
	global_load_lds_dwordx4 v[228:229], off
	v_lshl_add_u64 v[228:229], v[160:161], 0, s[8:9]
	s_add_i32 m0, s14, 0xe000
	s_nop 0
	global_load_lds_dwordx4 v[228:229], off
	s_waitcnt lgkmcnt(8)
	s_barrier
	s_waitcnt lgkmcnt(0)
	s_waitcnt lgkmcnt(0)
	v_mfma_f32_16x16x32_bf16 v[124:127], v[164:167], v[192:195], v[124:127]
	v_mfma_f32_16x16x32_bf16 v[120:123], v[184:187], v[192:195], v[120:123]
	v_mfma_f32_16x16x32_bf16 v[116:119], v[164:167], v[200:203], v[116:119]
	v_mfma_f32_16x16x32_bf16 v[112:115], v[184:187], v[200:203], v[112:115]
	v_mfma_f32_16x16x32_bf16 v[108:111], v[164:167], v[208:211], v[108:111]
	v_mfma_f32_16x16x32_bf16 v[104:107], v[184:187], v[208:211], v[104:107]
	v_mfma_f32_16x16x32_bf16 v[100:103], v[164:167], v[220:223], v[100:103]
	v_mfma_f32_16x16x32_bf16 v[96:99], v[184:187], v[220:223], v[96:99]
	v_mfma_f32_16x16x32_bf16 v[124:127], v[180:183], v[196:199], v[124:127]
	v_mfma_f32_16x16x32_bf16 v[120:123], v[188:191], v[196:199], v[120:123]
	v_mfma_f32_16x16x32_bf16 v[116:119], v[180:183], v[204:207], v[116:119]
	v_mfma_f32_16x16x32_bf16 v[112:115], v[188:191], v[204:207], v[112:115]
	v_mfma_f32_16x16x32_bf16 v[108:111], v[180:183], v[216:219], v[108:111]
	v_mfma_f32_16x16x32_bf16 v[104:107], v[188:191], v[216:219], v[104:107]
	v_mfma_f32_16x16x32_bf16 v[100:103], v[180:183], v[224:227], v[100:103]
	v_mfma_f32_16x16x32_bf16 v[96:99], v[188:191], v[224:227], v[96:99]
	s_barrier
	s_add_i32 s5, s25, s3
	v_add_u32_e32 v149, s27, v171
	v_lshl_add_u64 v[244:245], v[162:163], 0, v[130:131]
	s_mov_b32 m0, s5
	ds_read_b128 v[228:231], v149
	ds_read_b128 v[232:235], v149 offset:1024
	ds_read_b128 v[236:239], v149 offset:2048
	ds_read_b128 v[240:243], v149 offset:3072
	global_load_lds_dwordx4 v[244:245], off
	v_lshl_add_u64 v[246:247], v[162:163], 0, v[134:135]
	s_add_i32 m0, s5, 0x2000
	s_nop 0
	global_load_lds_dwordx4 v[246:247], off
	s_barrier
	s_waitcnt lgkmcnt(0)
	s_waitcnt lgkmcnt(0)
	v_mfma_f32_16x16x32_bf16 v[92:95], v[228:231], v[192:195], v[92:95]
	v_mfma_f32_16x16x32_bf16 v[88:91], v[236:239], v[192:195], v[88:91]
	v_mfma_f32_16x16x32_bf16 v[84:87], v[228:231], v[200:203], v[84:87]
	v_mfma_f32_16x16x32_bf16 v[80:83], v[236:239], v[200:203], v[80:83]
	v_mfma_f32_16x16x32_bf16 v[76:79], v[228:231], v[208:211], v[76:79]
	v_mfma_f32_16x16x32_bf16 v[72:75], v[236:239], v[208:211], v[72:75]
	v_mfma_f32_16x16x32_bf16 v[68:71], v[228:231], v[220:223], v[68:71]
	v_mfma_f32_16x16x32_bf16 v[64:67], v[236:239], v[220:223], v[64:67]
	v_mfma_f32_16x16x32_bf16 v[92:95], v[232:235], v[196:199], v[92:95]
	v_mfma_f32_16x16x32_bf16 v[88:91], v[240:243], v[196:199], v[88:91]
	v_mfma_f32_16x16x32_bf16 v[84:87], v[232:235], v[204:207], v[84:87]
	v_mfma_f32_16x16x32_bf16 v[80:83], v[240:243], v[204:207], v[80:83]
	v_mfma_f32_16x16x32_bf16 v[76:79], v[232:235], v[216:219], v[76:79]
	v_mfma_f32_16x16x32_bf16 v[72:75], v[240:243], v[216:219], v[72:75]
	v_mfma_f32_16x16x32_bf16 v[68:71], v[232:235], v[224:227], v[68:71]
	v_mfma_f32_16x16x32_bf16 v[64:67], v[240:243], v[224:227], v[64:67]
	s_mov_b32 m0, s14
	v_lshl_add_u64 v[248:249], v[212:213], 0, v[128:129]
	s_barrier
	ds_read_b128 v[192:195], v174 offset:16384
	ds_read_b128 v[196:199], v174 offset:17408
	ds_read_b128 v[200:203], v174 offset:18432
	ds_read_b128 v[204:207], v174 offset:19456
	ds_read_b128 v[208:211], v174 offset:20480
	ds_read_b128 v[216:219], v174 offset:21504
	ds_read_b128 v[220:223], v174 offset:22528
	ds_read_b128 v[224:227], v174 offset:23552
	global_load_lds_dwordx4 v[248:249], off
	v_lshl_add_u64 v[250:251], v[212:213], 0, v[132:133]
	s_mov_b32 m0, s15
	s_nop 0
	global_load_lds_dwordx4 v[250:251], off
	s_barrier
	s_waitcnt lgkmcnt(0)
	s_waitcnt lgkmcnt(0)
	v_mfma_f32_16x16x32_bf16 v[60:63], v[164:167], v[192:195], v[60:63]
	v_mfma_f32_16x16x32_bf16 v[56:59], v[184:187], v[192:195], v[56:59]
	v_mfma_f32_16x16x32_bf16 v[52:55], v[164:167], v[200:203], v[52:55]
	v_mfma_f32_16x16x32_bf16 v[48:51], v[184:187], v[200:203], v[48:51]
	v_mfma_f32_16x16x32_bf16 v[44:47], v[164:167], v[208:211], v[44:47]
	v_mfma_f32_16x16x32_bf16 v[40:43], v[184:187], v[208:211], v[40:43]
	v_mfma_f32_16x16x32_bf16 v[36:39], v[164:167], v[220:223], v[36:39]
	v_mfma_f32_16x16x32_bf16 v[32:35], v[184:187], v[220:223], v[32:35]
	v_mfma_f32_16x16x32_bf16 v[60:63], v[180:183], v[196:199], v[60:63]
	v_mfma_f32_16x16x32_bf16 v[56:59], v[188:191], v[196:199], v[56:59]
	v_mfma_f32_16x16x32_bf16 v[52:55], v[180:183], v[204:207], v[52:55]
	v_mfma_f32_16x16x32_bf16 v[48:51], v[188:191], v[204:207], v[48:51]
	v_mfma_f32_16x16x32_bf16 v[44:47], v[180:183], v[216:219], v[44:47]
	v_mfma_f32_16x16x32_bf16 v[40:43], v[188:191], v[216:219], v[40:43]
	v_mfma_f32_16x16x32_bf16 v[36:39], v[180:183], v[224:227], v[36:39]
	v_mfma_f32_16x16x32_bf16 v[32:35], v[188:191], v[224:227], v[32:35]
	s_barrier
; #define PG8_STAGE(bufoff, gbase, voff) do { _Pragma("unroll") for (int _i = 0; _i < 2; ++_i) \
;         __builtin_amdgcn_global_load_lds((const unsigned*)((const char*)(gbase) + (voff)[_i]), (LAS unsigned*)(lds + (bufoff) + ldsw + _i * 8192), 16, 0, 0); } while (0)
; #define PG8_LDA(dst, b, h) do { _Pragma("unroll") for (int m = 0; m < 4; ++m) _Pragma("unroll") for (int k = 0; k < 2; ++k) dst[m][k] = *(const LAS bf16x8*)(lds + PG8_SA(b, h) + aoff + m * 2048 + k * 1024); } while (0)
; #define PG8_LDB(dst, b, h) do { _Pragma("unroll") for (int n = 0; n < 2; ++n) _Pragma("unroll") for (int k = 0; k < 2; ++k) dst[n][k] = *(const LAS bf16x8*)(lds + PG8_SB(b, h) + boff + n * 2048 + k * 1024); } while (0)
; #define PG8_MMA(ai, bj, At, Bt) do { __builtin_amdgcn_s_setprio(1); _Pragma("unroll") for (int m = 0; m < 4; ++m) _Pragma("unroll") for (int n = 0; n < 2; ++n) _Pragma("unroll") for (int k = 0; k < 2; ++k) \
;         acc[ai][bj][m][n] = __builtin_amdgcn_mfma_f32_16x16x32_bf16(Bt[n][k], At[m][k], acc[ai][bj][m][n], 0, 0, 0); __builtin_amdgcn_s_setprio(0); } while (0)
; #define PG8_WAIT_V(n) asm volatile("s_waitcnt vmcnt(" #n ")" ::: "memory")
; #define PG8_WAIT_L(n) asm volatile("s_waitcnt lgkmcnt(" #n ")" ::: "memory")
; #define PG8_BAR __builtin_amdgcn_s_barrier()
; #define PG8_SCHED __builtin_amdgcn_sched_barrier(0)
; template <class Epi, class Sched>
; __device__ __forceinline__ void gemm_phase(LAS unsigned char* lds, const int K, const int lda, Sched& S, const Epi& E) {
;     ...
;             PG8_STAGE(PG8_SB(0, 1), b2 + hstepB, voffB);
;             PG8_WAIT_V(6); PG8_BAR; PG8_MMA(1, 1, At, B1); PG8_BAR;
;             PG8_LDB(B0, 1, 0); PG8_SCHED; PG8_LDA(At, 1, 0); PG8_STAGE(PG8_SA(0, 1), a2 + hstepA, voffA);
;             PG8_WAIT_L(8); PG8_BAR; PG8_WAIT_L(0); PG8_MMA(0, 0, At, B0); PG8_BAR; PG8_SCHED;
;             PG8_LDB(B1, 1, 1); PG8_STAGE(PG8_SB(1, 0), b3, voffB);
;             PG8_BAR; PG8_WAIT_L(0); PG8_MMA(0, 1, At, B1); PG8_BAR;
;             PG8_LDA(At, 1, 1); PG8_STAGE(PG8_SA(1, 0), a3, voffA);
;             PG8_BAR; PG8_WAIT_L(0); PG8_MMA(1, 0, At, B0); PG8_BAR; PG8_SCHED;
	v_lshl_add_u64 v[164:165], v[162:163], 0, s[30:31]
	s_add_i32 s5, s27, s3
	v_lshl_add_u64 v[166:167], v[164:165], 0, v[130:131]
	s_mov_b32 m0, s5
	v_lshl_add_u64 v[164:165], v[164:165], 0, v[134:135]
	global_load_lds_dwordx4 v[166:167], off
	s_add_i32 m0, s5, 0x2000
	s_nop 0
	global_load_lds_dwordx4 v[164:165], off
	s_waitcnt vmcnt(6)
	s_barrier
	v_mfma_f32_16x16x32_bf16 v[28:31], v[228:231], v[192:195], v[28:31]
	v_mfma_f32_16x16x32_bf16 v[24:27], v[236:239], v[192:195], v[24:27]
	v_mfma_f32_16x16x32_bf16 v[20:23], v[228:231], v[200:203], v[20:23]
	v_mfma_f32_16x16x32_bf16 v[16:19], v[236:239], v[200:203], v[16:19]
	v_mfma_f32_16x16x32_bf16 v[12:15], v[228:231], v[208:211], v[12:15]
	v_mfma_f32_16x16x32_bf16 v[8:11], v[236:239], v[208:211], v[8:11]
	v_mfma_f32_16x16x32_bf16 v[4:7], v[228:231], v[220:223], v[4:7]
	v_mfma_f32_16x16x32_bf16 v[0:3], v[236:239], v[220:223], v[0:3]
	v_mfma_f32_16x16x32_bf16 v[28:31], v[232:235], v[196:199], v[28:31]
	v_mfma_f32_16x16x32_bf16 v[24:27], v[240:243], v[196:199], v[24:27]
	v_mfma_f32_16x16x32_bf16 v[20:23], v[232:235], v[204:207], v[20:23]
	v_mfma_f32_16x16x32_bf16 v[16:19], v[240:243], v[204:207], v[16:19]
	v_mfma_f32_16x16x32_bf16 v[12:15], v[232:235], v[216:219], v[12:15]
	v_mfma_f32_16x16x32_bf16 v[8:11], v[240:243], v[216:219], v[8:11]
	v_mfma_f32_16x16x32_bf16 v[4:7], v[232:235], v[224:227], v[4:7]
	v_mfma_f32_16x16x32_bf16 v[0:3], v[240:243], v[224:227], v[0:3]
	s_add_i32 s5, 0, 0x18000
	v_add_u32_e32 v149, s5, v171
	s_barrier
	ds_read_b128 v[164:167], v149
	ds_read_b128 v[180:183], v149 offset:1024
	ds_read_b128 v[184:187], v149 offset:2048
	ds_read_b128 v[188:191], v149 offset:3072
	v_lshl_add_u64 v[212:213], v[212:213], 0, s[30:31]
	s_mov_b32 m0, s20
	v_lshl_add_u64 v[228:229], v[212:213], 0, v[128:129]
	ds_read_b128 v[192:195], v174 offset:32768
	ds_read_b128 v[196:199], v174 offset:33792
	ds_read_b128 v[200:203], v174 offset:34816
	ds_read_b128 v[204:207], v174 offset:35840
	ds_read_b128 v[208:211], v174 offset:36864
	ds_read_b128 v[216:219], v174 offset:37888
	ds_read_b128 v[220:223], v174 offset:38912
	ds_read_b128 v[224:227], v174 offset:39936
	global_load_lds_dwordx4 v[228:229], off
	v_lshl_add_u64 v[212:213], v[212:213], 0, v[132:133]
	s_mov_b32 m0, s21
	s_nop 0
	global_load_lds_dwordx4 v[212:213], off
	s_waitcnt lgkmcnt(8)
	s_barrier
	s_waitcnt lgkmcnt(0)
	s_waitcnt lgkmcnt(0)
	v_mfma_f32_16x16x32_bf16 v[124:127], v[164:167], v[192:195], v[124:127]
	v_mfma_f32_16x16x32_bf16 v[120:123], v[184:187], v[192:195], v[120:123]
	v_mfma_f32_16x16x32_bf16 v[116:119], v[164:167], v[200:203], v[116:119]
	v_mfma_f32_16x16x32_bf16 v[112:115], v[184:187], v[200:203], v[112:115]
	v_mfma_f32_16x16x32_bf16 v[108:111], v[164:167], v[208:211], v[108:111]
	v_mfma_f32_16x16x32_bf16 v[104:107], v[184:187], v[208:211], v[104:107]
	v_mfma_f32_16x16x32_bf16 v[100:103], v[164:167], v[220:223], v[100:103]
	v_mfma_f32_16x16x32_bf16 v[96:99], v[184:187], v[220:223], v[96:99]
	v_mfma_f32_16x16x32_bf16 v[124:127], v[180:183], v[196:199], v[124:127]
	v_mfma_f32_16x16x32_bf16 v[120:123], v[188:191], v[196:199], v[120:123]
	v_mfma_f32_16x16x32_bf16 v[116:119], v[180:183], v[204:207], v[116:119]
	v_mfma_f32_16x16x32_bf16 v[112:115], v[188:191], v[204:207], v[112:115]
	v_mfma_f32_16x16x32_bf16 v[108:111], v[180:183], v[216:219], v[108:111]
	v_mfma_f32_16x16x32_bf16 v[104:107], v[188:191], v[216:219], v[104:107]
	v_mfma_f32_16x16x32_bf16 v[100:103], v[180:183], v[224:227], v[100:103]
	v_mfma_f32_16x16x32_bf16 v[96:99], v[188:191], v[224:227], v[96:99]
	s_barrier
	s_add_i32 s12, 0, 0x1c000
	s_add_i32 s5, s5, s3
	v_add_u32_e32 v149, s12, v171
	v_lshl_add_u64 v[212:213], v[244:245], 0, s[52:53]
	s_mov_b32 m0, s5
	ds_read_b128 v[228:231], v149
	ds_read_b128 v[232:235], v149 offset:1024
	ds_read_b128 v[236:239], v149 offset:2048
	ds_read_b128 v[240:243], v149 offset:3072
	global_load_lds_dwordx4 v[212:213], off
	v_lshl_add_u64 v[212:213], v[246:247], 0, s[52:53]
	s_add_i32 m0, s5, 0x2000
	s_nop 0
	global_load_lds_dwordx4 v[212:213], off
	s_barrier
	s_waitcnt lgkmcnt(0)
	s_waitcnt lgkmcnt(0)
	v_mfma_f32_16x16x32_bf16 v[92:95], v[228:231], v[192:195], v[92:95]
	v_mfma_f32_16x16x32_bf16 v[88:91], v[236:239], v[192:195], v[88:91]
	v_mfma_f32_16x16x32_bf16 v[84:87], v[228:231], v[200:203], v[84:87]
	v_mfma_f32_16x16x32_bf16 v[80:83], v[236:239], v[200:203], v[80:83]
	v_mfma_f32_16x16x32_bf16 v[76:79], v[228:231], v[208:211], v[76:79]
	v_mfma_f32_16x16x32_bf16 v[72:75], v[236:239], v[208:211], v[72:75]
	v_mfma_f32_16x16x32_bf16 v[68:71], v[228:231], v[220:223], v[68:71]
	v_mfma_f32_16x16x32_bf16 v[64:67], v[236:239], v[220:223], v[64:67]
	v_mfma_f32_16x16x32_bf16 v[92:95], v[232:235], v[196:199], v[92:95]
	v_mfma_f32_16x16x32_bf16 v[88:91], v[240:243], v[196:199], v[88:91]
	v_mfma_f32_16x16x32_bf16 v[84:87], v[232:235], v[204:207], v[84:87]
	v_mfma_f32_16x16x32_bf16 v[80:83], v[240:243], v[204:207], v[80:83]
	v_mfma_f32_16x16x32_bf16 v[76:79], v[232:235], v[216:219], v[76:79]
	v_mfma_f32_16x16x32_bf16 v[72:75], v[240:243], v[216:219], v[72:75]
	v_mfma_f32_16x16x32_bf16 v[68:71], v[232:235], v[224:227], v[68:71]
	v_mfma_f32_16x16x32_bf16 v[64:67], v[240:243], v[224:227], v[64:67]
	s_mov_b32 m0, s23
	v_lshl_add_u64 v[212:213], v[248:249], 0, s[52:53]
	s_barrier
; __device__ __forceinline__ float sigm(float x) { return __builtin_amdgcn_rcpf(1.f + __expf(-x)); }
; #define PG8_STAGE(bufoff, gbase, voff) do { _Pragma("unroll") for (int _i = 0; _i < 2; ++_i) \
;         __builtin_amdgcn_global_load_lds((const unsigned*)((const char*)(gbase) + (voff)[_i]), (LAS unsigned*)(lds + (bufoff) + ldsw + _i * 8192), 16, 0, 0); } while (0)
; #define PG8_MMA(ai, bj, At, Bt) do { __builtin_amdgcn_s_setprio(1); _Pragma("unroll") for (int m = 0; m < 4; ++m) _Pragma("unroll") for (int n = 0; n < 2; ++n) _Pragma("unroll") for (int k = 0; k < 2; ++k) \
;         acc[ai][bj][m][n] = __builtin_amdgcn_mfma_f32_16x16x32_bf16(Bt[n][k], At[m][k], acc[ai][bj][m][n], 0, 0, 0); __builtin_amdgcn_s_setprio(0); } while (0)
; #define PG8_WAIT_V(n) asm volatile("s_waitcnt vmcnt(" #n ")" ::: "memory")
; #define PG8_WAIT_L(n) asm volatile("s_waitcnt lgkmcnt(" #n ")" ::: "memory")
; #define PG8_BAR __builtin_amdgcn_s_barrier()
; #define PG8_SCHED __builtin_amdgcn_sched_barrier(0)
; template <class Epi, class Sched>
; __device__ __forceinline__ void gemm_phase(LAS unsigned char* lds, const int K, const int lda, Sched& S, const Epi& E) {
;     ...
;             PG8_BAR; PG8_WAIT_L(0); PG8_MMA(1, 0, At, B0); PG8_BAR; PG8_SCHED;
;             PG8_STAGE(PG8_SB(1, 1), b3 + hstepB, voffB);
;             PG8_WAIT_V(6); PG8_BAR; PG8_MMA(1, 1, At, B1); PG8_BAR;
;     __device__ __forceinline__ void operator()(f32x4 (&acc)[2][2][4][2], const Unit& u, int wr, int wc, int fr, int fq) const {
; #pragma unroll
;         for (int bj = 0; bj < 2; ++bj) {
;             const int colb = u.pn * 256 + bj * 128;
;             if (colb >= NIN) continue;
;             const int act = colb >= OFF_MERGE ? 2 : (colb >= OFF_GATE ? 1 : 0);
;             u16* pb = proj + (size_t)(u.pm * 256 + wr * 64 + fr) * NIN + colb + wc * 32 + 8 * fq;
; #pragma unroll
;             for (int ai = 0; ai < 2; ++ai)
; #pragma unroll
;                 for (int m = 0; m < 4; ++m) {
;                     f32x4 v0 = acc[ai][bj][m][0], v1 = acc[ai][bj][m][1];
;                     if (act == 1) {
; #pragma unroll
;                         for (int j = 0; j < 4; ++j) { v0[j] = v0[j] * sigm(v0[j]); v1[j] = v1[j] * sigm(v1[j]); }
	ds_read_b128 v[192:195], v174 offset:49152
	ds_read_b128 v[196:199], v174 offset:50176
	ds_read_b128 v[200:203], v174 offset:51200
	ds_read_b128 v[204:207], v174 offset:52224
	ds_read_b128 v[208:211], v174 offset:53248
	ds_read_b128 v[216:219], v174 offset:54272
	ds_read_b128 v[220:223], v174 offset:55296
	ds_read_b128 v[224:227], v174 offset:56320
	global_load_lds_dwordx4 v[212:213], off
	v_lshl_add_u64 v[212:213], v[250:251], 0, s[52:53]
	s_mov_b32 m0, s24
	s_nop 0
	global_load_lds_dwordx4 v[212:213], off
	s_barrier
	s_waitcnt lgkmcnt(0)
	s_waitcnt lgkmcnt(0)
	v_mfma_f32_16x16x32_bf16 v[60:63], v[164:167], v[192:195], v[60:63]
	v_mfma_f32_16x16x32_bf16 v[56:59], v[184:187], v[192:195], v[56:59]
	v_mfma_f32_16x16x32_bf16 v[52:55], v[164:167], v[200:203], v[52:55]
	v_mfma_f32_16x16x32_bf16 v[48:51], v[184:187], v[200:203], v[48:51]
	v_mfma_f32_16x16x32_bf16 v[44:47], v[164:167], v[208:211], v[44:47]
	v_mfma_f32_16x16x32_bf16 v[40:43], v[184:187], v[208:211], v[40:43]
	v_mfma_f32_16x16x32_bf16 v[36:39], v[164:167], v[220:223], v[36:39]
	v_mfma_f32_16x16x32_bf16 v[32:35], v[184:187], v[220:223], v[32:35]
	v_mfma_f32_16x16x32_bf16 v[60:63], v[180:183], v[196:199], v[60:63]
	v_mfma_f32_16x16x32_bf16 v[56:59], v[188:191], v[196:199], v[56:59]
	v_mfma_f32_16x16x32_bf16 v[52:55], v[180:183], v[204:207], v[52:55]
	v_mfma_f32_16x16x32_bf16 v[48:51], v[188:191], v[204:207], v[48:51]
	v_mfma_f32_16x16x32_bf16 v[44:47], v[180:183], v[216:219], v[44:47]
	v_mfma_f32_16x16x32_bf16 v[40:43], v[188:191], v[216:219], v[40:43]
	v_mfma_f32_16x16x32_bf16 v[36:39], v[180:183], v[224:227], v[36:39]
	v_mfma_f32_16x16x32_bf16 v[32:35], v[188:191], v[224:227], v[32:35]
	s_barrier
	v_lshl_add_u64 v[162:163], v[162:163], 0, s[54:55]
	s_add_i32 s5, s12, s3
	v_lshl_add_u64 v[164:165], v[162:163], 0, v[130:131]
	s_mov_b32 m0, s5
	v_lshl_add_u64 v[162:163], v[162:163], 0, v[134:135]
	global_load_lds_dwordx4 v[164:165], off
	s_add_i32 m0, s5, 0x2000
	s_nop 0
	global_load_lds_dwordx4 v[162:163], off
	s_waitcnt vmcnt(6)
	s_barrier
	v_mfma_f32_16x16x32_bf16 v[28:31], v[228:231], v[192:195], v[28:31]
	v_mfma_f32_16x16x32_bf16 v[24:27], v[236:239], v[192:195], v[24:27]
	v_mfma_f32_16x16x32_bf16 v[20:23], v[228:231], v[200:203], v[20:23]
	v_mfma_f32_16x16x32_bf16 v[16:19], v[236:239], v[200:203], v[16:19]
	v_mfma_f32_16x16x32_bf16 v[12:15], v[228:231], v[208:211], v[12:15]
	v_mfma_f32_16x16x32_bf16 v[8:11], v[236:239], v[208:211], v[8:11]
	v_mfma_f32_16x16x32_bf16 v[4:7], v[228:231], v[220:223], v[4:7]
	v_mfma_f32_16x16x32_bf16 v[0:3], v[236:239], v[220:223], v[0:3]
	v_mfma_f32_16x16x32_bf16 v[28:31], v[232:235], v[196:199], v[28:31]
	v_mfma_f32_16x16x32_bf16 v[24:27], v[240:243], v[196:199], v[24:27]
	v_mfma_f32_16x16x32_bf16 v[20:23], v[232:235], v[204:207], v[20:23]
	v_mfma_f32_16x16x32_bf16 v[16:19], v[240:243], v[204:207], v[16:19]
	v_mfma_f32_16x16x32_bf16 v[12:15], v[232:235], v[216:219], v[12:15]
	v_mfma_f32_16x16x32_bf16 v[8:11], v[240:243], v[216:219], v[8:11]
	v_mfma_f32_16x16x32_bf16 v[4:7], v[232:235], v[224:227], v[4:7]
	v_mfma_f32_16x16x32_bf16 v[0:3], v[240:243], v[224:227], v[0:3]
	s_add_i32 s4, s4, 2
	s_add_u32 s8, s8, 0x100
	s_addc_u32 s9, s9, 0
	s_cmp_gt_u32 s4, 29
	s_barrier
	s_cbranch_scc0 .LBB0_2968
	v_lshlrev_b32_e32 v156, 8, v172
	v_cmp_gt_i32_e32 vcc, 59, v172
	s_and_saveexec_b64 s[8:9], vcc
	s_cbranch_execz .LBB0_3019
	v_cmp_lt_i32_e32 vcc, 22, v172
	s_nop 1
	v_cndmask_b32_e64 v136, 0, 1, vcc
	v_cmp_gt_i32_e32 vcc, 35, v172
	s_nop 1
	v_cndmask_b32_e32 v139, 2, v136, vcc
	v_cmp_lt_i32_e32 vcc, 1, v139
	s_and_saveexec_b64 s[4:5], vcc
	s_xor_b64 s[64:65], exec, s[4:5]
	s_cbranch_execz .LBB0_2972
	v_mul_f32_e32 v136, 0xbfb8aa3b, v124
	v_exp_f32_e32 v136, v136
	v_mul_f32_e32 v147, 0xbfb8aa3b, v120
	v_exp_f32_e32 v147, v147
	v_mul_f32_e32 v149, 0xbfb8aa3b, v121
	v_add_f32_e32 v136, 1.0, v136
	v_rcp_f32_e32 v160, v136
	v_mul_f32_e32 v136, 0xbfb8aa3b, v125
	v_exp_f32_e32 v136, v136
	v_exp_f32_e32 v149, v149
	v_add_f32_e32 v147, 1.0, v147
	v_rcp_f32_e32 v162, v147
	v_add_f32_e32 v136, 1.0, v136
	v_mul_f32_e32 v147, 0xbfb8aa3b, v126
	v_rcp_f32_e32 v161, v136
	v_add_f32_e32 v136, 1.0, v149
	v_exp_f32_e32 v147, v147
	v_mul_f32_e32 v149, 0xbfb8aa3b, v122
	v_exp_f32_e32 v149, v149
	v_rcp_f32_e32 v163, v136
	v_add_f32_e32 v136, 1.0, v147
	v_mul_f32_e32 v147, 0xbfb8aa3b, v127
	v_rcp_f32_e32 v164, v136
	v_add_f32_e32 v136, 1.0, v149
	v_exp_f32_e32 v147, v147
	v_mul_f32_e32 v149, 0xbfb8aa3b, v123
	v_exp_f32_e32 v149, v149
	v_rcp_f32_e32 v166, v136
	v_add_f32_e32 v136, 1.0, v147
	v_rcp_f32_e32 v165, v136
	v_add_f32_e32 v136, 1.0, v149
	v_rcp_f32_e32 v167, v136

; #define PG8_WAIT_V(n) asm volatile("s_waitcnt vmcnt(" #n ")" ::: "memory")
; #define PG8_BAR __builtin_amdgcn_s_barrier()
; template <class Epi, class Sched>
; __device__ __forceinline__ void gemm_phase(LAS unsigned char* lds, const int K, const int lda, Sched& S, const Epi& E) {
;     ...
;     PG8_WAIT_V(0);
;     if (wr == 0) PG8_BAR;
;     PG8_BAR;
.LBB0_3071:
	s_or_b64 exec, exec, s[60:61]
	s_waitcnt vmcnt(0)
	s_setprio 0
	s_nop 0
	s_nop 0
	s_nop 0
	s_nop 0
	s_nop 0
	s_nop 0
	s_nop 0
	s_cmpk_gt_u32 s2, 0xff
	s_cbranch_scc1 .LBB0_3073
	s_barrier

; #define PG8_STAGE(bufoff, gbase, voff) do { _Pragma("unroll") for (int _i = 0; _i < 2; ++_i) \
;         __builtin_amdgcn_global_load_lds((const unsigned*)((const char*)(gbase) + (voff)[_i]), (LAS unsigned*)(lds + (bufoff) + ldsw + _i * 8192), 16, 0, 0); } while (0)
; #define PG8_BAR __builtin_amdgcn_s_barrier()
;     __device__ __forceinline__ const char* aptr(const Unit& u) const { return (const char*)(A + (size_t)u.pm * 256 * 2048); }
;     __device__ __forceinline__ const char* bptr(const Unit& u) const { return (const char*)(Bt + (size_t)u.pn * 256 * 2048); }
;     __device__ __forceinline__ const char* aptr(const Unit& u) const { return (const char*)(A + (size_t)u.pm * 256 * NIN + OFF_GATE + u.z * 1024); }
; template <class Epi, class Sched>
; __device__ __forceinline__ void gemm_phase(LAS unsigned char* lds, const int K, const int lda, Sched& S, const Epi& E) {
;     const int tid = opaque_tid(), wid = __builtin_amdgcn_readfirstlane(tid >> 6), lane = tid & 63, wr = wid >> 2, wc = wid & 3, fr = lane & 15, fq = lane >> 4;
;     const int nt = K / BK;
;     unsigned voffA[2], voffB[2];
; #pragma unroll
;     for (int i = 0; i < 2; ++i) { int R, C; stage_rc(tid * 16 + i * 8192, R, C); const int Rb = (R & ~31) + perm32(R & 31);
;         voffA[i] = (unsigned)(R * lda + C) * 2u; voffB[i] = (unsigned)(Rb * K + C) * 2u; }
;     const size_t kstep = (size_t)(BK * 2);
;     const size_t hstepA = (size_t)HALF * lda * 2, hstepB = (size_t)HALF * K * 2;
;     const unsigned ldsw = (unsigned)wid * 1024u;
;     const int aoff = lds_byte(wr * 64 + fr, fq * 8), boff = lds_byte(wc * 32 + fr, fq * 8);
;     ...
;     Unit cur, nxt; int ui = 0;
;     if (!S.next(0, cur)) return;
;     f32x4 acc[2][2][4][2];
; #pragma unroll
;     for (int a = 0; a < 2; ++a)
; #pragma unroll
;         for (int b = 0; b < 2; ++b)
; #pragma unroll
;             for (int m = 0; m < 4; ++m)
; #pragma unroll
;                 for (int n = 0; n < 2; ++n) acc[a][b][m][n] = (f32x4){0.f, 0.f, 0.f, 0.f};
;     bf16x8 At[4][2], B0[2][2], B1[2][2];
;     const char* cA = S.aptr(cur); const char* cB = S.bptr(cur);
;     PG8_STAGE(PG8_SB(0, 0), cB, voffB); PG8_STAGE(PG8_SA(0, 0), cA, voffA); PG8_STAGE(PG8_SB(0, 1), cB + hstepB, voffB); PG8_STAGE(PG8_SA(0, 1), cA + hstepA, voffA);
;     if (wr == 1) PG8_BAR;
.LBB0_3586:
	s_andn2_b64 vcc, exec, s[10:11]
	s_cbranch_vccnz .LBB0_3690
	v_ashrrev_i32_e32 v1, 31, v8
	v_lshrrev_b32_e32 v1, 26, v1
	v_add_u32_e32 v1, v8, v1
	v_ashrrev_i32_e32 v9, 6, v1
	v_bfe_i32 v1, v8, 27, 1
	v_lshlrev_b32_e32 v0, 4, v8
	v_lshrrev_b32_e32 v1, 22, v1
	v_add_u32_e32 v1, v0, v1
	v_and_b32_e32 v1, 0xfffffc00, v1
	v_sub_u32_e32 v1, v0, v1
	v_lshrrev_b32_e32 v2, 4, v1
	v_bitop3_b32 v2, v2, v1, 32 bitop3:0x6c
	v_ashrrev_i32_e32 v1, 31, v1
	v_lshrrev_b32_e32 v1, 26, v1
	v_add_u32_e32 v1, v2, v1
	v_ashrrev_i32_e32 v10, 6, v1
	v_lshlrev_b32_e32 v3, 3, v9
	v_mul_i32_i24_e32 v4, 64, v10
	v_and_b32_e32 v3, -16, v3
	v_sub_u32_e32 v2, v2, v4
	v_mov_b32_e32 v4, 1
	v_add_u32_e32 v1, v10, v3
	v_lshlrev_b32_e32 v3, 5, v9
	v_ashrrev_i16_sdwa v2, v4, sext(v2) dst_sel:DWORD dst_unused:UNUSED_PAD src0_sel:DWORD src1_sel:BYTE_0
	v_and_b32_e32 v3, 32, v3
	v_bfe_i32 v11, v2, 0, 16
	v_and_b32_e32 v6, 3, v10
	s_mov_b32 s1, 0xfffe0
	v_add_lshl_u32 v3, v3, v11, 1
	v_add_u32_e32 v0, 0x2000, v0
	v_lshlrev_b32_e32 v2, 1, v1
	v_lshrrev_b32_e32 v5, 2, v1
	v_and_or_b32 v6, v1, s1, v6
	v_lshl_add_u32 v128, v1, 12, v3
	v_ashrrev_i32_e32 v1, 31, v0
	v_lshrrev_b32_e32 v1, 22, v1
	v_add_u32_e32 v1, v0, v1
	v_ashrrev_i32_e32 v12, 10, v1
	v_mul_i32_i24_e32 v1, 0x400, v12
	v_sub_u32_e32 v0, v0, v1
	v_and_b32_e32 v2, 24, v2
	v_and_b32_e32 v5, 4, v5
	v_lshrrev_b32_e32 v1, 4, v0
	v_or3_b32 v2, v6, v5, v2
	v_bitop3_b32 v0, v1, v0, 32 bitop3:0x6c
	v_lshl_add_u32 v130, v2, 12, v3
	v_ashrrev_i32_e32 v2, 31, v0
	v_lshrrev_b32_e32 v2, 26, v2
	v_add_u32_e32 v2, v0, v2
	v_lshlrev_b32_e32 v1, 3, v12
	v_ashrrev_i32_e32 v13, 6, v2
	v_and_b32_e32 v2, 0xc0, v2
	v_and_b32_e32 v1, -16, v1
	v_sub_u32_e32 v0, v0, v2
	v_add_u32_e32 v1, v13, v1
	v_ashrrev_i16_sdwa v0, v4, sext(v0) dst_sel:DWORD dst_unused:UNUSED_PAD src0_sel:DWORD src1_sel:BYTE_0
	v_and_b32_e32 v4, 3, v13
	v_and_or_b32 v4, v1, s1, v4
	s_ashr_i32 s5, s3, 6
	s_ashr_i32 s9, s8, 31
	s_ashr_i32 s1, s0, 31
	s_ashr_i32 s4, s3, 8
	s_lshl_b32 s14, s5, 10
	s_lshl_b64 s[10:11], s[8:9], 20
	s_lshl_b64 s[12:13], s[0:1], 20
	s_add_u32 s68, s18, s12
	v_lshlrev_b32_e32 v3, 5, v12
	v_bfe_i32 v14, v0, 0, 16
	v_lshlrev_b32_e32 v0, 1, v1
	v_lshrrev_b32_e32 v2, 2, v1
	s_addc_u32 s69, s19, s13
	s_add_i32 s1, s14, 0
	v_and_b32_e32 v3, 32, v3
	v_and_b32_e32 v0, 24, v0
	v_and_b32_e32 v2, 4, v2
	s_add_i32 m0, s1, 0x10000
	v_or3_b32 v0, v4, v2, v0
	v_add_lshl_u32 v2, v3, v14, 1
	global_load_lds_dwordx4 v130, s[68:69]
	s_add_i32 m0, s1, 0x12000
	v_lshl_add_u32 v134, v0, 12, v2
	s_add_u32 s10, s34, s10
	global_load_lds_dwordx4 v134, s[68:69]
	s_addc_u32 s11, s35, s11
	s_mov_b32 m0, s1
	s_add_i32 s9, s1, 0x2000
	v_lshl_add_u32 v132, v1, 12, v2
	global_load_lds_dwordx4 v128, s[10:11]
	s_mov_b32 m0, s9
	s_add_u32 s12, s68, 0x80000
	global_load_lds_dwordx4 v132, s[10:11]
	s_addc_u32 s13, s69, 0
	s_add_i32 m0, s1, 0x14000
	v_mov_b32_e32 v137, 0
	global_load_lds_dwordx4 v130, s[12:13]
	s_add_i32 m0, s1, 0x16000
	v_mov_b32_e32 v131, v137
	global_load_lds_dwordx4 v134, s[12:13]
	s_add_u32 s12, s10, 0x80000
	s_addc_u32 s13, s11, 0
	s_add_i32 s15, s1, 0x4000
	s_mov_b32 m0, s15
	s_add_i32 s20, s1, 0x6000
	global_load_lds_dwordx4 v128, s[12:13]
	s_mov_b32 m0, s20
	v_mov_b32_e32 v135, v137
	global_load_lds_dwordx4 v132, s[12:13]
	v_mov_b32_e32 v129, v137
	v_mov_b32_e32 v133, v137
	s_mov_b32 s13, 0
	v_lshl_add_u64 v[6:7], s[68:69], 0, v[130:131]
	v_lshl_add_u64 v[4:5], s[68:69], 0, v[134:135]
	v_lshl_add_u64 v[2:3], s[10:11], 0, v[128:129]
	s_cmp_lg_u32 s4, 1
	v_lshl_add_u64 v[0:1], s[10:11], 0, v[132:133]
	s_cbranch_scc1 .LBB0_3589
	s_setprio 1
	s_nop 0
	s_nop 0
	s_nop 0
	s_nop 0
	s_nop 0
	s_nop 0
	s_nop 0
	s_barrier

; #define PG8_STAGE(bufoff, gbase, voff) do { _Pragma("unroll") for (int _i = 0; _i < 2; ++_i) \
;         __builtin_amdgcn_global_load_lds((const unsigned*)((const char*)(gbase) + (voff)[_i]), (LAS unsigned*)(lds + (bufoff) + ldsw + _i * 8192), 16, 0, 0); } while (0)
; #define PG8_LDA(dst, b, h) do { _Pragma("unroll") for (int m = 0; m < 4; ++m) _Pragma("unroll") for (int k = 0; k < 2; ++k) dst[m][k] = *(const LAS bf16x8*)(lds + PG8_SA(b, h) + aoff + m * 2048 + k * 1024); } while (0)
; #define PG8_LDB(dst, b, h) do { _Pragma("unroll") for (int n = 0; n < 2; ++n) _Pragma("unroll") for (int k = 0; k < 2; ++k) dst[n][k] = *(const LAS bf16x8*)(lds + PG8_SB(b, h) + boff + n * 2048 + k * 1024); } while (0)
; #define PG8_MMA(ai, bj, At, Bt) do { __builtin_amdgcn_s_setprio(1); _Pragma("unroll") for (int m = 0; m < 4; ++m) _Pragma("unroll") for (int n = 0; n < 2; ++n) _Pragma("unroll") for (int k = 0; k < 2; ++k) \
;         acc[ai][bj][m][n] = __builtin_amdgcn_mfma_f32_16x16x32_bf16(Bt[n][k], At[m][k], acc[ai][bj][m][n], 0, 0, 0); __builtin_amdgcn_s_setprio(0); } while (0)
; #define PG8_WAIT_L(n) asm volatile("s_waitcnt lgkmcnt(" #n ")" ::: "memory")
; #define PG8_BAR __builtin_amdgcn_s_barrier()
; #define PG8_SCHED __builtin_amdgcn_sched_barrier(0)
; template <class Epi, class Sched>
; __device__ __forceinline__ void gemm_phase(LAS unsigned char* lds, const int K, const int lda, Sched& S, const Epi& E) {
;     ...
;             PG8_LDB(B0, 0, 0); PG8_SCHED; PG8_LDA(At, 0, 0); PG8_STAGE(PG8_SA(1, 1), a1 + hstepA, voffA);
;             PG8_WAIT_L(8); PG8_BAR; PG8_WAIT_L(0); PG8_MMA(0, 0, At, B0); PG8_BAR; PG8_SCHED;
;             PG8_LDB(B1, 0, 1); PG8_STAGE(PG8_SB(0, 0), b2, voffB);
;             PG8_BAR; PG8_WAIT_L(0); PG8_MMA(0, 1, At, B1); PG8_BAR;
;             PG8_LDA(At, 0, 1); PG8_STAGE(PG8_SA(0, 0), a2, voffA);
;             PG8_BAR; PG8_WAIT_L(0); PG8_MMA(1, 0, At, B0); PG8_BAR; PG8_SCHED;
.LBB0_3600:
	v_add_u32_e32 v136, s25, v154
	s_add_u32 s76, s10, s68
	ds_read_b128 v[148:151], v136
	ds_read_b128 v[156:159], v136 offset:1024
	ds_read_b128 v[160:163], v136 offset:2048
	ds_read_b128 v[164:167], v136 offset:3072
	s_addc_u32 s77, s11, s69
	s_add_u32 s76, s76, 0x100
	s_addc_u32 s77, s77, 0
	s_add_u32 s83, s81, s68
	s_addc_u32 s84, s82, s69
	s_cmpk_eq_i32 s68, 0xf00
	s_cselect_b32 s79, s4, s77
	s_cselect_b32 s78, s5, s76
	s_cselect_b32 s77, s12, s84
	s_cselect_b32 s76, s53, s83
	v_lshl_add_u64 v[152:153], v[144:145], 0, s[68:69]
	s_add_i32 m0, s1, 0xc000
	ds_read_b128 v[168:171], v155
	ds_read_b128 v[172:175], v155 offset:1024
	ds_read_b128 v[176:179], v155 offset:2048
	ds_read_b128 v[180:183], v155 offset:3072
	ds_read_b128 v[184:187], v155 offset:4096
	ds_read_b128 v[188:191], v155 offset:5120
	ds_read_b128 v[192:195], v155 offset:6144
	ds_read_b128 v[196:199], v155 offset:7168
	global_load_lds_dwordx4 v[152:153], off
	v_lshl_add_u64 v[152:153], v[146:147], 0, s[68:69]
	s_add_i32 m0, s1, 0xe000
	s_nop 0
	global_load_lds_dwordx4 v[152:153], off
	s_waitcnt lgkmcnt(8)
	s_barrier
	s_waitcnt lgkmcnt(0)
	s_waitcnt lgkmcnt(0)
	v_mfma_f32_16x16x32_bf16 v[124:127], v[148:151], v[168:171], v[124:127]
	v_mfma_f32_16x16x32_bf16 v[120:123], v[160:163], v[168:171], v[120:123]
	v_mfma_f32_16x16x32_bf16 v[116:119], v[148:151], v[176:179], v[116:119]
	v_mfma_f32_16x16x32_bf16 v[112:115], v[160:163], v[176:179], v[112:115]
	v_mfma_f32_16x16x32_bf16 v[108:111], v[148:151], v[184:187], v[108:111]
	v_mfma_f32_16x16x32_bf16 v[104:107], v[160:163], v[184:187], v[104:107]
	v_mfma_f32_16x16x32_bf16 v[100:103], v[148:151], v[192:195], v[100:103]
	v_mfma_f32_16x16x32_bf16 v[96:99], v[160:163], v[192:195], v[96:99]
	v_mfma_f32_16x16x32_bf16 v[124:127], v[156:159], v[172:175], v[124:127]
	v_mfma_f32_16x16x32_bf16 v[120:123], v[164:167], v[172:175], v[120:123]
	v_mfma_f32_16x16x32_bf16 v[116:119], v[156:159], v[180:183], v[116:119]
	v_mfma_f32_16x16x32_bf16 v[112:115], v[164:167], v[180:183], v[112:115]
	v_mfma_f32_16x16x32_bf16 v[108:111], v[156:159], v[188:191], v[108:111]
	v_mfma_f32_16x16x32_bf16 v[104:107], v[164:167], v[188:191], v[104:107]
	v_mfma_f32_16x16x32_bf16 v[100:103], v[156:159], v[196:199], v[100:103]
	v_mfma_f32_16x16x32_bf16 v[96:99], v[164:167], v[196:199], v[96:99]
	s_barrier
	s_add_i32 s83, s25, s14
	v_add_u32_e32 v136, s27, v154
	v_lshl_add_u64 v[152:153], s[76:77], 0, v[130:131]
	s_mov_b32 m0, s83
	ds_read_b128 v[200:203], v136
	ds_read_b128 v[204:207], v136 offset:1024
	ds_read_b128 v[208:211], v136 offset:2048
	ds_read_b128 v[216:219], v136 offset:3072
	global_load_lds_dwordx4 v[152:153], off
	v_lshl_add_u64 v[212:213], s[76:77], 0, v[134:135]
	s_add_i32 m0, s83, 0x2000
	s_nop 0
	global_load_lds_dwordx4 v[212:213], off
	s_barrier
	s_waitcnt lgkmcnt(0)
	s_waitcnt lgkmcnt(0)
	v_mfma_f32_16x16x32_bf16 v[92:95], v[200:203], v[168:171], v[92:95]
	v_mfma_f32_16x16x32_bf16 v[88:91], v[208:211], v[168:171], v[88:91]
	v_mfma_f32_16x16x32_bf16 v[84:87], v[200:203], v[176:179], v[84:87]
	v_mfma_f32_16x16x32_bf16 v[80:83], v[208:211], v[176:179], v[80:83]
	v_mfma_f32_16x16x32_bf16 v[76:79], v[200:203], v[184:187], v[76:79]
	v_mfma_f32_16x16x32_bf16 v[72:75], v[208:211], v[184:187], v[72:75]
	v_mfma_f32_16x16x32_bf16 v[68:71], v[200:203], v[192:195], v[68:71]
	v_mfma_f32_16x16x32_bf16 v[64:67], v[208:211], v[192:195], v[64:67]
	v_mfma_f32_16x16x32_bf16 v[92:95], v[204:207], v[172:175], v[92:95]
	v_mfma_f32_16x16x32_bf16 v[88:91], v[216:219], v[172:175], v[88:91]
	v_mfma_f32_16x16x32_bf16 v[84:87], v[204:207], v[180:183], v[84:87]
	v_mfma_f32_16x16x32_bf16 v[80:83], v[216:219], v[180:183], v[80:83]
	v_mfma_f32_16x16x32_bf16 v[76:79], v[204:207], v[188:191], v[76:79]
	v_mfma_f32_16x16x32_bf16 v[72:75], v[216:219], v[188:191], v[72:75]
	v_mfma_f32_16x16x32_bf16 v[68:71], v[204:207], v[196:199], v[68:71]
	v_mfma_f32_16x16x32_bf16 v[64:67], v[216:219], v[196:199], v[64:67]
	s_mov_b32 m0, s1
	v_lshl_add_u64 v[220:221], s[78:79], 0, v[128:129]
	s_barrier
	ds_read_b128 v[168:171], v155 offset:16384
	ds_read_b128 v[172:175], v155 offset:17408
	ds_read_b128 v[176:179], v155 offset:18432
	ds_read_b128 v[180:183], v155 offset:19456
	ds_read_b128 v[184:187], v155 offset:20480
	ds_read_b128 v[188:191], v155 offset:21504
	ds_read_b128 v[192:195], v155 offset:22528
	ds_read_b128 v[196:199], v155 offset:23552
	global_load_lds_dwordx4 v[220:221], off
	v_lshl_add_u64 v[222:223], s[78:79], 0, v[132:133]
	s_mov_b32 m0, s9
	s_nop 0
	global_load_lds_dwordx4 v[222:223], off
	s_barrier
	s_waitcnt lgkmcnt(0)
	s_waitcnt lgkmcnt(0)
	v_mfma_f32_16x16x32_bf16 v[60:63], v[148:151], v[168:171], v[60:63]
	v_mfma_f32_16x16x32_bf16 v[56:59], v[160:163], v[168:171], v[56:59]
	v_mfma_f32_16x16x32_bf16 v[52:55], v[148:151], v[176:179], v[52:55]
	v_mfma_f32_16x16x32_bf16 v[48:51], v[160:163], v[176:179], v[48:51]
	v_mfma_f32_16x16x32_bf16 v[44:47], v[148:151], v[184:187], v[44:47]
	v_mfma_f32_16x16x32_bf16 v[40:43], v[160:163], v[184:187], v[40:43]
	v_mfma_f32_16x16x32_bf16 v[36:39], v[148:151], v[192:195], v[36:39]
	v_mfma_f32_16x16x32_bf16 v[32:35], v[160:163], v[192:195], v[32:35]
	v_mfma_f32_16x16x32_bf16 v[60:63], v[156:159], v[172:175], v[60:63]
	v_mfma_f32_16x16x32_bf16 v[56:59], v[164:167], v[172:175], v[56:59]
	v_mfma_f32_16x16x32_bf16 v[52:55], v[156:159], v[180:183], v[52:55]
	v_mfma_f32_16x16x32_bf16 v[48:51], v[164:167], v[180:183], v[48:51]
	v_mfma_f32_16x16x32_bf16 v[44:47], v[156:159], v[188:191], v[44:47]
	v_mfma_f32_16x16x32_bf16 v[40:43], v[164:167], v[188:191], v[40:43]
	v_mfma_f32_16x16x32_bf16 v[36:39], v[156:159], v[196:199], v[36:39]
	v_mfma_f32_16x16x32_bf16 v[32:35], v[164:167], v[196:199], v[32:35]
	s_barrier
; #define PG8_STAGE(bufoff, gbase, voff) do { _Pragma("unroll") for (int _i = 0; _i < 2; ++_i) \
;         __builtin_amdgcn_global_load_lds((const unsigned*)((const char*)(gbase) + (voff)[_i]), (LAS unsigned*)(lds + (bufoff) + ldsw + _i * 8192), 16, 0, 0); } while (0)
; #define PG8_LDA(dst, b, h) do { _Pragma("unroll") for (int m = 0; m < 4; ++m) _Pragma("unroll") for (int k = 0; k < 2; ++k) dst[m][k] = *(const LAS bf16x8*)(lds + PG8_SA(b, h) + aoff + m * 2048 + k * 1024); } while (0)
; #define PG8_LDB(dst, b, h) do { _Pragma("unroll") for (int n = 0; n < 2; ++n) _Pragma("unroll") for (int k = 0; k < 2; ++k) dst[n][k] = *(const LAS bf16x8*)(lds + PG8_SB(b, h) + boff + n * 2048 + k * 1024); } while (0)
; #define PG8_MMA(ai, bj, At, Bt) do { __builtin_amdgcn_s_setprio(1); _Pragma("unroll") for (int m = 0; m < 4; ++m) _Pragma("unroll") for (int n = 0; n < 2; ++n) _Pragma("unroll") for (int k = 0; k < 2; ++k) \
;         acc[ai][bj][m][n] = __builtin_amdgcn_mfma_f32_16x16x32_bf16(Bt[n][k], At[m][k], acc[ai][bj][m][n], 0, 0, 0); __builtin_amdgcn_s_setprio(0); } while (0)
; #define PG8_WAIT_V(n) asm volatile("s_waitcnt vmcnt(" #n ")" ::: "memory")
; #define PG8_WAIT_L(n) asm volatile("s_waitcnt lgkmcnt(" #n ")" ::: "memory")
; #define PG8_BAR __builtin_amdgcn_s_barrier()
; #define PG8_SCHED __builtin_amdgcn_sched_barrier(0)
; template <class Epi, class Sched>
; __device__ __forceinline__ void gemm_phase(LAS unsigned char* lds, const int K, const int lda, Sched& S, const Epi& E) {
;     ...
;             PG8_STAGE(PG8_SB(0, 1), b2 + hstepB, voffB);
;             PG8_WAIT_V(6); PG8_BAR; PG8_MMA(1, 1, At, B1); PG8_BAR;
;             PG8_LDB(B0, 1, 0); PG8_SCHED; PG8_LDA(At, 1, 0); PG8_STAGE(PG8_SA(0, 1), a2 + hstepA, voffA);
;             PG8_WAIT_L(8); PG8_BAR; PG8_WAIT_L(0); PG8_MMA(0, 0, At, B0); PG8_BAR; PG8_SCHED;
;             PG8_LDB(B1, 1, 1); PG8_STAGE(PG8_SB(1, 0), b3, voffB);
;             PG8_BAR; PG8_WAIT_L(0); PG8_MMA(0, 1, At, B1); PG8_BAR;
	s_add_u32 s84, s76, 0x80000
	s_addc_u32 s85, s77, 0
	s_add_i32 s83, s27, s14
	v_lshl_add_u64 v[148:149], s[84:85], 0, v[130:131]
	s_mov_b32 m0, s83
	s_nop 0
	global_load_lds_dwordx4 v[148:149], off
	v_lshl_add_u64 v[148:149], s[84:85], 0, v[134:135]
	s_add_i32 m0, s83, 0x2000
	s_nop 0
	global_load_lds_dwordx4 v[148:149], off
	s_waitcnt vmcnt(6)
	s_barrier
	v_mfma_f32_16x16x32_bf16 v[28:31], v[200:203], v[168:171], v[28:31]
	v_mfma_f32_16x16x32_bf16 v[24:27], v[208:211], v[168:171], v[24:27]
	v_mfma_f32_16x16x32_bf16 v[20:23], v[200:203], v[176:179], v[20:23]
	v_mfma_f32_16x16x32_bf16 v[16:19], v[208:211], v[176:179], v[16:19]
	v_mfma_f32_16x16x32_bf16 v[12:15], v[200:203], v[184:187], v[12:15]
	v_mfma_f32_16x16x32_bf16 v[8:11], v[208:211], v[184:187], v[8:11]
	v_mfma_f32_16x16x32_bf16 v[4:7], v[200:203], v[192:195], v[4:7]
	v_mfma_f32_16x16x32_bf16 v[0:3], v[208:211], v[192:195], v[0:3]
	v_mfma_f32_16x16x32_bf16 v[28:31], v[204:207], v[172:175], v[28:31]
	v_mfma_f32_16x16x32_bf16 v[24:27], v[216:219], v[172:175], v[24:27]
	v_mfma_f32_16x16x32_bf16 v[20:23], v[204:207], v[180:183], v[20:23]
	v_mfma_f32_16x16x32_bf16 v[16:19], v[216:219], v[180:183], v[16:19]
	v_mfma_f32_16x16x32_bf16 v[12:15], v[204:207], v[188:191], v[12:15]
	v_mfma_f32_16x16x32_bf16 v[8:11], v[216:219], v[188:191], v[8:11]
	v_mfma_f32_16x16x32_bf16 v[4:7], v[204:207], v[196:199], v[4:7]
	v_mfma_f32_16x16x32_bf16 v[0:3], v[216:219], v[196:199], v[0:3]
	s_add_i32 s83, 0, 0x18000
	v_add_u32_e32 v136, s83, v154
	s_barrier
	ds_read_b128 v[148:151], v136
	ds_read_b128 v[156:159], v136 offset:1024
	ds_read_b128 v[160:163], v136 offset:2048
	ds_read_b128 v[164:167], v136 offset:3072
	s_add_u32 s78, s78, 0x80000
	s_addc_u32 s79, s79, 0
	s_mov_b32 m0, s15
	v_lshl_add_u64 v[200:201], s[78:79], 0, v[128:129]
	ds_read_b128 v[168:171], v155 offset:32768
	ds_read_b128 v[172:175], v155 offset:33792
	ds_read_b128 v[176:179], v155 offset:34816
	ds_read_b128 v[180:183], v155 offset:35840
	ds_read_b128 v[184:187], v155 offset:36864
	ds_read_b128 v[188:191], v155 offset:37888
	ds_read_b128 v[192:195], v155 offset:38912
	ds_read_b128 v[196:199], v155 offset:39936
	global_load_lds_dwordx4 v[200:201], off
	v_lshl_add_u64 v[200:201], s[78:79], 0, v[132:133]
	s_mov_b32 m0, s20
	s_nop 0
	global_load_lds_dwordx4 v[200:201], off
	s_waitcnt lgkmcnt(8)
	s_barrier
	s_waitcnt lgkmcnt(0)
	s_waitcnt lgkmcnt(0)
	v_mfma_f32_16x16x32_bf16 v[124:127], v[148:151], v[168:171], v[124:127]
	v_mfma_f32_16x16x32_bf16 v[120:123], v[160:163], v[168:171], v[120:123]
	v_mfma_f32_16x16x32_bf16 v[116:119], v[148:151], v[176:179], v[116:119]
	v_mfma_f32_16x16x32_bf16 v[112:115], v[160:163], v[176:179], v[112:115]
	v_mfma_f32_16x16x32_bf16 v[108:111], v[148:151], v[184:187], v[108:111]
	v_mfma_f32_16x16x32_bf16 v[104:107], v[160:163], v[184:187], v[104:107]
	v_mfma_f32_16x16x32_bf16 v[100:103], v[148:151], v[192:195], v[100:103]
	v_mfma_f32_16x16x32_bf16 v[96:99], v[160:163], v[192:195], v[96:99]
	v_mfma_f32_16x16x32_bf16 v[124:127], v[156:159], v[172:175], v[124:127]
	v_mfma_f32_16x16x32_bf16 v[120:123], v[164:167], v[172:175], v[120:123]
	v_mfma_f32_16x16x32_bf16 v[116:119], v[156:159], v[180:183], v[116:119]
	v_mfma_f32_16x16x32_bf16 v[112:115], v[164:167], v[180:183], v[112:115]
	v_mfma_f32_16x16x32_bf16 v[108:111], v[156:159], v[188:191], v[108:111]
	v_mfma_f32_16x16x32_bf16 v[104:107], v[164:167], v[188:191], v[104:107]
	v_mfma_f32_16x16x32_bf16 v[100:103], v[156:159], v[196:199], v[100:103]
	v_mfma_f32_16x16x32_bf16 v[96:99], v[164:167], v[196:199], v[96:99]
	s_barrier
	s_add_i32 s78, 0, 0x1c000
	s_add_i32 s79, s83, s14
	v_add_u32_e32 v136, s78, v154
	v_lshl_add_u64 v[152:153], v[152:153], 0, s[30:31]
	s_mov_b32 m0, s79
	ds_read_b128 v[200:203], v136
	ds_read_b128 v[204:207], v136 offset:1024
	ds_read_b128 v[208:211], v136 offset:2048
	ds_read_b128 v[216:219], v136 offset:3072
	global_load_lds_dwordx4 v[152:153], off
	v_lshl_add_u64 v[152:153], v[212:213], 0, s[30:31]
	s_add_i32 m0, s79, 0x2000
	s_nop 0
	global_load_lds_dwordx4 v[152:153], off
	s_barrier
	s_waitcnt lgkmcnt(0)
	s_waitcnt lgkmcnt(0)
	v_mfma_f32_16x16x32_bf16 v[92:95], v[200:203], v[168:171], v[92:95]
	v_mfma_f32_16x16x32_bf16 v[88:91], v[208:211], v[168:171], v[88:91]
	v_mfma_f32_16x16x32_bf16 v[84:87], v[200:203], v[176:179], v[84:87]
	v_mfma_f32_16x16x32_bf16 v[80:83], v[208:211], v[176:179], v[80:83]
	v_mfma_f32_16x16x32_bf16 v[76:79], v[200:203], v[184:187], v[76:79]
	v_mfma_f32_16x16x32_bf16 v[72:75], v[208:211], v[184:187], v[72:75]
	v_mfma_f32_16x16x32_bf16 v[68:71], v[200:203], v[192:195], v[68:71]
	v_mfma_f32_16x16x32_bf16 v[64:67], v[208:211], v[192:195], v[64:67]
	v_mfma_f32_16x16x32_bf16 v[92:95], v[204:207], v[172:175], v[92:95]
	v_mfma_f32_16x16x32_bf16 v[88:91], v[216:219], v[172:175], v[88:91]
	v_mfma_f32_16x16x32_bf16 v[84:87], v[204:207], v[180:183], v[84:87]
	v_mfma_f32_16x16x32_bf16 v[80:83], v[216:219], v[180:183], v[80:83]
	v_mfma_f32_16x16x32_bf16 v[76:79], v[204:207], v[188:191], v[76:79]
	v_mfma_f32_16x16x32_bf16 v[72:75], v[216:219], v[188:191], v[72:75]
	v_mfma_f32_16x16x32_bf16 v[68:71], v[204:207], v[196:199], v[68:71]
	v_mfma_f32_16x16x32_bf16 v[64:67], v[216:219], v[196:199], v[64:67]
	s_mov_b32 m0, s23
	v_lshl_add_u64 v[152:153], v[220:221], 0, s[30:31]
	s_barrier
; __device__ __forceinline__ float sigm(float x) { return __builtin_amdgcn_rcpf(1.f + __expf(-x)); }
; #define PG8_STAGE(bufoff, gbase, voff) do { _Pragma("unroll") for (int _i = 0; _i < 2; ++_i) \
;         __builtin_amdgcn_global_load_lds((const unsigned*)((const char*)(gbase) + (voff)[_i]), (LAS unsigned*)(lds + (bufoff) + ldsw + _i * 8192), 16, 0, 0); } while (0)
; #define PG8_LDA(dst, b, h) do { _Pragma("unroll") for (int m = 0; m < 4; ++m) _Pragma("unroll") for (int k = 0; k < 2; ++k) dst[m][k] = *(const LAS bf16x8*)(lds + PG8_SA(b, h) + aoff + m * 2048 + k * 1024); } while (0)
; #define PG8_MMA(ai, bj, At, Bt) do { __builtin_amdgcn_s_setprio(1); _Pragma("unroll") for (int m = 0; m < 4; ++m) _Pragma("unroll") for (int n = 0; n < 2; ++n) _Pragma("unroll") for (int k = 0; k < 2; ++k) \
;         acc[ai][bj][m][n] = __builtin_amdgcn_mfma_f32_16x16x32_bf16(Bt[n][k], At[m][k], acc[ai][bj][m][n], 0, 0, 0); __builtin_amdgcn_s_setprio(0); } while (0)
; template <class Epi, class Sched>
; __device__ __forceinline__ void gemm_phase(LAS unsigned char* lds, const int K, const int lda, Sched& S, const Epi& E) {
;     ...
;             PG8_LDA(At, 1, 1); PG8_STAGE(PG8_SA(1, 0), a3, voffA);
;             PG8_BAR; PG8_WAIT_L(0); PG8_MMA(1, 0, At, B0); PG8_BAR; PG8_SCHED;
;             PG8_STAGE(PG8_SB(1, 1), b3 + hstepB, voffB);
;             PG8_WAIT_V(6); PG8_BAR; PG8_MMA(1, 1, At, B1); PG8_BAR;
;     __device__ __forceinline__ void operator()(f32x4 (&acc)[2][2][4][2], const Unit& u, int wr, int wc, int fr, int fq) const {
;     ...
;         for (int bj = 0; bj < 2; ++bj) {
;             const int colb = u.pn * 256 + bj * 128;
;             if (colb >= NIN) continue;
;             const int act = colb >= OFF_MERGE ? 2 : (colb >= OFF_GATE ? 1 : 0);
;             u16* pb = proj + (size_t)(u.pm * 256 + wr * 64 + fr) * NIN + colb + wc * 32 + 8 * fq;
; #pragma unroll
;             for (int ai = 0; ai < 2; ++ai)
; #pragma unroll
;                 for (int m = 0; m < 4; ++m) {
;                     f32x4 v0 = acc[ai][bj][m][0], v1 = acc[ai][bj][m][1];
;                     if (act == 1) {
; #pragma unroll
;                         for (int j = 0; j < 4; ++j) { v0[j] = v0[j] * sigm(v0[j]); v1[j] = v1[j] * sigm(v1[j]); }
;                     } else if (act == 2) {
; #pragma unroll
;                         for (int j = 0; j < 4; ++j) { v0[j] = sigm(v0[j]); v1[j] = sigm(v1[j]); }
	ds_read_b128 v[168:171], v155 offset:49152
	ds_read_b128 v[172:175], v155 offset:50176
	ds_read_b128 v[176:179], v155 offset:51200
	ds_read_b128 v[180:183], v155 offset:52224
	ds_read_b128 v[184:187], v155 offset:53248
	ds_read_b128 v[188:191], v155 offset:54272
	ds_read_b128 v[192:195], v155 offset:55296
	ds_read_b128 v[196:199], v155 offset:56320
	global_load_lds_dwordx4 v[152:153], off
	v_lshl_add_u64 v[152:153], v[222:223], 0, s[30:31]
	s_mov_b32 m0, s24
	s_nop 0
	global_load_lds_dwordx4 v[152:153], off
	s_barrier
	s_waitcnt lgkmcnt(0)
	s_waitcnt lgkmcnt(0)
	v_mfma_f32_16x16x32_bf16 v[60:63], v[148:151], v[168:171], v[60:63]
	v_mfma_f32_16x16x32_bf16 v[56:59], v[160:163], v[168:171], v[56:59]
	v_mfma_f32_16x16x32_bf16 v[52:55], v[148:151], v[176:179], v[52:55]
	v_mfma_f32_16x16x32_bf16 v[48:51], v[160:163], v[176:179], v[48:51]
	v_mfma_f32_16x16x32_bf16 v[44:47], v[148:151], v[184:187], v[44:47]
	v_mfma_f32_16x16x32_bf16 v[40:43], v[160:163], v[184:187], v[40:43]
	v_mfma_f32_16x16x32_bf16 v[36:39], v[148:151], v[192:195], v[36:39]
	v_mfma_f32_16x16x32_bf16 v[32:35], v[160:163], v[192:195], v[32:35]
	v_mfma_f32_16x16x32_bf16 v[60:63], v[156:159], v[172:175], v[60:63]
	v_mfma_f32_16x16x32_bf16 v[56:59], v[164:167], v[172:175], v[56:59]
	v_mfma_f32_16x16x32_bf16 v[52:55], v[156:159], v[180:183], v[52:55]
	v_mfma_f32_16x16x32_bf16 v[48:51], v[164:167], v[180:183], v[48:51]
	v_mfma_f32_16x16x32_bf16 v[44:47], v[156:159], v[188:191], v[44:47]
	v_mfma_f32_16x16x32_bf16 v[40:43], v[164:167], v[188:191], v[40:43]
	v_mfma_f32_16x16x32_bf16 v[36:39], v[156:159], v[196:199], v[36:39]
	v_mfma_f32_16x16x32_bf16 v[32:35], v[164:167], v[196:199], v[32:35]
	s_barrier
	s_add_u32 s76, s76, 0x80080
	s_addc_u32 s77, s77, 0
	s_add_i32 s78, s78, s14
	v_lshl_add_u64 v[148:149], s[76:77], 0, v[130:131]
	s_mov_b32 m0, s78
	s_nop 0
	global_load_lds_dwordx4 v[148:149], off
	v_lshl_add_u64 v[148:149], s[76:77], 0, v[134:135]
	s_add_i32 m0, s78, 0x2000
	s_nop 0
	global_load_lds_dwordx4 v[148:149], off
	s_waitcnt vmcnt(6)
	s_barrier
	v_mfma_f32_16x16x32_bf16 v[28:31], v[200:203], v[168:171], v[28:31]
	v_mfma_f32_16x16x32_bf16 v[24:27], v[208:211], v[168:171], v[24:27]
	v_mfma_f32_16x16x32_bf16 v[20:23], v[200:203], v[176:179], v[20:23]
	v_mfma_f32_16x16x32_bf16 v[16:19], v[208:211], v[176:179], v[16:19]
	v_mfma_f32_16x16x32_bf16 v[12:15], v[200:203], v[184:187], v[12:15]
	v_mfma_f32_16x16x32_bf16 v[8:11], v[208:211], v[184:187], v[8:11]
	v_mfma_f32_16x16x32_bf16 v[4:7], v[200:203], v[192:195], v[4:7]
	v_mfma_f32_16x16x32_bf16 v[0:3], v[208:211], v[192:195], v[0:3]
	v_mfma_f32_16x16x32_bf16 v[28:31], v[204:207], v[172:175], v[28:31]
	v_mfma_f32_16x16x32_bf16 v[24:27], v[216:219], v[172:175], v[24:27]
	v_mfma_f32_16x16x32_bf16 v[20:23], v[204:207], v[180:183], v[20:23]
	v_mfma_f32_16x16x32_bf16 v[16:19], v[216:219], v[180:183], v[16:19]
	v_mfma_f32_16x16x32_bf16 v[12:15], v[204:207], v[188:191], v[12:15]
	v_mfma_f32_16x16x32_bf16 v[8:11], v[216:219], v[188:191], v[8:11]
	v_mfma_f32_16x16x32_bf16 v[4:7], v[204:207], v[196:199], v[4:7]
	v_mfma_f32_16x16x32_bf16 v[0:3], v[216:219], v[196:199], v[0:3]
	s_add_i32 s55, s55, 2
	s_add_u32 s68, s68, 0x100
	s_addc_u32 s69, s69, 0
	s_cmp_gt_u32 s55, 29
	s_barrier
	s_cbranch_scc0 .LBB0_3600
	s_lshl_b32 s68, s0, 8
	s_cmp_gt_i32 s0, 58
	s_cbranch_scc1 .LBB0_3644
	s_cmp_gt_i32 s0, 22
	s_cselect_b64 s[4:5], -1, 0
	v_cndmask_b32_e64 v136, 0, 1, s[4:5]
	s_cmp_lt_i32 s0, 35
	v_readfirstlane_b32 s4, v136
	s_cselect_b32 s53, s4, 2
	s_cmp_gt_i32 s53, 1
	s_mov_b64 s[76:77], -1
	s_cbranch_scc0 .LBB0_3604
	v_mul_f32_e32 v136, 0xbfb8aa3b, v124
	v_exp_f32_e32 v136, v136
	v_mul_f32_e32 v144, 0xbfb8aa3b, v120
	v_exp_f32_e32 v144, v144
	v_mul_f32_e32 v145, 0xbfb8aa3b, v121
	v_add_f32_e32 v136, 1.0, v136
	v_rcp_f32_e32 v146, v136
	v_mul_f32_e32 v136, 0xbfb8aa3b, v125
	v_exp_f32_e32 v136, v136
	v_exp_f32_e32 v145, v145
	v_add_f32_e32 v144, 1.0, v144
	v_rcp_f32_e32 v148, v144
	v_add_f32_e32 v136, 1.0, v136
	v_mul_f32_e32 v144, 0xbfb8aa3b, v126
	v_rcp_f32_e32 v147, v136
	v_add_f32_e32 v136, 1.0, v145
	v_exp_f32_e32 v144, v144
	v_mul_f32_e32 v145, 0xbfb8aa3b, v122
	v_exp_f32_e32 v145, v145
	v_rcp_f32_e32 v149, v136
	v_add_f32_e32 v136, 1.0, v144
	v_mul_f32_e32 v144, 0xbfb8aa3b, v127
	v_rcp_f32_e32 v150, v136
	v_add_f32_e32 v136, 1.0, v145
	v_exp_f32_e32 v144, v144
	v_mul_f32_e32 v145, 0xbfb8aa3b, v123
	v_exp_f32_e32 v145, v145
	v_rcp_f32_e32 v152, v136
	v_add_f32_e32 v136, 1.0, v144
	v_rcp_f32_e32 v151, v136
	v_add_f32_e32 v136, 1.0, v145
	v_rcp_f32_e32 v153, v136
	s_mov_b64 s[76:77], 0

; #define PG8_WAIT_V(n) asm volatile("s_waitcnt vmcnt(" #n ")" ::: "memory")
; #define PG8_BAR __builtin_amdgcn_s_barrier()
; template <class Epi, class Sched>
; __device__ __forceinline__ void gemm_phase(LAS unsigned char* lds, const int K, const int lda, Sched& S, const Epi& E) {
;     ...
;     PG8_WAIT_V(0);
;     if (wr == 0) PG8_BAR;
;     PG8_BAR;
.LBB0_3687:
	s_waitcnt vmcnt(0)
	s_setprio 0
	s_nop 0
	s_nop 0
	s_nop 0
	s_nop 0
	s_nop 0
	s_nop 0
	s_nop 0
	s_cmpk_gt_u32 s3, 0xff
	s_cbranch_scc1 .LBB0_3689
	s_barrier

; #define PG8_STAGE(bufoff, gbase, voff) do { _Pragma("unroll") for (int _i = 0; _i < 2; ++_i) \
;         __builtin_amdgcn_global_load_lds((const unsigned*)((const char*)(gbase) + (voff)[_i]), (LAS unsigned*)(lds + (bufoff) + ldsw + _i * 8192), 16, 0, 0); } while (0)
; #define PG8_BAR __builtin_amdgcn_s_barrier()
;     __device__ __forceinline__ const char* aptr(const Unit& u) const { return (const char*)(A + (size_t)u.pm * 256 * 2048); }
;     __device__ __forceinline__ const char* bptr(const Unit& u) const { return (const char*)(Bt + (size_t)u.pn * 256 * 2048); }
;     __device__ __forceinline__ const char* aptr(const Unit& u) const { return (const char*)(A + (size_t)u.pm * 256 * NIN + OFF_GATE + u.z * 1024); }
; template <class Epi, class Sched>
; __device__ __forceinline__ void gemm_phase(LAS unsigned char* lds, const int K, const int lda, Sched& S, const Epi& E) {
;     const int tid = opaque_tid(), wid = __builtin_amdgcn_readfirstlane(tid >> 6), lane = tid & 63, wr = wid >> 2, wc = wid & 3, fr = lane & 15, fq = lane >> 4;
;     const int nt = K / BK;
;     unsigned voffA[2], voffB[2];
; #pragma unroll
;     for (int i = 0; i < 2; ++i) { int R, C; stage_rc(tid * 16 + i * 8192, R, C); const int Rb = (R & ~31) + perm32(R & 31);
;         voffA[i] = (unsigned)(R * lda + C) * 2u; voffB[i] = (unsigned)(Rb * K + C) * 2u; }
;     const size_t kstep = (size_t)(BK * 2);
;     const size_t hstepA = (size_t)HALF * lda * 2, hstepB = (size_t)HALF * K * 2;
;     const unsigned ldsw = (unsigned)wid * 1024u;
;     const int aoff = lds_byte(wr * 64 + fr, fq * 8), boff = lds_byte(wc * 32 + fr, fq * 8);
;     ...
;     Unit cur, nxt; int ui = 0;
;     if (!S.next(0, cur)) return;
;     f32x4 acc[2][2][4][2];
; #pragma unroll
;     for (int a = 0; a < 2; ++a)
; #pragma unroll
;         for (int b = 0; b < 2; ++b)
; #pragma unroll
;             for (int m = 0; m < 4; ++m)
; #pragma unroll
;                 for (int n = 0; n < 2; ++n) acc[a][b][m][n] = (f32x4){0.f, 0.f, 0.f, 0.f};
;     bf16x8 At[4][2], B0[2][2], B1[2][2];
;     const char* cA = S.aptr(cur); const char* cB = S.bptr(cur);
;     PG8_STAGE(PG8_SB(0, 0), cB, voffB); PG8_STAGE(PG8_SA(0, 0), cA, voffA); PG8_STAGE(PG8_SB(0, 1), cB + hstepB, voffB); PG8_STAGE(PG8_SA(0, 1), cA + hstepA, voffA);
;     if (wr == 1) PG8_BAR;
.LBB0_4348:
	s_and_b64 vcc, exec, s[96:97]
	s_cbranch_vccnz .LBB0_4494
	v_ashrrev_i32_e32 v1, 31, v4
	v_lshrrev_b32_e32 v1, 26, v1
	v_add_u32_e32 v1, v4, v1
	v_ashrrev_i32_e32 v5, 6, v1
	v_bfe_i32 v1, v4, 27, 1
	v_lshlrev_b32_e32 v0, 4, v4
	v_lshrrev_b32_e32 v1, 22, v1
	v_add_u32_e32 v1, v0, v1
	v_and_b32_e32 v1, 0xfffffc00, v1
	v_sub_u32_e32 v1, v0, v1
	v_lshrrev_b32_e32 v2, 4, v1
	v_bitop3_b32 v2, v2, v1, 32 bitop3:0x6c
	v_ashrrev_i32_e32 v1, 31, v1
	v_lshrrev_b32_e32 v1, 26, v1
	v_lshlrev_b32_e32 v3, 3, v5
	v_add_u32_e32 v1, v2, v1
	v_and_b32_e32 v3, -16, v3
	v_ashrrev_i32_e32 v7, 6, v1
	v_add_u32_e32 v1, v7, v3
	v_lshlrev_b32_e32 v3, 5, v5
	v_and_b32_e32 v6, 32, v3
	v_mul_i32_i24_e32 v3, 64, v7
	v_sub_u32_e32 v2, v2, v3
	v_mov_b32_e32 v3, 1
	v_ashrrev_i16_sdwa v2, v3, sext(v2) dst_sel:DWORD dst_unused:UNUSED_PAD src0_sel:DWORD src1_sel:BYTE_0
	v_bfe_i32 v8, v2, 0, 16
	v_lshlrev_b32_e32 v9, 1, v1
	v_lshrrev_b32_e32 v10, 2, v1
	v_and_b32_e32 v11, 3, v7
	s_mov_b32 s1, 0x1fffe0
	s_movk_i32 s4, 0x3a80
	v_add_u32_e32 v2, v6, v8
	v_and_b32_e32 v9, 24, v9
	v_and_b32_e32 v10, 4, v10
	v_and_or_b32 v11, v1, s1, v11
	v_mul_lo_u32 v1, v1, s4
	v_or3_b32 v9, v11, v10, v9
	v_add_lshl_u32 v192, v2, v1, 1
	v_lshlrev_b32_e32 v1, 1, v2
	v_add_u32_e32 v0, 0x2000, v0
	v_lshl_add_u32 v194, v9, 11, v1
	v_ashrrev_i32_e32 v1, 31, v0
	v_lshrrev_b32_e32 v1, 22, v1
	v_add_u32_e32 v1, v0, v1
	v_ashrrev_i32_e32 v9, 10, v1
	v_mul_i32_i24_e32 v1, 0x400, v9
	v_sub_u32_e32 v0, v0, v1
	v_lshrrev_b32_e32 v1, 4, v0
	v_bitop3_b32 v0, v1, v0, 32 bitop3:0x6c
	v_ashrrev_i32_e32 v2, 31, v0
	v_lshrrev_b32_e32 v2, 26, v2
	s_add_u32 s3, s74, 0x8205000
	v_lshlrev_b32_e32 v1, 3, v9
	v_add_u32_e32 v2, v0, v2
	s_addc_u32 s14, s75, 0
	v_and_b32_e32 v1, -16, v1
	v_ashrrev_i32_e32 v10, 6, v2
	s_ashr_i32 s12, s2, 6
	s_ashr_i32 s5, s2, 8
	v_add_u32_e32 v1, v10, v1
	v_and_b32_e32 v13, 3, v10
	s_lshl_b32 s15, s12, 10
	s_mul_i32 s6, s52, 0x750000
	v_and_or_b32 v13, v1, s1, v13
	s_mul_hi_i32 s1, s52, 0x750000
	s_add_u32 s10, s50, s6
	v_and_b32_e32 v2, 0xc0, v2
	s_addc_u32 s18, s51, s1
	s_ashr_i32 s1, s0, 31
	v_sub_u32_e32 v0, v0, v2
	s_lshl_b64 s[6:7], s[0:1], 19
	v_lshlrev_b32_e32 v11, 5, v9
	v_ashrrev_i16_sdwa v0, v3, sext(v0) dst_sel:DWORD dst_unused:UNUSED_PAD src0_sel:DWORD src1_sel:BYTE_0
	s_add_u32 s8, s3, s6
	v_and_b32_e32 v11, 32, v11
	v_bfe_i32 v12, v0, 0, 16
	v_lshlrev_b32_e32 v2, 1, v1
	v_lshrrev_b32_e32 v3, 2, v1
	s_addc_u32 s9, s14, s7
	s_add_i32 s38, s15, 0
	v_add_u32_e32 v0, v11, v12
	v_and_b32_e32 v2, 24, v2
	v_and_b32_e32 v3, 4, v3
	v_mul_lo_u32 v1, v1, s4
	s_add_i32 m0, s38, 0x10000
	v_or3_b32 v2, v13, v3, v2
	v_add_lshl_u32 v196, v0, v1, 1
	v_lshlrev_b32_e32 v0, 1, v0
	global_load_lds_dwordx4 v194, s[8:9]
	s_add_i32 m0, s38, 0x12000
	v_lshl_add_u32 v198, v2, 11, v0
	s_add_u32 s6, s10, 0x2d00
	global_load_lds_dwordx4 v198, s[8:9]
	s_addc_u32 s7, s18, 0
	s_mov_b32 m0, s38
	s_add_i32 s39, s38, 0x2000
	global_load_lds_dwordx4 v192, s[6:7]
	s_mov_b32 m0, s39
	s_add_u32 s20, s8, 0x40000
	global_load_lds_dwordx4 v196, s[6:7]
	s_addc_u32 s21, s9, 0
	s_add_i32 m0, s38, 0x14000
	v_mov_b32_e32 v201, 0
	global_load_lds_dwordx4 v194, s[20:21]
	s_add_i32 m0, s38, 0x16000
	v_mov_b32_e32 v195, v201
	global_load_lds_dwordx4 v198, s[20:21]
	s_add_u32 s20, s10, 0x3aad00
	s_addc_u32 s21, s18, 0
	s_add_i32 s40, s38, 0x4000
	s_mov_b32 m0, s40
	s_add_i32 s41, s38, 0x6000
	global_load_lds_dwordx4 v192, s[20:21]
	s_mov_b32 m0, s41
	v_mov_b32_e32 v199, v201
	global_load_lds_dwordx4 v196, s[20:21]
	s_mov_b32 s11, 0
	v_lshl_add_u64 v[2:3], s[8:9], 0, v[194:195]
	v_lshl_add_u64 v[0:1], s[8:9], 0, v[198:199]
	v_mov_b32_e32 v193, v201
	s_cmp_lg_u32 s5, 1
	v_mov_b32_e32 v197, v201
	s_cbranch_scc1 .LBB0_4351
	s_setprio 1
	s_nop 0
	s_nop 0
	s_nop 0
	s_nop 0
	s_nop 0
	s_nop 0
	s_nop 0
	s_barrier

; #define PG8_STAGE(bufoff, gbase, voff) do { _Pragma("unroll") for (int _i = 0; _i < 2; ++_i) \
;         __builtin_amdgcn_global_load_lds((const unsigned*)((const char*)(gbase) + (voff)[_i]), (LAS unsigned*)(lds + (bufoff) + ldsw + _i * 8192), 16, 0, 0); } while (0)
; #define PG8_LDA(dst, b, h) do { _Pragma("unroll") for (int m = 0; m < 4; ++m) _Pragma("unroll") for (int k = 0; k < 2; ++k) dst[m][k] = *(const LAS bf16x8*)(lds + PG8_SA(b, h) + aoff + m * 2048 + k * 1024); } while (0)
; #define PG8_LDB(dst, b, h) do { _Pragma("unroll") for (int n = 0; n < 2; ++n) _Pragma("unroll") for (int k = 0; k < 2; ++k) dst[n][k] = *(const LAS bf16x8*)(lds + PG8_SB(b, h) + boff + n * 2048 + k * 1024); } while (0)
; #define PG8_MMA(ai, bj, At, Bt) do { __builtin_amdgcn_s_setprio(1); _Pragma("unroll") for (int m = 0; m < 4; ++m) _Pragma("unroll") for (int n = 0; n < 2; ++n) _Pragma("unroll") for (int k = 0; k < 2; ++k) \
;         acc[ai][bj][m][n] = __builtin_amdgcn_mfma_f32_16x16x32_bf16(Bt[n][k], At[m][k], acc[ai][bj][m][n], 0, 0, 0); __builtin_amdgcn_s_setprio(0); } while (0)
; #define PG8_WAIT_L(n) asm volatile("s_waitcnt lgkmcnt(" #n ")" ::: "memory")
; #define PG8_BAR __builtin_amdgcn_s_barrier()
; #define PG8_SCHED __builtin_amdgcn_sched_barrier(0)
; template <class Epi, class Sched>
; __device__ __forceinline__ void gemm_phase(LAS unsigned char* lds, const int K, const int lda, Sched& S, const Epi& E) {
;     ...
;             PG8_LDB(B0, 0, 0); PG8_SCHED; PG8_LDA(At, 0, 0); PG8_STAGE(PG8_SA(1, 1), a1 + hstepA, voffA);
;             PG8_WAIT_L(8); PG8_BAR; PG8_WAIT_L(0); PG8_MMA(0, 0, At, B0); PG8_BAR; PG8_SCHED;
;             PG8_LDB(B1, 0, 1); PG8_STAGE(PG8_SB(0, 0), b2, voffB);
;             PG8_BAR; PG8_WAIT_L(0); PG8_MMA(0, 1, At, B1); PG8_BAR;
;             PG8_LDA(At, 0, 1); PG8_STAGE(PG8_SA(0, 0), a2, voffA);
;             PG8_BAR; PG8_WAIT_L(0); PG8_MMA(1, 0, At, B0); PG8_BAR; PG8_SCHED;
.LBB0_4359:
	v_add_u32_e32 v140, s44, v216
	ds_read_b128 v[128:131], v140
	ds_read_b128 v[132:135], v140 offset:1024
	ds_read_b128 v[136:139], v140 offset:2048
	ds_read_b128 v[140:143], v140 offset:3072
	s_add_u32 s8, s6, 0x100
	s_addc_u32 s9, s7, 0
	s_cmp_eq_u32 s23, 12
	s_cselect_b32 s37, s25, s9
	s_cselect_b32 s36, s24, s8
	s_cselect_b32 s31, s1, s21
	s_cselect_b32 s30, s4, s5
	v_lshl_add_u64 v[176:177], s[6:7], 0, v[202:203]
	s_add_i32 m0, s38, 0xc000
	ds_read_b128 v[144:147], v217
	ds_read_b128 v[148:151], v217 offset:1024
	ds_read_b128 v[152:155], v217 offset:2048
	ds_read_b128 v[156:159], v217 offset:3072
	ds_read_b128 v[160:163], v217 offset:4096
	ds_read_b128 v[164:167], v217 offset:5120
	ds_read_b128 v[168:171], v217 offset:6144
	ds_read_b128 v[172:175], v217 offset:7168
	global_load_lds_dwordx4 v[176:177], off
	v_lshl_add_u64 v[176:177], s[6:7], 0, v[204:205]
	s_add_i32 m0, s38, 0xe000
	s_nop 0
	global_load_lds_dwordx4 v[176:177], off
	s_waitcnt lgkmcnt(8)
	s_barrier
	s_waitcnt lgkmcnt(0)
	s_waitcnt lgkmcnt(0)
	v_mfma_f32_16x16x32_bf16 v[124:127], v[128:131], v[144:147], v[124:127]
	v_mfma_f32_16x16x32_bf16 v[120:123], v[136:139], v[144:147], v[120:123]
	v_mfma_f32_16x16x32_bf16 v[116:119], v[128:131], v[152:155], v[116:119]
	v_mfma_f32_16x16x32_bf16 v[112:115], v[136:139], v[152:155], v[112:115]
	v_mfma_f32_16x16x32_bf16 v[108:111], v[128:131], v[160:163], v[108:111]
	v_mfma_f32_16x16x32_bf16 v[104:107], v[136:139], v[160:163], v[104:107]
	v_mfma_f32_16x16x32_bf16 v[100:103], v[128:131], v[168:171], v[100:103]
	v_mfma_f32_16x16x32_bf16 v[96:99], v[136:139], v[168:171], v[96:99]
	v_mfma_f32_16x16x32_bf16 v[124:127], v[132:135], v[148:151], v[124:127]
	v_mfma_f32_16x16x32_bf16 v[120:123], v[140:143], v[148:151], v[120:123]
	v_mfma_f32_16x16x32_bf16 v[116:119], v[132:135], v[156:159], v[116:119]
	v_mfma_f32_16x16x32_bf16 v[112:115], v[140:143], v[156:159], v[112:115]
	v_mfma_f32_16x16x32_bf16 v[108:111], v[132:135], v[164:167], v[108:111]
	v_mfma_f32_16x16x32_bf16 v[104:107], v[140:143], v[164:167], v[104:107]
	v_mfma_f32_16x16x32_bf16 v[100:103], v[132:135], v[172:175], v[100:103]
	v_mfma_f32_16x16x32_bf16 v[96:99], v[140:143], v[172:175], v[96:99]
	s_barrier
	s_add_i32 s6, s44, s15
	v_add_u32_e32 v188, s45, v216
	v_lshl_add_u64 v[206:207], s[30:31], 0, v[194:195]
	s_mov_b32 m0, s6
	ds_read_b128 v[176:179], v188
	ds_read_b128 v[180:183], v188 offset:1024
	ds_read_b128 v[184:187], v188 offset:2048
	ds_read_b128 v[188:191], v188 offset:3072
	global_load_lds_dwordx4 v[206:207], off
	v_lshl_add_u64 v[208:209], s[30:31], 0, v[198:199]
	s_add_i32 m0, s6, 0x2000
	s_nop 0
	global_load_lds_dwordx4 v[208:209], off
	s_barrier
	s_waitcnt lgkmcnt(0)
	s_waitcnt lgkmcnt(0)
	v_mfma_f32_16x16x32_bf16 v[92:95], v[176:179], v[144:147], v[92:95]
	v_mfma_f32_16x16x32_bf16 v[88:91], v[184:187], v[144:147], v[88:91]
	v_mfma_f32_16x16x32_bf16 v[84:87], v[176:179], v[152:155], v[84:87]
	v_mfma_f32_16x16x32_bf16 v[80:83], v[184:187], v[152:155], v[80:83]
	v_mfma_f32_16x16x32_bf16 v[76:79], v[176:179], v[160:163], v[76:79]
	v_mfma_f32_16x16x32_bf16 v[72:75], v[184:187], v[160:163], v[72:75]
	v_mfma_f32_16x16x32_bf16 v[68:71], v[176:179], v[168:171], v[68:71]
	v_mfma_f32_16x16x32_bf16 v[64:67], v[184:187], v[168:171], v[64:67]
	v_mfma_f32_16x16x32_bf16 v[92:95], v[180:183], v[148:151], v[92:95]
	v_mfma_f32_16x16x32_bf16 v[88:91], v[188:191], v[148:151], v[88:91]
	v_mfma_f32_16x16x32_bf16 v[84:87], v[180:183], v[156:159], v[84:87]
	v_mfma_f32_16x16x32_bf16 v[80:83], v[188:191], v[156:159], v[80:83]
	v_mfma_f32_16x16x32_bf16 v[76:79], v[180:183], v[164:167], v[76:79]
	v_mfma_f32_16x16x32_bf16 v[72:75], v[188:191], v[164:167], v[72:75]
	v_mfma_f32_16x16x32_bf16 v[68:71], v[180:183], v[172:175], v[68:71]
	v_mfma_f32_16x16x32_bf16 v[64:67], v[188:191], v[172:175], v[64:67]
	s_mov_b32 m0, s38
	v_lshl_add_u64 v[210:211], s[36:37], 0, v[192:193]
	s_barrier
	ds_read_b128 v[144:147], v217 offset:16384
	ds_read_b128 v[148:151], v217 offset:17408
	ds_read_b128 v[152:155], v217 offset:18432
	ds_read_b128 v[156:159], v217 offset:19456
	ds_read_b128 v[160:163], v217 offset:20480
	ds_read_b128 v[164:167], v217 offset:21504
	ds_read_b128 v[168:171], v217 offset:22528
	ds_read_b128 v[172:175], v217 offset:23552
	global_load_lds_dwordx4 v[210:211], off
	v_lshl_add_u64 v[212:213], s[36:37], 0, v[196:197]
	s_mov_b32 m0, s39
	s_nop 0
	global_load_lds_dwordx4 v[212:213], off
	s_barrier
	s_waitcnt lgkmcnt(0)
	s_waitcnt lgkmcnt(0)
	v_mfma_f32_16x16x32_bf16 v[60:63], v[128:131], v[144:147], v[60:63]
	v_mfma_f32_16x16x32_bf16 v[56:59], v[136:139], v[144:147], v[56:59]
	v_mfma_f32_16x16x32_bf16 v[52:55], v[128:131], v[152:155], v[52:55]
	v_mfma_f32_16x16x32_bf16 v[48:51], v[136:139], v[152:155], v[48:51]
	v_mfma_f32_16x16x32_bf16 v[44:47], v[128:131], v[160:163], v[44:47]
	v_mfma_f32_16x16x32_bf16 v[40:43], v[136:139], v[160:163], v[40:43]
	v_mfma_f32_16x16x32_bf16 v[36:39], v[128:131], v[168:171], v[36:39]
	v_mfma_f32_16x16x32_bf16 v[32:35], v[136:139], v[168:171], v[32:35]
	v_mfma_f32_16x16x32_bf16 v[60:63], v[132:135], v[148:151], v[60:63]
	v_mfma_f32_16x16x32_bf16 v[56:59], v[140:143], v[148:151], v[56:59]
	v_mfma_f32_16x16x32_bf16 v[52:55], v[132:135], v[156:159], v[52:55]
	v_mfma_f32_16x16x32_bf16 v[48:51], v[140:143], v[156:159], v[48:51]
	v_mfma_f32_16x16x32_bf16 v[44:47], v[132:135], v[164:167], v[44:47]
	v_mfma_f32_16x16x32_bf16 v[40:43], v[140:143], v[164:167], v[40:43]
	v_mfma_f32_16x16x32_bf16 v[36:39], v[132:135], v[172:175], v[36:39]
	v_mfma_f32_16x16x32_bf16 v[32:35], v[140:143], v[172:175], v[32:35]
	s_barrier
; #define PG8_STAGE(bufoff, gbase, voff) do { _Pragma("unroll") for (int _i = 0; _i < 2; ++_i) \
;         __builtin_amdgcn_global_load_lds((const unsigned*)((const char*)(gbase) + (voff)[_i]), (LAS unsigned*)(lds + (bufoff) + ldsw + _i * 8192), 16, 0, 0); } while (0)
; #define PG8_LDA(dst, b, h) do { _Pragma("unroll") for (int m = 0; m < 4; ++m) _Pragma("unroll") for (int k = 0; k < 2; ++k) dst[m][k] = *(const LAS bf16x8*)(lds + PG8_SA(b, h) + aoff + m * 2048 + k * 1024); } while (0)
; #define PG8_LDB(dst, b, h) do { _Pragma("unroll") for (int n = 0; n < 2; ++n) _Pragma("unroll") for (int k = 0; k < 2; ++k) dst[n][k] = *(const LAS bf16x8*)(lds + PG8_SB(b, h) + boff + n * 2048 + k * 1024); } while (0)
; #define PG8_MMA(ai, bj, At, Bt) do { __builtin_amdgcn_s_setprio(1); _Pragma("unroll") for (int m = 0; m < 4; ++m) _Pragma("unroll") for (int n = 0; n < 2; ++n) _Pragma("unroll") for (int k = 0; k < 2; ++k) \
;         acc[ai][bj][m][n] = __builtin_amdgcn_mfma_f32_16x16x32_bf16(Bt[n][k], At[m][k], acc[ai][bj][m][n], 0, 0, 0); __builtin_amdgcn_s_setprio(0); } while (0)
; #define PG8_WAIT_V(n) asm volatile("s_waitcnt vmcnt(" #n ")" ::: "memory")
; #define PG8_WAIT_L(n) asm volatile("s_waitcnt lgkmcnt(" #n ")" ::: "memory")
; #define PG8_BAR __builtin_amdgcn_s_barrier()
; #define PG8_SCHED __builtin_amdgcn_sched_barrier(0)
; template <class Epi, class Sched>
; __device__ __forceinline__ void gemm_phase(LAS unsigned char* lds, const int K, const int lda, Sched& S, const Epi& E) {
;     ...
;             PG8_STAGE(PG8_SB(0, 1), b2 + hstepB, voffB);
;             PG8_WAIT_V(6); PG8_BAR; PG8_MMA(1, 1, At, B1); PG8_BAR;
;             PG8_LDB(B0, 1, 0); PG8_SCHED; PG8_LDA(At, 1, 0); PG8_STAGE(PG8_SA(0, 1), a2 + hstepA, voffA);
;             PG8_WAIT_L(8); PG8_BAR; PG8_WAIT_L(0); PG8_MMA(0, 0, At, B0); PG8_BAR; PG8_SCHED;
;             PG8_LDB(B1, 1, 1); PG8_STAGE(PG8_SB(1, 0), b3, voffB);
;             PG8_BAR; PG8_WAIT_L(0); PG8_MMA(0, 1, At, B1); PG8_BAR;
	s_add_u32 s6, s30, 0x40000
	s_addc_u32 s7, s31, 0
	s_add_i32 s53, s45, s15
	v_lshl_add_u64 v[128:129], s[6:7], 0, v[194:195]
	s_mov_b32 m0, s53
	s_nop 0
	global_load_lds_dwordx4 v[128:129], off
	v_lshl_add_u64 v[128:129], s[6:7], 0, v[198:199]
	s_add_i32 m0, s53, 0x2000
	s_nop 0
	global_load_lds_dwordx4 v[128:129], off
	s_waitcnt vmcnt(6)
	s_barrier
	v_mfma_f32_16x16x32_bf16 v[28:31], v[176:179], v[144:147], v[28:31]
	v_mfma_f32_16x16x32_bf16 v[24:27], v[184:187], v[144:147], v[24:27]
	v_mfma_f32_16x16x32_bf16 v[20:23], v[176:179], v[152:155], v[20:23]
	v_mfma_f32_16x16x32_bf16 v[16:19], v[184:187], v[152:155], v[16:19]
	v_mfma_f32_16x16x32_bf16 v[12:15], v[176:179], v[160:163], v[12:15]
	v_mfma_f32_16x16x32_bf16 v[8:11], v[184:187], v[160:163], v[8:11]
	v_mfma_f32_16x16x32_bf16 v[4:7], v[176:179], v[168:171], v[4:7]
	v_mfma_f32_16x16x32_bf16 v[0:3], v[184:187], v[168:171], v[0:3]
	v_mfma_f32_16x16x32_bf16 v[28:31], v[180:183], v[148:151], v[28:31]
	v_mfma_f32_16x16x32_bf16 v[24:27], v[188:191], v[148:151], v[24:27]
	v_mfma_f32_16x16x32_bf16 v[20:23], v[180:183], v[156:159], v[20:23]
	v_mfma_f32_16x16x32_bf16 v[16:19], v[188:191], v[156:159], v[16:19]
	v_mfma_f32_16x16x32_bf16 v[12:15], v[180:183], v[164:167], v[12:15]
	v_mfma_f32_16x16x32_bf16 v[8:11], v[188:191], v[164:167], v[8:11]
	v_mfma_f32_16x16x32_bf16 v[4:7], v[180:183], v[172:175], v[4:7]
	v_mfma_f32_16x16x32_bf16 v[0:3], v[188:191], v[172:175], v[0:3]
	s_add_i32 s53, 0, 0x18000
	v_add_u32_e32 v140, s53, v216
	s_barrier
	ds_read_b128 v[128:131], v140
	ds_read_b128 v[132:135], v140 offset:1024
	ds_read_b128 v[136:139], v140 offset:2048
	ds_read_b128 v[140:143], v140 offset:3072
	s_add_u32 s6, s36, 0x3a8000
	s_addc_u32 s7, s37, 0
	s_mov_b32 m0, s40
	v_lshl_add_u64 v[176:177], s[6:7], 0, v[192:193]
	ds_read_b128 v[144:147], v217 offset:32768
	ds_read_b128 v[148:151], v217 offset:33792
	ds_read_b128 v[152:155], v217 offset:34816
	ds_read_b128 v[156:159], v217 offset:35840
	ds_read_b128 v[160:163], v217 offset:36864
	ds_read_b128 v[164:167], v217 offset:37888
	ds_read_b128 v[168:171], v217 offset:38912
	ds_read_b128 v[172:175], v217 offset:39936
	global_load_lds_dwordx4 v[176:177], off
	v_lshl_add_u64 v[176:177], s[6:7], 0, v[196:197]
	s_mov_b32 m0, s41
	s_nop 0
	global_load_lds_dwordx4 v[176:177], off
	s_waitcnt lgkmcnt(8)
	s_barrier
	s_waitcnt lgkmcnt(0)
	s_waitcnt lgkmcnt(0)
	v_mfma_f32_16x16x32_bf16 v[124:127], v[128:131], v[144:147], v[124:127]
	v_mfma_f32_16x16x32_bf16 v[120:123], v[136:139], v[144:147], v[120:123]
	v_mfma_f32_16x16x32_bf16 v[116:119], v[128:131], v[152:155], v[116:119]
	v_mfma_f32_16x16x32_bf16 v[112:115], v[136:139], v[152:155], v[112:115]
	v_mfma_f32_16x16x32_bf16 v[108:111], v[128:131], v[160:163], v[108:111]
	v_mfma_f32_16x16x32_bf16 v[104:107], v[136:139], v[160:163], v[104:107]
	v_mfma_f32_16x16x32_bf16 v[100:103], v[128:131], v[168:171], v[100:103]
	v_mfma_f32_16x16x32_bf16 v[96:99], v[136:139], v[168:171], v[96:99]
	v_mfma_f32_16x16x32_bf16 v[124:127], v[132:135], v[148:151], v[124:127]
	v_mfma_f32_16x16x32_bf16 v[120:123], v[140:143], v[148:151], v[120:123]
	v_mfma_f32_16x16x32_bf16 v[116:119], v[132:135], v[156:159], v[116:119]
	v_mfma_f32_16x16x32_bf16 v[112:115], v[140:143], v[156:159], v[112:115]
	v_mfma_f32_16x16x32_bf16 v[108:111], v[132:135], v[164:167], v[108:111]
	v_mfma_f32_16x16x32_bf16 v[104:107], v[140:143], v[164:167], v[104:107]
	v_mfma_f32_16x16x32_bf16 v[100:103], v[132:135], v[172:175], v[100:103]
	v_mfma_f32_16x16x32_bf16 v[96:99], v[140:143], v[172:175], v[96:99]
	s_barrier
	s_add_i32 s36, 0, 0x1c000
	s_add_i32 s6, s53, s15
	v_add_u32_e32 v188, s36, v216
	v_lshl_add_u64 v[206:207], v[206:207], 0, s[12:13]
	s_mov_b32 m0, s6
	ds_read_b128 v[176:179], v188
	ds_read_b128 v[180:183], v188 offset:1024
	ds_read_b128 v[184:187], v188 offset:2048
	ds_read_b128 v[188:191], v188 offset:3072
	global_load_lds_dwordx4 v[206:207], off
	v_lshl_add_u64 v[206:207], v[208:209], 0, s[12:13]
	s_add_i32 m0, s6, 0x2000
	s_nop 0
	global_load_lds_dwordx4 v[206:207], off
	s_barrier
	s_waitcnt lgkmcnt(0)
	s_waitcnt lgkmcnt(0)
	v_mfma_f32_16x16x32_bf16 v[92:95], v[176:179], v[144:147], v[92:95]
	v_mfma_f32_16x16x32_bf16 v[88:91], v[184:187], v[144:147], v[88:91]
	v_mfma_f32_16x16x32_bf16 v[84:87], v[176:179], v[152:155], v[84:87]
	v_mfma_f32_16x16x32_bf16 v[80:83], v[184:187], v[152:155], v[80:83]
	v_mfma_f32_16x16x32_bf16 v[76:79], v[176:179], v[160:163], v[76:79]
	v_mfma_f32_16x16x32_bf16 v[72:75], v[184:187], v[160:163], v[72:75]
	v_mfma_f32_16x16x32_bf16 v[68:71], v[176:179], v[168:171], v[68:71]
	v_mfma_f32_16x16x32_bf16 v[64:67], v[184:187], v[168:171], v[64:67]
	v_mfma_f32_16x16x32_bf16 v[92:95], v[180:183], v[148:151], v[92:95]
	v_mfma_f32_16x16x32_bf16 v[88:91], v[188:191], v[148:151], v[88:91]
	v_mfma_f32_16x16x32_bf16 v[84:87], v[180:183], v[156:159], v[84:87]
	v_mfma_f32_16x16x32_bf16 v[80:83], v[188:191], v[156:159], v[80:83]
	v_mfma_f32_16x16x32_bf16 v[76:79], v[180:183], v[164:167], v[76:79]
	v_mfma_f32_16x16x32_bf16 v[72:75], v[188:191], v[164:167], v[72:75]
	v_mfma_f32_16x16x32_bf16 v[68:71], v[180:183], v[172:175], v[68:71]
	v_mfma_f32_16x16x32_bf16 v[64:67], v[188:191], v[172:175], v[64:67]
	s_mov_b32 m0, s42
	v_lshl_add_u64 v[206:207], v[210:211], 0, s[12:13]
	s_barrier
; #define PG8_STAGE(bufoff, gbase, voff) do { _Pragma("unroll") for (int _i = 0; _i < 2; ++_i) \
;         __builtin_amdgcn_global_load_lds((const unsigned*)((const char*)(gbase) + (voff)[_i]), (LAS unsigned*)(lds + (bufoff) + ldsw + _i * 8192), 16, 0, 0); } while (0)
; #define PG8_LDA(dst, b, h) do { _Pragma("unroll") for (int m = 0; m < 4; ++m) _Pragma("unroll") for (int k = 0; k < 2; ++k) dst[m][k] = *(const LAS bf16x8*)(lds + PG8_SA(b, h) + aoff + m * 2048 + k * 1024); } while (0)
; #define PG8_MMA(ai, bj, At, Bt) do { __builtin_amdgcn_s_setprio(1); _Pragma("unroll") for (int m = 0; m < 4; ++m) _Pragma("unroll") for (int n = 0; n < 2; ++n) _Pragma("unroll") for (int k = 0; k < 2; ++k) \
;         acc[ai][bj][m][n] = __builtin_amdgcn_mfma_f32_16x16x32_bf16(Bt[n][k], At[m][k], acc[ai][bj][m][n], 0, 0, 0); __builtin_amdgcn_s_setprio(0); } while (0)
; #define PG8_WAIT_V(n) asm volatile("s_waitcnt vmcnt(" #n ")" ::: "memory")
; #define PG8_WAIT_L(n) asm volatile("s_waitcnt lgkmcnt(" #n ")" ::: "memory")
; #define PG8_BAR __builtin_amdgcn_s_barrier()
; #define PG8_SCHED __builtin_amdgcn_sched_barrier(0)
; template <class Epi, class Sched>
; __device__ __forceinline__ void gemm_phase(LAS unsigned char* lds, const int K, const int lda, Sched& S, const Epi& E) {
;     ...
;             PG8_LDA(At, 1, 1); PG8_STAGE(PG8_SA(1, 0), a3, voffA);
;             PG8_BAR; PG8_WAIT_L(0); PG8_MMA(1, 0, At, B0); PG8_BAR; PG8_SCHED;
;             PG8_STAGE(PG8_SB(1, 1), b3 + hstepB, voffB);
;             PG8_WAIT_V(6); PG8_BAR; PG8_MMA(1, 1, At, B1); PG8_BAR;
;     __device__ __forceinline__ void operator()(f32x4 (&acc)[2][2][4][2], const Unit& u, int wr, int wc, int fr, int fq) const {
;     ...
;         const u16* gbase = proj + (size_t)(u.pm * 256 + wr * 64 + fr) * NIN + OFF_MERGE + b * 2048 + u.pn * 256 + wc * 32 + 8 * fq;
;         u16* mbase = merged + (size_t)(u.pm * 256 + wr * 64 + fr) * 2048 + u.pn * 256 + wc * 32 + 8 * fq;
; #pragma unroll
;         for (int ai = 0; ai < 2; ++ai) {
;             u32x4 g[4][2], gn[4][2];
; #pragma unroll
;             for (int m = 0; m < 4; ++m)
; #pragma unroll
;                 for (int bj = 0; bj < 2; ++bj) {
;                     const u16* gp = gbase + (size_t)(ai * 128 + m * 16) * NIN + bj * 128;
;                     g[m][bj] = *(const u32x4*)gp;
;                     if (b < 2) gn[m][bj] = *(const u32x4*)(gp + 2048);
	ds_read_b128 v[144:147], v217 offset:49152
	ds_read_b128 v[148:151], v217 offset:50176
	ds_read_b128 v[152:155], v217 offset:51200
	ds_read_b128 v[156:159], v217 offset:52224
	ds_read_b128 v[160:163], v217 offset:53248
	ds_read_b128 v[164:167], v217 offset:54272
	ds_read_b128 v[168:171], v217 offset:55296
	ds_read_b128 v[172:175], v217 offset:56320
	global_load_lds_dwordx4 v[206:207], off
	v_lshl_add_u64 v[206:207], v[212:213], 0, s[12:13]
	s_mov_b32 m0, s43
	s_nop 0
	global_load_lds_dwordx4 v[206:207], off
	s_barrier
	s_waitcnt lgkmcnt(0)
	s_waitcnt lgkmcnt(0)
	v_mfma_f32_16x16x32_bf16 v[60:63], v[128:131], v[144:147], v[60:63]
	v_mfma_f32_16x16x32_bf16 v[56:59], v[136:139], v[144:147], v[56:59]
	v_mfma_f32_16x16x32_bf16 v[52:55], v[128:131], v[152:155], v[52:55]
	v_mfma_f32_16x16x32_bf16 v[48:51], v[136:139], v[152:155], v[48:51]
	v_mfma_f32_16x16x32_bf16 v[44:47], v[128:131], v[160:163], v[44:47]
	v_mfma_f32_16x16x32_bf16 v[40:43], v[136:139], v[160:163], v[40:43]
	v_mfma_f32_16x16x32_bf16 v[36:39], v[128:131], v[168:171], v[36:39]
	v_mfma_f32_16x16x32_bf16 v[32:35], v[136:139], v[168:171], v[32:35]
	v_mfma_f32_16x16x32_bf16 v[60:63], v[132:135], v[148:151], v[60:63]
	v_mfma_f32_16x16x32_bf16 v[56:59], v[140:143], v[148:151], v[56:59]
	v_mfma_f32_16x16x32_bf16 v[52:55], v[132:135], v[156:159], v[52:55]
	v_mfma_f32_16x16x32_bf16 v[48:51], v[140:143], v[156:159], v[48:51]
	v_mfma_f32_16x16x32_bf16 v[44:47], v[132:135], v[164:167], v[44:47]
	v_mfma_f32_16x16x32_bf16 v[40:43], v[140:143], v[164:167], v[40:43]
	v_mfma_f32_16x16x32_bf16 v[36:39], v[132:135], v[172:175], v[36:39]
	v_mfma_f32_16x16x32_bf16 v[32:35], v[140:143], v[172:175], v[32:35]
	s_barrier
	s_add_u32 s6, s30, 0x40080
	s_addc_u32 s7, s31, 0
	s_add_i32 s30, s36, s15
	v_lshl_add_u64 v[128:129], s[6:7], 0, v[194:195]
	s_mov_b32 m0, s30
	s_nop 0
	global_load_lds_dwordx4 v[128:129], off
	v_lshl_add_u64 v[128:129], s[6:7], 0, v[198:199]
	s_add_i32 m0, s30, 0x2000
	s_nop 0
	global_load_lds_dwordx4 v[128:129], off
	s_waitcnt vmcnt(6)
	s_barrier
	v_mfma_f32_16x16x32_bf16 v[28:31], v[176:179], v[144:147], v[28:31]
	v_mfma_f32_16x16x32_bf16 v[24:27], v[184:187], v[144:147], v[24:27]
	v_mfma_f32_16x16x32_bf16 v[20:23], v[176:179], v[152:155], v[20:23]
	v_mfma_f32_16x16x32_bf16 v[16:19], v[184:187], v[152:155], v[16:19]
	v_mfma_f32_16x16x32_bf16 v[12:15], v[176:179], v[160:163], v[12:15]
	v_mfma_f32_16x16x32_bf16 v[8:11], v[184:187], v[160:163], v[8:11]
	v_mfma_f32_16x16x32_bf16 v[4:7], v[176:179], v[168:171], v[4:7]
	v_mfma_f32_16x16x32_bf16 v[0:3], v[184:187], v[168:171], v[0:3]
	v_mfma_f32_16x16x32_bf16 v[28:31], v[180:183], v[148:151], v[28:31]
	v_mfma_f32_16x16x32_bf16 v[24:27], v[188:191], v[148:151], v[24:27]
	v_mfma_f32_16x16x32_bf16 v[20:23], v[180:183], v[156:159], v[20:23]
	v_mfma_f32_16x16x32_bf16 v[16:19], v[188:191], v[156:159], v[16:19]
	v_mfma_f32_16x16x32_bf16 v[12:15], v[180:183], v[164:167], v[12:15]
	v_mfma_f32_16x16x32_bf16 v[8:11], v[188:191], v[164:167], v[8:11]
	v_mfma_f32_16x16x32_bf16 v[4:7], v[180:183], v[172:175], v[4:7]
	v_mfma_f32_16x16x32_bf16 v[0:3], v[188:191], v[172:175], v[0:3]
	s_add_i32 s23, s23, 2
	s_add_u32 s5, s5, 0x100
	s_addc_u32 s21, s21, 0
	s_cmp_gt_u32 s23, 13
	s_mov_b64 s[6:7], s[8:9]
	s_barrier
	s_cbranch_scc0 .LBB0_4359
	v_lshl_add_u32 v206, s52, 8, v215
	v_mov_b64_e32 v[128:129], s[50:51]
	v_mad_i64_i32 v[128:129], s[4:5], v206, s46, v[128:129]
	s_lshl_b32 s4, s49, 11
	s_ashr_i32 s5, s4, 31
	s_lshl_b32 s6, s0, 8
	v_lshl_add_u64 v[128:129], s[4:5], 1, v[128:129]
	s_ashr_i32 s7, s6, 31
	v_lshl_add_u64 v[128:129], s[6:7], 1, v[128:129]
	v_lshl_add_u64 v[128:129], v[128:129], 0, s[10:11]
	v_lshl_add_u64 v[128:129], v[128:129], 0, v[200:201]
	v_add_co_u32_e32 v130, vcc, 0x4000, v128
	s_cmp_lt_i32 s49, 2
	s_nop 0
	v_addc_co_u32_e32 v131, vcc, 0, v129, vcc
	global_load_dwordx4 v[188:191], v[130:131], off offset:1280
	s_cselect_b64 s[0:1], -1, 0
	s_cmp_gt_i32 s49, 1
	s_cselect_b64 s[30:31], -1, 0
	v_lshl_add_u64 v[208:209], v[128:129], 0, s[18:19]
	s_and_b64 vcc, exec, s[30:31]
	s_cbranch_vccnz .LBB0_4362
	v_add_co_u32_e32 v128, vcc, 0x1000, v208
	s_nop 1
	v_addc_co_u32_e32 v129, vcc, 0, v209, vcc
	global_load_dwordx4 v[156:159], v[128:129], off

; #define PG8_STAGE(bufoff, gbase, voff) do { _Pragma("unroll") for (int _i = 0; _i < 2; ++_i) \
;         __builtin_amdgcn_global_load_lds((const unsigned*)((const char*)(gbase) + (voff)[_i]), (LAS unsigned*)(lds + (bufoff) + ldsw + _i * 8192), 16, 0, 0); } while (0)
; #define PG8_BAR __builtin_amdgcn_s_barrier()
;     __device__ __forceinline__ const char* aptr(const Unit& u) const { return (const char*)(A + (size_t)u.pm * 256 * 2048); }
;     __device__ __forceinline__ const char* bptr(const Unit& u) const { return (const char*)(Bt + (size_t)u.pn * 256 * 2048); }
; template <class Epi, class Sched>
; __device__ __forceinline__ void gemm_phase(LAS unsigned char* lds, const int K, const int lda, Sched& S, const Epi& E) {
;     const int tid = opaque_tid(), wid = __builtin_amdgcn_readfirstlane(tid >> 6), lane = tid & 63, wr = wid >> 2, wc = wid & 3, fr = lane & 15, fq = lane >> 4;
;     const int nt = K / BK;
;     unsigned voffA[2], voffB[2];
; #pragma unroll
;     for (int i = 0; i < 2; ++i) { int R, C; stage_rc(tid * 16 + i * 8192, R, C); const int Rb = (R & ~31) + perm32(R & 31);
;         voffA[i] = (unsigned)(R * lda + C) * 2u; voffB[i] = (unsigned)(Rb * K + C) * 2u; }
;     const size_t kstep = (size_t)(BK * 2);
;     const size_t hstepA = (size_t)HALF * lda * 2, hstepB = (size_t)HALF * K * 2;
;     const unsigned ldsw = (unsigned)wid * 1024u;
;     const int aoff = lds_byte(wr * 64 + fr, fq * 8), boff = lds_byte(wc * 32 + fr, fq * 8);
;     ...
;     Unit cur, nxt; int ui = 0;
;     if (!S.next(0, cur)) return;
;     f32x4 acc[2][2][4][2];
; #pragma unroll
;     for (int a = 0; a < 2; ++a)
; #pragma unroll
;         for (int b = 0; b < 2; ++b)
; #pragma unroll
;             for (int m = 0; m < 4; ++m)
; #pragma unroll
;                 for (int n = 0; n < 2; ++n) acc[a][b][m][n] = (f32x4){0.f, 0.f, 0.f, 0.f};
;     bf16x8 At[4][2], B0[2][2], B1[2][2];
;     const char* cA = S.aptr(cur); const char* cB = S.bptr(cur);
;     PG8_STAGE(PG8_SB(0, 0), cB, voffB); PG8_STAGE(PG8_SA(0, 0), cA, voffA); PG8_STAGE(PG8_SB(0, 1), cB + hstepB, voffB); PG8_STAGE(PG8_SA(0, 1), cA + hstepA, voffA);
;     if (wr == 1) PG8_BAR;
; __device__ __forceinline__ int xcd_remap(int L, int nwg) {
;     const int q = nwg >> 3, r = nwg & 7, xcd = L & 7, off = L >> 3;
;     return (xcd < r ? xcd * (q + 1) : r * (q + 1) + (xcd - r) * q) + off;
; }
.LBB0_4551:
	s_or_b64 exec, exec, s[0:1]
	s_mov_b64 s[0:1], src_shared_base
	s_waitcnt lgkmcnt(0)
	s_barrier
	s_add_u32 s14, s74, 0x9605000
	s_getreg_b32 s0, hwreg(HW_REG_HW_ID, 0, 6)
	s_addc_u32 s15, s75, 0
	s_and_b32 s0, s0, 63
	s_lshl_b32 s0, s0, 2
	s_add_i32 s0, s0, 0
	s_add_i32 s0, s0, 0x20100
	v_mov_b32_e32 v0, s0
	v_mov_b32_e32 v1, s1
	flat_load_dword v0, v[0:1] sc0 sc1
	s_waitcnt vmcnt(0)
	s_and_b64 vcc, exec, s[96:97]
	s_waitcnt lgkmcnt(0)
	v_readfirstlane_b32 s0, v0
	s_nop 1
	v_lshl_or_b32 v9, s0, 6, v214
	s_nop 0
	v_readfirstlane_b32 s58, v9
	s_cbranch_vccnz .LBB0_4567
	v_lshlrev_b32_e32 v0, 4, v9
	v_add_u32_e32 v1, 0x2000, v0
	v_ashrrev_i32_e32 v2, 31, v1
	v_lshrrev_b32_e32 v2, 22, v2
	v_add_u32_e32 v2, v1, v2
	v_ashrrev_i32_e32 v8, 10, v2
	v_mul_i32_i24_e32 v2, 0x400, v8
	v_sub_u32_e32 v1, v1, v2
	v_lshrrev_b32_e32 v2, 4, v1
	v_bitop3_b32 v1, v2, v1, 32 bitop3:0x6c
	v_ashrrev_i32_e32 v2, 31, v1
	v_lshrrev_b32_e32 v2, 26, v2
	v_add_u32_e32 v2, v1, v2
	v_lshlrev_b32_e32 v3, 3, v8
	v_ashrrev_i32_e32 v10, 6, v2
	v_and_b32_e32 v3, -16, v3
	v_add_u32_e32 v3, v10, v3
	v_and_b32_e32 v4, 3, v10
	s_mov_b32 s1, 0xfffe0
	v_lshrrev_b32_e32 v5, 2, v3
	v_lshlrev_b32_e32 v6, 1, v3
	v_and_b32_e32 v2, 0xc0, v2
	v_and_or_b32 v4, v3, s1, v4
	v_and_b32_e32 v5, 4, v5
	v_and_b32_e32 v6, 24, v6
	v_sub_u32_e32 v1, v1, v2
	v_mov_b32_e32 v2, 1
	v_or3_b32 v4, v4, v5, v6
	v_lshlrev_b32_e32 v5, 5, v8
	v_ashrrev_i16_sdwa v1, v2, sext(v1) dst_sel:DWORD dst_unused:UNUSED_PAD src0_sel:DWORD src1_sel:BYTE_0
	v_and_b32_e32 v5, 32, v5
	v_bfe_i32 v11, v1, 0, 16
	v_add_lshl_u32 v1, v5, v11, 1
	v_lshl_add_u32 v128, v4, 12, v1
	v_lshl_add_u32 v130, v3, 12, v1
	v_bfe_i32 v1, v9, 27, 1
	v_lshrrev_b32_e32 v1, 22, v1
	v_add_u32_e32 v1, v0, v1
	v_and_b32_e32 v1, 0xfffffc00, v1
	v_sub_u32_e32 v0, v0, v1
	v_lshrrev_b32_e32 v1, 4, v0
	v_bitop3_b32 v1, v1, v0, 32 bitop3:0x6c
	v_ashrrev_i32_e32 v0, 31, v0
	v_lshrrev_b32_e32 v0, 26, v0
	v_add_u32_e32 v0, v1, v0
	v_ashrrev_i32_e32 v12, 6, v0
	v_ashrrev_i32_e32 v0, 31, v9
	v_lshrrev_b32_e32 v0, 26, v0
	v_add_u32_e32 v0, v9, v0
	v_ashrrev_i32_e32 v13, 6, v0
	v_lshlrev_b32_e32 v0, 3, v13
	v_and_b32_e32 v0, -16, v0
	v_add_u32_e32 v0, v12, v0
	v_and_b32_e32 v3, 3, v12
	v_and_or_b32 v3, v0, s1, v3
	s_lshl_b32 s1, s92, 6
	s_and_b32 s1, s1, 0x1c0
	s_ashr_i32 s2, s92, 3
	s_add_i32 s1, s1, s2
	s_ashr_i32 s2, s1, 31
	s_lshr_b32 s2, s2, 26
	s_add_i32 s2, s1, s2
	s_ashr_i32 s4, s2, 6
	s_andn2_b32 s2, s2, 63
	s_sub_i32 s1, s1, s2
	s_bfe_i32 s2, s1, 0x80000
	s_bfe_u32 s2, s2, 0x3000c
	s_add_i32 s5, s1, s2
	s_bfe_i32 s2, s5, 0x80000
	s_and_b32 s5, s5, 0xf8
	v_lshrrev_b32_e32 v4, 2, v0
	v_lshlrev_b32_e32 v5, 1, v0
	s_sub_i32 s1, s1, s5
	v_and_b32_e32 v4, 4, v4
	v_and_b32_e32 v5, 24, v5
	s_lshl_b32 s4, s4, 3
	s_sext_i32_i16 s2, s2
	s_sext_i32_i8 s1, s1
	s_ashr_i32 s3, s58, 8
	v_or3_b32 v3, v3, v4, v5
	v_mul_i32_i24_e32 v5, 64, v12
	s_lshr_b32 s2, s2, 3
	s_add_i32 s50, s4, s1
	s_ashr_i32 s0, s58, 6
	v_sub_u32_e32 v1, v1, v5
	s_ashr_i32 s51, s50, 31
	s_bfe_i64 s[6:7], s[2:3], 0x100000
	s_lshl_b32 s59, s0, 10
	v_lshlrev_b32_e32 v4, 5, v13
	v_ashrrev_i16_sdwa v1, v2, sext(v1) dst_sel:DWORD dst_unused:UNUSED_PAD src0_sel:DWORD src1_sel:BYTE_0
	s_lshl_b64 s[4:5], s[50:51], 20
	s_lshl_b64 s[6:7], s[6:7], 20
	v_and_b32_e32 v4, 32, v4
	v_bfe_i32 v14, v1, 0, 16
	s_add_u32 s54, s14, s6
	v_add_lshl_u32 v1, v4, v14, 1
	s_addc_u32 s55, s15, s7
	s_add_i32 s60, s59, 0
	v_lshl_add_u32 v132, v3, 12, v1
	s_add_i32 m0, s60, 0x10000
	v_lshl_add_u32 v134, v0, 12, v1
	global_load_lds_dwordx4 v132, s[54:55]
	s_add_i32 m0, s60, 0x12000
	s_add_u32 s52, s34, s4
	global_load_lds_dwordx4 v128, s[54:55]
	s_addc_u32 s53, s35, s5
	s_mov_b32 m0, s60
	s_add_i32 s61, s60, 0x2000
	global_load_lds_dwordx4 v134, s[52:53]
	s_mov_b32 m0, s61
	s_add_u32 s4, s54, 0x80000
	global_load_lds_dwordx4 v130, s[52:53]
	s_addc_u32 s5, s55, 0
	s_add_i32 m0, s60, 0x14000
	v_mov_b32_e32 v137, 0
	global_load_lds_dwordx4 v132, s[4:5]
	s_add_i32 m0, s60, 0x16000
	v_mov_b32_e32 v133, v137
	global_load_lds_dwordx4 v128, s[4:5]
	s_add_u32 s4, s52, 0x80000
	s_addc_u32 s5, s53, 0
	s_add_i32 s62, s60, 0x4000
	s_mov_b32 m0, s62
	s_add_i32 s63, s60, 0x6000
	global_load_lds_dwordx4 v134, s[4:5]
	s_mov_b32 m0, s63
	v_mov_b32_e32 v129, v137
	global_load_lds_dwordx4 v130, s[4:5]
	v_mov_b32_e32 v135, v137
	v_mov_b32_e32 v131, v137
	v_lshl_add_u64 v[6:7], s[54:55], 0, v[132:133]
	v_lshl_add_u64 v[4:5], s[54:55], 0, v[128:129]
	v_lshl_add_u64 v[2:3], s[52:53], 0, v[134:135]
	s_cmp_lg_u32 s3, 1
	v_lshl_add_u64 v[0:1], s[52:53], 0, v[130:131]
	s_cbranch_scc1 .LBB0_4554
	s_setprio 1
	s_nop 0
	s_nop 0
	s_nop 0
	s_nop 0
	s_nop 0
	s_nop 0
	s_nop 0
	s_barrier

; #define PG8_STAGE(bufoff, gbase, voff) do { _Pragma("unroll") for (int _i = 0; _i < 2; ++_i) \
;         __builtin_amdgcn_global_load_lds((const unsigned*)((const char*)(gbase) + (voff)[_i]), (LAS unsigned*)(lds + (bufoff) + ldsw + _i * 8192), 16, 0, 0); } while (0)
; #define PG8_LDA(dst, b, h) do { _Pragma("unroll") for (int m = 0; m < 4; ++m) _Pragma("unroll") for (int k = 0; k < 2; ++k) dst[m][k] = *(const LAS bf16x8*)(lds + PG8_SA(b, h) + aoff + m * 2048 + k * 1024); } while (0)
; #define PG8_LDB(dst, b, h) do { _Pragma("unroll") for (int n = 0; n < 2; ++n) _Pragma("unroll") for (int k = 0; k < 2; ++k) dst[n][k] = *(const LAS bf16x8*)(lds + PG8_SB(b, h) + boff + n * 2048 + k * 1024); } while (0)
; #define PG8_MMA(ai, bj, At, Bt) do { __builtin_amdgcn_s_setprio(1); _Pragma("unroll") for (int m = 0; m < 4; ++m) _Pragma("unroll") for (int n = 0; n < 2; ++n) _Pragma("unroll") for (int k = 0; k < 2; ++k) \
;         acc[ai][bj][m][n] = __builtin_amdgcn_mfma_f32_16x16x32_bf16(Bt[n][k], At[m][k], acc[ai][bj][m][n], 0, 0, 0); __builtin_amdgcn_s_setprio(0); } while (0)
; #define PG8_WAIT_L(n) asm volatile("s_waitcnt lgkmcnt(" #n ")" ::: "memory")
; #define PG8_BAR __builtin_amdgcn_s_barrier()
; #define PG8_SCHED __builtin_amdgcn_sched_barrier(0)
; template <class Epi, class Sched>
; __device__ __forceinline__ void gemm_phase(LAS unsigned char* lds, const int K, const int lda, Sched& S, const Epi& E) {
;     ...
;             PG8_LDB(B0, 0, 0); PG8_SCHED; PG8_LDA(At, 0, 0); PG8_STAGE(PG8_SA(1, 1), a1 + hstepA, voffA);
;             PG8_WAIT_L(8); PG8_BAR; PG8_WAIT_L(0); PG8_MMA(0, 0, At, B0); PG8_BAR; PG8_SCHED;
;             PG8_LDB(B1, 0, 1); PG8_STAGE(PG8_SB(0, 0), b2, voffB);
;             PG8_BAR; PG8_WAIT_L(0); PG8_MMA(0, 1, At, B1); PG8_BAR;
;             PG8_LDA(At, 0, 1); PG8_STAGE(PG8_SA(0, 0), a2, voffA);
;             PG8_BAR; PG8_WAIT_L(0); PG8_MMA(1, 0, At, B0); PG8_BAR; PG8_SCHED;
.LBB0_4559:
	ds_read_b128 v[142:145], v151
	ds_read_b128 v[154:157], v151 offset:1024
	ds_read_b128 v[158:161], v151 offset:2048
	ds_read_b128 v[162:165], v151 offset:3072
	s_add_u32 s54, s52, 0xfff80080
	s_addc_u32 s55, s53, -1
	s_cmp_eq_u32 s85, 28
	s_cselect_b32 s57, s4, s55
	s_cselect_b32 s56, s5, s54
	s_cselect_b32 s55, s41, s84
	s_cselect_b32 s54, s43, s51
	v_lshl_add_u64 v[146:147], s[52:53], 0, v[138:139]
	s_add_i32 m0, s60, 0xc000
	ds_read_b128 v[166:169], v152
	ds_read_b128 v[170:173], v152 offset:1024
	ds_read_b128 v[174:177], v152 offset:2048
	ds_read_b128 v[178:181], v152 offset:3072
	ds_read_b128 v[182:185], v152 offset:4096
	ds_read_b128 v[186:189], v152 offset:5120
	ds_read_b128 v[190:193], v152 offset:6144
	ds_read_b128 v[194:197], v152 offset:7168
	global_load_lds_dwordx4 v[146:147], off
	v_lshl_add_u64 v[146:147], s[52:53], 0, v[140:141]
	s_add_i32 m0, s60, 0xe000
	s_nop 0
	global_load_lds_dwordx4 v[146:147], off
	s_waitcnt lgkmcnt(8)
	s_barrier
	s_waitcnt lgkmcnt(0)
	s_waitcnt lgkmcnt(0)
	v_mfma_f32_16x16x32_bf16 v[124:127], v[142:145], v[166:169], v[124:127]
	v_mfma_f32_16x16x32_bf16 v[120:123], v[158:161], v[166:169], v[120:123]
	v_mfma_f32_16x16x32_bf16 v[116:119], v[142:145], v[174:177], v[116:119]
	v_mfma_f32_16x16x32_bf16 v[112:115], v[158:161], v[174:177], v[112:115]
	v_mfma_f32_16x16x32_bf16 v[104:107], v[142:145], v[182:185], v[104:107]
	v_mfma_f32_16x16x32_bf16 v[96:99], v[158:161], v[182:185], v[96:99]
	v_mfma_f32_16x16x32_bf16 v[80:83], v[142:145], v[190:193], v[80:83]
	v_mfma_f32_16x16x32_bf16 v[72:75], v[158:161], v[190:193], v[72:75]
	v_mfma_f32_16x16x32_bf16 v[124:127], v[154:157], v[170:173], v[124:127]
	v_mfma_f32_16x16x32_bf16 v[120:123], v[162:165], v[170:173], v[120:123]
	v_mfma_f32_16x16x32_bf16 v[116:119], v[154:157], v[178:181], v[116:119]
	v_mfma_f32_16x16x32_bf16 v[112:115], v[162:165], v[178:181], v[112:115]
	v_mfma_f32_16x16x32_bf16 v[104:107], v[154:157], v[186:189], v[104:107]
	v_mfma_f32_16x16x32_bf16 v[96:99], v[162:165], v[186:189], v[96:99]
	v_mfma_f32_16x16x32_bf16 v[80:83], v[154:157], v[194:197], v[80:83]
	v_mfma_f32_16x16x32_bf16 v[72:75], v[162:165], v[194:197], v[72:75]
	s_barrier
	s_add_i32 s86, s67, s59
	v_lshl_add_u64 v[146:147], s[54:55], 0, v[132:133]
	s_mov_b32 m0, s86
	ds_read_b128 v[198:201], v153
	ds_read_b128 v[202:205], v153 offset:1024
	ds_read_b128 v[206:209], v153 offset:2048
	ds_read_b128 v[210:213], v153 offset:3072
	global_load_lds_dwordx4 v[146:147], off
	v_lshl_add_u64 v[216:217], s[54:55], 0, v[128:129]
	s_add_i32 m0, s86, 0x2000
	s_nop 0
	global_load_lds_dwordx4 v[216:217], off
	s_barrier
	s_waitcnt lgkmcnt(0)
	s_waitcnt lgkmcnt(0)
	v_mfma_f32_16x16x32_bf16 v[108:111], v[198:201], v[166:169], v[108:111]
	v_mfma_f32_16x16x32_bf16 v[100:103], v[206:209], v[166:169], v[100:103]
	v_mfma_f32_16x16x32_bf16 v[92:95], v[198:201], v[174:177], v[92:95]
	v_mfma_f32_16x16x32_bf16 v[88:91], v[206:209], v[174:177], v[88:91]
	v_mfma_f32_16x16x32_bf16 v[84:87], v[198:201], v[182:185], v[84:87]
	v_mfma_f32_16x16x32_bf16 v[76:79], v[206:209], v[182:185], v[76:79]
	v_mfma_f32_16x16x32_bf16 v[68:71], v[198:201], v[190:193], v[68:71]
	v_mfma_f32_16x16x32_bf16 v[64:67], v[206:209], v[190:193], v[64:67]
	v_mfma_f32_16x16x32_bf16 v[108:111], v[202:205], v[170:173], v[108:111]
	v_mfma_f32_16x16x32_bf16 v[100:103], v[210:213], v[170:173], v[100:103]
	v_mfma_f32_16x16x32_bf16 v[92:95], v[202:205], v[178:181], v[92:95]
	v_mfma_f32_16x16x32_bf16 v[88:91], v[210:213], v[178:181], v[88:91]
	v_mfma_f32_16x16x32_bf16 v[84:87], v[202:205], v[186:189], v[84:87]
	v_mfma_f32_16x16x32_bf16 v[76:79], v[210:213], v[186:189], v[76:79]
	v_mfma_f32_16x16x32_bf16 v[68:71], v[202:205], v[194:197], v[68:71]
	v_mfma_f32_16x16x32_bf16 v[64:67], v[210:213], v[194:197], v[64:67]
	s_mov_b32 m0, s60
	v_lshl_add_u64 v[218:219], s[56:57], 0, v[134:135]
	s_barrier
	ds_read_b128 v[166:169], v152 offset:16384
	ds_read_b128 v[170:173], v152 offset:17408
	ds_read_b128 v[174:177], v152 offset:18432
	ds_read_b128 v[178:181], v152 offset:19456
	ds_read_b128 v[182:185], v152 offset:20480
	ds_read_b128 v[186:189], v152 offset:21504
	ds_read_b128 v[190:193], v152 offset:22528
	ds_read_b128 v[194:197], v152 offset:23552
	global_load_lds_dwordx4 v[218:219], off
	v_lshl_add_u64 v[220:221], s[56:57], 0, v[130:131]
	s_mov_b32 m0, s61
	s_nop 0
	global_load_lds_dwordx4 v[220:221], off
	s_barrier
	s_waitcnt lgkmcnt(0)
	s_waitcnt lgkmcnt(0)
	v_mfma_f32_16x16x32_bf16 v[60:63], v[142:145], v[166:169], v[60:63]
	v_mfma_f32_16x16x32_bf16 v[56:59], v[158:161], v[166:169], v[56:59]
	v_mfma_f32_16x16x32_bf16 v[52:55], v[142:145], v[174:177], v[52:55]
	v_mfma_f32_16x16x32_bf16 v[48:51], v[158:161], v[174:177], v[48:51]
	v_mfma_f32_16x16x32_bf16 v[32:35], v[142:145], v[182:185], v[32:35]
	v_mfma_f32_16x16x32_bf16 v[24:27], v[158:161], v[182:185], v[24:27]
	v_mfma_f32_16x16x32_bf16 v[20:23], v[142:145], v[190:193], v[20:23]
	v_mfma_f32_16x16x32_bf16 v[8:11], v[158:161], v[190:193], v[8:11]
	v_mfma_f32_16x16x32_bf16 v[60:63], v[154:157], v[170:173], v[60:63]
	v_mfma_f32_16x16x32_bf16 v[56:59], v[162:165], v[170:173], v[56:59]
	v_mfma_f32_16x16x32_bf16 v[52:55], v[154:157], v[178:181], v[52:55]
	v_mfma_f32_16x16x32_bf16 v[48:51], v[162:165], v[178:181], v[48:51]
	v_mfma_f32_16x16x32_bf16 v[32:35], v[154:157], v[186:189], v[32:35]
	v_mfma_f32_16x16x32_bf16 v[24:27], v[162:165], v[186:189], v[24:27]
	v_mfma_f32_16x16x32_bf16 v[20:23], v[154:157], v[194:197], v[20:23]
	v_mfma_f32_16x16x32_bf16 v[8:11], v[162:165], v[194:197], v[8:11]
	s_barrier
; #define PG8_STAGE(bufoff, gbase, voff) do { _Pragma("unroll") for (int _i = 0; _i < 2; ++_i) \
;         __builtin_amdgcn_global_load_lds((const unsigned*)((const char*)(gbase) + (voff)[_i]), (LAS unsigned*)(lds + (bufoff) + ldsw + _i * 8192), 16, 0, 0); } while (0)
; #define PG8_LDA(dst, b, h) do { _Pragma("unroll") for (int m = 0; m < 4; ++m) _Pragma("unroll") for (int k = 0; k < 2; ++k) dst[m][k] = *(const LAS bf16x8*)(lds + PG8_SA(b, h) + aoff + m * 2048 + k * 1024); } while (0)
; #define PG8_LDB(dst, b, h) do { _Pragma("unroll") for (int n = 0; n < 2; ++n) _Pragma("unroll") for (int k = 0; k < 2; ++k) dst[n][k] = *(const LAS bf16x8*)(lds + PG8_SB(b, h) + boff + n * 2048 + k * 1024); } while (0)
; #define PG8_MMA(ai, bj, At, Bt) do { __builtin_amdgcn_s_setprio(1); _Pragma("unroll") for (int m = 0; m < 4; ++m) _Pragma("unroll") for (int n = 0; n < 2; ++n) _Pragma("unroll") for (int k = 0; k < 2; ++k) \
;         acc[ai][bj][m][n] = __builtin_amdgcn_mfma_f32_16x16x32_bf16(Bt[n][k], At[m][k], acc[ai][bj][m][n], 0, 0, 0); __builtin_amdgcn_s_setprio(0); } while (0)
; #define PG8_WAIT_V(n) asm volatile("s_waitcnt vmcnt(" #n ")" ::: "memory")
; #define PG8_WAIT_L(n) asm volatile("s_waitcnt lgkmcnt(" #n ")" ::: "memory")
; #define PG8_BAR __builtin_amdgcn_s_barrier()
; #define PG8_SCHED __builtin_amdgcn_sched_barrier(0)
; template <class Epi, class Sched>
; __device__ __forceinline__ void gemm_phase(LAS unsigned char* lds, const int K, const int lda, Sched& S, const Epi& E) {
;     ...
;             PG8_STAGE(PG8_SB(0, 1), b2 + hstepB, voffB);
;             PG8_WAIT_V(6); PG8_BAR; PG8_MMA(1, 1, At, B1); PG8_BAR;
;             PG8_LDB(B0, 1, 0); PG8_SCHED; PG8_LDA(At, 1, 0); PG8_STAGE(PG8_SA(0, 1), a2 + hstepA, voffA);
;             PG8_WAIT_L(8); PG8_BAR; PG8_WAIT_L(0); PG8_MMA(0, 0, At, B0); PG8_BAR; PG8_SCHED;
;             PG8_LDB(B1, 1, 1); PG8_STAGE(PG8_SB(1, 0), b3, voffB);
	s_add_u32 s86, s54, 0x80000
	s_addc_u32 s87, s55, 0
	s_add_i32 s88, s68, s59
	v_lshl_add_u64 v[142:143], s[86:87], 0, v[132:133]
	s_mov_b32 m0, s88
	s_nop 0
	global_load_lds_dwordx4 v[142:143], off
	v_lshl_add_u64 v[142:143], s[86:87], 0, v[128:129]
	s_add_i32 m0, s88, 0x2000
	s_nop 0
	global_load_lds_dwordx4 v[142:143], off
	s_waitcnt vmcnt(6)
	s_barrier
	v_mfma_f32_16x16x32_bf16 v[44:47], v[198:201], v[166:169], v[44:47]
	v_mfma_f32_16x16x32_bf16 v[40:43], v[206:209], v[166:169], v[40:43]
	v_mfma_f32_16x16x32_bf16 v[36:39], v[198:201], v[174:177], v[36:39]
	v_mfma_f32_16x16x32_bf16 v[28:31], v[206:209], v[174:177], v[28:31]
	v_mfma_f32_16x16x32_bf16 v[16:19], v[198:201], v[182:185], v[16:19]
	v_mfma_f32_16x16x32_bf16 v[12:15], v[206:209], v[182:185], v[12:15]
	v_mfma_f32_16x16x32_bf16 v[4:7], v[198:201], v[190:193], v[4:7]
	v_mfma_f32_16x16x32_bf16 v[0:3], v[206:209], v[190:193], v[0:3]
	v_mfma_f32_16x16x32_bf16 v[44:47], v[202:205], v[170:173], v[44:47]
	v_mfma_f32_16x16x32_bf16 v[40:43], v[210:213], v[170:173], v[40:43]
	v_mfma_f32_16x16x32_bf16 v[36:39], v[202:205], v[178:181], v[36:39]
	v_mfma_f32_16x16x32_bf16 v[28:31], v[210:213], v[178:181], v[28:31]
	v_mfma_f32_16x16x32_bf16 v[16:19], v[202:205], v[186:189], v[16:19]
	v_mfma_f32_16x16x32_bf16 v[12:15], v[210:213], v[186:189], v[12:15]
	v_mfma_f32_16x16x32_bf16 v[4:7], v[202:205], v[194:197], v[4:7]
	v_mfma_f32_16x16x32_bf16 v[0:3], v[210:213], v[194:197], v[0:3]
	s_add_i32 s86, 0, 0x18000
	v_add_u32_e32 v136, s86, v149
	s_barrier
	ds_read_b128 v[142:145], v136
	ds_read_b128 v[154:157], v136 offset:1024
	ds_read_b128 v[158:161], v136 offset:2048
	ds_read_b128 v[162:165], v136 offset:3072
	s_add_u32 s56, s56, 0x80000
	s_addc_u32 s57, s57, 0
	s_mov_b32 m0, s62
	v_lshl_add_u64 v[198:199], s[56:57], 0, v[134:135]
	ds_read_b128 v[166:169], v152 offset:32768
	ds_read_b128 v[170:173], v152 offset:33792
	ds_read_b128 v[174:177], v152 offset:34816
	ds_read_b128 v[178:181], v152 offset:35840
	ds_read_b128 v[182:185], v152 offset:36864
	ds_read_b128 v[186:189], v152 offset:37888
	ds_read_b128 v[190:193], v152 offset:38912
	ds_read_b128 v[194:197], v152 offset:39936
	global_load_lds_dwordx4 v[198:199], off
	v_lshl_add_u64 v[198:199], s[56:57], 0, v[130:131]
	s_mov_b32 m0, s63
	s_nop 0
	global_load_lds_dwordx4 v[198:199], off
	s_waitcnt lgkmcnt(8)
	s_barrier
	s_waitcnt lgkmcnt(0)
	s_waitcnt lgkmcnt(0)
	v_mfma_f32_16x16x32_bf16 v[124:127], v[142:145], v[166:169], v[124:127]
	v_mfma_f32_16x16x32_bf16 v[120:123], v[158:161], v[166:169], v[120:123]
	v_mfma_f32_16x16x32_bf16 v[116:119], v[142:145], v[174:177], v[116:119]
	v_mfma_f32_16x16x32_bf16 v[112:115], v[158:161], v[174:177], v[112:115]
	v_mfma_f32_16x16x32_bf16 v[104:107], v[142:145], v[182:185], v[104:107]
	v_mfma_f32_16x16x32_bf16 v[96:99], v[158:161], v[182:185], v[96:99]
	v_mfma_f32_16x16x32_bf16 v[80:83], v[142:145], v[190:193], v[80:83]
	v_mfma_f32_16x16x32_bf16 v[72:75], v[158:161], v[190:193], v[72:75]
	v_mfma_f32_16x16x32_bf16 v[124:127], v[154:157], v[170:173], v[124:127]
	v_mfma_f32_16x16x32_bf16 v[120:123], v[162:165], v[170:173], v[120:123]
	v_mfma_f32_16x16x32_bf16 v[116:119], v[154:157], v[178:181], v[116:119]
	v_mfma_f32_16x16x32_bf16 v[112:115], v[162:165], v[178:181], v[112:115]
	v_mfma_f32_16x16x32_bf16 v[104:107], v[154:157], v[186:189], v[104:107]
	v_mfma_f32_16x16x32_bf16 v[96:99], v[162:165], v[186:189], v[96:99]
	v_mfma_f32_16x16x32_bf16 v[80:83], v[154:157], v[194:197], v[80:83]
	v_mfma_f32_16x16x32_bf16 v[72:75], v[162:165], v[194:197], v[72:75]
	s_barrier
	s_add_i32 s56, 0, 0x1c000
	s_add_i32 s57, s86, s59
	v_add_u32_e32 v136, s56, v149
	v_lshl_add_u64 v[146:147], v[146:147], 0, s[0:1]
	s_mov_b32 m0, s57
	ds_read_b128 v[198:201], v136
	ds_read_b128 v[202:205], v136 offset:1024
	ds_read_b128 v[206:209], v136 offset:2048
	ds_read_b128 v[210:213], v136 offset:3072
	global_load_lds_dwordx4 v[146:147], off
	v_lshl_add_u64 v[146:147], v[216:217], 0, s[0:1]
	s_add_i32 m0, s57, 0x2000
	s_nop 0
	global_load_lds_dwordx4 v[146:147], off
	s_barrier
; #define PG8_STAGE(bufoff, gbase, voff) do { _Pragma("unroll") for (int _i = 0; _i < 2; ++_i) \
;         __builtin_amdgcn_global_load_lds((const unsigned*)((const char*)(gbase) + (voff)[_i]), (LAS unsigned*)(lds + (bufoff) + ldsw + _i * 8192), 16, 0, 0); } while (0)
; #define PG8_LDA(dst, b, h) do { _Pragma("unroll") for (int m = 0; m < 4; ++m) _Pragma("unroll") for (int k = 0; k < 2; ++k) dst[m][k] = *(const LAS bf16x8*)(lds + PG8_SA(b, h) + aoff + m * 2048 + k * 1024); } while (0)
; #define PG8_MMA(ai, bj, At, Bt) do { __builtin_amdgcn_s_setprio(1); _Pragma("unroll") for (int m = 0; m < 4; ++m) _Pragma("unroll") for (int n = 0; n < 2; ++n) _Pragma("unroll") for (int k = 0; k < 2; ++k) \
;         acc[ai][bj][m][n] = __builtin_amdgcn_mfma_f32_16x16x32_bf16(Bt[n][k], At[m][k], acc[ai][bj][m][n], 0, 0, 0); __builtin_amdgcn_s_setprio(0); } while (0)
; #define PG8_WAIT_V(n) asm volatile("s_waitcnt vmcnt(" #n ")" ::: "memory")
; #define PG8_WAIT_L(n) asm volatile("s_waitcnt lgkmcnt(" #n ")" ::: "memory")
; #define PG8_BAR __builtin_amdgcn_s_barrier()
; #define PG8_SCHED __builtin_amdgcn_sched_barrier(0)
; template <class Epi, class Sched>
; __device__ __forceinline__ void gemm_phase(LAS unsigned char* lds, const int K, const int lda, Sched& S, const Epi& E) {
;     ...
;             PG8_BAR; PG8_WAIT_L(0); PG8_MMA(0, 1, At, B1); PG8_BAR;
;             PG8_LDA(At, 1, 1); PG8_STAGE(PG8_SA(1, 0), a3, voffA);
;             PG8_BAR; PG8_WAIT_L(0); PG8_MMA(1, 0, At, B0); PG8_BAR; PG8_SCHED;
;             PG8_STAGE(PG8_SB(1, 1), b3 + hstepB, voffB);
;             PG8_WAIT_V(6); PG8_BAR; PG8_MMA(1, 1, At, B1); PG8_BAR;
;     __device__ __forceinline__ void operator()(f32x4 (&acc)[2][2][4][2], const Unit& u, int wr, int wc, int fr, int fq) const {
;         const int r0 = u.pm * 256 + wr * 64 + fr, c0 = u.pn * 256 + wc * 32 + 8 * fq;
;         const float* src = (r0 < MP ? xp + (size_t)r0 * D : xs + (size_t)(r0 - MP) * D) + c0;
;         float* dst = out + (size_t)r0 * D + c0;
	s_waitcnt lgkmcnt(0)
	s_waitcnt lgkmcnt(0)
	v_mfma_f32_16x16x32_bf16 v[108:111], v[198:201], v[166:169], v[108:111]
	v_mfma_f32_16x16x32_bf16 v[100:103], v[206:209], v[166:169], v[100:103]
	v_mfma_f32_16x16x32_bf16 v[92:95], v[198:201], v[174:177], v[92:95]
	v_mfma_f32_16x16x32_bf16 v[88:91], v[206:209], v[174:177], v[88:91]
	v_mfma_f32_16x16x32_bf16 v[84:87], v[198:201], v[182:185], v[84:87]
	v_mfma_f32_16x16x32_bf16 v[76:79], v[206:209], v[182:185], v[76:79]
	v_mfma_f32_16x16x32_bf16 v[68:71], v[198:201], v[190:193], v[68:71]
	v_mfma_f32_16x16x32_bf16 v[64:67], v[206:209], v[190:193], v[64:67]
	v_mfma_f32_16x16x32_bf16 v[108:111], v[202:205], v[170:173], v[108:111]
	v_mfma_f32_16x16x32_bf16 v[100:103], v[210:213], v[170:173], v[100:103]
	v_mfma_f32_16x16x32_bf16 v[92:95], v[202:205], v[178:181], v[92:95]
	v_mfma_f32_16x16x32_bf16 v[88:91], v[210:213], v[178:181], v[88:91]
	v_mfma_f32_16x16x32_bf16 v[84:87], v[202:205], v[186:189], v[84:87]
	v_mfma_f32_16x16x32_bf16 v[76:79], v[210:213], v[186:189], v[76:79]
	v_mfma_f32_16x16x32_bf16 v[68:71], v[202:205], v[194:197], v[68:71]
	v_mfma_f32_16x16x32_bf16 v[64:67], v[210:213], v[194:197], v[64:67]
	s_mov_b32 m0, s64
	v_lshl_add_u64 v[146:147], v[218:219], 0, s[0:1]
	s_barrier
	ds_read_b128 v[166:169], v152 offset:49152
	ds_read_b128 v[170:173], v152 offset:50176
	ds_read_b128 v[174:177], v152 offset:51200
	ds_read_b128 v[178:181], v152 offset:52224
	ds_read_b128 v[182:185], v152 offset:53248
	ds_read_b128 v[186:189], v152 offset:54272
	ds_read_b128 v[190:193], v152 offset:55296
	ds_read_b128 v[194:197], v152 offset:56320
	global_load_lds_dwordx4 v[146:147], off
	v_lshl_add_u64 v[146:147], v[220:221], 0, s[0:1]
	s_mov_b32 m0, s65
	s_nop 0
	global_load_lds_dwordx4 v[146:147], off
	s_barrier
	s_waitcnt lgkmcnt(0)
	s_waitcnt lgkmcnt(0)
	v_mfma_f32_16x16x32_bf16 v[60:63], v[142:145], v[166:169], v[60:63]
	v_mfma_f32_16x16x32_bf16 v[56:59], v[158:161], v[166:169], v[56:59]
	v_mfma_f32_16x16x32_bf16 v[52:55], v[142:145], v[174:177], v[52:55]
	v_mfma_f32_16x16x32_bf16 v[48:51], v[158:161], v[174:177], v[48:51]
	v_mfma_f32_16x16x32_bf16 v[32:35], v[142:145], v[182:185], v[32:35]
	v_mfma_f32_16x16x32_bf16 v[24:27], v[158:161], v[182:185], v[24:27]
	v_mfma_f32_16x16x32_bf16 v[20:23], v[142:145], v[190:193], v[20:23]
	v_mfma_f32_16x16x32_bf16 v[8:11], v[158:161], v[190:193], v[8:11]
	v_mfma_f32_16x16x32_bf16 v[60:63], v[154:157], v[170:173], v[60:63]
	v_mfma_f32_16x16x32_bf16 v[56:59], v[162:165], v[170:173], v[56:59]
	v_mfma_f32_16x16x32_bf16 v[52:55], v[154:157], v[178:181], v[52:55]
	v_mfma_f32_16x16x32_bf16 v[48:51], v[162:165], v[178:181], v[48:51]
	v_mfma_f32_16x16x32_bf16 v[32:35], v[154:157], v[186:189], v[32:35]
	v_mfma_f32_16x16x32_bf16 v[24:27], v[162:165], v[186:189], v[24:27]
	v_mfma_f32_16x16x32_bf16 v[20:23], v[154:157], v[194:197], v[20:23]
	v_mfma_f32_16x16x32_bf16 v[8:11], v[162:165], v[194:197], v[8:11]
	s_barrier
	s_add_u32 s54, s54, 0x80080
	s_addc_u32 s55, s55, 0
	s_add_i32 s56, s56, s59
	v_lshl_add_u64 v[142:143], s[54:55], 0, v[132:133]
	s_mov_b32 m0, s56
	s_nop 0
	global_load_lds_dwordx4 v[142:143], off
	v_lshl_add_u64 v[142:143], s[54:55], 0, v[128:129]
	s_add_i32 m0, s56, 0x2000
	s_nop 0
	global_load_lds_dwordx4 v[142:143], off
	s_waitcnt vmcnt(6)
	s_barrier
	v_mfma_f32_16x16x32_bf16 v[44:47], v[198:201], v[166:169], v[44:47]
	v_mfma_f32_16x16x32_bf16 v[40:43], v[206:209], v[166:169], v[40:43]
	v_mfma_f32_16x16x32_bf16 v[36:39], v[198:201], v[174:177], v[36:39]
	v_mfma_f32_16x16x32_bf16 v[28:31], v[206:209], v[174:177], v[28:31]
	v_mfma_f32_16x16x32_bf16 v[16:19], v[198:201], v[182:185], v[16:19]
	v_mfma_f32_16x16x32_bf16 v[12:15], v[206:209], v[182:185], v[12:15]
	v_mfma_f32_16x16x32_bf16 v[4:7], v[198:201], v[190:193], v[4:7]
	v_mfma_f32_16x16x32_bf16 v[0:3], v[206:209], v[190:193], v[0:3]
	v_mfma_f32_16x16x32_bf16 v[44:47], v[202:205], v[170:173], v[44:47]
	v_mfma_f32_16x16x32_bf16 v[40:43], v[210:213], v[170:173], v[40:43]
	v_mfma_f32_16x16x32_bf16 v[36:39], v[202:205], v[178:181], v[36:39]
	v_mfma_f32_16x16x32_bf16 v[28:31], v[210:213], v[178:181], v[28:31]
	v_mfma_f32_16x16x32_bf16 v[16:19], v[202:205], v[186:189], v[16:19]
	v_mfma_f32_16x16x32_bf16 v[12:15], v[210:213], v[186:189], v[12:15]
	v_mfma_f32_16x16x32_bf16 v[4:7], v[202:205], v[194:197], v[4:7]
	v_mfma_f32_16x16x32_bf16 v[0:3], v[210:213], v[194:197], v[0:3]
	s_add_i32 s85, s85, 2
	s_add_u32 s52, s52, 0x100
	s_addc_u32 s53, s53, 0
	s_add_u32 s51, s51, 0x100
	s_addc_u32 s84, s84, 0
	s_cmp_gt_u32 s85, 29
	s_barrier
	s_cbranch_scc0 .LBB0_4559
	v_lshl_add_u32 v146, s50, 8, v148
	v_cmp_lt_i32_e32 vcc, s69, v146
	s_and_saveexec_b64 s[4:5], vcc
	s_xor_b64 s[50:51], exec, s[4:5]
	v_add_u32_e32 v136, 0xffffc000, v146
	v_lshlrev_b64 v[142:143], 13, v[136:137]
	v_mov_b32_e32 v147, v137
	v_lshl_add_u64 v[144:145], s[16:17], 0, v[142:143]
	v_lshlrev_b64 v[142:143], 13, v[146:147]
	s_andn2_saveexec_b64 s[50:51], s[50:51]
	s_cbranch_execz .LBB0_4555
	v_ashrrev_i32_e32 v147, 31, v146
	v_lshlrev_b64 v[142:143], 13, v[146:147]
	v_lshl_add_u64 v[144:145], s[72:73], 0, v[142:143]
	s_branch .LBB0_4555
.LBB0_4564:
	s_waitcnt vmcnt(0)
	s_setprio 0
	s_nop 0
	s_nop 0
	s_nop 0
	s_nop 0
	s_nop 0
	s_nop 0
	s_nop 0
	s_cmpk_gt_u32 s58, 0xff
	s_cbranch_scc1 .LBB0_4566
	s_barrier
